# GEMM phases: per-cluster s_setprio flips removed, one static s_setprio 1 for waves 4-7 per phase
# speedup vs baseline: 1.0442x; 1.0026x over previous
; #define PG8_LAS __attribute__((address_space(3)))
; #define PG8_STAGE(bufoff, gbase, voff) do { _Pragma("unroll") for (int _i = 0; _i < 2; ++_i) \
;         __builtin_amdgcn_global_load_lds((const unsigned*)((const char*)(gbase) + (voff)[_i]), (PG8_LAS unsigned*)(lds + (bufoff) + ldsw + _i * 8192), 16, 0, 0); } while (0)
; #define PG8_WAIT_V(n) asm volatile("s_waitcnt vmcnt(" #n ")" ::: "memory")
; template <class Epi, class Sched>
; __device__ __forceinline__ void gemm_phase(PG8_LAS unsigned char* lds, const Gemm g, const Sched& S, const Epi& E) {
;     int tid = threadIdx.x; asm volatile("" : "+v"(tid));
;     const int wid = __builtin_amdgcn_readfirstlane(tid >> 6), lane = tid & 63, wr = wid >> 2, wc = wid & 3, fr = lane & 15, fq = lane >> 4;
;     const int K = g.K, nt = K / BK;
;     unsigned voffA[2], voffB[2];
; #pragma unroll
;     for (int i = 0; i < 2; ++i) { int R, C; stage_rc(tid * 16 + i * 8192, R, C); const int Rb = Epi::PERM ? ((R & ~31) + perm32(R & 31)) : R;
;         voffA[i] = (unsigned)(R * K + C) * 2u; voffB[i] = (unsigned)(Rb * K + C) * 2u; }
;     const size_t kstep = (size_t)(BK * 2);
;     const size_t hstep = (size_t)HALF * K * 2;
;     const size_t tstep = 2 * hstep;
;     const unsigned ldsw = (unsigned)wid * 1024u;
;     const int aoff = lds_byte(wr * 64 + fr, fq * 8), boff = lds_byte(wc * 32 + fr, fq * 8);
;     ...
;     Unit cur, nxt; int ui = 0;
;     if (!S.next(0, cur)) return;
;     f32x4 acc[2][2][4][2];
; #pragma unroll
;     for (int a = 0; a < 2; ++a)
; #pragma unroll
;         for (int b = 0; b < 2; ++b)
; #pragma unroll
;             for (int m = 0; m < 4; ++m)
; #pragma unroll
;                 for (int n = 0; n < 2; ++n) acc[a][b][m][n] = (f32x4){0.f, 0.f, 0.f, 0.f};
;     bf16x8 At[4][2], B0[2][2], B1[2][2];
;     const char* cA = (const char*)g.A + (size_t)cur.pm * tstep; const char* cB = (const char*)g.Bt + (size_t)cur.pn * tstep;
;     float epre[Epi::NPRE]; E.preload(cur, wr, fr, epre);
;     S.a_ready(cur);
;     PG8_STAGE(PG8_SB(0, 0), cB, voffB); PG8_STAGE(PG8_SA(0, 0), cA, voffA); PG8_STAGE(PG8_SB(0, 1), cB + hstep, voffB); PG8_STAGE(PG8_SA(0, 1), cA + hstep, voffA);
;     if (wr == 1) PG8_BAR;
;     PG8_WAIT_V(4); PG8_BAR;
;     PG8_STAGE(PG8_SB(1, 0), cB + kstep, voffB); PG8_STAGE(PG8_SA(1, 0), cA + kstep, voffA); PG8_STAGE(PG8_SB(1, 1), cB + hstep + kstep, voffB);
;     PG8_WAIT_V(6); PG8_BAR;
.LBB0_144:
	s_add_u32 s82, s64, 0x96f5e00
	s_addc_u32 s83, s65, 0
	s_add_u32 s84, s64, 0x2375e00
	s_addc_u32 s85, s65, 0
	s_add_u32 s80, s64, 0x33f5e00
	s_addc_u32 s81, s65, 0
	s_add_u32 s10, s64, 0x6575e00
	s_addc_u32 s11, s65, 0
	v_writelane_b32 v247, s10, 36
	s_add_u32 s90, s64, 0x75f5e00
	s_addc_u32 s91, s65, 0
	v_writelane_b32 v247, s11, 37
	v_writelane_b32 v247, s64, 38
	s_andn2_b64 vcc, exec, s[4:5]
	s_nop 0
	v_writelane_b32 v247, s65, 39
	v_writelane_b32 v247, s66, 40
	v_writelane_b32 v247, s67, 41
	s_cbranch_vccnz .LBB0_261
	v_ashrrev_i32_e32 v1, 31, v8
	v_lshrrev_b32_e32 v1, 26, v1
	v_add_u32_e32 v1, v8, v1
	v_ashrrev_i32_e32 v9, 6, v1
	v_bfe_i32 v1, v8, 27, 1
	v_lshlrev_b32_e32 v0, 4, v8
	v_lshrrev_b32_e32 v1, 22, v1
	v_add_u32_e32 v1, v0, v1
	v_and_b32_e32 v1, 0xfffffc00, v1
	v_sub_u32_e32 v1, v0, v1
	v_lshrrev_b32_e32 v2, 4, v1
	v_bitop3_b32 v1, v2, v1, 32 bitop3:0x6c
	v_ashrrev_i32_e32 v3, 31, v1
	v_lshrrev_b32_e32 v3, 26, v3
	v_add_u32_e32 v3, v1, v3
	v_lshlrev_b32_e32 v2, 3, v9
	v_ashrrev_i32_e32 v10, 6, v3
	v_and_b32_e32 v3, 0xc0, v3
	v_and_b32_e32 v2, -16, v2
	v_sub_u32_e32 v1, v1, v3
	v_mov_b32_e32 v3, 1
	v_add_u32_e32 v2, v10, v2
	v_ashrrev_i16_sdwa v1, v3, sext(v1) dst_sel:DWORD dst_unused:UNUSED_PAD src0_sel:DWORD src1_sel:BYTE_0
	v_lshlrev_b32_e32 v4, 5, v9
	v_bfe_i32 v11, v1, 0, 16
	v_lshlrev_b32_e32 v1, 1, v2
	v_lshrrev_b32_e32 v5, 2, v2
	v_and_b32_e32 v6, 3, v10
	s_mov_b32 s1, 0x1fffe0
	v_and_b32_e32 v4, 32, v4
	v_and_b32_e32 v1, 24, v1
	v_and_b32_e32 v5, 4, v5
	v_and_or_b32 v6, v2, s1, v6
	v_or3_b32 v1, v6, v5, v1
	v_add_lshl_u32 v4, v4, v11, 1
	v_add_u32_e32 v0, 0x2000, v0
	v_lshl_add_u32 v138, v1, 11, v4
	v_ashrrev_i32_e32 v1, 31, v0
	v_lshrrev_b32_e32 v1, 22, v1
	v_add_u32_e32 v1, v0, v1
	v_ashrrev_i32_e32 v12, 10, v1
	v_mul_i32_i24_e32 v1, 0x400, v12
	v_sub_u32_e32 v0, v0, v1
	v_lshrrev_b32_e32 v1, 4, v0
	v_bitop3_b32 v0, v1, v0, 32 bitop3:0x6c
	v_lshl_add_u32 v136, v2, 11, v4
	v_ashrrev_i32_e32 v2, 31, v0
	v_lshrrev_b32_e32 v2, 26, v2
	v_add_u32_e32 v2, v0, v2
	v_lshlrev_b32_e32 v1, 3, v12
	v_ashrrev_i32_e32 v13, 6, v2
	v_and_b32_e32 v2, 0xc0, v2
	v_and_b32_e32 v1, -16, v1
	v_sub_u32_e32 v0, v0, v2
	v_add_u32_e32 v1, v13, v1
	v_ashrrev_i16_sdwa v0, v3, sext(v0) dst_sel:DWORD dst_unused:UNUSED_PAD src0_sel:DWORD src1_sel:BYTE_0
	v_and_b32_e32 v3, 3, v13
	s_ashr_i32 s5, s0, 6
	s_ashr_i32 s7, s6, 31
	s_ashr_i32 s29, s28, 31
	s_ashr_i32 s4, s0, 8
	v_and_or_b32 v3, v1, s1, v3
	s_lshl_b32 s1, s5, 10
	s_lshl_b64 s[10:11], s[6:7], 19
	s_lshl_b64 s[12:13], s[28:29], 19
	s_add_u32 s34, s64, s12
	v_lshlrev_b32_e32 v4, 5, v12
	v_bfe_i32 v14, v0, 0, 16
	v_lshlrev_b32_e32 v0, 1, v1
	v_lshrrev_b32_e32 v2, 2, v1
	s_addc_u32 s35, s65, s13
	s_add_i32 s3, s1, 0
	v_and_b32_e32 v4, 32, v4
	v_and_b32_e32 v0, 24, v0
	v_and_b32_e32 v2, 4, v2
	s_add_i32 m0, s3, 0x10000
	v_or3_b32 v0, v3, v2, v0
	v_add_lshl_u32 v2, v4, v14, 1
	global_load_lds_dwordx4 v138, s[34:35]
	s_add_i32 m0, s3, 0x12000
	v_lshl_add_u32 v142, v0, 11, v2
	s_add_u32 s30, s82, s10
	global_load_lds_dwordx4 v142, s[34:35]
	s_addc_u32 s31, s83, s11
	s_mov_b32 m0, s3
	s_add_i32 s33, s3, 0x2000
	v_lshl_add_u32 v140, v1, 11, v2
	global_load_lds_dwordx4 v136, s[30:31]
	s_mov_b32 m0, s33
	s_add_u32 s10, s34, 0x40000
	global_load_lds_dwordx4 v140, s[30:31]
	s_addc_u32 s11, s35, 0
	s_add_i32 m0, s3, 0x14000
	v_mov_b32_e32 v145, 0
	global_load_lds_dwordx4 v138, s[10:11]
	s_add_i32 m0, s3, 0x16000
	v_mov_b32_e32 v139, v145
	global_load_lds_dwordx4 v142, s[10:11]
	s_add_u32 s10, s30, 0x40000
	s_addc_u32 s11, s31, 0
	s_add_i32 s38, s3, 0x4000
	s_mov_b32 m0, s38
	s_add_i32 s39, s3, 0x6000
	global_load_lds_dwordx4 v136, s[10:11]
	s_mov_b32 m0, s39
	v_mov_b32_e32 v143, v145
	global_load_lds_dwordx4 v140, s[10:11]
	v_mov_b32_e32 v137, v145
	v_mov_b32_e32 v141, v145
	s_mov_b32 s40, 0
	v_lshl_add_u64 v[6:7], s[34:35], 0, v[138:139]
	v_lshl_add_u64 v[4:5], s[34:35], 0, v[142:143]
	v_lshl_add_u64 v[2:3], s[30:31], 0, v[136:137]
	s_cmp_lg_u32 s4, 1
	v_lshl_add_u64 v[0:1], s[30:31], 0, v[140:141]
	s_cbranch_scc1 .LBB0_147
	s_barrier
	s_setprio 1

; #define PG8_STAGE(bufoff, gbase, voff) do { _Pragma("unroll") for (int _i = 0; _i < 2; ++_i) \
;         __builtin_amdgcn_global_load_lds((const unsigned*)((const char*)(gbase) + (voff)[_i]), (PG8_LAS unsigned*)(lds + (bufoff) + ldsw + _i * 8192), 16, 0, 0); } while (0)
; #define PG8_LDA(dst, b, h) do { _Pragma("unroll") for (int m = 0; m < 4; ++m) _Pragma("unroll") for (int k = 0; k < 2; ++k) dst[m][k] = *(const PG8_LAS bf16x8*)(lds + PG8_SA(b, h) + aoff + m * 2048 + k * 1024); } while (0)
; #define PG8_LDB(dst, b, h) do { _Pragma("unroll") for (int n = 0; n < 2; ++n) _Pragma("unroll") for (int k = 0; k < 2; ++k) dst[n][k] = *(const PG8_LAS bf16x8*)(lds + PG8_SB(b, h) + boff + n * 2048 + k * 1024); } while (0)
; #define PG8_MMA(ai, bj, At, Bt) do { __builtin_amdgcn_s_setprio(1); _Pragma("unroll") for (int m = 0; m < 4; ++m) _Pragma("unroll") for (int n = 0; n < 2; ++n) _Pragma("unroll") for (int k = 0; k < 2; ++k) \
;         acc[ai][bj][m][n] = __builtin_amdgcn_mfma_f32_16x16x32_bf16(Bt[n][k], At[m][k], acc[ai][bj][m][n], 0, 0, 0); __builtin_amdgcn_s_setprio(0); } while (0)
; #define PG8_WAIT_L(n) asm volatile("s_waitcnt lgkmcnt(" #n ")" ::: "memory")
; #define PG8_BAR __builtin_amdgcn_s_barrier()
; #define PG8_SCHED __builtin_amdgcn_sched_barrier(0)
; template <class Epi, class Sched>
; __device__ __forceinline__ void gemm_phase(PG8_LAS unsigned char* lds, const Gemm g, const Sched& S, const Epi& E) {
;     ...
;             PG8_LDB(B0, 0, 0); PG8_SCHED; PG8_LDA(At, 0, 0); PG8_STAGE(PG8_SA(1, 1), a1 + hstep, voffA);
;             PG8_WAIT_L(8); PG8_BAR; PG8_WAIT_L(0); PG8_MMA(0, 0, At, B0); PG8_BAR; PG8_SCHED;
;             PG8_LDB(B1, 0, 1); PG8_STAGE(PG8_SB(0, 0), b2, voffB);
;             PG8_BAR; PG8_WAIT_L(0); PG8_MMA(0, 1, At, B1); PG8_BAR;
;             PG8_LDA(At, 0, 1); PG8_STAGE(PG8_SA(0, 0), a2, voffA);
;             PG8_BAR; PG8_WAIT_L(0); PG8_MMA(1, 0, At, B0); PG8_BAR; PG8_SCHED;
.LBB0_152:
	ds_read_b128 v[128:131], v167
	ds_read_b128 v[132:135], v167 offset:1024
	ds_read_b128 v[156:159], v167 offset:2048
	ds_read_b128 v[160:163], v167 offset:3072
	s_add_u32 s34, s30, 0xfffc0080
	s_addc_u32 s35, s31, -1
	s_cmp_eq_u32 s50, 12
	s_cselect_b32 s37, s7, s35
	s_cselect_b32 s36, s23, s34
	s_cselect_b32 s35, s21, s49
	s_cselect_b32 s34, s29, s48
	v_lshl_add_u64 v[204:205], s[30:31], 0, v[148:149]
	s_add_i32 m0, s3, 0xc000
	ds_read_b128 v[172:175], v168
	ds_read_b128 v[180:183], v168 offset:1024
	ds_read_b128 v[184:187], v168 offset:2048
	ds_read_b128 v[188:191], v168 offset:3072
	ds_read_b128 v[192:195], v168 offset:4096
	ds_read_b128 v[196:199], v168 offset:5120
	ds_read_b128 v[200:203], v168 offset:6144
	ds_read_b128 v[208:211], v168 offset:7168
	global_load_lds_dwordx4 v[204:205], off
	v_lshl_add_u64 v[204:205], s[30:31], 0, v[150:151]
	s_add_i32 m0, s3, 0xe000
	s_nop 0
	global_load_lds_dwordx4 v[204:205], off
	s_waitcnt lgkmcnt(8)
	s_barrier
	s_waitcnt lgkmcnt(0)
	s_waitcnt lgkmcnt(0)
	v_mfma_f32_16x16x32_bf16 v[124:127], v[128:131], v[172:175], v[124:127]
	v_mfma_f32_16x16x32_bf16 v[120:123], v[156:159], v[172:175], v[120:123]
	v_mfma_f32_16x16x32_bf16 v[108:111], v[128:131], v[184:187], v[108:111]
	v_mfma_f32_16x16x32_bf16 v[104:107], v[156:159], v[184:187], v[104:107]
	v_mfma_f32_16x16x32_bf16 v[92:95], v[128:131], v[192:195], v[92:95]
	v_mfma_f32_16x16x32_bf16 v[88:91], v[156:159], v[192:195], v[88:91]
	v_mfma_f32_16x16x32_bf16 v[76:79], v[128:131], v[200:203], v[76:79]
	v_mfma_f32_16x16x32_bf16 v[72:75], v[156:159], v[200:203], v[72:75]
	v_mfma_f32_16x16x32_bf16 v[124:127], v[132:135], v[180:183], v[124:127]
	v_mfma_f32_16x16x32_bf16 v[120:123], v[160:163], v[180:183], v[120:123]
	v_mfma_f32_16x16x32_bf16 v[108:111], v[132:135], v[188:191], v[108:111]
	v_mfma_f32_16x16x32_bf16 v[104:107], v[160:163], v[188:191], v[104:107]
	v_mfma_f32_16x16x32_bf16 v[92:95], v[132:135], v[196:199], v[92:95]
	v_mfma_f32_16x16x32_bf16 v[88:91], v[160:163], v[196:199], v[88:91]
	v_mfma_f32_16x16x32_bf16 v[76:79], v[132:135], v[208:211], v[76:79]
	v_mfma_f32_16x16x32_bf16 v[72:75], v[160:163], v[208:211], v[72:75]
	s_barrier
	s_add_i32 s51, s45, s1
	v_lshl_add_u64 v[204:205], s[34:35], 0, v[138:139]
	s_mov_b32 m0, s51
	ds_read_b128 v[212:215], v169
	ds_read_b128 v[216:219], v169 offset:1024
	ds_read_b128 v[220:223], v169 offset:2048
	ds_read_b128 v[224:227], v169 offset:3072
	global_load_lds_dwordx4 v[204:205], off
	v_lshl_add_u64 v[228:229], s[34:35], 0, v[142:143]
	s_add_i32 m0, s51, 0x2000
	s_nop 0
	global_load_lds_dwordx4 v[228:229], off
	s_barrier
	s_waitcnt lgkmcnt(0)
	s_waitcnt lgkmcnt(0)
	v_mfma_f32_16x16x32_bf16 v[116:119], v[212:215], v[172:175], v[116:119]
	v_mfma_f32_16x16x32_bf16 v[112:115], v[220:223], v[172:175], v[112:115]
	v_mfma_f32_16x16x32_bf16 v[100:103], v[212:215], v[184:187], v[100:103]
	v_mfma_f32_16x16x32_bf16 v[96:99], v[220:223], v[184:187], v[96:99]
	v_mfma_f32_16x16x32_bf16 v[84:87], v[212:215], v[192:195], v[84:87]
	v_mfma_f32_16x16x32_bf16 v[80:83], v[220:223], v[192:195], v[80:83]
	v_mfma_f32_16x16x32_bf16 v[68:71], v[212:215], v[200:203], v[68:71]
	v_mfma_f32_16x16x32_bf16 v[64:67], v[220:223], v[200:203], v[64:67]
	v_mfma_f32_16x16x32_bf16 v[116:119], v[216:219], v[180:183], v[116:119]
	v_mfma_f32_16x16x32_bf16 v[112:115], v[224:227], v[180:183], v[112:115]
	v_mfma_f32_16x16x32_bf16 v[100:103], v[216:219], v[188:191], v[100:103]
	v_mfma_f32_16x16x32_bf16 v[96:99], v[224:227], v[188:191], v[96:99]
	v_mfma_f32_16x16x32_bf16 v[84:87], v[216:219], v[196:199], v[84:87]
	v_mfma_f32_16x16x32_bf16 v[80:83], v[224:227], v[196:199], v[80:83]
	v_mfma_f32_16x16x32_bf16 v[68:71], v[216:219], v[208:211], v[68:71]
	v_mfma_f32_16x16x32_bf16 v[64:67], v[224:227], v[208:211], v[64:67]
	s_mov_b32 m0, s3
	v_lshl_add_u64 v[230:231], s[36:37], 0, v[136:137]
	s_barrier
	ds_read_b128 v[172:175], v168 offset:16384
	ds_read_b128 v[180:183], v168 offset:17408
	ds_read_b128 v[184:187], v168 offset:18432
	ds_read_b128 v[188:191], v168 offset:19456
	ds_read_b128 v[192:195], v168 offset:20480
	ds_read_b128 v[196:199], v168 offset:21504
	ds_read_b128 v[200:203], v168 offset:22528
	ds_read_b128 v[208:211], v168 offset:23552
	global_load_lds_dwordx4 v[230:231], off
	v_lshl_add_u64 v[232:233], s[36:37], 0, v[140:141]
	s_mov_b32 m0, s33
	s_nop 0
	global_load_lds_dwordx4 v[232:233], off
	s_barrier
	s_waitcnt lgkmcnt(0)
	s_waitcnt lgkmcnt(0)
	v_mfma_f32_16x16x32_bf16 v[60:63], v[128:131], v[172:175], v[60:63]
	v_mfma_f32_16x16x32_bf16 v[56:59], v[156:159], v[172:175], v[56:59]
	v_mfma_f32_16x16x32_bf16 v[44:47], v[128:131], v[184:187], v[44:47]
	v_mfma_f32_16x16x32_bf16 v[40:43], v[156:159], v[184:187], v[40:43]
	v_mfma_f32_16x16x32_bf16 v[28:31], v[128:131], v[192:195], v[28:31]
	v_mfma_f32_16x16x32_bf16 v[24:27], v[156:159], v[192:195], v[24:27]
	v_mfma_f32_16x16x32_bf16 v[12:15], v[128:131], v[200:203], v[12:15]
	v_mfma_f32_16x16x32_bf16 v[8:11], v[156:159], v[200:203], v[8:11]
	v_mfma_f32_16x16x32_bf16 v[60:63], v[132:135], v[180:183], v[60:63]
	v_mfma_f32_16x16x32_bf16 v[56:59], v[160:163], v[180:183], v[56:59]
	v_mfma_f32_16x16x32_bf16 v[44:47], v[132:135], v[188:191], v[44:47]
	v_mfma_f32_16x16x32_bf16 v[40:43], v[160:163], v[188:191], v[40:43]
	v_mfma_f32_16x16x32_bf16 v[28:31], v[132:135], v[196:199], v[28:31]
	v_mfma_f32_16x16x32_bf16 v[24:27], v[160:163], v[196:199], v[24:27]
	v_mfma_f32_16x16x32_bf16 v[12:15], v[132:135], v[208:211], v[12:15]
	v_mfma_f32_16x16x32_bf16 v[8:11], v[160:163], v[208:211], v[8:11]
	s_barrier
; #define PG8_STAGE(bufoff, gbase, voff) do { _Pragma("unroll") for (int _i = 0; _i < 2; ++_i) \
;         __builtin_amdgcn_global_load_lds((const unsigned*)((const char*)(gbase) + (voff)[_i]), (PG8_LAS unsigned*)(lds + (bufoff) + ldsw + _i * 8192), 16, 0, 0); } while (0)
; #define PG8_LDA(dst, b, h) do { _Pragma("unroll") for (int m = 0; m < 4; ++m) _Pragma("unroll") for (int k = 0; k < 2; ++k) dst[m][k] = *(const PG8_LAS bf16x8*)(lds + PG8_SA(b, h) + aoff + m * 2048 + k * 1024); } while (0)
; #define PG8_LDB(dst, b, h) do { _Pragma("unroll") for (int n = 0; n < 2; ++n) _Pragma("unroll") for (int k = 0; k < 2; ++k) dst[n][k] = *(const PG8_LAS bf16x8*)(lds + PG8_SB(b, h) + boff + n * 2048 + k * 1024); } while (0)
; #define PG8_MMA(ai, bj, At, Bt) do { __builtin_amdgcn_s_setprio(1); _Pragma("unroll") for (int m = 0; m < 4; ++m) _Pragma("unroll") for (int n = 0; n < 2; ++n) _Pragma("unroll") for (int k = 0; k < 2; ++k) \
;         acc[ai][bj][m][n] = __builtin_amdgcn_mfma_f32_16x16x32_bf16(Bt[n][k], At[m][k], acc[ai][bj][m][n], 0, 0, 0); __builtin_amdgcn_s_setprio(0); } while (0)
; #define PG8_WAIT_V(n) asm volatile("s_waitcnt vmcnt(" #n ")" ::: "memory")
; #define PG8_WAIT_L(n) asm volatile("s_waitcnt lgkmcnt(" #n ")" ::: "memory")
; #define PG8_BAR __builtin_amdgcn_s_barrier()
; #define PG8_SCHED __builtin_amdgcn_sched_barrier(0)
; template <class Epi, class Sched>
; __device__ __forceinline__ void gemm_phase(PG8_LAS unsigned char* lds, const Gemm g, const Sched& S, const Epi& E) {
;     ...
;             PG8_STAGE(PG8_SB(0, 1), b2 + hstep, voffB);
;             PG8_WAIT_V(6); PG8_BAR; PG8_MMA(1, 1, At, B1); PG8_BAR;
;             PG8_LDB(B0, 1, 0); PG8_SCHED; PG8_LDA(At, 1, 0); PG8_STAGE(PG8_SA(0, 1), a2 + hstep, voffA);
;             PG8_WAIT_L(8); PG8_BAR; PG8_WAIT_L(0); PG8_MMA(0, 0, At, B0); PG8_BAR; PG8_SCHED;
;             PG8_LDB(B1, 1, 1); PG8_STAGE(PG8_SB(1, 0), b3, voffB);
;             PG8_BAR; PG8_WAIT_L(0); PG8_MMA(0, 1, At, B1); PG8_BAR;
	s_add_u32 s64, s34, 0x40000
	s_addc_u32 s65, s35, 0
	s_add_i32 s51, s46, s1
	v_lshl_add_u64 v[128:129], s[64:65], 0, v[138:139]
	s_mov_b32 m0, s51
	s_nop 0
	global_load_lds_dwordx4 v[128:129], off
	v_lshl_add_u64 v[128:129], s[64:65], 0, v[142:143]
	s_add_i32 m0, s51, 0x2000
	s_nop 0
	global_load_lds_dwordx4 v[128:129], off
	s_waitcnt vmcnt(6)
	s_barrier
	v_mfma_f32_16x16x32_bf16 v[52:55], v[212:215], v[172:175], v[52:55]
	v_mfma_f32_16x16x32_bf16 v[48:51], v[220:223], v[172:175], v[48:51]
	v_mfma_f32_16x16x32_bf16 v[36:39], v[212:215], v[184:187], v[36:39]
	v_mfma_f32_16x16x32_bf16 v[32:35], v[220:223], v[184:187], v[32:35]
	v_mfma_f32_16x16x32_bf16 v[20:23], v[212:215], v[192:195], v[20:23]
	v_mfma_f32_16x16x32_bf16 v[16:19], v[220:223], v[192:195], v[16:19]
	v_mfma_f32_16x16x32_bf16 v[4:7], v[212:215], v[200:203], v[4:7]
	v_mfma_f32_16x16x32_bf16 v[0:3], v[220:223], v[200:203], v[0:3]
	v_mfma_f32_16x16x32_bf16 v[52:55], v[216:219], v[180:183], v[52:55]
	v_mfma_f32_16x16x32_bf16 v[48:51], v[224:227], v[180:183], v[48:51]
	v_mfma_f32_16x16x32_bf16 v[36:39], v[216:219], v[188:191], v[36:39]
	v_mfma_f32_16x16x32_bf16 v[32:35], v[224:227], v[188:191], v[32:35]
	v_mfma_f32_16x16x32_bf16 v[20:23], v[216:219], v[196:199], v[20:23]
	v_mfma_f32_16x16x32_bf16 v[16:19], v[224:227], v[196:199], v[16:19]
	v_mfma_f32_16x16x32_bf16 v[4:7], v[216:219], v[208:211], v[4:7]
	v_mfma_f32_16x16x32_bf16 v[0:3], v[224:227], v[208:211], v[0:3]
	s_add_i32 s51, 0, 0x18000
	v_add_u32_e32 v144, s51, v164
	s_barrier
	ds_read_b128 v[128:131], v144
	ds_read_b128 v[132:135], v144 offset:1024
	ds_read_b128 v[156:159], v144 offset:2048
	ds_read_b128 v[160:163], v144 offset:3072
	s_add_u32 s36, s36, 0x40000
	s_addc_u32 s37, s37, 0
	s_mov_b32 m0, s38
	v_lshl_add_u64 v[212:213], s[36:37], 0, v[136:137]
	ds_read_b128 v[172:175], v168 offset:32768
	ds_read_b128 v[180:183], v168 offset:33792
	ds_read_b128 v[184:187], v168 offset:34816
	ds_read_b128 v[188:191], v168 offset:35840
	ds_read_b128 v[192:195], v168 offset:36864
	ds_read_b128 v[196:199], v168 offset:37888
	ds_read_b128 v[200:203], v168 offset:38912
	ds_read_b128 v[208:211], v168 offset:39936
	global_load_lds_dwordx4 v[212:213], off
	v_lshl_add_u64 v[212:213], s[36:37], 0, v[140:141]
	s_mov_b32 m0, s39
	s_nop 0
	global_load_lds_dwordx4 v[212:213], off
	s_waitcnt lgkmcnt(8)
	s_barrier
	s_waitcnt lgkmcnt(0)
	s_waitcnt lgkmcnt(0)
	v_mfma_f32_16x16x32_bf16 v[124:127], v[128:131], v[172:175], v[124:127]
	v_mfma_f32_16x16x32_bf16 v[120:123], v[156:159], v[172:175], v[120:123]
	v_mfma_f32_16x16x32_bf16 v[108:111], v[128:131], v[184:187], v[108:111]
	v_mfma_f32_16x16x32_bf16 v[104:107], v[156:159], v[184:187], v[104:107]
	v_mfma_f32_16x16x32_bf16 v[92:95], v[128:131], v[192:195], v[92:95]
	v_mfma_f32_16x16x32_bf16 v[88:91], v[156:159], v[192:195], v[88:91]
	v_mfma_f32_16x16x32_bf16 v[76:79], v[128:131], v[200:203], v[76:79]
	v_mfma_f32_16x16x32_bf16 v[72:75], v[156:159], v[200:203], v[72:75]
	v_mfma_f32_16x16x32_bf16 v[124:127], v[132:135], v[180:183], v[124:127]
	v_mfma_f32_16x16x32_bf16 v[120:123], v[160:163], v[180:183], v[120:123]
	v_mfma_f32_16x16x32_bf16 v[108:111], v[132:135], v[188:191], v[108:111]
	v_mfma_f32_16x16x32_bf16 v[104:107], v[160:163], v[188:191], v[104:107]
	v_mfma_f32_16x16x32_bf16 v[92:95], v[132:135], v[196:199], v[92:95]
	v_mfma_f32_16x16x32_bf16 v[88:91], v[160:163], v[196:199], v[88:91]
	v_mfma_f32_16x16x32_bf16 v[76:79], v[132:135], v[208:211], v[76:79]
	v_mfma_f32_16x16x32_bf16 v[72:75], v[160:163], v[208:211], v[72:75]
	s_barrier
	s_add_i32 s36, 0, 0x1c000
	s_add_i32 s37, s51, s1
	v_add_u32_e32 v144, s36, v164
	v_lshl_add_u64 v[204:205], v[204:205], 0, s[12:13]
	s_mov_b32 m0, s37
	ds_read_b128 v[212:215], v144
	ds_read_b128 v[216:219], v144 offset:1024
	ds_read_b128 v[220:223], v144 offset:2048
	ds_read_b128 v[224:227], v144 offset:3072
	global_load_lds_dwordx4 v[204:205], off
	v_lshl_add_u64 v[204:205], v[228:229], 0, s[12:13]
	s_add_i32 m0, s37, 0x2000
	s_nop 0
	global_load_lds_dwordx4 v[204:205], off
	s_barrier
	s_waitcnt lgkmcnt(0)
	s_waitcnt lgkmcnt(0)
	v_mfma_f32_16x16x32_bf16 v[116:119], v[212:215], v[172:175], v[116:119]
	v_mfma_f32_16x16x32_bf16 v[112:115], v[220:223], v[172:175], v[112:115]
	v_mfma_f32_16x16x32_bf16 v[100:103], v[212:215], v[184:187], v[100:103]
	v_mfma_f32_16x16x32_bf16 v[96:99], v[220:223], v[184:187], v[96:99]
	v_mfma_f32_16x16x32_bf16 v[84:87], v[212:215], v[192:195], v[84:87]
	v_mfma_f32_16x16x32_bf16 v[80:83], v[220:223], v[192:195], v[80:83]
	v_mfma_f32_16x16x32_bf16 v[68:71], v[212:215], v[200:203], v[68:71]
	v_mfma_f32_16x16x32_bf16 v[64:67], v[220:223], v[200:203], v[64:67]
	v_mfma_f32_16x16x32_bf16 v[116:119], v[216:219], v[180:183], v[116:119]
	v_mfma_f32_16x16x32_bf16 v[112:115], v[224:227], v[180:183], v[112:115]
	v_mfma_f32_16x16x32_bf16 v[100:103], v[216:219], v[188:191], v[100:103]
	v_mfma_f32_16x16x32_bf16 v[96:99], v[224:227], v[188:191], v[96:99]
	v_mfma_f32_16x16x32_bf16 v[84:87], v[216:219], v[196:199], v[84:87]
	v_mfma_f32_16x16x32_bf16 v[80:83], v[224:227], v[196:199], v[80:83]
	v_mfma_f32_16x16x32_bf16 v[68:71], v[216:219], v[208:211], v[68:71]
	v_mfma_f32_16x16x32_bf16 v[64:67], v[224:227], v[208:211], v[64:67]
	s_mov_b32 m0, s42
	v_lshl_add_u64 v[204:205], v[230:231], 0, s[12:13]
	s_barrier
; __device__ __forceinline__ unsigned cvt_pk_bf16(float lo, float hi) { unsigned r; asm volatile("v_cvt_pk_bf16_f32 %0, %1, %2" : "=v"(r) : "v"(lo), "v"(hi)); return r; }
; #define PG8_STAGE(bufoff, gbase, voff) do { _Pragma("unroll") for (int _i = 0; _i < 2; ++_i) \
;         __builtin_amdgcn_global_load_lds((const unsigned*)((const char*)(gbase) + (voff)[_i]), (PG8_LAS unsigned*)(lds + (bufoff) + ldsw + _i * 8192), 16, 0, 0); } while (0)
; #define PG8_WAIT_V(n) asm volatile("s_waitcnt vmcnt(" #n ")" ::: "memory")
; #define PG8_WAIT_L(n) asm volatile("s_waitcnt lgkmcnt(" #n ")" ::: "memory")
; template <class Epi, class Sched>
; __device__ __forceinline__ void gemm_phase(PG8_LAS unsigned char* lds, const Gemm g, const Sched& S, const Epi& E) {
;     ...
;             PG8_LDA(At, 1, 1); PG8_STAGE(PG8_SA(1, 0), a3, voffA);
;             PG8_BAR; PG8_WAIT_L(0); PG8_MMA(1, 0, At, B0); PG8_BAR; PG8_SCHED;
;             PG8_STAGE(PG8_SB(1, 1), b3 + hstep, voffB);
;             PG8_WAIT_V(6); PG8_BAR; PG8_MMA(1, 1, At, B1); PG8_BAR;
;     __device__ __forceinline__ void operator()(const f32x4 (&acc)[2][2][4][2], const Unit& u, int wr, int wc, int fr, int fq, const float (&epre)[1]) const {
;     ...
;             const int cu = (pn - 8) * 128 + wc * 32 + 8 * fq;
; #pragma unroll
;             for (int ai = 0; ai < 2; ++ai)
; #pragma unroll
;                 for (int m = 0; m < 4; ++m) { const int row = row0 + ai * 128 + m * 16;
;                     f32x4 u0, u1;
; #pragma unroll
;                     for (int j = 0; j < 4; ++j) { u0[j] = acc[ai][0][m][0][j] * sigmoidf_(acc[ai][1][m][0][j]); u1[j] = acc[ai][0][m][1][j] * sigmoidf_(acc[ai][1][m][1][j]); }
;                     u32x4 w; w.x = cvt_pk_bf16(u0[0], u0[1]); w.y = cvt_pk_bf16(u0[2], u0[3]); w.z = cvt_pk_bf16(u1[0], u1[1]); w.w = cvt_pk_bf16(u1[2], u1[3]);
;                     *(u32x4*)(U + (size_t)row * 512 + cu) = w;
;                     if (row < MP) { const int t = row & (SEQ - 1);
;                         if (t >= SEQ - (CW - 1)) { float* o = scp + ((size_t)((row >> 11) * (CW - 1) + t - (SEQ - (CW - 1)))) * MIXB + cu; __builtin_nontemporal_store(u0, (f32x4*)o); __builtin_nontemporal_store(u1, (f32x4*)(o + 4)); }
;                     } else { const int rs = row - MP; float* o = scs + ((size_t)((rs >> 2) * (CW - 1) + (CW - 1 - DS) + (rs & 3))) * MIXB + cu; *(f32x4*)o = u0; *(f32x4*)(o + 4) = u1; }
	ds_read_b128 v[172:175], v168 offset:49152
	ds_read_b128 v[180:183], v168 offset:50176
	ds_read_b128 v[184:187], v168 offset:51200
	ds_read_b128 v[188:191], v168 offset:52224
	ds_read_b128 v[192:195], v168 offset:53248
	ds_read_b128 v[196:199], v168 offset:54272
	ds_read_b128 v[200:203], v168 offset:55296
	ds_read_b128 v[208:211], v168 offset:56320
	global_load_lds_dwordx4 v[204:205], off
	v_lshl_add_u64 v[204:205], v[232:233], 0, s[12:13]
	s_mov_b32 m0, s43
	s_nop 0
	global_load_lds_dwordx4 v[204:205], off
	s_barrier
	s_waitcnt lgkmcnt(0)
	s_waitcnt lgkmcnt(0)
	v_mfma_f32_16x16x32_bf16 v[60:63], v[128:131], v[172:175], v[60:63]
	v_mfma_f32_16x16x32_bf16 v[56:59], v[156:159], v[172:175], v[56:59]
	v_mfma_f32_16x16x32_bf16 v[44:47], v[128:131], v[184:187], v[44:47]
	v_mfma_f32_16x16x32_bf16 v[40:43], v[156:159], v[184:187], v[40:43]
	v_mfma_f32_16x16x32_bf16 v[28:31], v[128:131], v[192:195], v[28:31]
	v_mfma_f32_16x16x32_bf16 v[24:27], v[156:159], v[192:195], v[24:27]
	v_mfma_f32_16x16x32_bf16 v[12:15], v[128:131], v[200:203], v[12:15]
	v_mfma_f32_16x16x32_bf16 v[8:11], v[156:159], v[200:203], v[8:11]
	v_mfma_f32_16x16x32_bf16 v[60:63], v[132:135], v[180:183], v[60:63]
	v_mfma_f32_16x16x32_bf16 v[56:59], v[160:163], v[180:183], v[56:59]
	v_mfma_f32_16x16x32_bf16 v[44:47], v[132:135], v[188:191], v[44:47]
	v_mfma_f32_16x16x32_bf16 v[40:43], v[160:163], v[188:191], v[40:43]
	v_mfma_f32_16x16x32_bf16 v[28:31], v[132:135], v[196:199], v[28:31]
	v_mfma_f32_16x16x32_bf16 v[24:27], v[160:163], v[196:199], v[24:27]
	v_mfma_f32_16x16x32_bf16 v[12:15], v[132:135], v[208:211], v[12:15]
	v_mfma_f32_16x16x32_bf16 v[8:11], v[160:163], v[208:211], v[8:11]
	s_barrier
	s_add_u32 s34, s34, 0x40080
	s_addc_u32 s35, s35, 0
	s_add_i32 s36, s36, s1
	v_lshl_add_u64 v[128:129], s[34:35], 0, v[138:139]
	s_mov_b32 m0, s36
	s_nop 0
	global_load_lds_dwordx4 v[128:129], off
	v_lshl_add_u64 v[128:129], s[34:35], 0, v[142:143]
	s_add_i32 m0, s36, 0x2000
	s_nop 0
	global_load_lds_dwordx4 v[128:129], off
	s_waitcnt vmcnt(6)
	s_barrier
	v_mfma_f32_16x16x32_bf16 v[52:55], v[212:215], v[172:175], v[52:55]
	v_mfma_f32_16x16x32_bf16 v[48:51], v[220:223], v[172:175], v[48:51]
	v_mfma_f32_16x16x32_bf16 v[36:39], v[212:215], v[184:187], v[36:39]
	v_mfma_f32_16x16x32_bf16 v[32:35], v[220:223], v[184:187], v[32:35]
	v_mfma_f32_16x16x32_bf16 v[20:23], v[212:215], v[192:195], v[20:23]
	v_mfma_f32_16x16x32_bf16 v[16:19], v[220:223], v[192:195], v[16:19]
	v_mfma_f32_16x16x32_bf16 v[4:7], v[212:215], v[200:203], v[4:7]
	v_mfma_f32_16x16x32_bf16 v[0:3], v[220:223], v[200:203], v[0:3]
	v_mfma_f32_16x16x32_bf16 v[52:55], v[216:219], v[180:183], v[52:55]
	v_mfma_f32_16x16x32_bf16 v[48:51], v[224:227], v[180:183], v[48:51]
	v_mfma_f32_16x16x32_bf16 v[36:39], v[216:219], v[188:191], v[36:39]
	v_mfma_f32_16x16x32_bf16 v[32:35], v[224:227], v[188:191], v[32:35]
	v_mfma_f32_16x16x32_bf16 v[20:23], v[216:219], v[196:199], v[20:23]
	v_mfma_f32_16x16x32_bf16 v[16:19], v[224:227], v[196:199], v[16:19]
	v_mfma_f32_16x16x32_bf16 v[4:7], v[216:219], v[208:211], v[4:7]
	v_mfma_f32_16x16x32_bf16 v[0:3], v[224:227], v[208:211], v[0:3]
	s_add_i32 s50, s50, 2
	s_add_u32 s30, s30, 0x100
	s_addc_u32 s31, s31, 0
	s_add_u32 s48, s48, 0x100
	s_addc_u32 s49, s49, 0
	s_cmp_gt_u32 s50, 13
	s_barrier
	s_cbranch_scc0 .LBB0_152
	s_lshl_b32 s23, s6, 8
	s_lshl_b32 s6, s28, 2
	s_lshr_b64 s[6:7], s[14:15], s6
	s_add_i32 s23, s23, s41
	s_and_b32 s21, s6, 15
	v_or_b32_e32 v156, s23, v147
	s_cmp_gt_u32 s21, 7
	s_mov_b64 s[6:7], -1
	s_cbranch_scc0 .LBB0_187
	v_mul_f32_e32 v129, 0xbfb8aa3b, v112
	v_mul_f32_e32 v130, 0xbfb8aa3b, v117
	v_exp_f32_e32 v129, v129
	v_exp_f32_e32 v131, v130
	v_mul_f32_e32 v130, 0xbfb8aa3b, v113
	v_exp_f32_e32 v132, v130
	v_add_f32_e32 v129, 1.0, v129
	v_rcp_f32_e32 v130, v129
	v_add_f32_e32 v129, 1.0, v131
	v_add_f32_e32 v131, 1.0, v132
	v_mul_f32_e32 v132, 0xbfb8aa3b, v118
	v_exp_f32_e32 v132, v132
	v_mul_f32_e32 v133, 0xbfb8aa3b, v114
	v_exp_f32_e32 v133, v133
	v_mul_f32_e32 v128, 0xbfb8aa3b, v116
	v_add_f32_e32 v132, 1.0, v132
	v_rcp_f32_e32 v134, v132
	v_add_f32_e32 v132, 1.0, v133
	v_mul_f32_e32 v133, 0xbfb8aa3b, v119
	v_exp_f32_e32 v133, v133
	v_mul_f32_e32 v135, 0xbfb8aa3b, v115
	v_exp_f32_e32 v128, v128
	v_exp_f32_e32 v157, v135
	v_rcp_f32_e32 v158, v132
	v_add_f32_e32 v132, 1.0, v133
	v_add_f32_e32 v128, 1.0, v128
	v_rcp_f32_e32 v135, v132
	v_add_f32_e32 v132, 1.0, v157
	v_rcp_f32_e32 v128, v128
	v_rcp_f32_e32 v129, v129
	v_rcp_f32_e32 v131, v131
	v_rcp_f32_e32 v159, v132
	v_ashrrev_i32_e32 v157, 31, v156
	v_readlane_b32 s6, v247, 36
	v_lshlrev_b64 v[162:163], 10, v[156:157]
	v_readlane_b32 s7, v247, 37
	v_lshl_add_u32 v144, s21, 7, v166
	v_pk_mul_f32 v[132:133], v[124:125], v[128:129]
	v_lshl_add_u64 v[162:163], s[6:7], 0, v[162:163]
	v_pk_mul_f32 v[128:129], v[120:121], v[130:131]
	v_pk_mul_f32 v[134:135], v[126:127], v[134:135]
	v_pk_mul_f32 v[130:131], v[122:123], v[158:159]
	v_lshl_add_u64 v[162:163], v[144:145], 1, v[162:163]
	v_cmp_lt_i32_e32 vcc, s47, v156
	v_cvt_pk_bf16_f32 v158, v132, v133
	v_cvt_pk_bf16_f32 v159, v134, v135
	v_cvt_pk_bf16_f32 v160, v128, v129
	v_cvt_pk_bf16_f32 v161, v130, v131
	global_store_dwordx4 v[162:163], v[158:161], off
	s_and_saveexec_b64 s[6:7], vcc
	s_cbranch_execz .LBB0_156
	v_add_u32_e32 v158, 0xffffc000, v156
	v_lshrrev_b32_e32 v158, 2, v158
	v_mad_u64_u32 v[158:159], s[28:29], v158, 30, v[146:147]
	v_mov_b32_e32 v159, v145
	v_lshlrev_b64 v[158:159], 11, v[158:159]
	v_lshl_add_u64 v[158:159], s[8:9], 0, v[158:159]
	v_lshl_add_u64 v[158:159], v[144:145], 2, v[158:159]
	global_store_dwordx4 v[158:159], v[132:135], off
	global_store_dwordx4 v[158:159], v[128:131], off offset:16

; #define PG8_WAIT_V(n) asm volatile("s_waitcnt vmcnt(" #n ")" ::: "memory")
; #define PG8_BAR __builtin_amdgcn_s_barrier()
; __host__ __device__ __forceinline__ int permcol(int c) { return perm12(c >> 8) * 256 + (c & 255); }
; template <class Epi, class Sched>
; __device__ __forceinline__ void gemm_phase(PG8_LAS unsigned char* lds, const Gemm g, const Sched& S, const Epi& E) {
;     ...
;     PG8_WAIT_V(0);
;     if (wr == 0) PG8_BAR;
;     PG8_BAR;
; __global__ void __launch_bounds__(512, 2) hymba_fwd(Params p) {
;     ...
;         for (int u = bx; u < 16 * 48; u += G) { const int rb = u / 48, ct = u % 48; int br0, br1;
;             if (ct < 32) { br0 = ct * 64; br1 = br0 + 32; } else { br0 = 2048 + ((ct - 32) >> 2) * 256 + ((ct - 32) & 3) * 32; br1 = br0 + 128; }
;             small_gemm<DM>(lds, g.A, g.Bt, MP + 32 * rb, permcol(br0), permcol(br1), E); }
.LBB0_234:
	s_mov_b32 s6, 0x76981032
	s_lshl_b32 s0, s2, 6
	s_lshl_b32 s1, s66, 6
	s_lshl_b32 s3, s2, 5
	s_lshl_b32 s18, s66, 5
	s_mov_b32 s7, 0xba54
	s_movk_i32 s19, 0x100
	v_mov_b32_e32 v41, 0
	s_movk_i32 s20, 0x90
	s_movk_i32 s21, 0x7ff
	s_movk_i32 s22, 0x7f
	s_mov_b32 s23, s2
	s_barrier
	s_setprio 0
	s_branch .LBB0_237

; #define PG8_STAGE(bufoff, gbase, voff) do { _Pragma("unroll") for (int _i = 0; _i < 2; ++_i) \
;         __builtin_amdgcn_global_load_lds((const unsigned*)((const char*)(gbase) + (voff)[_i]), (PG8_LAS unsigned*)(lds + (bufoff) + ldsw + _i * 8192), 16, 0, 0); } while (0)
; #define PG8_BAR __builtin_amdgcn_s_barrier()
; template <class Epi, class Sched>
; __device__ __forceinline__ void gemm_phase(PG8_LAS unsigned char* lds, const Gemm g, const Sched& S, const Epi& E) {
;     ...
;     for (int i = 0; i < 2; ++i) { int R, C; stage_rc(tid * 16 + i * 8192, R, C); const int Rb = Epi::PERM ? ((R & ~31) + perm32(R & 31)) : R;
;         voffA[i] = (unsigned)(R * K + C) * 2u; voffB[i] = (unsigned)(Rb * K + C) * 2u; }
;     const size_t kstep = (size_t)(BK * 2);
;     const size_t hstep = (size_t)HALF * K * 2;
;     const size_t tstep = 2 * hstep;
;     const unsigned ldsw = (unsigned)wid * 1024u;
;     const int aoff = lds_byte(wr * 64 + fr, fq * 8), boff = lds_byte(wc * 32 + fr, fq * 8);
;     ...
;     Unit cur, nxt; int ui = 0;
;     if (!S.next(0, cur)) return;
;     f32x4 acc[2][2][4][2];
; #pragma unroll
;     for (int a = 0; a < 2; ++a)
; #pragma unroll
;         for (int b = 0; b < 2; ++b)
; #pragma unroll
;             for (int m = 0; m < 4; ++m)
; #pragma unroll
;                 for (int n = 0; n < 2; ++n) acc[a][b][m][n] = (f32x4){0.f, 0.f, 0.f, 0.f};
;     bf16x8 At[4][2], B0[2][2], B1[2][2];
;     const char* cA = (const char*)g.A + (size_t)cur.pm * tstep; const char* cB = (const char*)g.Bt + (size_t)cur.pn * tstep;
;     float epre[Epi::NPRE]; E.preload(cur, wr, fr, epre);
;     S.a_ready(cur);
;     PG8_STAGE(PG8_SB(0, 0), cB, voffB); PG8_STAGE(PG8_SA(0, 0), cA, voffA); PG8_STAGE(PG8_SB(0, 1), cB + hstep, voffB); PG8_STAGE(PG8_SA(0, 1), cA + hstep, voffA);
;     if (wr == 1) PG8_BAR;
.LBB0_608:
	v_ashrrev_i32_e32 v1, 31, v8
	v_lshrrev_b32_e32 v1, 26, v1
	v_add_u32_e32 v1, v8, v1
	v_ashrrev_i32_e32 v9, 6, v1
	v_bfe_i32 v1, v8, 27, 1
	v_lshlrev_b32_e32 v0, 4, v8
	v_lshrrev_b32_e32 v1, 22, v1
	v_add_u32_e32 v1, v0, v1
	v_and_b32_e32 v1, 0xfffffc00, v1
	v_sub_u32_e32 v1, v0, v1
	v_lshrrev_b32_e32 v2, 4, v1
	v_bitop3_b32 v1, v2, v1, 32 bitop3:0x6c
	v_ashrrev_i32_e32 v3, 31, v1
	v_lshrrev_b32_e32 v3, 26, v3
	v_add_u32_e32 v3, v1, v3
	v_lshlrev_b32_e32 v2, 3, v9
	v_ashrrev_i32_e32 v10, 6, v3
	v_and_b32_e32 v3, 0xc0, v3
	v_and_b32_e32 v2, -16, v2
	v_sub_u32_e32 v1, v1, v3
	v_mov_b32_e32 v3, 1
	v_add_u32_e32 v2, v10, v2
	v_ashrrev_i16_sdwa v1, v3, sext(v1) dst_sel:DWORD dst_unused:UNUSED_PAD src0_sel:DWORD src1_sel:BYTE_0
	s_ashr_i32 s5, s3, 3
	v_lshlrev_b32_e32 v4, 5, v9
	v_bfe_i32 v11, v1, 0, 16
	v_lshlrev_b32_e32 v1, 1, v2
	v_lshrrev_b32_e32 v5, 2, v2
	v_and_b32_e32 v6, 3, v10
	s_mov_b32 s3, 0x1fffe0
	v_and_b32_e32 v4, 32, v4
	v_and_b32_e32 v1, 24, v1
	v_and_b32_e32 v5, 4, v5
	v_and_or_b32 v6, v2, s3, v6
	s_add_u32 s12, s64, 0x600000
	v_or3_b32 v1, v6, v5, v1
	v_add_lshl_u32 v4, v4, v11, 1
	v_add_u32_e32 v0, 0x2000, v0
	s_addc_u32 s13, s65, 0
	v_lshl_add_u32 v146, v1, 11, v4
	v_ashrrev_i32_e32 v1, 31, v0
	s_add_i32 s4, s4, s5
	v_lshrrev_b32_e32 v1, 22, v1
	s_ashr_i32 s5, s4, 31
	v_add_u32_e32 v1, v0, v1
	s_lshr_b32 s5, s5, 27
	s_waitcnt vmcnt(0)
	v_ashrrev_i32_e32 v12, 10, v1
	s_add_i32 s5, s4, s5
	v_mul_i32_i24_e32 v1, 0x400, v12
	s_ashr_i32 s6, s5, 5
	s_andn2_b32 s5, s5, 31
	v_sub_u32_e32 v0, v0, v1
	s_sub_i32 s4, s4, s5
	v_lshrrev_b32_e32 v1, 4, v0
	s_bfe_i32 s5, s4, 0x80000
	v_bitop3_b32 v0, v1, v0, 32 bitop3:0x6c
	s_bfe_u32 s5, s5, 0x3000c
	v_lshl_add_u32 v144, v2, 11, v4
	v_ashrrev_i32_e32 v2, 31, v0
	s_add_i32 s5, s4, s5
	v_lshrrev_b32_e32 v2, 26, v2
	s_lshl_b32 s9, s6, 3
	s_bfe_i32 s6, s5, 0x80000
	s_and_b32 s5, s5, 0xf8
	v_add_u32_e32 v2, v0, v2
	s_sub_i32 s4, s4, s5
	v_lshlrev_b32_e32 v1, 3, v12
	v_ashrrev_i32_e32 v13, 6, v2
	v_and_b32_e32 v2, 0xc0, v2
	s_sext_i32_i16 s6, s6
	s_sext_i32_i8 s4, s4
	s_ashr_i32 s7, s0, 8
	v_and_b32_e32 v1, -16, v1
	v_sub_u32_e32 v0, v0, v2
	s_lshr_b32 s6, s6, 3
	s_add_i32 s24, s9, s4
	v_add_u32_e32 v1, v13, v1
	v_ashrrev_i16_sdwa v0, v3, sext(v0) dst_sel:DWORD dst_unused:UNUSED_PAD src0_sel:DWORD src1_sel:BYTE_0
	v_and_b32_e32 v3, 3, v13
	s_ashr_i32 s8, s0, 6
	s_ashr_i32 s25, s24, 31
	s_bfe_i64 s[4:5], s[6:7], 0x100000
	v_and_or_b32 v3, v1, s3, v3
	s_lshl_b32 s3, s8, 10
	s_lshl_b64 s[14:15], s[24:25], 19
	s_lshl_b64 s[4:5], s[4:5], 19
	s_add_u32 s28, s12, s4
	v_lshlrev_b32_e32 v4, 5, v12
	v_bfe_i32 v14, v0, 0, 16
	v_lshlrev_b32_e32 v0, 1, v1
	v_lshrrev_b32_e32 v2, 2, v1
	s_addc_u32 s29, s13, s5
	s_add_i32 s4, s3, 0
	v_and_b32_e32 v4, 32, v4
	v_and_b32_e32 v0, 24, v0
	v_and_b32_e32 v2, 4, v2
	s_add_i32 m0, s4, 0x10000
	v_or3_b32 v0, v3, v2, v0
	v_add_lshl_u32 v2, v4, v14, 1
	global_load_lds_dwordx4 v146, s[28:29]
	s_add_i32 m0, s4, 0x12000
	v_lshl_add_u32 v150, v0, 11, v2
	s_add_u32 s26, s82, s14
	global_load_lds_dwordx4 v150, s[28:29]
	s_addc_u32 s27, s83, s15
	s_mov_b32 m0, s4
	s_add_i32 s5, s4, 0x2000
	v_lshl_add_u32 v148, v1, 11, v2
	global_load_lds_dwordx4 v144, s[26:27]
	s_mov_b32 m0, s5
	s_add_u32 s14, s28, 0x40000
	global_load_lds_dwordx4 v148, s[26:27]
	s_addc_u32 s15, s29, 0
	s_add_i32 m0, s4, 0x14000
	v_mov_b32_e32 v153, 0
	global_load_lds_dwordx4 v146, s[14:15]
	s_add_i32 m0, s4, 0x16000
	v_mov_b32_e32 v147, v153
	global_load_lds_dwordx4 v150, s[14:15]
	s_add_u32 s14, s26, 0x40000
	s_addc_u32 s15, s27, 0
	s_add_i32 s33, s4, 0x4000
	s_mov_b32 m0, s33
	s_add_i32 s34, s4, 0x6000
	global_load_lds_dwordx4 v144, s[14:15]
	s_mov_b32 m0, s34
	v_mov_b32_e32 v151, v153
	global_load_lds_dwordx4 v148, s[14:15]
	v_mov_b32_e32 v145, v153
	v_mov_b32_e32 v149, v153
	s_mov_b32 s35, 0
	v_lshl_add_u64 v[6:7], s[28:29], 0, v[146:147]
	v_lshl_add_u64 v[4:5], s[28:29], 0, v[150:151]
	v_lshl_add_u64 v[2:3], s[26:27], 0, v[144:145]
	v_lshl_add_u64 v[0:1], s[26:27], 0, v[148:149]
	s_cmp_lg_u32 s7, 1
	s_movk_i32 s36, 0x4000
	s_cbranch_scc1 .LBB0_610
	s_barrier
	s_setprio 1

; #define PG8_STAGE(bufoff, gbase, voff) do { _Pragma("unroll") for (int _i = 0; _i < 2; ++_i) \
;         __builtin_amdgcn_global_load_lds((const unsigned*)((const char*)(gbase) + (voff)[_i]), (PG8_LAS unsigned*)(lds + (bufoff) + ldsw + _i * 8192), 16, 0, 0); } while (0)
; #define PG8_LDA(dst, b, h) do { _Pragma("unroll") for (int m = 0; m < 4; ++m) _Pragma("unroll") for (int k = 0; k < 2; ++k) dst[m][k] = *(const PG8_LAS bf16x8*)(lds + PG8_SA(b, h) + aoff + m * 2048 + k * 1024); } while (0)
; #define PG8_LDB(dst, b, h) do { _Pragma("unroll") for (int n = 0; n < 2; ++n) _Pragma("unroll") for (int k = 0; k < 2; ++k) dst[n][k] = *(const PG8_LAS bf16x8*)(lds + PG8_SB(b, h) + boff + n * 2048 + k * 1024); } while (0)
; #define PG8_MMA(ai, bj, At, Bt) do { __builtin_amdgcn_s_setprio(1); _Pragma("unroll") for (int m = 0; m < 4; ++m) _Pragma("unroll") for (int n = 0; n < 2; ++n) _Pragma("unroll") for (int k = 0; k < 2; ++k) \
;         acc[ai][bj][m][n] = __builtin_amdgcn_mfma_f32_16x16x32_bf16(Bt[n][k], At[m][k], acc[ai][bj][m][n], 0, 0, 0); __builtin_amdgcn_s_setprio(0); } while (0)
; #define PG8_WAIT_V(n) asm volatile("s_waitcnt vmcnt(" #n ")" ::: "memory")
; #define PG8_WAIT_L(n) asm volatile("s_waitcnt lgkmcnt(" #n ")" ::: "memory")
; #define PG8_BAR __builtin_amdgcn_s_barrier()
; #define PG8_SCHED __builtin_amdgcn_sched_barrier(0)
; template <class Epi, class Sched>
; __device__ __forceinline__ void gemm_phase(PG8_LAS unsigned char* lds, const Gemm g, const Sched& S, const Epi& E) {
;     ...
;             PG8_LDB(B0, 0, 0); PG8_SCHED; PG8_LDA(At, 0, 0); PG8_STAGE(PG8_SA(1, 1), a1 + hstep, voffA);
;             PG8_WAIT_L(8); PG8_BAR; PG8_WAIT_L(0); PG8_MMA(0, 0, At, B0); PG8_BAR; PG8_SCHED;
;             PG8_LDB(B1, 0, 1); PG8_STAGE(PG8_SB(0, 0), b2, voffB);
;             PG8_BAR; PG8_WAIT_L(0); PG8_MMA(0, 1, At, B1); PG8_BAR;
;             PG8_LDA(At, 0, 1); PG8_STAGE(PG8_SA(0, 0), a2, voffA);
;             PG8_BAR; PG8_WAIT_L(0); PG8_MMA(1, 0, At, B0); PG8_BAR; PG8_SCHED;
;             PG8_STAGE(PG8_SB(0, 1), b2 + hstep, voffB);
;             PG8_WAIT_V(6); PG8_BAR; PG8_MMA(1, 1, At, B1); PG8_BAR;
.LBB0_619:
	ds_read_b128 v[128:131], v175
	ds_read_b128 v[132:135], v175 offset:1024
	ds_read_b128 v[136:139], v175 offset:2048
	ds_read_b128 v[140:143], v175 offset:3072
	s_add_u32 s28, s26, 0xfffc0080
	s_addc_u32 s29, s27, -1
	s_cmp_eq_u32 s49, 12
	s_cselect_b32 s31, s19, s29
	s_cselect_b32 s30, s45, s28
	s_cselect_b32 s29, s17, s48
	s_cselect_b32 s28, s46, s47
	v_lshl_add_u64 v[170:171], s[26:27], 0, v[154:155]
	s_add_i32 m0, s4, 0xc000
	ds_read_b128 v[162:165], v177
	ds_read_b128 v[166:169], v177 offset:1024
	ds_read_b128 v[182:185], v177 offset:2048
	ds_read_b128 v[186:189], v177 offset:3072
	ds_read_b128 v[190:193], v177 offset:4096
	ds_read_b128 v[194:197], v177 offset:5120
	ds_read_b128 v[198:201], v177 offset:6144
	ds_read_b128 v[202:205], v177 offset:7168
	global_load_lds_dwordx4 v[170:171], off
	v_lshl_add_u64 v[170:171], s[26:27], 0, v[156:157]
	s_add_i32 m0, s4, 0xe000
	s_nop 0
	global_load_lds_dwordx4 v[170:171], off
	s_waitcnt lgkmcnt(8)
	s_barrier
	s_waitcnt lgkmcnt(0)
	s_waitcnt lgkmcnt(0)
	v_mfma_f32_16x16x32_bf16 v[124:127], v[128:131], v[162:165], v[124:127]
	v_mfma_f32_16x16x32_bf16 v[120:123], v[136:139], v[162:165], v[120:123]
	v_mfma_f32_16x16x32_bf16 v[108:111], v[128:131], v[182:185], v[108:111]
	v_mfma_f32_16x16x32_bf16 v[104:107], v[136:139], v[182:185], v[104:107]
	v_mfma_f32_16x16x32_bf16 v[92:95], v[128:131], v[190:193], v[92:95]
	v_mfma_f32_16x16x32_bf16 v[88:91], v[136:139], v[190:193], v[88:91]
	v_mfma_f32_16x16x32_bf16 v[76:79], v[128:131], v[198:201], v[76:79]
	v_mfma_f32_16x16x32_bf16 v[72:75], v[136:139], v[198:201], v[72:75]
	v_mfma_f32_16x16x32_bf16 v[124:127], v[132:135], v[166:169], v[124:127]
	v_mfma_f32_16x16x32_bf16 v[120:123], v[140:143], v[166:169], v[120:123]
	v_mfma_f32_16x16x32_bf16 v[108:111], v[132:135], v[186:189], v[108:111]
	v_mfma_f32_16x16x32_bf16 v[104:107], v[140:143], v[186:189], v[104:107]
	v_mfma_f32_16x16x32_bf16 v[92:95], v[132:135], v[194:197], v[92:95]
	v_mfma_f32_16x16x32_bf16 v[88:91], v[140:143], v[194:197], v[88:91]
	v_mfma_f32_16x16x32_bf16 v[76:79], v[132:135], v[202:205], v[76:79]
	v_mfma_f32_16x16x32_bf16 v[72:75], v[140:143], v[202:205], v[72:75]
	s_barrier
	s_add_i32 s50, s39, s3
	v_lshl_add_u64 v[170:171], s[28:29], 0, v[146:147]
	s_mov_b32 m0, s50
	ds_read_b128 v[208:211], v180
	ds_read_b128 v[212:215], v180 offset:1024
	ds_read_b128 v[216:219], v180 offset:2048
	ds_read_b128 v[220:223], v180 offset:3072
	global_load_lds_dwordx4 v[170:171], off
	v_lshl_add_u64 v[224:225], s[28:29], 0, v[150:151]
	s_add_i32 m0, s50, 0x2000
	s_nop 0
	global_load_lds_dwordx4 v[224:225], off
	s_barrier
	s_waitcnt lgkmcnt(0)
	s_waitcnt lgkmcnt(0)
	v_mfma_f32_16x16x32_bf16 v[116:119], v[208:211], v[162:165], v[116:119]
	v_mfma_f32_16x16x32_bf16 v[112:115], v[216:219], v[162:165], v[112:115]
	v_mfma_f32_16x16x32_bf16 v[100:103], v[208:211], v[182:185], v[100:103]
	v_mfma_f32_16x16x32_bf16 v[96:99], v[216:219], v[182:185], v[96:99]
	v_mfma_f32_16x16x32_bf16 v[84:87], v[208:211], v[190:193], v[84:87]
	v_mfma_f32_16x16x32_bf16 v[80:83], v[216:219], v[190:193], v[80:83]
	v_mfma_f32_16x16x32_bf16 v[68:71], v[208:211], v[198:201], v[68:71]
	v_mfma_f32_16x16x32_bf16 v[64:67], v[216:219], v[198:201], v[64:67]
	v_mfma_f32_16x16x32_bf16 v[116:119], v[212:215], v[166:169], v[116:119]
	v_mfma_f32_16x16x32_bf16 v[112:115], v[220:223], v[166:169], v[112:115]
	v_mfma_f32_16x16x32_bf16 v[100:103], v[212:215], v[186:189], v[100:103]
	v_mfma_f32_16x16x32_bf16 v[96:99], v[220:223], v[186:189], v[96:99]
	v_mfma_f32_16x16x32_bf16 v[84:87], v[212:215], v[194:197], v[84:87]
	v_mfma_f32_16x16x32_bf16 v[80:83], v[220:223], v[194:197], v[80:83]
	v_mfma_f32_16x16x32_bf16 v[68:71], v[212:215], v[202:205], v[68:71]
	v_mfma_f32_16x16x32_bf16 v[64:67], v[220:223], v[202:205], v[64:67]
	s_mov_b32 m0, s4
	v_lshl_add_u64 v[226:227], s[30:31], 0, v[144:145]
	s_barrier
	ds_read_b128 v[162:165], v177 offset:16384
	ds_read_b128 v[166:169], v177 offset:17408
	ds_read_b128 v[182:185], v177 offset:18432
	ds_read_b128 v[186:189], v177 offset:19456
	ds_read_b128 v[190:193], v177 offset:20480
	ds_read_b128 v[194:197], v177 offset:21504
	ds_read_b128 v[198:201], v177 offset:22528
	ds_read_b128 v[202:205], v177 offset:23552
	global_load_lds_dwordx4 v[226:227], off
	v_lshl_add_u64 v[228:229], s[30:31], 0, v[148:149]
	s_mov_b32 m0, s5
	s_nop 0
	global_load_lds_dwordx4 v[228:229], off
	s_barrier
	s_waitcnt lgkmcnt(0)
	s_waitcnt lgkmcnt(0)
	v_mfma_f32_16x16x32_bf16 v[60:63], v[128:131], v[162:165], v[60:63]
	v_mfma_f32_16x16x32_bf16 v[56:59], v[136:139], v[162:165], v[56:59]
	v_mfma_f32_16x16x32_bf16 v[44:47], v[128:131], v[182:185], v[44:47]
	v_mfma_f32_16x16x32_bf16 v[40:43], v[136:139], v[182:185], v[40:43]
	v_mfma_f32_16x16x32_bf16 v[28:31], v[128:131], v[190:193], v[28:31]
	v_mfma_f32_16x16x32_bf16 v[24:27], v[136:139], v[190:193], v[24:27]
	v_mfma_f32_16x16x32_bf16 v[12:15], v[128:131], v[198:201], v[12:15]
	v_mfma_f32_16x16x32_bf16 v[8:11], v[136:139], v[198:201], v[8:11]
	v_mfma_f32_16x16x32_bf16 v[60:63], v[132:135], v[166:169], v[60:63]
	v_mfma_f32_16x16x32_bf16 v[56:59], v[140:143], v[166:169], v[56:59]
	v_mfma_f32_16x16x32_bf16 v[44:47], v[132:135], v[186:189], v[44:47]
	v_mfma_f32_16x16x32_bf16 v[40:43], v[140:143], v[186:189], v[40:43]
	v_mfma_f32_16x16x32_bf16 v[28:31], v[132:135], v[194:197], v[28:31]
	v_mfma_f32_16x16x32_bf16 v[24:27], v[140:143], v[194:197], v[24:27]
	v_mfma_f32_16x16x32_bf16 v[12:15], v[132:135], v[202:205], v[12:15]
	v_mfma_f32_16x16x32_bf16 v[8:11], v[140:143], v[202:205], v[8:11]
	s_barrier
; #define PG8_STAGE(bufoff, gbase, voff) do { _Pragma("unroll") for (int _i = 0; _i < 2; ++_i) \
;         __builtin_amdgcn_global_load_lds((const unsigned*)((const char*)(gbase) + (voff)[_i]), (PG8_LAS unsigned*)(lds + (bufoff) + ldsw + _i * 8192), 16, 0, 0); } while (0)
; #define PG8_LDA(dst, b, h) do { _Pragma("unroll") for (int m = 0; m < 4; ++m) _Pragma("unroll") for (int k = 0; k < 2; ++k) dst[m][k] = *(const PG8_LAS bf16x8*)(lds + PG8_SA(b, h) + aoff + m * 2048 + k * 1024); } while (0)
; #define PG8_LDB(dst, b, h) do { _Pragma("unroll") for (int n = 0; n < 2; ++n) _Pragma("unroll") for (int k = 0; k < 2; ++k) dst[n][k] = *(const PG8_LAS bf16x8*)(lds + PG8_SB(b, h) + boff + n * 2048 + k * 1024); } while (0)
; #define PG8_MMA(ai, bj, At, Bt) do { __builtin_amdgcn_s_setprio(1); _Pragma("unroll") for (int m = 0; m < 4; ++m) _Pragma("unroll") for (int n = 0; n < 2; ++n) _Pragma("unroll") for (int k = 0; k < 2; ++k) \
;         acc[ai][bj][m][n] = __builtin_amdgcn_mfma_f32_16x16x32_bf16(Bt[n][k], At[m][k], acc[ai][bj][m][n], 0, 0, 0); __builtin_amdgcn_s_setprio(0); } while (0)
; #define PG8_WAIT_V(n) asm volatile("s_waitcnt vmcnt(" #n ")" ::: "memory")
; #define PG8_WAIT_L(n) asm volatile("s_waitcnt lgkmcnt(" #n ")" ::: "memory")
; #define PG8_BAR __builtin_amdgcn_s_barrier()
; #define PG8_SCHED __builtin_amdgcn_sched_barrier(0)
; template <class Epi, class Sched>
; __device__ __forceinline__ void gemm_phase(PG8_LAS unsigned char* lds, const Gemm g, const Sched& S, const Epi& E) {
;     ...
;             PG8_STAGE(PG8_SB(0, 1), b2 + hstep, voffB);
;             PG8_WAIT_V(6); PG8_BAR; PG8_MMA(1, 1, At, B1); PG8_BAR;
;             PG8_LDB(B0, 1, 0); PG8_SCHED; PG8_LDA(At, 1, 0); PG8_STAGE(PG8_SA(0, 1), a2 + hstep, voffA);
;             PG8_WAIT_L(8); PG8_BAR; PG8_WAIT_L(0); PG8_MMA(0, 0, At, B0); PG8_BAR; PG8_SCHED;
;             PG8_LDB(B1, 1, 1); PG8_STAGE(PG8_SB(1, 0), b3, voffB);
;             PG8_BAR; PG8_WAIT_L(0); PG8_MMA(0, 1, At, B1); PG8_BAR;
;             PG8_LDA(At, 1, 1); PG8_STAGE(PG8_SA(1, 0), a3, voffA);
;             PG8_BAR; PG8_WAIT_L(0); PG8_MMA(1, 0, At, B0); PG8_BAR; PG8_SCHED;
	s_add_u32 s50, s28, 0x40000
	s_addc_u32 s51, s29, 0
	s_add_i32 s60, s40, s3
	v_lshl_add_u64 v[128:129], s[50:51], 0, v[146:147]
	s_mov_b32 m0, s60
	s_nop 0
	global_load_lds_dwordx4 v[128:129], off
	v_lshl_add_u64 v[128:129], s[50:51], 0, v[150:151]
	s_add_i32 m0, s60, 0x2000
	s_nop 0
	global_load_lds_dwordx4 v[128:129], off
	s_waitcnt vmcnt(6)
	s_barrier
	v_mfma_f32_16x16x32_bf16 v[52:55], v[208:211], v[162:165], v[52:55]
	v_mfma_f32_16x16x32_bf16 v[48:51], v[216:219], v[162:165], v[48:51]
	v_mfma_f32_16x16x32_bf16 v[36:39], v[208:211], v[182:185], v[36:39]
	v_mfma_f32_16x16x32_bf16 v[32:35], v[216:219], v[182:185], v[32:35]
	v_mfma_f32_16x16x32_bf16 v[20:23], v[208:211], v[190:193], v[20:23]
	v_mfma_f32_16x16x32_bf16 v[16:19], v[216:219], v[190:193], v[16:19]
	v_mfma_f32_16x16x32_bf16 v[4:7], v[208:211], v[198:201], v[4:7]
	v_mfma_f32_16x16x32_bf16 v[0:3], v[216:219], v[198:201], v[0:3]
	v_mfma_f32_16x16x32_bf16 v[52:55], v[212:215], v[166:169], v[52:55]
	v_mfma_f32_16x16x32_bf16 v[48:51], v[220:223], v[166:169], v[48:51]
	v_mfma_f32_16x16x32_bf16 v[36:39], v[212:215], v[186:189], v[36:39]
	v_mfma_f32_16x16x32_bf16 v[32:35], v[220:223], v[186:189], v[32:35]
	v_mfma_f32_16x16x32_bf16 v[20:23], v[212:215], v[194:197], v[20:23]
	v_mfma_f32_16x16x32_bf16 v[16:19], v[220:223], v[194:197], v[16:19]
	v_mfma_f32_16x16x32_bf16 v[4:7], v[212:215], v[202:205], v[4:7]
	v_mfma_f32_16x16x32_bf16 v[0:3], v[220:223], v[202:205], v[0:3]
	s_add_i32 s50, 0, 0x18000
	v_add_u32_e32 v140, s50, v173
	s_barrier
	ds_read_b128 v[128:131], v140
	ds_read_b128 v[132:135], v140 offset:1024
	ds_read_b128 v[136:139], v140 offset:2048
	ds_read_b128 v[140:143], v140 offset:3072
	s_add_u32 s30, s30, 0x40000
	s_addc_u32 s31, s31, 0
	s_mov_b32 m0, s33
	v_lshl_add_u64 v[208:209], s[30:31], 0, v[144:145]
	ds_read_b128 v[162:165], v177 offset:32768
	ds_read_b128 v[166:169], v177 offset:33792
	ds_read_b128 v[182:185], v177 offset:34816
	ds_read_b128 v[186:189], v177 offset:35840
	ds_read_b128 v[190:193], v177 offset:36864
	ds_read_b128 v[194:197], v177 offset:37888
	ds_read_b128 v[198:201], v177 offset:38912
	ds_read_b128 v[202:205], v177 offset:39936
	global_load_lds_dwordx4 v[208:209], off
	v_lshl_add_u64 v[208:209], s[30:31], 0, v[148:149]
	s_mov_b32 m0, s34
	s_nop 0
	global_load_lds_dwordx4 v[208:209], off
	s_waitcnt lgkmcnt(8)
	s_barrier
	s_waitcnt lgkmcnt(0)
	s_waitcnt lgkmcnt(0)
	v_mfma_f32_16x16x32_bf16 v[124:127], v[128:131], v[162:165], v[124:127]
	v_mfma_f32_16x16x32_bf16 v[120:123], v[136:139], v[162:165], v[120:123]
	v_mfma_f32_16x16x32_bf16 v[108:111], v[128:131], v[182:185], v[108:111]
	v_mfma_f32_16x16x32_bf16 v[104:107], v[136:139], v[182:185], v[104:107]
	v_mfma_f32_16x16x32_bf16 v[92:95], v[128:131], v[190:193], v[92:95]
	v_mfma_f32_16x16x32_bf16 v[88:91], v[136:139], v[190:193], v[88:91]
	v_mfma_f32_16x16x32_bf16 v[76:79], v[128:131], v[198:201], v[76:79]
	v_mfma_f32_16x16x32_bf16 v[72:75], v[136:139], v[198:201], v[72:75]
	v_mfma_f32_16x16x32_bf16 v[124:127], v[132:135], v[166:169], v[124:127]
	v_mfma_f32_16x16x32_bf16 v[120:123], v[140:143], v[166:169], v[120:123]
	v_mfma_f32_16x16x32_bf16 v[108:111], v[132:135], v[186:189], v[108:111]
	v_mfma_f32_16x16x32_bf16 v[104:107], v[140:143], v[186:189], v[104:107]
	v_mfma_f32_16x16x32_bf16 v[92:95], v[132:135], v[194:197], v[92:95]
	v_mfma_f32_16x16x32_bf16 v[88:91], v[140:143], v[194:197], v[88:91]
	v_mfma_f32_16x16x32_bf16 v[76:79], v[132:135], v[202:205], v[76:79]
	v_mfma_f32_16x16x32_bf16 v[72:75], v[140:143], v[202:205], v[72:75]
	s_barrier
	s_add_i32 s30, 0, 0x1c000
	s_add_i32 s31, s50, s3
	v_add_u32_e32 v152, s30, v173
	v_lshl_add_u64 v[170:171], v[170:171], 0, s[14:15]
	s_mov_b32 m0, s31
	ds_read_b128 v[208:211], v152
	ds_read_b128 v[212:215], v152 offset:1024
	ds_read_b128 v[216:219], v152 offset:2048
	ds_read_b128 v[220:223], v152 offset:3072
	global_load_lds_dwordx4 v[170:171], off
	v_lshl_add_u64 v[170:171], v[224:225], 0, s[14:15]
	s_add_i32 m0, s31, 0x2000
	s_nop 0
	global_load_lds_dwordx4 v[170:171], off
	s_barrier
	s_waitcnt lgkmcnt(0)
	s_waitcnt lgkmcnt(0)
	v_mfma_f32_16x16x32_bf16 v[116:119], v[208:211], v[162:165], v[116:119]
	v_mfma_f32_16x16x32_bf16 v[112:115], v[216:219], v[162:165], v[112:115]
	v_mfma_f32_16x16x32_bf16 v[100:103], v[208:211], v[182:185], v[100:103]
	v_mfma_f32_16x16x32_bf16 v[96:99], v[216:219], v[182:185], v[96:99]
	v_mfma_f32_16x16x32_bf16 v[84:87], v[208:211], v[190:193], v[84:87]
	v_mfma_f32_16x16x32_bf16 v[80:83], v[216:219], v[190:193], v[80:83]
	v_mfma_f32_16x16x32_bf16 v[68:71], v[208:211], v[198:201], v[68:71]
	v_mfma_f32_16x16x32_bf16 v[64:67], v[216:219], v[198:201], v[64:67]
	v_mfma_f32_16x16x32_bf16 v[116:119], v[212:215], v[166:169], v[116:119]
	v_mfma_f32_16x16x32_bf16 v[112:115], v[220:223], v[166:169], v[112:115]
	v_mfma_f32_16x16x32_bf16 v[100:103], v[212:215], v[186:189], v[100:103]
	v_mfma_f32_16x16x32_bf16 v[96:99], v[220:223], v[186:189], v[96:99]
	v_mfma_f32_16x16x32_bf16 v[84:87], v[212:215], v[194:197], v[84:87]
	v_mfma_f32_16x16x32_bf16 v[80:83], v[220:223], v[194:197], v[80:83]
	v_mfma_f32_16x16x32_bf16 v[68:71], v[212:215], v[202:205], v[68:71]
	v_mfma_f32_16x16x32_bf16 v[64:67], v[220:223], v[202:205], v[64:67]
	s_mov_b32 m0, s37
	v_lshl_add_u64 v[170:171], v[226:227], 0, s[14:15]
	s_barrier
	ds_read_b128 v[162:165], v177 offset:49152
	ds_read_b128 v[166:169], v177 offset:50176
	ds_read_b128 v[182:185], v177 offset:51200
	ds_read_b128 v[186:189], v177 offset:52224
	ds_read_b128 v[190:193], v177 offset:53248
	ds_read_b128 v[194:197], v177 offset:54272
	ds_read_b128 v[198:201], v177 offset:55296
	ds_read_b128 v[202:205], v177 offset:56320
	global_load_lds_dwordx4 v[170:171], off
	v_lshl_add_u64 v[170:171], v[228:229], 0, s[14:15]
	s_mov_b32 m0, s38
	s_nop 0
	global_load_lds_dwordx4 v[170:171], off
	s_barrier
; #define PG8_STAGE(bufoff, gbase, voff) do { _Pragma("unroll") for (int _i = 0; _i < 2; ++_i) \
;         __builtin_amdgcn_global_load_lds((const unsigned*)((const char*)(gbase) + (voff)[_i]), (PG8_LAS unsigned*)(lds + (bufoff) + ldsw + _i * 8192), 16, 0, 0); } while (0)
; #define PG8_MMA(ai, bj, At, Bt) do { __builtin_amdgcn_s_setprio(1); _Pragma("unroll") for (int m = 0; m < 4; ++m) _Pragma("unroll") for (int n = 0; n < 2; ++n) _Pragma("unroll") for (int k = 0; k < 2; ++k) \
;         acc[ai][bj][m][n] = __builtin_amdgcn_mfma_f32_16x16x32_bf16(Bt[n][k], At[m][k], acc[ai][bj][m][n], 0, 0, 0); __builtin_amdgcn_s_setprio(0); } while (0)
; #define PG8_WAIT_V(n) asm volatile("s_waitcnt vmcnt(" #n ")" ::: "memory")
; #define PG8_BAR __builtin_amdgcn_s_barrier()
; template <class Epi, class Sched>
; __device__ __forceinline__ void gemm_phase(PG8_LAS unsigned char* lds, const Gemm g, const Sched& S, const Epi& E) {
;     ...
;             PG8_STAGE(PG8_SB(1, 1), b3 + hstep, voffB);
;             PG8_WAIT_V(6); PG8_BAR; PG8_MMA(1, 1, At, B1); PG8_BAR;
;     __device__ __forceinline__ void operator()(const f32x4 (&acc)[2][2][4][2], const Unit& u, int wr, int wc, int fr, int fq, const float (&epre)[1]) const {
;         const int row0 = u.pm * 256 + wr * 64 + fr, col0 = u.pn * 256 + wc * 32 + 8 * fq;
; #pragma unroll
;         for (int ai = 0; ai < 2; ++ai) {
;             float ssv[4];
;             f32x4 bv[4][2][2];
; #pragma unroll
;             for (int m = 0; m < 4; ++m) { const int row = row0 + ai * 128 + m * 16;
; #pragma unroll
;                 for (int bj = 0; bj < 2; ++bj) {
;                     if (BASEBF) { unpack8(*(const u32x4*)(HB + (size_t)row * DM + col0 + bj * 128), bv[m][bj][0], bv[m][bj][1]); }
;                     else { const float* bp = (row < MP ? base0 + (size_t)row * DM : base1 + (size_t)(row - MP) * DM) + col0 + bj * 128; bv[m][bj][0] = __builtin_nontemporal_load((const f32x4*)bp); bv[m][bj][1] = __builtin_nontemporal_load((const f32x4*)(bp + 4)); } } }
	s_waitcnt lgkmcnt(0)
	s_waitcnt lgkmcnt(0)
	v_mfma_f32_16x16x32_bf16 v[60:63], v[128:131], v[162:165], v[60:63]
	v_mfma_f32_16x16x32_bf16 v[56:59], v[136:139], v[162:165], v[56:59]
	v_mfma_f32_16x16x32_bf16 v[44:47], v[128:131], v[182:185], v[44:47]
	v_mfma_f32_16x16x32_bf16 v[40:43], v[136:139], v[182:185], v[40:43]
	v_mfma_f32_16x16x32_bf16 v[28:31], v[128:131], v[190:193], v[28:31]
	v_mfma_f32_16x16x32_bf16 v[24:27], v[136:139], v[190:193], v[24:27]
	v_mfma_f32_16x16x32_bf16 v[12:15], v[128:131], v[198:201], v[12:15]
	v_mfma_f32_16x16x32_bf16 v[8:11], v[136:139], v[198:201], v[8:11]
	v_mfma_f32_16x16x32_bf16 v[60:63], v[132:135], v[166:169], v[60:63]
	v_mfma_f32_16x16x32_bf16 v[56:59], v[140:143], v[166:169], v[56:59]
	v_mfma_f32_16x16x32_bf16 v[44:47], v[132:135], v[186:189], v[44:47]
	v_mfma_f32_16x16x32_bf16 v[40:43], v[140:143], v[186:189], v[40:43]
	v_mfma_f32_16x16x32_bf16 v[28:31], v[132:135], v[194:197], v[28:31]
	v_mfma_f32_16x16x32_bf16 v[24:27], v[140:143], v[194:197], v[24:27]
	v_mfma_f32_16x16x32_bf16 v[12:15], v[132:135], v[202:205], v[12:15]
	v_mfma_f32_16x16x32_bf16 v[8:11], v[140:143], v[202:205], v[8:11]
	s_barrier
	s_add_u32 s28, s28, 0x40080
	s_addc_u32 s29, s29, 0
	s_add_i32 s30, s30, s3
	v_lshl_add_u64 v[128:129], s[28:29], 0, v[146:147]
	s_mov_b32 m0, s30
	s_nop 0
	global_load_lds_dwordx4 v[128:129], off
	v_lshl_add_u64 v[128:129], s[28:29], 0, v[150:151]
	s_add_i32 m0, s30, 0x2000
	s_nop 0
	global_load_lds_dwordx4 v[128:129], off
	s_waitcnt vmcnt(6)
	s_barrier
	v_mfma_f32_16x16x32_bf16 v[52:55], v[208:211], v[162:165], v[52:55]
	v_mfma_f32_16x16x32_bf16 v[48:51], v[216:219], v[162:165], v[48:51]
	v_mfma_f32_16x16x32_bf16 v[36:39], v[208:211], v[182:185], v[36:39]
	v_mfma_f32_16x16x32_bf16 v[32:35], v[216:219], v[182:185], v[32:35]
	v_mfma_f32_16x16x32_bf16 v[20:23], v[208:211], v[190:193], v[20:23]
	v_mfma_f32_16x16x32_bf16 v[16:19], v[216:219], v[190:193], v[16:19]
	v_mfma_f32_16x16x32_bf16 v[4:7], v[208:211], v[198:201], v[4:7]
	v_mfma_f32_16x16x32_bf16 v[0:3], v[216:219], v[198:201], v[0:3]
	v_mfma_f32_16x16x32_bf16 v[52:55], v[212:215], v[166:169], v[52:55]
	v_mfma_f32_16x16x32_bf16 v[48:51], v[220:223], v[166:169], v[48:51]
	v_mfma_f32_16x16x32_bf16 v[36:39], v[212:215], v[186:189], v[36:39]
	v_mfma_f32_16x16x32_bf16 v[32:35], v[220:223], v[186:189], v[32:35]
	v_mfma_f32_16x16x32_bf16 v[20:23], v[212:215], v[194:197], v[20:23]
	v_mfma_f32_16x16x32_bf16 v[16:19], v[220:223], v[194:197], v[16:19]
	v_mfma_f32_16x16x32_bf16 v[4:7], v[212:215], v[202:205], v[4:7]
	v_mfma_f32_16x16x32_bf16 v[0:3], v[220:223], v[202:205], v[0:3]
	s_add_i32 s49, s49, 2
	s_add_u32 s26, s26, 0x100
	s_addc_u32 s27, s27, 0
	s_add_u32 s47, s47, 0x100
	s_addc_u32 s48, s48, 0
	s_cmp_gt_u32 s49, 13
	s_barrier
	s_cbranch_scc0 .LBB0_619
	v_lshl_add_u32 v164, s24, 8, v172
	v_ashrrev_i32_e32 v165, 31, v164
	v_add_u32_e32 v152, 0xffffc000, v164
	v_readlane_b32 s48, v247, 0
	v_lshl_or_b32 v128, s25, 8, v174
	v_lshlrev_b64 v[130:131], 12, v[152:153]
	v_readlane_b32 s49, v247, 1
	v_readlane_b32 s50, v247, 2
	v_readlane_b32 s51, v247, 3
	v_lshlrev_b64 v[132:133], 12, v[164:165]
	v_ashrrev_i32_e32 v129, 31, v128
	v_lshl_add_u64 v[130:131], s[50:51], 0, v[130:131]
	v_lshl_add_u64 v[132:133], s[48:49], 0, v[132:133]
	v_cmp_gt_i32_e32 vcc, s36, v164
	v_lshlrev_b64 v[166:167], 2, v[128:129]
	v_or_b32_e32 v232, 16, v164
	v_cndmask_b32_e32 v131, v131, v133, vcc
	v_cndmask_b32_e32 v130, v130, v132, vcc
	v_lshl_add_u64 v[130:131], v[130:131], 0, v[166:167]
	global_load_dwordx4 v[182:185], v[130:131], off nt
	global_load_dwordx4 v[186:189], v[130:131], off offset:16 nt
	global_load_dwordx4 v[190:193], v[130:131], off offset:512 nt
	global_load_dwordx4 v[194:197], v[130:131], off offset:528 nt
	v_add_u32_e32 v152, 0xffffc010, v164
	v_ashrrev_i32_e32 v233, 31, v232
	v_lshlrev_b64 v[130:131], 12, v[152:153]
	v_lshlrev_b64 v[132:133], 12, v[232:233]
	v_lshl_add_u64 v[130:131], s[50:51], 0, v[130:131]
	v_lshl_add_u64 v[132:133], s[48:49], 0, v[132:133]
	v_cmp_gt_i32_e32 vcc, s36, v232
	v_or_b32_e32 v170, 32, v164
	v_ashrrev_i32_e32 v171, 31, v170
	v_cndmask_b32_e32 v131, v131, v133, vcc
	v_cndmask_b32_e32 v130, v130, v132, vcc
	v_lshl_add_u64 v[130:131], v[130:131], 0, v[166:167]
	global_load_dwordx4 v[198:201], v[130:131], off nt
	global_load_dwordx4 v[202:205], v[130:131], off offset:16 nt
	global_load_dwordx4 v[208:211], v[130:131], off offset:528 nt
	global_load_dwordx4 v[212:215], v[130:131], off offset:512 nt
	v_lshlrev_b64 v[132:133], 11, v[164:165]
	v_add_u32_e32 v152, 0xffffc020, v164
	v_lshlrev_b64 v[162:163], 1, v[128:129]
	v_lshlrev_b64 v[128:129], 12, v[170:171]
	v_lshl_add_u64 v[132:133], s[84:85], 0, v[132:133]
	v_lshlrev_b64 v[136:137], 12, v[152:153]
	v_lshl_add_u64 v[128:129], s[48:49], 0, v[128:129]
	v_lshl_add_u64 v[234:235], v[132:133], 0, v[162:163]
	v_lshl_add_u64 v[132:133], s[50:51], 0, v[136:137]
	v_cmp_gt_i32_e32 vcc, s36, v170
	v_or_b32_e32 v168, 48, v164
	v_ashrrev_i32_e32 v169, 31, v168
	v_cndmask_b32_e32 v129, v133, v129, vcc
	v_cndmask_b32_e32 v128, v132, v128, vcc
	v_lshl_add_u64 v[128:129], v[128:129], 0, v[166:167]
	global_load_dwordx4 v[216:219], v[128:129], off offset:16 nt
	global_load_dwordx4 v[220:223], v[128:129], off nt
	global_load_dwordx4 v[224:227], v[128:129], off offset:528 nt
	global_load_dwordx4 v[228:231], v[128:129], off offset:512 nt
	v_add_u32_e32 v152, 0xffffc030, v164
	v_lshlrev_b64 v[134:135], 12, v[168:169]
	v_lshlrev_b64 v[136:137], 12, v[152:153]
	v_lshl_add_u64 v[134:135], s[48:49], 0, v[134:135]
	v_lshl_add_u64 v[130:131], s[50:51], 0, v[136:137]
	v_cmp_gt_i32_e32 vcc, s36, v168
	v_readlane_b32 s52, v247, 4
	v_readlane_b32 s53, v247, 5
	v_cndmask_b32_e32 v131, v131, v135, vcc
	v_cndmask_b32_e32 v130, v130, v134, vcc
	v_lshl_add_u64 v[132:133], v[130:131], 0, v[166:167]
	global_load_dwordx4 v[136:139], v[132:133], off offset:16 nt
	global_load_dwordx4 v[140:143], v[132:133], off nt
	global_load_dwordx4 v[128:131], v[132:133], off offset:528 nt
	s_nop 0
	global_load_dwordx4 v[132:135], v[132:133], off offset:512 nt
	v_readlane_b32 s54, v247, 6
	v_readlane_b32 s55, v247, 7
	v_readlane_b32 s56, v247, 8
	v_readlane_b32 s57, v247, 9
	v_readlane_b32 s58, v247, 10
	v_readlane_b32 s59, v247, 11
	v_readlane_b32 s60, v247, 12
	v_readlane_b32 s61, v247, 13
	v_readlane_b32 s62, v247, 14
	v_readlane_b32 s63, v247, 15
	s_waitcnt vmcnt(0)
; __device__ __forceinline__ unsigned cvt_pk_bf16(float lo, float hi) { unsigned r; asm volatile("v_cvt_pk_bf16_f32 %0, %1, %2" : "=v"(r) : "v"(lo), "v"(hi)); return r; }
;     __device__ __forceinline__ void operator()(const f32x4 (&acc)[2][2][4][2], const Unit& u, int wr, int wc, int fr, int fq, const float (&epre)[1]) const {
;     ...
;             for (int m = 0; m < 4; ++m) { const int row = row0 + ai * 128 + m * 16;
;                 float ss = 0.f;
; #pragma unroll
;                 for (int bj = 0; bj < 2; ++bj) { const f32x4 h0 = bv[m][bj][0] + acc[ai][bj][m][0], h1 = bv[m][bj][1] + acc[ai][bj][m][1];
;                     u32x4 w; w.x = cvt_pk_bf16(h0[0], h0[1]); w.y = cvt_pk_bf16(h0[2], h0[3]); w.z = cvt_pk_bf16(h1[0], h1[1]); w.w = cvt_pk_bf16(h1[2], h1[3]);
;                     *(u32x4*)(HBo + (size_t)row * DM + col0 + bj * 128) = w;
;                     ss += (h0[0] * h0[0] + h0[1] * h0[1]) + (h0[2] * h0[2] + h0[3] * h0[3]) + (h1[0] * h1[0] + h1[1] * h1[1]) + (h1[2] * h1[2] + h1[3] * h1[3]); }
;                 ssv[m] = ss;
;             }
	v_pk_add_f32 v[126:127], v[126:127], v[184:185]
	v_pk_add_f32 v[124:125], v[124:125], v[182:183]
	v_pk_add_f32 v[120:121], v[120:121], v[186:187]
	v_pk_add_f32 v[184:185], v[112:113], v[194:195]
	v_cvt_pk_bf16_f32 v112, v124, v125
	v_cvt_pk_bf16_f32 v113, v126, v127
	v_mul_f32_e32 v125, v125, v125
	v_mul_f32_e32 v127, v127, v127
	v_pk_add_f32 v[122:123], v[122:123], v[188:189]
	v_pk_add_f32 v[182:183], v[114:115], v[196:197]
	v_cvt_pk_bf16_f32 v114, v120, v121
	v_mul_f32_e32 v121, v121, v121
	v_fmac_f32_e32 v125, v124, v124
	v_fmac_f32_e32 v127, v126, v126
	v_cvt_pk_bf16_f32 v115, v122, v123
	v_mul_f32_e32 v123, v123, v123
	global_store_dwordx4 v[234:235], v[112:115], off
	v_fmac_f32_e32 v121, v120, v120
	v_fmac_f32_e32 v123, v122, v122
	v_add_f32_e32 v113, v125, v127
	v_add_f32_e32 v113, v113, v121
	v_pk_add_f32 v[118:119], v[118:119], v[192:193]
	v_pk_add_f32 v[116:117], v[116:117], v[190:191]
	v_add_f32_e32 v120, v123, v113
	v_cvt_pk_bf16_f32 v112, v116, v117
	v_cvt_pk_bf16_f32 v113, v118, v119
	v_cvt_pk_bf16_f32 v114, v184, v185
	v_cvt_pk_bf16_f32 v115, v182, v183
	global_store_dwordx4 v[234:235], v[112:115], off offset:256
	v_pk_add_f32 v[110:111], v[110:111], v[200:201]
	v_pk_add_f32 v[108:109], v[108:109], v[198:199]
	v_mul_f32_e32 v112, v117, v117
	v_mul_f32_e32 v113, v119, v119
	v_fmac_f32_e32 v112, v116, v116
	v_fmac_f32_e32 v113, v118, v118
	v_add_f32_e32 v112, v112, v113
	v_mul_f32_e32 v113, v185, v185
	v_fmac_f32_e32 v113, v184, v184
	v_add_f32_e32 v112, v112, v113
	v_mul_f32_e32 v113, v183, v183
	v_fmac_f32_e32 v113, v182, v182
	v_add_f32_e32 v112, v113, v112
	v_add_f32_e32 v118, v120, v112
	v_lshlrev_b64 v[112:113], 11, v[232:233]
	v_lshl_add_u64 v[112:113], s[84:85], 0, v[112:113]
	v_pk_add_f32 v[116:117], v[104:105], v[202:203]
	v_cvt_pk_bf16_f32 v104, v108, v109
	v_cvt_pk_bf16_f32 v105, v110, v111
	v_lshl_add_u64 v[112:113], v[112:113], 0, v[162:163]
	v_pk_add_f32 v[114:115], v[106:107], v[204:205]
	v_cvt_pk_bf16_f32 v106, v116, v117
	v_pk_add_f32 v[102:103], v[102:103], v[214:215]
	v_cvt_pk_bf16_f32 v107, v114, v115
	global_store_dwordx4 v[112:113], v[104:107], off
	v_pk_add_f32 v[100:101], v[100:101], v[212:213]
	v_pk_add_f32 v[94:95], v[94:95], v[222:223]
	v_mul_f32_e32 v104, v109, v109
	v_mul_f32_e32 v105, v111, v111
	v_fmac_f32_e32 v104, v108, v108
	v_fmac_f32_e32 v105, v110, v110
	v_add_f32_e32 v104, v104, v105
	v_mul_f32_e32 v105, v117, v117
	v_fmac_f32_e32 v105, v116, v116
	v_add_f32_e32 v104, v104, v105
	v_mul_f32_e32 v105, v115, v115
	v_fmac_f32_e32 v105, v114, v114
	v_pk_add_f32 v[106:107], v[96:97], v[208:209]
	v_cvt_pk_bf16_f32 v96, v100, v101
	v_cvt_pk_bf16_f32 v97, v102, v103
	v_add_f32_e32 v108, v105, v104
	v_pk_add_f32 v[104:105], v[98:99], v[210:211]
	v_cvt_pk_bf16_f32 v98, v106, v107
	v_pk_add_f32 v[92:93], v[92:93], v[220:221]
	v_cvt_pk_bf16_f32 v99, v104, v105
	global_store_dwordx4 v[112:113], v[96:99], off offset:256
	v_pk_add_f32 v[86:87], v[86:87], v[230:231]
	v_pk_add_f32 v[84:85], v[84:85], v[228:229]
	v_mul_f32_e32 v96, v101, v101
	v_mul_f32_e32 v97, v103, v103
	v_fmac_f32_e32 v96, v100, v100
	v_fmac_f32_e32 v97, v102, v102
	v_add_f32_e32 v96, v96, v97
	v_mul_f32_e32 v97, v107, v107
	v_fmac_f32_e32 v97, v106, v106
	v_add_f32_e32 v96, v96, v97
	v_mul_f32_e32 v97, v105, v105
	v_fmac_f32_e32 v97, v104, v104
	v_add_f32_e32 v96, v97, v96
	v_add_f32_e32 v102, v108, v96
	v_lshlrev_b64 v[96:97], 11, v[170:171]
	v_lshl_add_u64 v[96:97], s[84:85], 0, v[96:97]
	v_pk_add_f32 v[100:101], v[88:89], v[216:217]
	v_cvt_pk_bf16_f32 v88, v92, v93
	v_cvt_pk_bf16_f32 v89, v94, v95
	v_lshl_add_u64 v[96:97], v[96:97], 0, v[162:163]
	v_pk_add_f32 v[98:99], v[90:91], v[218:219]
	v_cvt_pk_bf16_f32 v90, v100, v101
	v_pk_add_f32 v[78:79], v[78:79], v[142:143]
	v_cvt_pk_bf16_f32 v91, v98, v99
	global_store_dwordx4 v[96:97], v[88:91], off
	v_pk_add_f32 v[76:77], v[76:77], v[140:141]
	v_pk_add_f32 v[70:71], v[70:71], v[134:135]
	v_mul_f32_e32 v88, v93, v93
	v_mul_f32_e32 v89, v95, v95
	v_fmac_f32_e32 v88, v92, v92
	v_fmac_f32_e32 v89, v94, v94
	v_add_f32_e32 v88, v88, v89
	v_mul_f32_e32 v89, v101, v101
	v_fmac_f32_e32 v89, v100, v100
	v_add_f32_e32 v88, v88, v89
	v_mul_f32_e32 v89, v99, v99
	v_fmac_f32_e32 v89, v98, v98
	v_pk_add_f32 v[90:91], v[80:81], v[224:225]
	v_cvt_pk_bf16_f32 v80, v84, v85
	v_cvt_pk_bf16_f32 v81, v86, v87
	v_add_f32_e32 v92, v89, v88
	v_pk_add_f32 v[88:89], v[82:83], v[226:227]
	v_cvt_pk_bf16_f32 v82, v90, v91
	v_pk_add_f32 v[68:69], v[68:69], v[132:133]
	v_cvt_pk_bf16_f32 v83, v88, v89
	global_store_dwordx4 v[96:97], v[80:83], off offset:256
	s_nop 1
	v_mul_f32_e32 v80, v85, v85
	v_mul_f32_e32 v81, v87, v87
	v_fmac_f32_e32 v80, v84, v84
	v_fmac_f32_e32 v81, v86, v86
	v_add_f32_e32 v80, v80, v81
	v_mul_f32_e32 v81, v91, v91
	v_fmac_f32_e32 v81, v90, v90
	v_add_f32_e32 v80, v80, v81
	v_mul_f32_e32 v81, v89, v89
	v_fmac_f32_e32 v81, v88, v88
	v_add_f32_e32 v80, v81, v80
	v_add_f32_e32 v87, v92, v80
	v_lshlrev_b64 v[80:81], 11, v[168:169]
	v_lshl_add_u64 v[80:81], s[84:85], 0, v[80:81]
	v_pk_add_f32 v[82:83], v[74:75], v[138:139]
	v_pk_add_f32 v[84:85], v[72:73], v[136:137]
	v_cvt_pk_bf16_f32 v72, v76, v77
	v_cvt_pk_bf16_f32 v73, v78, v79
	v_lshl_add_u64 v[80:81], v[80:81], 0, v[162:163]
	v_cvt_pk_bf16_f32 v74, v84, v85
	v_cvt_pk_bf16_f32 v75, v82, v83
	global_store_dwordx4 v[80:81], v[72:75], off
	s_nop 1
	v_mul_f32_e32 v72, v77, v77
	v_mul_f32_e32 v73, v79, v79
	v_pk_add_f32 v[74:75], v[64:65], v[128:129]
	v_mul_f32_e32 v64, v69, v69
	v_mul_f32_e32 v65, v71, v71
	v_fmac_f32_e32 v72, v76, v76
	v_fmac_f32_e32 v73, v78, v78
	v_fmac_f32_e32 v64, v68, v68
	v_fmac_f32_e32 v65, v70, v70
	v_add_f32_e32 v72, v72, v73
	v_mul_f32_e32 v73, v85, v85
	v_add_f32_e32 v64, v64, v65
	v_mul_f32_e32 v65, v75, v75
	v_fmac_f32_e32 v73, v84, v84
	v_pk_add_f32 v[76:77], v[66:67], v[130:131]
	v_fmac_f32_e32 v65, v74, v74
	v_add_f32_e32 v72, v72, v73
	v_mul_f32_e32 v73, v83, v83
	v_add_f32_e32 v64, v64, v65
	v_mul_f32_e32 v65, v77, v77
	v_fmac_f32_e32 v73, v82, v82
	v_fmac_f32_e32 v65, v76, v76
	v_add_f32_e32 v73, v73, v72
	v_add_f32_e32 v64, v65, v64
	v_and_b32_e32 v65, 64, v181
	v_cvt_pk_bf16_f32 v72, v68, v69
	v_add_f32_e32 v67, v73, v64
	v_xor_b32_e32 v64, 16, v181
	v_add_u32_e32 v68, 64, v65
	v_cmp_lt_i32_e32 vcc, v64, v68
	v_cvt_pk_bf16_f32 v73, v70, v71
	v_cvt_pk_bf16_f32 v74, v74, v75
	v_cvt_pk_bf16_f32 v75, v76, v77
	global_store_dwordx4 v[80:81], v[72:75], off offset:256
	v_lshl_add_u64 v[80:81], v[164:165], 2, s[10:11]
	v_cndmask_b32_e32 v64, v181, v64, vcc
	v_lshlrev_b32_e32 v86, 2, v64
	ds_bpermute_b32 v69, v86, v67
	ds_bpermute_b32 v64, v86, v118
	ds_bpermute_b32 v65, v86, v102
	ds_bpermute_b32 v66, v86, v87
	s_waitcnt lgkmcnt(0)
;     __device__ __forceinline__ void operator()(const f32x4 (&acc)[2][2][4][2], const Unit& u, int wr, int wc, int fr, int fq, const float (&epre)[1]) const {
;     ...
; #pragma unroll
;             for (int m = 0; m < 4; ++m) ssv[m] += __shfl_xor(ssv[m], 16);
; #pragma unroll
;             for (int m = 0; m < 4; ++m) ssv[m] += __shfl_xor(ssv[m], 32);
;             if (fq == 0) {
; #pragma unroll
;                 for (int m = 0; m < 4; ++m) atomicAdd(sumsq + row0 + ai * 128 + m * 16, ssv[m]); }
	v_add_f32_e32 v67, v67, v69
	v_xor_b32_e32 v69, 32, v181
	v_cmp_lt_i32_e32 vcc, v69, v68
	v_add_f32_e32 v64, v118, v64
	v_add_f32_e32 v65, v102, v65
	v_cndmask_b32_e32 v68, v181, v69, vcc
	v_add_f32_e32 v66, v87, v66
	v_lshlrev_b32_e32 v87, 2, v68
	ds_bpermute_b32 v68, v87, v64
	ds_bpermute_b32 v69, v87, v65
	ds_bpermute_b32 v70, v87, v66
	ds_bpermute_b32 v71, v87, v67
	s_and_saveexec_b64 s[24:25], s[6:7]
	s_cbranch_execz .LBB0_622
	s_waitcnt lgkmcnt(3)
	v_add_f32_e32 v64, v64, v68
	s_waitcnt lgkmcnt(0)
	v_add_f32_e32 v67, v67, v71
	v_add_f32_e32 v66, v66, v70
	v_add_f32_e32 v65, v65, v69
	global_atomic_add_f32 v[80:81], v64, off
	global_atomic_add_f32 v[80:81], v65, off offset:64
	global_atomic_add_f32 v[80:81], v66, off offset:128
	global_atomic_add_f32 v[80:81], v67, off offset:192

; #define PG8_WAIT_V(n) asm volatile("s_waitcnt vmcnt(" #n ")" ::: "memory")
; #define PG8_BAR __builtin_amdgcn_s_barrier()
; template <class Epi, class Sched>
; __device__ __forceinline__ void gemm_phase(PG8_LAS unsigned char* lds, const Gemm g, const Sched& S, const Epi& E) {
;     ...
;     PG8_WAIT_V(0);
;     if (wr == 0) PG8_BAR;
;     PG8_BAR;
; __global__ void __launch_bounds__(512, 2) hymba_fwd(Params p) {
;     ...
;         for (int u = bx; u < 256; u += G) small_gemm<DM>(lds, g.A, g.Bt, MP + 32 * (u >> 4), (u & 15) * 64, (u & 15) * 64 + 32, E);
.LBB0_626:
	v_and_b32_e32 v0, 7, v176
	v_cmp_eq_u32_e32 vcc, 0, v0
	s_lshl_b32 s0, s2, 1
	s_lshl_b32 s1, s66, 1
	s_lshl_b32 s3, s2, 6
	s_lshl_b32 s4, s66, 6
	s_movk_i32 s5, 0x4000
	s_movk_i32 s16, 0x100
	v_mov_b32_e32 v41, 0
	v_mov_b32_e32 v42, 0x10000
	s_movk_i32 s17, 0x90
	s_mov_b32 s18, s2
	s_barrier
	s_setprio 0
	s_branch .LBB0_628

; #define PG8_STAGE(bufoff, gbase, voff) do { _Pragma("unroll") for (int _i = 0; _i < 2; ++_i) \
;         __builtin_amdgcn_global_load_lds((const unsigned*)((const char*)(gbase) + (voff)[_i]), (PG8_LAS unsigned*)(lds + (bufoff) + ldsw + _i * 8192), 16, 0, 0); } while (0)
; #define PG8_WAIT_V(n) asm volatile("s_waitcnt vmcnt(" #n ")" ::: "memory")
; template <class Epi, class Sched>
; __device__ __forceinline__ void gemm_phase(PG8_LAS unsigned char* lds, const Gemm g, const Sched& S, const Epi& E) {
;     ...
;     for (int i = 0; i < 2; ++i) { int R, C; stage_rc(tid * 16 + i * 8192, R, C); const int Rb = Epi::PERM ? ((R & ~31) + perm32(R & 31)) : R;
;         voffA[i] = (unsigned)(R * K + C) * 2u; voffB[i] = (unsigned)(Rb * K + C) * 2u; }
;     const size_t kstep = (size_t)(BK * 2);
;     const size_t hstep = (size_t)HALF * K * 2;
;     const size_t tstep = 2 * hstep;
;     const unsigned ldsw = (unsigned)wid * 1024u;
;     const int aoff = lds_byte(wr * 64 + fr, fq * 8), boff = lds_byte(wc * 32 + fr, fq * 8);
;     ...
;     Unit cur, nxt; int ui = 0;
;     if (!S.next(0, cur)) return;
;     f32x4 acc[2][2][4][2];
; #pragma unroll
;     for (int a = 0; a < 2; ++a)
; #pragma unroll
;         for (int b = 0; b < 2; ++b)
; #pragma unroll
;             for (int m = 0; m < 4; ++m)
; #pragma unroll
;                 for (int n = 0; n < 2; ++n) acc[a][b][m][n] = (f32x4){0.f, 0.f, 0.f, 0.f};
;     bf16x8 At[4][2], B0[2][2], B1[2][2];
;     const char* cA = (const char*)g.A + (size_t)cur.pm * tstep; const char* cB = (const char*)g.Bt + (size_t)cur.pn * tstep;
;     float epre[Epi::NPRE]; E.preload(cur, wr, fr, epre);
;     S.a_ready(cur);
;     PG8_STAGE(PG8_SB(0, 0), cB, voffB); PG8_STAGE(PG8_SA(0, 0), cA, voffA); PG8_STAGE(PG8_SB(0, 1), cB + hstep, voffB); PG8_STAGE(PG8_SA(0, 1), cA + hstep, voffA);
;     if (wr == 1) PG8_BAR;
;     PG8_WAIT_V(4); PG8_BAR;
;     PG8_STAGE(PG8_SB(1, 0), cB + kstep, voffB); PG8_STAGE(PG8_SA(1, 0), cA + kstep, voffA); PG8_STAGE(PG8_SB(1, 1), cB + hstep + kstep, voffB);
;     PG8_WAIT_V(6); PG8_BAR;
;     __device__ __forceinline__ void preload(const Unit& u, int wr, int fr, float (&pre)[8]) const { const int row0 = u.pm * 256 + wr * 64 + fr;
; #pragma unroll
;         for (int ai = 0; ai < 2; ++ai)
; #pragma unroll
;             for (int m = 0; m < 4; ++m) pre[ai * 4 + m] = sumsq[row0 + ai * 128 + m * 16]; }
.LBB0_692:
	v_ashrrev_i32_e32 v1, 31, v8
	v_lshrrev_b32_e32 v1, 26, v1
	v_add_u32_e32 v1, v8, v1
	v_ashrrev_i32_e32 v9, 6, v1
	v_bfe_i32 v1, v8, 27, 1
	v_lshlrev_b32_e32 v0, 4, v8
	v_lshrrev_b32_e32 v1, 22, v1
	v_add_u32_e32 v1, v0, v1
	v_and_b32_e32 v1, 0xfffffc00, v1
	v_sub_u32_e32 v1, v0, v1
	v_lshrrev_b32_e32 v2, 4, v1
	v_bitop3_b32 v1, v2, v1, 32 bitop3:0x6c
	v_ashrrev_i32_e32 v3, 31, v1
	v_lshrrev_b32_e32 v3, 26, v3
	v_add_u32_e32 v3, v1, v3
	v_lshlrev_b32_e32 v2, 3, v9
	v_ashrrev_i32_e32 v10, 6, v3
	v_and_b32_e32 v3, 0xc0, v3
	v_and_b32_e32 v2, -16, v2
	v_sub_u32_e32 v1, v1, v3
	v_mov_b32_e32 v3, 1
	v_add_u32_e32 v2, v10, v2
	v_ashrrev_i16_sdwa v1, v3, sext(v1) dst_sel:DWORD dst_unused:UNUSED_PAD src0_sel:DWORD src1_sel:BYTE_0
	v_lshlrev_b32_e32 v4, 5, v9
	v_bfe_i32 v11, v1, 0, 16
	v_lshlrev_b32_e32 v1, 1, v2
	v_lshrrev_b32_e32 v5, 2, v2
	v_and_b32_e32 v6, 3, v10
	s_mov_b32 s4, 0x1fffe0
	v_and_b32_e32 v4, 32, v4
	v_and_b32_e32 v1, 24, v1
	v_and_b32_e32 v5, 4, v5
	v_and_or_b32 v6, v2, s4, v6
	v_or3_b32 v1, v6, v5, v1
	v_add_lshl_u32 v4, v4, v11, 1
	v_add_u32_e32 v0, 0x2000, v0
	v_lshl_add_u32 v130, v1, 11, v4
	v_ashrrev_i32_e32 v1, 31, v0
	v_lshrrev_b32_e32 v1, 22, v1
	v_add_u32_e32 v1, v0, v1
	s_waitcnt vmcnt(0)
	v_ashrrev_i32_e32 v12, 10, v1
	v_mul_i32_i24_e32 v1, 0x400, v12
	v_sub_u32_e32 v0, v0, v1
	v_lshrrev_b32_e32 v1, 4, v0
	v_bitop3_b32 v0, v1, v0, 32 bitop3:0x6c
	v_lshl_add_u32 v128, v2, 11, v4
	v_ashrrev_i32_e32 v2, 31, v0
	v_lshrrev_b32_e32 v2, 26, v2
	v_add_u32_e32 v2, v0, v2
	v_lshlrev_b32_e32 v1, 3, v12
	v_ashrrev_i32_e32 v13, 6, v2
	v_and_b32_e32 v2, 0xc0, v2
	s_add_u32 s1, s64, 0x800000
	v_and_b32_e32 v1, -16, v1
	v_sub_u32_e32 v0, v0, v2
	s_addc_u32 s3, s65, 0
	s_ashr_i32 s6, s0, 8
	v_add_u32_e32 v1, v13, v1
	v_ashrrev_i16_sdwa v0, v3, sext(v0) dst_sel:DWORD dst_unused:UNUSED_PAD src0_sel:DWORD src1_sel:BYTE_0
	v_and_b32_e32 v3, 3, v13
	s_ashr_i32 s7, s0, 6
	s_ashr_i32 s21, s20, 31
	s_ashr_i32 s23, s22, 31
	v_and_or_b32 v3, v1, s4, v3
	s_lshl_b32 s4, s7, 10
	s_lshl_b32 s8, s6, 6
	s_lshl_b64 s[12:13], s[20:21], 19
	s_lshl_b64 s[14:15], s[22:23], 19
	v_lshlrev_b32_e32 v4, 5, v12
	v_bfe_i32 v14, v0, 0, 16
	v_lshlrev_b32_e32 v0, 1, v1
	v_lshrrev_b32_e32 v2, 2, v1
	s_add_u32 s26, s1, s14
	v_and_b32_e32 v4, 32, v4
	v_and_b32_e32 v0, 24, v0
	v_and_b32_e32 v2, 4, v2
	s_addc_u32 s27, s3, s15
	s_lshl_b32 s5, s20, 8
	v_or3_b32 v0, v3, v2, v0
	v_add_lshl_u32 v2, v4, v14, 1
	v_and_b32_e32 v15, 15, v8
	s_add_i32 s5, s5, s8
	v_lshl_add_u32 v134, v0, 11, v2
	v_or_b32_e32 v0, s5, v15
	v_lshl_add_u32 v132, v1, 11, v2
	v_ashrrev_i32_e32 v1, 31, v0
	s_add_i32 s5, s4, 0
	v_lshl_add_u64 v[0:1], v[0:1], 2, s[10:11]
	s_add_i32 m0, s5, 0x10000
	global_load_dword v156, v[0:1], off
	global_load_dword v155, v[0:1], off offset:64
	global_load_dword v154, v[0:1], off offset:128
	global_load_dword v153, v[0:1], off offset:192
	global_load_dword v152, v[0:1], off offset:512
	global_load_dword v151, v[0:1], off offset:576
	global_load_dword v150, v[0:1], off offset:640
	global_load_dword v142, v[0:1], off offset:704
	v_mov_b32_e32 v131, 0
	global_load_lds_dwordx4 v130, s[26:27]
	s_add_i32 m0, s5, 0x12000
	s_add_u32 s24, s84, s12
	global_load_lds_dwordx4 v134, s[26:27]
	s_addc_u32 s25, s85, s13
	s_mov_b32 m0, s5
	s_add_i32 s23, s5, 0x2000
	global_load_lds_dwordx4 v128, s[24:25]
	s_mov_b32 m0, s23
	s_add_u32 s12, s26, 0x40000
	global_load_lds_dwordx4 v132, s[24:25]
	s_addc_u32 s13, s27, 0
	s_add_i32 m0, s5, 0x14000
	v_mov_b32_e32 v135, v131
	global_load_lds_dwordx4 v130, s[12:13]
	s_add_i32 m0, s5, 0x16000
	v_mov_b32_e32 v129, v131
	global_load_lds_dwordx4 v134, s[12:13]
	s_add_u32 s12, s24, 0x40000
	s_addc_u32 s13, s25, 0
	s_add_i32 s30, s5, 0x4000
	s_mov_b32 m0, s30
	s_add_i32 s31, s5, 0x6000
	global_load_lds_dwordx4 v128, s[12:13]
	s_mov_b32 m0, s31
	v_mov_b32_e32 v133, v131
	global_load_lds_dwordx4 v132, s[12:13]
	s_mov_b32 s33, 0
	v_lshl_add_u64 v[6:7], s[26:27], 0, v[130:131]
	v_lshl_add_u64 v[4:5], s[26:27], 0, v[134:135]
	v_lshl_add_u64 v[2:3], s[24:25], 0, v[128:129]
	s_cmp_lg_u32 s6, 1
	v_lshl_add_u64 v[0:1], s[24:25], 0, v[132:133]
	s_cbranch_scc1 .LBB0_694
	s_barrier
	s_setprio 1

; #define PG8_STAGE(bufoff, gbase, voff) do { _Pragma("unroll") for (int _i = 0; _i < 2; ++_i) \
;         __builtin_amdgcn_global_load_lds((const unsigned*)((const char*)(gbase) + (voff)[_i]), (PG8_LAS unsigned*)(lds + (bufoff) + ldsw + _i * 8192), 16, 0, 0); } while (0)
; #define PG8_LDA(dst, b, h) do { _Pragma("unroll") for (int m = 0; m < 4; ++m) _Pragma("unroll") for (int k = 0; k < 2; ++k) dst[m][k] = *(const PG8_LAS bf16x8*)(lds + PG8_SA(b, h) + aoff + m * 2048 + k * 1024); } while (0)
; #define PG8_LDB(dst, b, h) do { _Pragma("unroll") for (int n = 0; n < 2; ++n) _Pragma("unroll") for (int k = 0; k < 2; ++k) dst[n][k] = *(const PG8_LAS bf16x8*)(lds + PG8_SB(b, h) + boff + n * 2048 + k * 1024); } while (0)
; #define PG8_MMA(ai, bj, At, Bt) do { __builtin_amdgcn_s_setprio(1); _Pragma("unroll") for (int m = 0; m < 4; ++m) _Pragma("unroll") for (int n = 0; n < 2; ++n) _Pragma("unroll") for (int k = 0; k < 2; ++k) \
;         acc[ai][bj][m][n] = __builtin_amdgcn_mfma_f32_16x16x32_bf16(Bt[n][k], At[m][k], acc[ai][bj][m][n], 0, 0, 0); __builtin_amdgcn_s_setprio(0); } while (0)
; #define PG8_WAIT_V(n) asm volatile("s_waitcnt vmcnt(" #n ")" ::: "memory")
; #define PG8_WAIT_L(n) asm volatile("s_waitcnt lgkmcnt(" #n ")" ::: "memory")
; #define PG8_BAR __builtin_amdgcn_s_barrier()
; #define PG8_SCHED __builtin_amdgcn_sched_barrier(0)
; template <class Epi, class Sched>
; __device__ __forceinline__ void gemm_phase(PG8_LAS unsigned char* lds, const Gemm g, const Sched& S, const Epi& E) {
;     ...
;             PG8_LDB(B0, 0, 0); PG8_SCHED; PG8_LDA(At, 0, 0); PG8_STAGE(PG8_SA(1, 1), a1 + hstep, voffA);
;             PG8_WAIT_L(8); PG8_BAR; PG8_WAIT_L(0); PG8_MMA(0, 0, At, B0); PG8_BAR; PG8_SCHED;
;             PG8_LDB(B1, 0, 1); PG8_STAGE(PG8_SB(0, 0), b2, voffB);
;             PG8_BAR; PG8_WAIT_L(0); PG8_MMA(0, 1, At, B1); PG8_BAR;
;             PG8_LDA(At, 0, 1); PG8_STAGE(PG8_SA(0, 0), a2, voffA);
;             PG8_BAR; PG8_WAIT_L(0); PG8_MMA(1, 0, At, B0); PG8_BAR; PG8_SCHED;
;             PG8_STAGE(PG8_SB(0, 1), b2 + hstep, voffB);
;             PG8_WAIT_V(6); PG8_BAR; PG8_MMA(1, 1, At, B1); PG8_BAR;
.LBB0_702:
	ds_read_b128 v[158:161], v146
	ds_read_b128 v[162:165], v146 offset:1024
	ds_read_b128 v[166:169], v146 offset:2048
	ds_read_b128 v[170:173], v146 offset:3072
	s_add_u32 s26, s24, 0xfffc0080
	s_addc_u32 s27, s25, -1
	s_cmp_eq_u32 s45, 12
	s_cselect_b32 s29, s13, s27
	s_cselect_b32 s28, s21, s26
	s_cselect_b32 s27, s9, s44
	s_cselect_b32 s26, s42, s43
	v_lshl_add_u64 v[174:175], s[24:25], 0, v[136:137]
	s_add_i32 m0, s5, 0xc000
	ds_read_b128 v[180:183], v147
	ds_read_b128 v[184:187], v147 offset:1024
	ds_read_b128 v[188:191], v147 offset:2048
	ds_read_b128 v[192:195], v147 offset:3072
	ds_read_b128 v[196:199], v147 offset:4096
	ds_read_b128 v[200:203], v147 offset:5120
	ds_read_b128 v[208:211], v147 offset:6144
	ds_read_b128 v[212:215], v147 offset:7168
	global_load_lds_dwordx4 v[174:175], off
	v_lshl_add_u64 v[174:175], s[24:25], 0, v[138:139]
	s_add_i32 m0, s5, 0xe000
	s_nop 0
	global_load_lds_dwordx4 v[174:175], off
	s_waitcnt lgkmcnt(8)
	s_barrier
	s_waitcnt lgkmcnt(0)
	s_waitcnt lgkmcnt(0)
	v_mfma_f32_16x16x32_bf16 v[124:127], v[158:161], v[180:183], v[124:127]
	v_mfma_f32_16x16x32_bf16 v[116:119], v[166:169], v[180:183], v[116:119]
	v_mfma_f32_16x16x32_bf16 v[108:111], v[158:161], v[188:191], v[108:111]
	v_mfma_f32_16x16x32_bf16 v[100:103], v[166:169], v[188:191], v[100:103]
	v_mfma_f32_16x16x32_bf16 v[92:95], v[158:161], v[196:199], v[92:95]
	v_mfma_f32_16x16x32_bf16 v[84:87], v[166:169], v[196:199], v[84:87]
	v_mfma_f32_16x16x32_bf16 v[76:79], v[158:161], v[208:211], v[76:79]
	v_mfma_f32_16x16x32_bf16 v[68:71], v[166:169], v[208:211], v[68:71]
	v_mfma_f32_16x16x32_bf16 v[124:127], v[162:165], v[184:187], v[124:127]
	v_mfma_f32_16x16x32_bf16 v[116:119], v[170:173], v[184:187], v[116:119]
	v_mfma_f32_16x16x32_bf16 v[108:111], v[162:165], v[192:195], v[108:111]
	v_mfma_f32_16x16x32_bf16 v[100:103], v[170:173], v[192:195], v[100:103]
	v_mfma_f32_16x16x32_bf16 v[92:95], v[162:165], v[200:203], v[92:95]
	v_mfma_f32_16x16x32_bf16 v[84:87], v[170:173], v[200:203], v[84:87]
	v_mfma_f32_16x16x32_bf16 v[76:79], v[162:165], v[212:215], v[76:79]
	v_mfma_f32_16x16x32_bf16 v[68:71], v[170:173], v[212:215], v[68:71]
	s_barrier
	s_add_i32 s46, s38, s4
	v_lshl_add_u64 v[174:175], s[26:27], 0, v[130:131]
	s_mov_b32 m0, s46
	ds_read_b128 v[216:219], v148
	ds_read_b128 v[220:223], v148 offset:1024
	ds_read_b128 v[224:227], v148 offset:2048
	ds_read_b128 v[228:231], v148 offset:3072
	global_load_lds_dwordx4 v[174:175], off
	v_lshl_add_u64 v[204:205], s[26:27], 0, v[134:135]
	s_add_i32 m0, s46, 0x2000
	s_nop 0
	global_load_lds_dwordx4 v[204:205], off
	s_barrier
	s_waitcnt lgkmcnt(0)
	s_waitcnt lgkmcnt(0)
	v_mfma_f32_16x16x32_bf16 v[120:123], v[216:219], v[180:183], v[120:123]
	v_mfma_f32_16x16x32_bf16 v[112:115], v[224:227], v[180:183], v[112:115]
	v_mfma_f32_16x16x32_bf16 v[104:107], v[216:219], v[188:191], v[104:107]
	v_mfma_f32_16x16x32_bf16 v[96:99], v[224:227], v[188:191], v[96:99]
	v_mfma_f32_16x16x32_bf16 v[88:91], v[216:219], v[196:199], v[88:91]
	v_mfma_f32_16x16x32_bf16 v[80:83], v[224:227], v[196:199], v[80:83]
	v_mfma_f32_16x16x32_bf16 v[72:75], v[216:219], v[208:211], v[72:75]
	v_mfma_f32_16x16x32_bf16 v[64:67], v[224:227], v[208:211], v[64:67]
	v_mfma_f32_16x16x32_bf16 v[120:123], v[220:223], v[184:187], v[120:123]
	v_mfma_f32_16x16x32_bf16 v[112:115], v[228:231], v[184:187], v[112:115]
	v_mfma_f32_16x16x32_bf16 v[104:107], v[220:223], v[192:195], v[104:107]
	v_mfma_f32_16x16x32_bf16 v[96:99], v[228:231], v[192:195], v[96:99]
	v_mfma_f32_16x16x32_bf16 v[88:91], v[220:223], v[200:203], v[88:91]
	v_mfma_f32_16x16x32_bf16 v[80:83], v[228:231], v[200:203], v[80:83]
	v_mfma_f32_16x16x32_bf16 v[72:75], v[220:223], v[212:215], v[72:75]
	v_mfma_f32_16x16x32_bf16 v[64:67], v[228:231], v[212:215], v[64:67]
	s_mov_b32 m0, s5
	v_lshl_add_u64 v[232:233], s[28:29], 0, v[128:129]
	s_barrier
	ds_read_b128 v[180:183], v147 offset:16384
	ds_read_b128 v[184:187], v147 offset:17408
	ds_read_b128 v[188:191], v147 offset:18432
	ds_read_b128 v[192:195], v147 offset:19456
	ds_read_b128 v[196:199], v147 offset:20480
	ds_read_b128 v[200:203], v147 offset:21504
	ds_read_b128 v[208:211], v147 offset:22528
	ds_read_b128 v[212:215], v147 offset:23552
	global_load_lds_dwordx4 v[232:233], off
	v_lshl_add_u64 v[234:235], s[28:29], 0, v[132:133]
	s_mov_b32 m0, s23
	s_nop 0
	global_load_lds_dwordx4 v[234:235], off
	s_barrier
	s_waitcnt lgkmcnt(0)
	s_waitcnt lgkmcnt(0)
	v_mfma_f32_16x16x32_bf16 v[60:63], v[158:161], v[180:183], v[60:63]
	v_mfma_f32_16x16x32_bf16 v[52:55], v[166:169], v[180:183], v[52:55]
	v_mfma_f32_16x16x32_bf16 v[44:47], v[158:161], v[188:191], v[44:47]
	v_mfma_f32_16x16x32_bf16 v[36:39], v[166:169], v[188:191], v[36:39]
	v_mfma_f32_16x16x32_bf16 v[28:31], v[158:161], v[196:199], v[28:31]
	v_mfma_f32_16x16x32_bf16 v[20:23], v[166:169], v[196:199], v[20:23]
	v_mfma_f32_16x16x32_bf16 v[12:15], v[158:161], v[208:211], v[12:15]
	v_mfma_f32_16x16x32_bf16 v[4:7], v[166:169], v[208:211], v[4:7]
	v_mfma_f32_16x16x32_bf16 v[60:63], v[162:165], v[184:187], v[60:63]
	v_mfma_f32_16x16x32_bf16 v[52:55], v[170:173], v[184:187], v[52:55]
	v_mfma_f32_16x16x32_bf16 v[44:47], v[162:165], v[192:195], v[44:47]
	v_mfma_f32_16x16x32_bf16 v[36:39], v[170:173], v[192:195], v[36:39]
	v_mfma_f32_16x16x32_bf16 v[28:31], v[162:165], v[200:203], v[28:31]
	v_mfma_f32_16x16x32_bf16 v[20:23], v[170:173], v[200:203], v[20:23]
	v_mfma_f32_16x16x32_bf16 v[12:15], v[162:165], v[212:215], v[12:15]
	v_mfma_f32_16x16x32_bf16 v[4:7], v[170:173], v[212:215], v[4:7]
	s_barrier
; #define PG8_STAGE(bufoff, gbase, voff) do { _Pragma("unroll") for (int _i = 0; _i < 2; ++_i) \
;         __builtin_amdgcn_global_load_lds((const unsigned*)((const char*)(gbase) + (voff)[_i]), (PG8_LAS unsigned*)(lds + (bufoff) + ldsw + _i * 8192), 16, 0, 0); } while (0)
; #define PG8_LDA(dst, b, h) do { _Pragma("unroll") for (int m = 0; m < 4; ++m) _Pragma("unroll") for (int k = 0; k < 2; ++k) dst[m][k] = *(const PG8_LAS bf16x8*)(lds + PG8_SA(b, h) + aoff + m * 2048 + k * 1024); } while (0)
; #define PG8_LDB(dst, b, h) do { _Pragma("unroll") for (int n = 0; n < 2; ++n) _Pragma("unroll") for (int k = 0; k < 2; ++k) dst[n][k] = *(const PG8_LAS bf16x8*)(lds + PG8_SB(b, h) + boff + n * 2048 + k * 1024); } while (0)
; #define PG8_MMA(ai, bj, At, Bt) do { __builtin_amdgcn_s_setprio(1); _Pragma("unroll") for (int m = 0; m < 4; ++m) _Pragma("unroll") for (int n = 0; n < 2; ++n) _Pragma("unroll") for (int k = 0; k < 2; ++k) \
;         acc[ai][bj][m][n] = __builtin_amdgcn_mfma_f32_16x16x32_bf16(Bt[n][k], At[m][k], acc[ai][bj][m][n], 0, 0, 0); __builtin_amdgcn_s_setprio(0); } while (0)
; #define PG8_WAIT_V(n) asm volatile("s_waitcnt vmcnt(" #n ")" ::: "memory")
; #define PG8_WAIT_L(n) asm volatile("s_waitcnt lgkmcnt(" #n ")" ::: "memory")
; #define PG8_BAR __builtin_amdgcn_s_barrier()
; #define PG8_SCHED __builtin_amdgcn_sched_barrier(0)
; template <class Epi, class Sched>
; __device__ __forceinline__ void gemm_phase(PG8_LAS unsigned char* lds, const Gemm g, const Sched& S, const Epi& E) {
;     ...
;             PG8_STAGE(PG8_SB(0, 1), b2 + hstep, voffB);
;             PG8_WAIT_V(6); PG8_BAR; PG8_MMA(1, 1, At, B1); PG8_BAR;
;             PG8_LDB(B0, 1, 0); PG8_SCHED; PG8_LDA(At, 1, 0); PG8_STAGE(PG8_SA(0, 1), a2 + hstep, voffA);
;             PG8_WAIT_L(8); PG8_BAR; PG8_WAIT_L(0); PG8_MMA(0, 0, At, B0); PG8_BAR; PG8_SCHED;
;             PG8_LDB(B1, 1, 1); PG8_STAGE(PG8_SB(1, 0), b3, voffB);
;             PG8_BAR; PG8_WAIT_L(0); PG8_MMA(0, 1, At, B1); PG8_BAR;
;             PG8_LDA(At, 1, 1); PG8_STAGE(PG8_SA(1, 0), a3, voffA);
;             PG8_BAR; PG8_WAIT_L(0); PG8_MMA(1, 0, At, B0); PG8_BAR; PG8_SCHED;
	s_add_u32 s46, s26, 0x40000
	s_addc_u32 s47, s27, 0
	s_add_i32 s48, s39, s4
	v_lshl_add_u64 v[158:159], s[46:47], 0, v[130:131]
	s_mov_b32 m0, s48
	s_nop 0
	global_load_lds_dwordx4 v[158:159], off
	v_lshl_add_u64 v[158:159], s[46:47], 0, v[134:135]
	s_add_i32 m0, s48, 0x2000
	s_nop 0
	global_load_lds_dwordx4 v[158:159], off
	s_waitcnt vmcnt(6)
	s_barrier
	v_mfma_f32_16x16x32_bf16 v[56:59], v[216:219], v[180:183], v[56:59]
	v_mfma_f32_16x16x32_bf16 v[48:51], v[224:227], v[180:183], v[48:51]
	v_mfma_f32_16x16x32_bf16 v[40:43], v[216:219], v[188:191], v[40:43]
	v_mfma_f32_16x16x32_bf16 v[32:35], v[224:227], v[188:191], v[32:35]
	v_mfma_f32_16x16x32_bf16 v[24:27], v[216:219], v[196:199], v[24:27]
	v_mfma_f32_16x16x32_bf16 v[16:19], v[224:227], v[196:199], v[16:19]
	v_mfma_f32_16x16x32_bf16 v[8:11], v[216:219], v[208:211], v[8:11]
	v_mfma_f32_16x16x32_bf16 v[0:3], v[224:227], v[208:211], v[0:3]
	v_mfma_f32_16x16x32_bf16 v[56:59], v[220:223], v[184:187], v[56:59]
	v_mfma_f32_16x16x32_bf16 v[48:51], v[228:231], v[184:187], v[48:51]
	v_mfma_f32_16x16x32_bf16 v[40:43], v[220:223], v[192:195], v[40:43]
	v_mfma_f32_16x16x32_bf16 v[32:35], v[228:231], v[192:195], v[32:35]
	v_mfma_f32_16x16x32_bf16 v[24:27], v[220:223], v[200:203], v[24:27]
	v_mfma_f32_16x16x32_bf16 v[16:19], v[228:231], v[200:203], v[16:19]
	v_mfma_f32_16x16x32_bf16 v[8:11], v[220:223], v[212:215], v[8:11]
	v_mfma_f32_16x16x32_bf16 v[0:3], v[228:231], v[212:215], v[0:3]
	s_add_i32 s46, 0, 0x18000
	v_add_u32_e32 v157, s46, v144
	s_barrier
	ds_read_b128 v[158:161], v157
	ds_read_b128 v[162:165], v157 offset:1024
	ds_read_b128 v[166:169], v157 offset:2048
	ds_read_b128 v[170:173], v157 offset:3072
	s_add_u32 s28, s28, 0x40000
	s_addc_u32 s29, s29, 0
	s_mov_b32 m0, s30
	v_lshl_add_u64 v[216:217], s[28:29], 0, v[128:129]
	ds_read_b128 v[180:183], v147 offset:32768
	ds_read_b128 v[184:187], v147 offset:33792
	ds_read_b128 v[188:191], v147 offset:34816
	ds_read_b128 v[192:195], v147 offset:35840
	ds_read_b128 v[196:199], v147 offset:36864
	ds_read_b128 v[200:203], v147 offset:37888
	ds_read_b128 v[208:211], v147 offset:38912
	ds_read_b128 v[212:215], v147 offset:39936
	global_load_lds_dwordx4 v[216:217], off
	v_lshl_add_u64 v[216:217], s[28:29], 0, v[132:133]
	s_mov_b32 m0, s31
	s_nop 0
	global_load_lds_dwordx4 v[216:217], off
	s_waitcnt lgkmcnt(8)
	s_barrier
	s_waitcnt lgkmcnt(0)
	s_waitcnt lgkmcnt(0)
	v_mfma_f32_16x16x32_bf16 v[124:127], v[158:161], v[180:183], v[124:127]
	v_mfma_f32_16x16x32_bf16 v[116:119], v[166:169], v[180:183], v[116:119]
	v_mfma_f32_16x16x32_bf16 v[108:111], v[158:161], v[188:191], v[108:111]
	v_mfma_f32_16x16x32_bf16 v[100:103], v[166:169], v[188:191], v[100:103]
	v_mfma_f32_16x16x32_bf16 v[92:95], v[158:161], v[196:199], v[92:95]
	v_mfma_f32_16x16x32_bf16 v[84:87], v[166:169], v[196:199], v[84:87]
	v_mfma_f32_16x16x32_bf16 v[76:79], v[158:161], v[208:211], v[76:79]
	v_mfma_f32_16x16x32_bf16 v[68:71], v[166:169], v[208:211], v[68:71]
	v_mfma_f32_16x16x32_bf16 v[124:127], v[162:165], v[184:187], v[124:127]
	v_mfma_f32_16x16x32_bf16 v[116:119], v[170:173], v[184:187], v[116:119]
	v_mfma_f32_16x16x32_bf16 v[108:111], v[162:165], v[192:195], v[108:111]
	v_mfma_f32_16x16x32_bf16 v[100:103], v[170:173], v[192:195], v[100:103]
	v_mfma_f32_16x16x32_bf16 v[92:95], v[162:165], v[200:203], v[92:95]
	v_mfma_f32_16x16x32_bf16 v[84:87], v[170:173], v[200:203], v[84:87]
	v_mfma_f32_16x16x32_bf16 v[76:79], v[162:165], v[212:215], v[76:79]
	v_mfma_f32_16x16x32_bf16 v[68:71], v[170:173], v[212:215], v[68:71]
	s_barrier
	s_add_i32 s28, 0, 0x1c000
	s_add_i32 s29, s46, s4
	v_add_u32_e32 v157, s28, v144
	v_lshl_add_u64 v[174:175], v[174:175], 0, s[6:7]
	s_mov_b32 m0, s29
	ds_read_b128 v[216:219], v157
	ds_read_b128 v[220:223], v157 offset:1024
	ds_read_b128 v[224:227], v157 offset:2048
	ds_read_b128 v[228:231], v157 offset:3072
	global_load_lds_dwordx4 v[174:175], off
	v_lshl_add_u64 v[174:175], v[204:205], 0, s[6:7]
	s_add_i32 m0, s29, 0x2000
	s_nop 0
	global_load_lds_dwordx4 v[174:175], off
	s_barrier
	s_waitcnt lgkmcnt(0)
	s_waitcnt lgkmcnt(0)
	v_mfma_f32_16x16x32_bf16 v[120:123], v[216:219], v[180:183], v[120:123]
	v_mfma_f32_16x16x32_bf16 v[112:115], v[224:227], v[180:183], v[112:115]
	v_mfma_f32_16x16x32_bf16 v[104:107], v[216:219], v[188:191], v[104:107]
	v_mfma_f32_16x16x32_bf16 v[96:99], v[224:227], v[188:191], v[96:99]
	v_mfma_f32_16x16x32_bf16 v[88:91], v[216:219], v[196:199], v[88:91]
	v_mfma_f32_16x16x32_bf16 v[80:83], v[224:227], v[196:199], v[80:83]
	v_mfma_f32_16x16x32_bf16 v[72:75], v[216:219], v[208:211], v[72:75]
	v_mfma_f32_16x16x32_bf16 v[64:67], v[224:227], v[208:211], v[64:67]
	v_mfma_f32_16x16x32_bf16 v[120:123], v[220:223], v[184:187], v[120:123]
	v_mfma_f32_16x16x32_bf16 v[112:115], v[228:231], v[184:187], v[112:115]
	v_mfma_f32_16x16x32_bf16 v[104:107], v[220:223], v[192:195], v[104:107]
	v_mfma_f32_16x16x32_bf16 v[96:99], v[228:231], v[192:195], v[96:99]
	v_mfma_f32_16x16x32_bf16 v[88:91], v[220:223], v[200:203], v[88:91]
	v_mfma_f32_16x16x32_bf16 v[80:83], v[228:231], v[200:203], v[80:83]
	v_mfma_f32_16x16x32_bf16 v[72:75], v[220:223], v[212:215], v[72:75]
	v_mfma_f32_16x16x32_bf16 v[64:67], v[228:231], v[212:215], v[64:67]
	s_mov_b32 m0, s34
	v_lshl_add_u64 v[174:175], v[232:233], 0, s[6:7]
	s_barrier
	ds_read_b128 v[180:183], v147 offset:49152
	ds_read_b128 v[184:187], v147 offset:50176
	ds_read_b128 v[188:191], v147 offset:51200
	ds_read_b128 v[192:195], v147 offset:52224
	ds_read_b128 v[196:199], v147 offset:53248
	ds_read_b128 v[200:203], v147 offset:54272
	ds_read_b128 v[208:211], v147 offset:55296
	ds_read_b128 v[212:215], v147 offset:56320
	global_load_lds_dwordx4 v[174:175], off
	v_lshl_add_u64 v[174:175], v[234:235], 0, s[6:7]
	s_mov_b32 m0, s35
	s_nop 0
	global_load_lds_dwordx4 v[174:175], off
	s_barrier
; __device__ __forceinline__ unsigned cvt_pk_bf16(float lo, float hi) { unsigned r; asm volatile("v_cvt_pk_bf16_f32 %0, %1, %2" : "=v"(r) : "v"(lo), "v"(hi)); return r; }
; #define PG8_STAGE(bufoff, gbase, voff) do { _Pragma("unroll") for (int _i = 0; _i < 2; ++_i) \
;         __builtin_amdgcn_global_load_lds((const unsigned*)((const char*)(gbase) + (voff)[_i]), (PG8_LAS unsigned*)(lds + (bufoff) + ldsw + _i * 8192), 16, 0, 0); } while (0)
; #define PG8_MMA(ai, bj, At, Bt) do { __builtin_amdgcn_s_setprio(1); _Pragma("unroll") for (int m = 0; m < 4; ++m) _Pragma("unroll") for (int n = 0; n < 2; ++n) _Pragma("unroll") for (int k = 0; k < 2; ++k) \
;         acc[ai][bj][m][n] = __builtin_amdgcn_mfma_f32_16x16x32_bf16(Bt[n][k], At[m][k], acc[ai][bj][m][n], 0, 0, 0); __builtin_amdgcn_s_setprio(0); } while (0)
; template <class Epi, class Sched>
; __device__ __forceinline__ void gemm_phase(PG8_LAS unsigned char* lds, const Gemm g, const Sched& S, const Epi& E) {
;     ...
;             PG8_STAGE(PG8_SB(1, 1), b3 + hstep, voffB);
;             PG8_WAIT_V(6); PG8_BAR; PG8_MMA(1, 1, At, B1); PG8_BAR;
;     __device__ __forceinline__ void operator()(const f32x4 (&acc)[2][2][4][2], const Unit& u, int wr, int wc, int fr, int fq, const float (&epre)[8]) const {
;         const int row0 = u.pm * 256 + wr * 64 + fr, col0 = u.pn * 128 + wc * 32 + 8 * fq;
; #pragma unroll
;         for (int ai = 0; ai < 2; ++ai)
; #pragma unroll
;             for (int m = 0; m < 4; ++m) { const int row = row0 + ai * 128 + m * 16;
;                 const float rstd = rsqrtf(epre[ai * 4 + m] * (1.0f / DM) + EPS), c1 = -1.44269504f * rstd, c2 = rstd * rstd;
;                 f32x4 av[2];
; #pragma unroll
;                 for (int n = 0; n < 2; ++n) { const f32x4 g = acc[ai][0][m][n], t = g * c1; f32x4 e;
; #pragma unroll
;                     for (int j = 0; j < 4; ++j) e[j] = __builtin_amdgcn_exp2f(t[j]);
;                     const f32x4 d = e + 1.0f; f32x4 r;
; #pragma unroll
;                     for (int j = 0; j < 4; ++j) r[j] = frcp(d[j]);
;                     av[n] = (g * acc[ai][1][m][n]) * (r * c2); }
;                 u32x4 w; w.x = cvt_pk_bf16(av[0][0], av[0][1]); w.y = cvt_pk_bf16(av[0][2], av[0][3]); w.z = cvt_pk_bf16(av[1][0], av[1][1]); w.w = cvt_pk_bf16(av[1][2], av[1][3]);
;                 *(u32x4*)(ACT + (size_t)row * DFF + col0) = w; }
	s_waitcnt lgkmcnt(0)
	s_waitcnt lgkmcnt(0)
	v_mfma_f32_16x16x32_bf16 v[60:63], v[158:161], v[180:183], v[60:63]
	v_mfma_f32_16x16x32_bf16 v[52:55], v[166:169], v[180:183], v[52:55]
	v_mfma_f32_16x16x32_bf16 v[44:47], v[158:161], v[188:191], v[44:47]
	v_mfma_f32_16x16x32_bf16 v[36:39], v[166:169], v[188:191], v[36:39]
	v_mfma_f32_16x16x32_bf16 v[28:31], v[158:161], v[196:199], v[28:31]
	v_mfma_f32_16x16x32_bf16 v[20:23], v[166:169], v[196:199], v[20:23]
	v_mfma_f32_16x16x32_bf16 v[12:15], v[158:161], v[208:211], v[12:15]
	v_mfma_f32_16x16x32_bf16 v[4:7], v[166:169], v[208:211], v[4:7]
	v_mfma_f32_16x16x32_bf16 v[60:63], v[162:165], v[184:187], v[60:63]
	v_mfma_f32_16x16x32_bf16 v[52:55], v[170:173], v[184:187], v[52:55]
	v_mfma_f32_16x16x32_bf16 v[44:47], v[162:165], v[192:195], v[44:47]
	v_mfma_f32_16x16x32_bf16 v[36:39], v[170:173], v[192:195], v[36:39]
	v_mfma_f32_16x16x32_bf16 v[28:31], v[162:165], v[200:203], v[28:31]
	v_mfma_f32_16x16x32_bf16 v[20:23], v[170:173], v[200:203], v[20:23]
	v_mfma_f32_16x16x32_bf16 v[12:15], v[162:165], v[212:215], v[12:15]
	v_mfma_f32_16x16x32_bf16 v[4:7], v[170:173], v[212:215], v[4:7]
	s_barrier
	s_add_u32 s26, s26, 0x40080
	s_addc_u32 s27, s27, 0
	s_add_i32 s28, s28, s4
	v_lshl_add_u64 v[158:159], s[26:27], 0, v[130:131]
	s_mov_b32 m0, s28
	s_nop 0
	global_load_lds_dwordx4 v[158:159], off
	v_lshl_add_u64 v[158:159], s[26:27], 0, v[134:135]
	s_add_i32 m0, s28, 0x2000
	s_nop 0
	global_load_lds_dwordx4 v[158:159], off
	s_waitcnt vmcnt(6)
	s_barrier
	v_mfma_f32_16x16x32_bf16 v[56:59], v[216:219], v[180:183], v[56:59]
	v_mfma_f32_16x16x32_bf16 v[48:51], v[224:227], v[180:183], v[48:51]
	v_mfma_f32_16x16x32_bf16 v[40:43], v[216:219], v[188:191], v[40:43]
	v_mfma_f32_16x16x32_bf16 v[32:35], v[224:227], v[188:191], v[32:35]
	v_mfma_f32_16x16x32_bf16 v[24:27], v[216:219], v[196:199], v[24:27]
	v_mfma_f32_16x16x32_bf16 v[16:19], v[224:227], v[196:199], v[16:19]
	v_mfma_f32_16x16x32_bf16 v[8:11], v[216:219], v[208:211], v[8:11]
	v_mfma_f32_16x16x32_bf16 v[0:3], v[224:227], v[208:211], v[0:3]
	v_mfma_f32_16x16x32_bf16 v[56:59], v[220:223], v[184:187], v[56:59]
	v_mfma_f32_16x16x32_bf16 v[48:51], v[228:231], v[184:187], v[48:51]
	v_mfma_f32_16x16x32_bf16 v[40:43], v[220:223], v[192:195], v[40:43]
	v_mfma_f32_16x16x32_bf16 v[32:35], v[228:231], v[192:195], v[32:35]
	v_mfma_f32_16x16x32_bf16 v[24:27], v[220:223], v[200:203], v[24:27]
	v_mfma_f32_16x16x32_bf16 v[16:19], v[228:231], v[200:203], v[16:19]
	v_mfma_f32_16x16x32_bf16 v[8:11], v[220:223], v[212:215], v[8:11]
	v_mfma_f32_16x16x32_bf16 v[0:3], v[228:231], v[212:215], v[0:3]
	s_add_i32 s45, s45, 2
	s_add_u32 s24, s24, 0x100
	s_addc_u32 s25, s25, 0
	s_add_u32 s43, s43, 0x100
	s_addc_u32 s44, s44, 0
	s_cmp_gt_u32 s45, 13
	s_barrier
	s_cbranch_scc0 .LBB0_702
	s_waitcnt vmcnt(0)
	v_fmamk_f32 v156, v156, 0x3a800000, v149
	v_mul_f32_e32 v157, 0x4b800000, v156
	v_cmp_gt_f32_e32 vcc, s40, v156
	v_pk_mul_f32 v[122:123], v[126:127], v[122:123]
	v_pk_mul_f32 v[120:121], v[124:125], v[120:121]
	v_cndmask_b32_e32 v156, v156, v157, vcc
	v_rsq_f32_e32 v157, v156
	v_pk_mul_f32 v[114:115], v[118:119], v[114:115]
	v_pk_mul_f32 v[112:113], v[116:117], v[112:113]
	v_lshl_or_b32 v158, s22, 7, v145
	v_mul_f32_e32 v160, 0x45800000, v157
	v_cndmask_b32_e32 v157, v157, v160, vcc
	v_mul_f32_e32 v160, 0xbfb8aa3b, v157
	v_pk_mul_f32 v[166:167], v[160:161], v[124:125] op_sel_hi:[0,1]
	v_mul_f32_e32 v162, v157, v157
	v_exp_f32_e32 v157, v166
	v_pk_mul_f32 v[164:165], v[160:161], v[126:127] op_sel_hi:[0,1]
	v_exp_f32_e32 v161, v167
	v_exp_f32_e32 v163, v164
	v_exp_f32_e32 v167, v165
	v_add_f32_e32 v157, 1.0, v157
	v_rcp_f32_e32 v164, v157
	v_add_f32_e32 v157, 1.0, v161
	v_rcp_f32_e32 v165, v157
	v_add_f32_e32 v157, 1.0, v163
	v_rcp_f32_e32 v166, v157
	v_add_f32_e32 v157, 1.0, v167
	v_rcp_f32_e32 v167, v157
	v_pk_mul_f32 v[124:125], v[162:163], v[164:165] op_sel_hi:[0,1]
	v_pk_mul_f32 v[120:121], v[124:125], v[120:121]
	v_pk_mul_f32 v[124:125], v[160:161], v[118:119] op_sel_hi:[0,1]
	v_pk_mul_f32 v[126:127], v[162:163], v[166:167] op_sel_hi:[0,1]
	v_pk_mul_f32 v[122:123], v[126:127], v[122:123]
	v_pk_mul_f32 v[126:127], v[160:161], v[116:117] op_sel_hi:[0,1]
	v_exp_f32_e32 v126, v126
	v_exp_f32_e32 v127, v127
	v_exp_f32_e32 v157, v124
	v_exp_f32_e32 v160, v125
	v_add_f32_e32 v124, 1.0, v126
	v_add_f32_e32 v125, 1.0, v127
	v_add_f32_e32 v126, 1.0, v157
	v_add_f32_e32 v127, 1.0, v160
	v_rcp_f32_e32 v126, v126
	v_rcp_f32_e32 v127, v127
	v_rcp_f32_e32 v124, v124
	v_rcp_f32_e32 v125, v125
	v_lshl_add_u32 v156, s20, 8, v143
	v_pk_mul_f32 v[118:119], v[162:163], v[126:127] op_sel_hi:[0,1]
	v_pk_mul_f32 v[114:115], v[118:119], v[114:115]
	v_pk_mul_f32 v[116:117], v[162:163], v[124:125] op_sel_hi:[0,1]
	v_pk_mul_f32 v[112:113], v[116:117], v[112:113]
	v_cvt_pk_bf16_f32 v116, v120, v121
	v_cvt_pk_bf16_f32 v117, v122, v123
	v_ashrrev_i32_e32 v159, 31, v158
	v_cvt_pk_bf16_f32 v118, v112, v113
	v_cvt_pk_bf16_f32 v119, v114, v115
	v_fmamk_f32 v114, v155, 0x3a800000, v149
	v_mul_f32_e32 v115, 0x4b800000, v114
	v_cmp_gt_f32_e32 vcc, s40, v114
	v_mov_b64_e32 v[112:113], s[82:83]
	v_mad_i64_i32 v[120:121], s[20:21], v156, s41, v[112:113]
	v_cndmask_b32_e32 v114, v114, v115, vcc
	v_rsq_f32_e32 v122, v114
	v_lshlrev_b64 v[114:115], 1, v[158:159]
	v_lshl_add_u64 v[120:121], v[120:121], 0, v[114:115]
	global_store_dwordx4 v[120:121], v[116:119], off
	v_pk_mul_f32 v[106:107], v[110:111], v[106:107]
	v_pk_mul_f32 v[104:105], v[108:109], v[104:105]
	v_mul_f32_e32 v116, 0x45800000, v122
	v_cndmask_b32_e32 v117, v122, v116, vcc
	v_mul_f32_e32 v116, 0xbfb8aa3b, v117
	v_pk_mul_f32 v[122:123], v[116:117], v[108:109] op_sel_hi:[0,1]
; __device__ __forceinline__ unsigned cvt_pk_bf16(float lo, float hi) { unsigned r; asm volatile("v_cvt_pk_bf16_f32 %0, %1, %2" : "=v"(r) : "v"(lo), "v"(hi)); return r; }
; __device__ __forceinline__ float frcp(float x) { return __builtin_amdgcn_rcpf(x); }
;     __device__ __forceinline__ void operator()(const f32x4 (&acc)[2][2][4][2], const Unit& u, int wr, int wc, int fr, int fq, const float (&epre)[8]) const {
;         const int row0 = u.pm * 256 + wr * 64 + fr, col0 = u.pn * 128 + wc * 32 + 8 * fq;
; #pragma unroll
;         for (int ai = 0; ai < 2; ++ai)
; #pragma unroll
;             for (int m = 0; m < 4; ++m) { const int row = row0 + ai * 128 + m * 16;
;                 const float rstd = rsqrtf(epre[ai * 4 + m] * (1.0f / DM) + EPS), c1 = -1.44269504f * rstd, c2 = rstd * rstd;
;                 f32x4 av[2];
; #pragma unroll
;                 for (int n = 0; n < 2; ++n) { const f32x4 g = acc[ai][0][m][n], t = g * c1; f32x4 e;
; #pragma unroll
;                     for (int j = 0; j < 4; ++j) e[j] = __builtin_amdgcn_exp2f(t[j]);
;                     const f32x4 d = e + 1.0f; f32x4 r;
; #pragma unroll
;                     for (int j = 0; j < 4; ++j) r[j] = frcp(d[j]);
;                     av[n] = (g * acc[ai][1][m][n]) * (r * c2); }
;                 u32x4 w; w.x = cvt_pk_bf16(av[0][0], av[0][1]); w.y = cvt_pk_bf16(av[0][2], av[0][3]); w.z = cvt_pk_bf16(av[1][0], av[1][1]); w.w = cvt_pk_bf16(av[1][2], av[1][3]);
;                 *(u32x4*)(ACT + (size_t)row * DFF + col0) = w; }
	v_mul_f32_e32 v118, v117, v117
	v_pk_mul_f32 v[120:121], v[116:117], v[110:111] op_sel_hi:[0,1]
	v_exp_f32_e32 v117, v122
	v_exp_f32_e32 v119, v123
	v_exp_f32_e32 v122, v120
	v_exp_f32_e32 v123, v121
	v_add_f32_e32 v117, 1.0, v117
	v_rcp_f32_e32 v120, v117
	v_add_f32_e32 v117, 1.0, v119
	v_rcp_f32_e32 v121, v117
	v_add_f32_e32 v117, 1.0, v122
	v_rcp_f32_e32 v122, v117
	v_add_f32_e32 v117, 1.0, v123
	v_rcp_f32_e32 v123, v117
	v_pk_mul_f32 v[108:109], v[118:119], v[120:121] op_sel_hi:[0,1]
	v_pk_mul_f32 v[104:105], v[108:109], v[104:105]
	v_pk_mul_f32 v[108:109], v[116:117], v[102:103] op_sel_hi:[0,1]
	v_pk_mul_f32 v[110:111], v[118:119], v[122:123] op_sel_hi:[0,1]
	v_pk_mul_f32 v[106:107], v[110:111], v[106:107]
	v_pk_mul_f32 v[110:111], v[116:117], v[100:101] op_sel_hi:[0,1]
	v_exp_f32_e32 v110, v110
	v_exp_f32_e32 v111, v111
	v_exp_f32_e32 v116, v108
	v_exp_f32_e32 v117, v109
	v_add_f32_e32 v108, 1.0, v110
	v_add_f32_e32 v109, 1.0, v111
	v_add_f32_e32 v110, 1.0, v116
	v_add_f32_e32 v111, 1.0, v117
	v_rcp_f32_e32 v108, v108
	v_rcp_f32_e32 v109, v109
	v_rcp_f32_e32 v110, v110
	v_rcp_f32_e32 v111, v111
	v_pk_mul_f32 v[98:99], v[102:103], v[98:99]
	v_pk_mul_f32 v[96:97], v[100:101], v[96:97]
	v_pk_mul_f32 v[100:101], v[118:119], v[108:109] op_sel_hi:[0,1]
	v_pk_mul_f32 v[102:103], v[118:119], v[110:111] op_sel_hi:[0,1]
	v_pk_mul_f32 v[102:103], v[102:103], v[98:99]
	v_pk_mul_f32 v[98:99], v[100:101], v[96:97]
	v_fmamk_f32 v101, v154, 0x3a800000, v149
	v_cvt_pk_bf16_f32 v96, v104, v105
	v_cvt_pk_bf16_f32 v97, v106, v107
	v_cvt_pk_bf16_f32 v98, v98, v99
	v_cvt_pk_bf16_f32 v99, v102, v103
	v_mul_f32_e32 v102, 0x4b800000, v101
	v_cmp_gt_f32_e32 vcc, s40, v101
	v_or_b32_e32 v100, 16, v156
	v_pk_mul_f32 v[90:91], v[94:95], v[90:91]
	v_cndmask_b32_e32 v101, v101, v102, vcc
	v_rsq_f32_e32 v102, v101
	v_mad_i64_i32 v[100:101], s[20:21], v100, s41, v[112:113]
	v_lshl_add_u64 v[100:101], v[100:101], 0, v[114:115]
	global_store_dwordx4 v[100:101], v[96:99], off
	v_pk_mul_f32 v[88:89], v[92:93], v[88:89]
	v_pk_mul_f32 v[82:83], v[86:87], v[82:83]
	v_mul_f32_e32 v96, 0x45800000, v102
	v_cndmask_b32_e32 v97, v102, v96, vcc
	v_mul_f32_e32 v96, 0xbfb8aa3b, v97
	v_pk_mul_f32 v[102:103], v[96:97], v[92:93] op_sel_hi:[0,1]
	v_mul_f32_e32 v98, v97, v97
	v_pk_mul_f32 v[100:101], v[96:97], v[94:95] op_sel_hi:[0,1]
	v_exp_f32_e32 v97, v102
	v_exp_f32_e32 v99, v103
	v_exp_f32_e32 v102, v100
	v_exp_f32_e32 v103, v101
	v_add_f32_e32 v97, 1.0, v97
	v_rcp_f32_e32 v100, v97
	v_add_f32_e32 v97, 1.0, v99
	v_rcp_f32_e32 v101, v97
	v_add_f32_e32 v97, 1.0, v102
	v_rcp_f32_e32 v102, v97
	v_add_f32_e32 v97, 1.0, v103
	v_rcp_f32_e32 v103, v97
	v_pk_mul_f32 v[92:93], v[98:99], v[100:101] op_sel_hi:[0,1]
	v_pk_mul_f32 v[88:89], v[92:93], v[88:89]
	v_pk_mul_f32 v[92:93], v[96:97], v[86:87] op_sel_hi:[0,1]
	v_pk_mul_f32 v[94:95], v[98:99], v[102:103] op_sel_hi:[0,1]
	v_pk_mul_f32 v[90:91], v[94:95], v[90:91]
	v_pk_mul_f32 v[94:95], v[96:97], v[84:85] op_sel_hi:[0,1]
	v_exp_f32_e32 v94, v94
	v_exp_f32_e32 v95, v95
	v_exp_f32_e32 v96, v92
	v_exp_f32_e32 v97, v93
	v_add_f32_e32 v92, 1.0, v94
	v_add_f32_e32 v93, 1.0, v95
	v_add_f32_e32 v94, 1.0, v96
	v_add_f32_e32 v95, 1.0, v97
	v_rcp_f32_e32 v92, v92
	v_rcp_f32_e32 v93, v93
	v_rcp_f32_e32 v94, v94
	v_rcp_f32_e32 v95, v95
	v_pk_mul_f32 v[80:81], v[84:85], v[80:81]
	v_pk_mul_f32 v[84:85], v[98:99], v[92:93] op_sel_hi:[0,1]
	v_pk_mul_f32 v[74:75], v[78:79], v[74:75]
	v_pk_mul_f32 v[86:87], v[98:99], v[94:95] op_sel_hi:[0,1]
	v_pk_mul_f32 v[86:87], v[86:87], v[82:83]
	v_pk_mul_f32 v[82:83], v[84:85], v[80:81]
	v_fmamk_f32 v85, v153, 0x3a800000, v149
	v_cvt_pk_bf16_f32 v80, v88, v89
	v_cvt_pk_bf16_f32 v81, v90, v91
	v_cvt_pk_bf16_f32 v82, v82, v83
	v_cvt_pk_bf16_f32 v83, v86, v87
	v_mul_f32_e32 v86, 0x4b800000, v85
	v_cmp_gt_f32_e32 vcc, s40, v85
	v_or_b32_e32 v84, 32, v156
	v_pk_mul_f32 v[72:73], v[76:77], v[72:73]
	v_cndmask_b32_e32 v85, v85, v86, vcc
	v_rsq_f32_e32 v86, v85
	v_mad_i64_i32 v[84:85], s[20:21], v84, s41, v[112:113]
	v_lshl_add_u64 v[84:85], v[84:85], 0, v[114:115]
	global_store_dwordx4 v[84:85], v[80:83], off
	v_pk_mul_f32 v[66:67], v[70:71], v[66:67]
	v_pk_mul_f32 v[64:65], v[68:69], v[64:65]
	v_mul_f32_e32 v80, 0x45800000, v86
	v_cndmask_b32_e32 v81, v86, v80, vcc
	v_mul_f32_e32 v80, 0xbfb8aa3b, v81
	v_pk_mul_f32 v[86:87], v[80:81], v[76:77] op_sel_hi:[0,1]
	v_mul_f32_e32 v82, v81, v81
	v_pk_mul_f32 v[84:85], v[80:81], v[78:79] op_sel_hi:[0,1]
	v_exp_f32_e32 v81, v86
	v_exp_f32_e32 v83, v87
	v_exp_f32_e32 v86, v84
	v_exp_f32_e32 v87, v85
	v_add_f32_e32 v81, 1.0, v81
	v_rcp_f32_e32 v84, v81
	v_add_f32_e32 v81, 1.0, v83
	v_rcp_f32_e32 v85, v81
	v_add_f32_e32 v81, 1.0, v86
	v_rcp_f32_e32 v86, v81
	v_add_f32_e32 v81, 1.0, v87
	v_rcp_f32_e32 v87, v81
	v_pk_mul_f32 v[76:77], v[82:83], v[84:85] op_sel_hi:[0,1]
	v_pk_mul_f32 v[72:73], v[76:77], v[72:73]
	v_pk_mul_f32 v[76:77], v[80:81], v[70:71] op_sel_hi:[0,1]
	v_pk_mul_f32 v[78:79], v[82:83], v[86:87] op_sel_hi:[0,1]
	v_pk_mul_f32 v[74:75], v[78:79], v[74:75]
	v_pk_mul_f32 v[78:79], v[80:81], v[68:69] op_sel_hi:[0,1]
	v_exp_f32_e32 v78, v78
	v_exp_f32_e32 v79, v79
	v_exp_f32_e32 v80, v76
	v_exp_f32_e32 v81, v77
	v_add_f32_e32 v76, 1.0, v78
	v_add_f32_e32 v77, 1.0, v79
	v_add_f32_e32 v78, 1.0, v80
	v_add_f32_e32 v79, 1.0, v81
	v_rcp_f32_e32 v76, v76
	v_rcp_f32_e32 v77, v77
	v_rcp_f32_e32 v78, v78
	v_rcp_f32_e32 v79, v79
	v_pk_mul_f32 v[58:59], v[62:63], v[58:59]
	v_pk_mul_f32 v[68:69], v[82:83], v[76:77] op_sel_hi:[0,1]
	v_pk_mul_f32 v[56:57], v[60:61], v[56:57]
	v_pk_mul_f32 v[70:71], v[82:83], v[78:79] op_sel_hi:[0,1]
	v_pk_mul_f32 v[70:71], v[70:71], v[66:67]
; __device__ __forceinline__ unsigned cvt_pk_bf16(float lo, float hi) { unsigned r; asm volatile("v_cvt_pk_bf16_f32 %0, %1, %2" : "=v"(r) : "v"(lo), "v"(hi)); return r; }
; __device__ __forceinline__ float frcp(float x) { return __builtin_amdgcn_rcpf(x); }
;     __device__ __forceinline__ void operator()(const f32x4 (&acc)[2][2][4][2], const Unit& u, int wr, int wc, int fr, int fq, const float (&epre)[8]) const {
;         const int row0 = u.pm * 256 + wr * 64 + fr, col0 = u.pn * 128 + wc * 32 + 8 * fq;
; #pragma unroll
;         for (int ai = 0; ai < 2; ++ai)
; #pragma unroll
;             for (int m = 0; m < 4; ++m) { const int row = row0 + ai * 128 + m * 16;
;                 const float rstd = rsqrtf(epre[ai * 4 + m] * (1.0f / DM) + EPS), c1 = -1.44269504f * rstd, c2 = rstd * rstd;
;                 f32x4 av[2];
; #pragma unroll
;                 for (int n = 0; n < 2; ++n) { const f32x4 g = acc[ai][0][m][n], t = g * c1; f32x4 e;
; #pragma unroll
;                     for (int j = 0; j < 4; ++j) e[j] = __builtin_amdgcn_exp2f(t[j]);
;                     const f32x4 d = e + 1.0f; f32x4 r;
; #pragma unroll
;                     for (int j = 0; j < 4; ++j) r[j] = frcp(d[j]);
;                     av[n] = (g * acc[ai][1][m][n]) * (r * c2); }
;                 u32x4 w; w.x = cvt_pk_bf16(av[0][0], av[0][1]); w.y = cvt_pk_bf16(av[0][2], av[0][3]); w.z = cvt_pk_bf16(av[1][0], av[1][1]); w.w = cvt_pk_bf16(av[1][2], av[1][3]);
;                 *(u32x4*)(ACT + (size_t)row * DFF + col0) = w; }
	v_pk_mul_f32 v[66:67], v[68:69], v[64:65]
	v_cvt_pk_bf16_f32 v64, v72, v73
	v_cvt_pk_bf16_f32 v65, v74, v75
	v_or_b32_e32 v68, 48, v156
	v_cvt_pk_bf16_f32 v66, v66, v67
	v_cvt_pk_bf16_f32 v67, v70, v71
	v_fmamk_f32 v70, v152, 0x3a800000, v149
	v_mul_f32_e32 v71, 0x4b800000, v70
	v_cmp_gt_f32_e32 vcc, s40, v70
	v_mad_i64_i32 v[68:69], s[20:21], v68, s41, v[112:113]
	s_nop 0
	v_cndmask_b32_e32 v70, v70, v71, vcc
	v_rsq_f32_e32 v70, v70
	v_lshl_add_u64 v[68:69], v[68:69], 0, v[114:115]
	global_store_dwordx4 v[68:69], v[64:67], off
	v_pk_mul_f32 v[50:51], v[54:55], v[50:51]
	v_pk_mul_f32 v[48:49], v[52:53], v[48:49]
	v_mul_f32_e32 v64, 0x45800000, v70
	v_cndmask_b32_e32 v66, v70, v64, vcc
	v_add_u32_e32 v65, 0x80, v156
	v_mul_f32_e32 v64, 0xbfb8aa3b, v66
	v_pk_mul_f32 v[70:71], v[64:65], v[60:61] op_sel_hi:[0,1]
	v_exp_f32_e32 v67, v70
	v_pk_mul_f32 v[68:69], v[64:65], v[62:63] op_sel_hi:[0,1]
	v_exp_f32_e32 v70, v71
	v_exp_f32_e32 v71, v68
	v_exp_f32_e32 v72, v69
	v_add_f32_e32 v67, 1.0, v67
	v_rcp_f32_e32 v68, v67
	v_add_f32_e32 v67, 1.0, v70
	v_rcp_f32_e32 v69, v67
	v_add_f32_e32 v67, 1.0, v71
	v_rcp_f32_e32 v70, v67
	v_add_f32_e32 v67, 1.0, v72
	v_rcp_f32_e32 v71, v67
	v_mul_f32_e32 v66, v66, v66
	v_pk_mul_f32 v[60:61], v[66:67], v[68:69] op_sel_hi:[0,1]
	v_pk_mul_f32 v[56:57], v[60:61], v[56:57]
	v_pk_mul_f32 v[62:63], v[66:67], v[70:71] op_sel_hi:[0,1]
	v_pk_mul_f32 v[58:59], v[62:63], v[58:59]
	v_pk_mul_f32 v[60:61], v[64:65], v[54:55] op_sel_hi:[0,1]
	v_pk_mul_f32 v[62:63], v[64:65], v[52:53] op_sel_hi:[0,1]
	v_exp_f32_e32 v62, v62
	v_exp_f32_e32 v63, v63
	v_exp_f32_e32 v64, v60
	v_exp_f32_e32 v67, v61
	v_add_f32_e32 v60, 1.0, v62
	v_add_f32_e32 v61, 1.0, v63
	v_add_f32_e32 v62, 1.0, v64
	v_add_f32_e32 v63, 1.0, v67
	v_rcp_f32_e32 v60, v60
	v_rcp_f32_e32 v61, v61
	v_rcp_f32_e32 v62, v62
	v_rcp_f32_e32 v63, v63
	v_pk_mul_f32 v[42:43], v[46:47], v[42:43]
	v_pk_mul_f32 v[52:53], v[66:67], v[60:61] op_sel_hi:[0,1]
	v_pk_mul_f32 v[40:41], v[44:45], v[40:41]
	v_pk_mul_f32 v[54:55], v[66:67], v[62:63] op_sel_hi:[0,1]
	v_pk_mul_f32 v[54:55], v[54:55], v[50:51]
	v_pk_mul_f32 v[50:51], v[52:53], v[48:49]
	v_fmamk_f32 v52, v151, 0x3a800000, v149
	v_mul_f32_e32 v53, 0x4b800000, v52
	v_cmp_gt_f32_e32 vcc, s40, v52
	v_cvt_pk_bf16_f32 v48, v56, v57
	v_cvt_pk_bf16_f32 v49, v58, v59
	v_cvt_pk_bf16_f32 v50, v50, v51
	v_cvt_pk_bf16_f32 v51, v54, v55
	v_pk_mul_f32 v[34:35], v[38:39], v[34:35]
	s_nop 0
	v_cndmask_b32_e32 v52, v52, v53, vcc
	v_rsq_f32_e32 v54, v52
	v_mad_i64_i32 v[52:53], s[20:21], v65, s41, v[112:113]
	v_lshl_add_u64 v[52:53], v[52:53], 0, v[114:115]
	global_store_dwordx4 v[52:53], v[48:51], off
	v_pk_mul_f32 v[32:33], v[36:37], v[32:33]
	v_pk_mul_f32 v[26:27], v[30:31], v[26:27]
	v_mul_f32_e32 v48, 0x45800000, v54
	v_cndmask_b32_e32 v49, v54, v48, vcc
	v_mul_f32_e32 v48, 0xbfb8aa3b, v49
	v_pk_mul_f32 v[54:55], v[48:49], v[44:45] op_sel_hi:[0,1]
	v_mul_f32_e32 v50, v49, v49
	v_pk_mul_f32 v[52:53], v[48:49], v[46:47] op_sel_hi:[0,1]
	v_exp_f32_e32 v49, v54
	v_exp_f32_e32 v51, v55
	v_exp_f32_e32 v54, v52
	v_exp_f32_e32 v55, v53
	v_add_f32_e32 v49, 1.0, v49
	v_rcp_f32_e32 v52, v49
	v_add_f32_e32 v49, 1.0, v51
	v_rcp_f32_e32 v53, v49
	v_add_f32_e32 v49, 1.0, v54
	v_rcp_f32_e32 v54, v49
	v_add_f32_e32 v49, 1.0, v55
	v_rcp_f32_e32 v55, v49
	v_pk_mul_f32 v[44:45], v[50:51], v[52:53] op_sel_hi:[0,1]
	v_pk_mul_f32 v[40:41], v[44:45], v[40:41]
	v_pk_mul_f32 v[44:45], v[48:49], v[38:39] op_sel_hi:[0,1]
	v_pk_mul_f32 v[46:47], v[50:51], v[54:55] op_sel_hi:[0,1]
	v_pk_mul_f32 v[42:43], v[46:47], v[42:43]
	v_pk_mul_f32 v[46:47], v[48:49], v[36:37] op_sel_hi:[0,1]
	v_exp_f32_e32 v46, v46
	v_exp_f32_e32 v47, v47
	v_exp_f32_e32 v48, v44
	v_exp_f32_e32 v49, v45
	v_add_f32_e32 v44, 1.0, v46
	v_add_f32_e32 v45, 1.0, v47
	v_add_f32_e32 v46, 1.0, v48
	v_add_f32_e32 v47, 1.0, v49
	v_rcp_f32_e32 v44, v44
	v_rcp_f32_e32 v45, v45
	v_rcp_f32_e32 v46, v46
	v_rcp_f32_e32 v47, v47
	v_pk_mul_f32 v[24:25], v[28:29], v[24:25]
	v_pk_mul_f32 v[36:37], v[50:51], v[44:45] op_sel_hi:[0,1]
	v_pk_mul_f32 v[18:19], v[22:23], v[18:19]
	v_pk_mul_f32 v[38:39], v[50:51], v[46:47] op_sel_hi:[0,1]
	v_pk_mul_f32 v[38:39], v[38:39], v[34:35]
	v_pk_mul_f32 v[34:35], v[36:37], v[32:33]
	v_fmamk_f32 v37, v150, 0x3a800000, v149
	v_cvt_pk_bf16_f32 v32, v40, v41
	v_cvt_pk_bf16_f32 v33, v42, v43
	v_cvt_pk_bf16_f32 v34, v34, v35
	v_cvt_pk_bf16_f32 v35, v38, v39
	v_mul_f32_e32 v38, 0x4b800000, v37
	v_cmp_gt_f32_e32 vcc, s40, v37
	v_add_u32_e32 v36, 0x90, v156
	v_pk_mul_f32 v[16:17], v[20:21], v[16:17]
; __device__ __forceinline__ unsigned cvt_pk_bf16(float lo, float hi) { unsigned r; asm volatile("v_cvt_pk_bf16_f32 %0, %1, %2" : "=v"(r) : "v"(lo), "v"(hi)); return r; }
; __device__ __forceinline__ float frcp(float x) { return __builtin_amdgcn_rcpf(x); }
; template <class Epi, class Sched>
; __device__ __forceinline__ void gemm_phase(PG8_LAS unsigned char* lds, const Gemm g, const Sched& S, const Epi& E) {
;     ...
;         E(acc, cur, wr, wc, fr, fq, epre); S.done(cur);
;         if (!has_next) break;
;         E.preload(nxt, wr, fr, epre);
;     __device__ __forceinline__ void operator()(const f32x4 (&acc)[2][2][4][2], const Unit& u, int wr, int wc, int fr, int fq, const float (&epre)[8]) const {
;         const int row0 = u.pm * 256 + wr * 64 + fr, col0 = u.pn * 128 + wc * 32 + 8 * fq;
; #pragma unroll
;         for (int ai = 0; ai < 2; ++ai)
; #pragma unroll
;             for (int m = 0; m < 4; ++m) { const int row = row0 + ai * 128 + m * 16;
;                 const float rstd = rsqrtf(epre[ai * 4 + m] * (1.0f / DM) + EPS), c1 = -1.44269504f * rstd, c2 = rstd * rstd;
;                 f32x4 av[2];
; #pragma unroll
;                 for (int n = 0; n < 2; ++n) { const f32x4 g = acc[ai][0][m][n], t = g * c1; f32x4 e;
; #pragma unroll
;                     for (int j = 0; j < 4; ++j) e[j] = __builtin_amdgcn_exp2f(t[j]);
;                     const f32x4 d = e + 1.0f; f32x4 r;
; #pragma unroll
;                     for (int j = 0; j < 4; ++j) r[j] = frcp(d[j]);
;                     av[n] = (g * acc[ai][1][m][n]) * (r * c2); }
;                 u32x4 w; w.x = cvt_pk_bf16(av[0][0], av[0][1]); w.y = cvt_pk_bf16(av[0][2], av[0][3]); w.z = cvt_pk_bf16(av[1][0], av[1][1]); w.w = cvt_pk_bf16(av[1][2], av[1][3]);
;                 *(u32x4*)(ACT + (size_t)row * DFF + col0) = w; }
	v_cndmask_b32_e32 v37, v37, v38, vcc
	v_rsq_f32_e32 v38, v37
	v_mad_i64_i32 v[36:37], s[20:21], v36, s41, v[112:113]
	v_lshl_add_u64 v[36:37], v[36:37], 0, v[114:115]
	global_store_dwordx4 v[36:37], v[32:35], off
	v_pk_mul_f32 v[10:11], v[14:15], v[10:11]
	v_pk_mul_f32 v[8:9], v[12:13], v[8:9]
	v_mul_f32_e32 v32, 0x45800000, v38
	v_cndmask_b32_e32 v33, v38, v32, vcc
	v_mul_f32_e32 v32, 0xbfb8aa3b, v33
	v_pk_mul_f32 v[38:39], v[32:33], v[28:29] op_sel_hi:[0,1]
	v_mul_f32_e32 v34, v33, v33
	v_pk_mul_f32 v[36:37], v[32:33], v[30:31] op_sel_hi:[0,1]
	v_exp_f32_e32 v33, v38
	v_exp_f32_e32 v35, v39
	v_exp_f32_e32 v38, v36
	v_exp_f32_e32 v39, v37
	v_add_f32_e32 v33, 1.0, v33
	v_rcp_f32_e32 v36, v33
	v_add_f32_e32 v33, 1.0, v35
	v_rcp_f32_e32 v37, v33
	v_add_f32_e32 v33, 1.0, v38
	v_rcp_f32_e32 v38, v33
	v_add_f32_e32 v33, 1.0, v39
	v_rcp_f32_e32 v39, v33
	v_pk_mul_f32 v[28:29], v[34:35], v[36:37] op_sel_hi:[0,1]
	v_pk_mul_f32 v[24:25], v[28:29], v[24:25]
	v_pk_mul_f32 v[28:29], v[32:33], v[22:23] op_sel_hi:[0,1]
	v_pk_mul_f32 v[30:31], v[34:35], v[38:39] op_sel_hi:[0,1]
	v_pk_mul_f32 v[26:27], v[30:31], v[26:27]
	v_pk_mul_f32 v[30:31], v[32:33], v[20:21] op_sel_hi:[0,1]
	v_exp_f32_e32 v30, v30
	v_exp_f32_e32 v31, v31
	v_exp_f32_e32 v32, v28
	v_exp_f32_e32 v33, v29
	v_add_f32_e32 v28, 1.0, v30
	v_add_f32_e32 v29, 1.0, v31
	v_add_f32_e32 v30, 1.0, v32
	v_add_f32_e32 v31, 1.0, v33
	v_rcp_f32_e32 v28, v28
	v_rcp_f32_e32 v29, v29
	v_rcp_f32_e32 v30, v30
	v_rcp_f32_e32 v31, v31
	v_pk_mul_f32 v[2:3], v[6:7], v[2:3]
	v_pk_mul_f32 v[20:21], v[34:35], v[28:29] op_sel_hi:[0,1]
	v_pk_mul_f32 v[0:1], v[4:5], v[0:1]
	v_pk_mul_f32 v[22:23], v[34:35], v[30:31] op_sel_hi:[0,1]
	v_pk_mul_f32 v[22:23], v[22:23], v[18:19]
	v_pk_mul_f32 v[18:19], v[20:21], v[16:17]
	v_fmamk_f32 v21, v142, 0x3a800000, v149
	v_cvt_pk_bf16_f32 v16, v24, v25
	v_cvt_pk_bf16_f32 v17, v26, v27
	v_cvt_pk_bf16_f32 v18, v18, v19
	v_cvt_pk_bf16_f32 v19, v22, v23
	v_mul_f32_e32 v22, 0x4b800000, v21
	v_cmp_gt_f32_e32 vcc, s40, v21
	v_add_u32_e32 v20, 0xa0, v156
	s_nop 0
	v_cndmask_b32_e32 v21, v21, v22, vcc
	v_rsq_f32_e32 v22, v21
	v_mad_i64_i32 v[20:21], s[20:21], v20, s41, v[112:113]
	v_lshl_add_u64 v[20:21], v[20:21], 0, v[114:115]
	global_store_dwordx4 v[20:21], v[16:19], off
	s_nop 1
	v_mul_f32_e32 v16, 0x45800000, v22
	v_cndmask_b32_e32 v17, v22, v16, vcc
	v_mul_f32_e32 v16, 0xbfb8aa3b, v17
	v_pk_mul_f32 v[22:23], v[16:17], v[12:13] op_sel_hi:[0,1]
	v_mul_f32_e32 v18, v17, v17
	v_pk_mul_f32 v[20:21], v[16:17], v[14:15] op_sel_hi:[0,1]
	v_exp_f32_e32 v17, v22
	v_exp_f32_e32 v19, v23
	v_exp_f32_e32 v22, v20
	v_exp_f32_e32 v23, v21
	v_add_f32_e32 v17, 1.0, v17
	v_rcp_f32_e32 v20, v17
	v_add_f32_e32 v17, 1.0, v19
	v_rcp_f32_e32 v21, v17
	v_add_f32_e32 v17, 1.0, v22
	v_rcp_f32_e32 v22, v17
	v_add_f32_e32 v17, 1.0, v23
	v_rcp_f32_e32 v23, v17
	v_pk_mul_f32 v[12:13], v[18:19], v[20:21] op_sel_hi:[0,1]
	v_pk_mul_f32 v[8:9], v[12:13], v[8:9]
	v_pk_mul_f32 v[12:13], v[16:17], v[6:7] op_sel_hi:[0,1]
	v_pk_mul_f32 v[14:15], v[18:19], v[22:23] op_sel_hi:[0,1]
	v_pk_mul_f32 v[10:11], v[14:15], v[10:11]
	v_pk_mul_f32 v[14:15], v[16:17], v[4:5] op_sel_hi:[0,1]
	v_exp_f32_e32 v14, v14
	v_exp_f32_e32 v15, v15
	v_exp_f32_e32 v16, v12
	v_exp_f32_e32 v17, v13
	v_add_f32_e32 v12, 1.0, v14
	v_add_f32_e32 v13, 1.0, v15
	v_add_f32_e32 v14, 1.0, v16
	v_add_f32_e32 v15, 1.0, v17
	v_rcp_f32_e32 v12, v12
	v_rcp_f32_e32 v13, v13
	v_rcp_f32_e32 v14, v14
	v_rcp_f32_e32 v15, v15
	s_and_b64 vcc, s[16:17], exec
	v_pk_mul_f32 v[4:5], v[18:19], v[12:13] op_sel_hi:[0,1]
	v_pk_mul_f32 v[6:7], v[18:19], v[14:15] op_sel_hi:[0,1]
	v_pk_mul_f32 v[6:7], v[6:7], v[2:3]
	v_pk_mul_f32 v[2:3], v[4:5], v[0:1]
	v_add_u32_e32 v4, 0xb0, v156
	v_mad_i64_i32 v[4:5], s[20:21], v4, s41, v[112:113]
	v_lshl_add_u64 v[4:5], v[4:5], 0, v[114:115]
	s_mov_b64 s[20:21], -1
	v_cvt_pk_bf16_f32 v0, v8, v9
	v_cvt_pk_bf16_f32 v1, v10, v11
	v_cvt_pk_bf16_f32 v2, v2, v3
	v_cvt_pk_bf16_f32 v3, v6, v7
	global_store_dwordx4 v[4:5], v[0:3], off
	s_cbranch_vccz .LBB0_695
	s_nop 0
	v_lshl_add_u32 v0, s12, 8, v143
	v_ashrrev_i32_e32 v1, 31, v0
	v_lshl_add_u64 v[0:1], v[0:1], 2, s[10:11]
	global_load_dword v156, v[0:1], off
	global_load_dword v155, v[0:1], off offset:64
	global_load_dword v154, v[0:1], off offset:128
	global_load_dword v153, v[0:1], off offset:192
	global_load_dword v152, v[0:1], off offset:512
	global_load_dword v151, v[0:1], off offset:576
	global_load_dword v150, v[0:1], off offset:640
	global_load_dword v142, v[0:1], off offset:704
	s_mov_b64 s[20:21], 0
	s_branch .LBB0_695

; #define PG8_WAIT_V(n) asm volatile("s_waitcnt vmcnt(" #n ")" ::: "memory")
; #define PG8_BAR __builtin_amdgcn_s_barrier()
; template <class Epi, class Sched>
; __device__ __forceinline__ void gemm_phase(PG8_LAS unsigned char* lds, const Gemm g, const Sched& S, const Epi& E) {
;     ...
;     PG8_WAIT_V(0);
;     if (wr == 0) PG8_BAR;
;     PG8_BAR;
.LBB0_707:
	s_barrier
	s_setprio 0

; #define PG8_STAGE(bufoff, gbase, voff) do { _Pragma("unroll") for (int _i = 0; _i < 2; ++_i) \
;         __builtin_amdgcn_global_load_lds((const unsigned*)((const char*)(gbase) + (voff)[_i]), (PG8_LAS unsigned*)(lds + (bufoff) + ldsw + _i * 8192), 16, 0, 0); } while (0)
; #define PG8_WAIT_V(n) asm volatile("s_waitcnt vmcnt(" #n ")" ::: "memory")
; #define PG8_BAR __builtin_amdgcn_s_barrier()
; template <class Epi, class Sched>
; __device__ __forceinline__ void gemm_phase(PG8_LAS unsigned char* lds, const Gemm g, const Sched& S, const Epi& E) {
;     ...
;     for (int i = 0; i < 2; ++i) { int R, C; stage_rc(tid * 16 + i * 8192, R, C); const int Rb = Epi::PERM ? ((R & ~31) + perm32(R & 31)) : R;
;         voffA[i] = (unsigned)(R * K + C) * 2u; voffB[i] = (unsigned)(Rb * K + C) * 2u; }
;     const size_t kstep = (size_t)(BK * 2);
;     const size_t hstep = (size_t)HALF * K * 2;
;     const size_t tstep = 2 * hstep;
;     const unsigned ldsw = (unsigned)wid * 1024u;
;     const int aoff = lds_byte(wr * 64 + fr, fq * 8), boff = lds_byte(wc * 32 + fr, fq * 8);
;     ...
;     Unit cur, nxt; int ui = 0;
;     if (!S.next(0, cur)) return;
;     f32x4 acc[2][2][4][2];
; #pragma unroll
;     for (int a = 0; a < 2; ++a)
; #pragma unroll
;         for (int b = 0; b < 2; ++b)
; #pragma unroll
;             for (int m = 0; m < 4; ++m)
; #pragma unroll
;                 for (int n = 0; n < 2; ++n) acc[a][b][m][n] = (f32x4){0.f, 0.f, 0.f, 0.f};
;     bf16x8 At[4][2], B0[2][2], B1[2][2];
;     const char* cA = (const char*)g.A + (size_t)cur.pm * tstep; const char* cB = (const char*)g.Bt + (size_t)cur.pn * tstep;
;     float epre[Epi::NPRE]; E.preload(cur, wr, fr, epre);
;     S.a_ready(cur);
;     PG8_STAGE(PG8_SB(0, 0), cB, voffB); PG8_STAGE(PG8_SA(0, 0), cA, voffA); PG8_STAGE(PG8_SB(0, 1), cB + hstep, voffB); PG8_STAGE(PG8_SA(0, 1), cA + hstep, voffA);
;     if (wr == 1) PG8_BAR;
;     PG8_WAIT_V(4); PG8_BAR;
;     PG8_STAGE(PG8_SB(1, 0), cB + kstep, voffB); PG8_STAGE(PG8_SA(1, 0), cA + kstep, voffA); PG8_STAGE(PG8_SB(1, 1), cB + hstep + kstep, voffB);
;     PG8_WAIT_V(6); PG8_BAR;
.LBB0_765:
	v_ashrrev_i32_e32 v1, 31, v8
	v_lshrrev_b32_e32 v1, 26, v1
	v_add_u32_e32 v1, v8, v1
	v_ashrrev_i32_e32 v9, 6, v1
	v_bfe_i32 v1, v8, 27, 1
	v_lshlrev_b32_e32 v0, 4, v8
	v_lshrrev_b32_e32 v1, 22, v1
	v_add_u32_e32 v1, v0, v1
	v_and_b32_e32 v1, 0xfffffc00, v1
	v_sub_u32_e32 v1, v0, v1
	v_lshrrev_b32_e32 v2, 4, v1
	v_bitop3_b32 v1, v2, v1, 32 bitop3:0x6c
	v_ashrrev_i32_e32 v3, 31, v1
	v_lshrrev_b32_e32 v3, 26, v3
	v_lshlrev_b32_e32 v2, 3, v9
	v_add_u32_e32 v3, v1, v3
	v_and_b32_e32 v2, -16, v2
	v_ashrrev_i32_e32 v11, 6, v3
	v_and_b32_e32 v3, 0xc0, v3
	v_add_u32_e32 v2, v11, v2
	v_lshlrev_b32_e32 v4, 5, v9
	v_sub_u32_e32 v1, v1, v3
	v_mov_b32_e32 v3, 1
	v_and_b32_e32 v10, 32, v4
	v_ashrrev_i16_sdwa v1, v3, sext(v1) dst_sel:DWORD dst_unused:UNUSED_PAD src0_sel:DWORD src1_sel:BYTE_0
	v_lshlrev_b32_e32 v4, 1, v2
	v_lshrrev_b32_e32 v5, 2, v2
	v_and_b32_e32 v6, 3, v11
	s_mov_b32 s5, 0xffffe0
	s_waitcnt vmcnt(0)
	v_bfe_i32 v12, v1, 0, 16
	v_and_b32_e32 v4, 24, v4
	v_and_b32_e32 v5, 4, v5
	v_and_or_b32 v6, v2, s5, v6
	s_movk_i32 s8, 0xb00
	v_add_u32_e32 v1, v10, v12
	v_or3_b32 v4, v6, v5, v4
	v_mul_lo_u32 v2, v2, s8
	s_ashr_i32 s7, s3, 3
	v_add_lshl_u32 v128, v1, v2, 1
	v_mul_u32_u24_e32 v2, 0xb00, v4
	v_add_u32_e32 v0, 0x2000, v0
	s_add_u32 s3, s64, 0x1300000
	v_add_lshl_u32 v130, v2, v1, 1
	v_ashrrev_i32_e32 v1, 31, v0
	s_addc_u32 s4, s65, 0
	v_lshrrev_b32_e32 v1, 22, v1
	s_add_i32 s7, s10, s7
	v_add_u32_e32 v1, v0, v1
	s_ashr_i32 s10, s7, 31
	v_ashrrev_i32_e32 v13, 10, v1
	s_lshr_b32 s10, s10, 27
	v_mul_i32_i24_e32 v1, 0x400, v13
	s_add_i32 s10, s7, s10
	v_sub_u32_e32 v0, v0, v1
	s_ashr_i32 s11, s10, 5
	s_andn2_b32 s10, s10, 31
	v_lshrrev_b32_e32 v1, 4, v0
	s_sub_i32 s10, s7, s10
	v_bitop3_b32 v0, v1, v0, 32 bitop3:0x6c
	s_bfe_i32 s7, s10, 0x80000
	v_ashrrev_i32_e32 v2, 31, v0
	s_bfe_u32 s7, s7, 0x3000c
	v_lshrrev_b32_e32 v2, 26, v2
	s_add_i32 s12, s10, s7
	v_lshlrev_b32_e32 v1, 3, v13
	v_add_u32_e32 v2, v0, v2
	s_bfe_i32 s7, s12, 0x80000
	s_and_b32 s12, s12, 0xf8
	v_and_b32_e32 v1, -16, v1
	v_ashrrev_i32_e32 v14, 6, v2
	v_lshlrev_b32_e32 v4, 5, v13
	s_sext_i32_i16 s13, s7
	s_sub_i32 s10, s10, s12
	v_add_u32_e32 v1, v14, v1
	v_and_b32_e32 v15, 32, v4
	v_and_b32_e32 v2, 0xc0, v2
	v_and_b32_e32 v4, 3, v14
	s_ashr_i32 s9, s0, 6
	s_lshl_b32 s11, s11, 3
	s_sext_i32_i8 s10, s10
	s_ashr_i32 s12, s13, 3
	s_ashr_i32 s6, s0, 8
	v_sub_u32_e32 v0, v0, v2
	v_and_or_b32 v4, v1, s5, v4
	s_lshl_b32 s5, s9, 10
	s_lshr_b32 s7, s13, 3
	s_add_i32 s46, s11, s10
	s_mul_hi_i32 s13, s12, 0x160000
	s_mul_i32 s12, s12, 0x160000
	v_ashrrev_i16_sdwa v0, v3, sext(v0) dst_sel:DWORD dst_unused:UNUSED_PAD src0_sel:DWORD src1_sel:BYTE_0
	v_lshlrev_b32_e32 v2, 1, v1
	v_lshrrev_b32_e32 v3, 2, v1
	s_add_u32 s28, s3, s12
	v_bfe_i32 v16, v0, 0, 16
	v_and_b32_e32 v2, 24, v2
	v_and_b32_e32 v3, 4, v3
	s_addc_u32 s29, s4, s13
	s_add_i32 s33, s5, 0
	v_add_u32_e32 v0, v15, v16
	v_or3_b32 v2, v4, v3, v2
	v_mul_lo_u32 v1, v1, s8
	s_add_i32 m0, s33, 0x10000
	v_add_lshl_u32 v132, v0, v1, 1
	v_mul_u32_u24_e32 v1, 0xb00, v2
	s_mul_i32 s11, s46, 0x160000
	global_load_lds_dwordx4 v130, s[28:29]
	s_add_i32 m0, s33, 0x12000
	v_add_lshl_u32 v134, v1, v0, 1
	s_mul_hi_i32 s10, s46, 0x160000
	s_add_u32 s26, s82, s11
	global_load_lds_dwordx4 v134, s[28:29]
	s_addc_u32 s27, s83, s10
	s_mov_b32 m0, s33
	s_add_i32 s36, s33, 0x2000
	global_load_lds_dwordx4 v128, s[26:27]
	s_mov_b32 m0, s36
	s_add_u32 s10, s28, 0xb0000
	global_load_lds_dwordx4 v132, s[26:27]
	s_addc_u32 s11, s29, 0
	s_add_i32 m0, s33, 0x14000
	v_mov_b32_e32 v131, 0
	global_load_lds_dwordx4 v130, s[10:11]
	s_add_i32 m0, s33, 0x16000
	v_mov_b32_e32 v135, v131
	global_load_lds_dwordx4 v134, s[10:11]
	s_add_u32 s10, s26, 0xb0000
	s_addc_u32 s11, s27, 0
	s_add_i32 s37, s33, 0x4000
	s_mov_b32 m0, s37
	s_add_i32 s38, s33, 0x6000
	global_load_lds_dwordx4 v128, s[10:11]
	s_mov_b32 m0, s38
	v_mov_b32_e32 v129, v131
	global_load_lds_dwordx4 v132, s[10:11]
	v_mov_b32_e32 v133, v131
	s_mov_b32 s39, 0
	v_lshl_add_u64 v[6:7], s[28:29], 0, v[130:131]
	v_lshl_add_u64 v[4:5], s[28:29], 0, v[134:135]
	v_lshl_add_u64 v[2:3], s[26:27], 0, v[128:129]
	s_cmp_lg_u32 s6, 1
	v_lshl_add_u64 v[0:1], s[26:27], 0, v[132:133]
	s_cbranch_scc1 .LBB0_767
	s_barrier
	s_setprio 1

; #define PG8_STAGE(bufoff, gbase, voff) do { _Pragma("unroll") for (int _i = 0; _i < 2; ++_i) \
;         __builtin_amdgcn_global_load_lds((const unsigned*)((const char*)(gbase) + (voff)[_i]), (PG8_LAS unsigned*)(lds + (bufoff) + ldsw + _i * 8192), 16, 0, 0); } while (0)
; #define PG8_LDA(dst, b, h) do { _Pragma("unroll") for (int m = 0; m < 4; ++m) _Pragma("unroll") for (int k = 0; k < 2; ++k) dst[m][k] = *(const PG8_LAS bf16x8*)(lds + PG8_SA(b, h) + aoff + m * 2048 + k * 1024); } while (0)
; #define PG8_LDB(dst, b, h) do { _Pragma("unroll") for (int n = 0; n < 2; ++n) _Pragma("unroll") for (int k = 0; k < 2; ++k) dst[n][k] = *(const PG8_LAS bf16x8*)(lds + PG8_SB(b, h) + boff + n * 2048 + k * 1024); } while (0)
; #define PG8_MMA(ai, bj, At, Bt) do { __builtin_amdgcn_s_setprio(1); _Pragma("unroll") for (int m = 0; m < 4; ++m) _Pragma("unroll") for (int n = 0; n < 2; ++n) _Pragma("unroll") for (int k = 0; k < 2; ++k) \
;         acc[ai][bj][m][n] = __builtin_amdgcn_mfma_f32_16x16x32_bf16(Bt[n][k], At[m][k], acc[ai][bj][m][n], 0, 0, 0); __builtin_amdgcn_s_setprio(0); } while (0)
; #define PG8_WAIT_V(n) asm volatile("s_waitcnt vmcnt(" #n ")" ::: "memory")
; #define PG8_WAIT_L(n) asm volatile("s_waitcnt lgkmcnt(" #n ")" ::: "memory")
; #define PG8_BAR __builtin_amdgcn_s_barrier()
; #define PG8_SCHED __builtin_amdgcn_sched_barrier(0)
; template <class Epi, class Sched>
; __device__ __forceinline__ void gemm_phase(PG8_LAS unsigned char* lds, const Gemm g, const Sched& S, const Epi& E) {
;     ...
;             PG8_LDB(B0, 0, 0); PG8_SCHED; PG8_LDA(At, 0, 0); PG8_STAGE(PG8_SA(1, 1), a1 + hstep, voffA);
;             PG8_WAIT_L(8); PG8_BAR; PG8_WAIT_L(0); PG8_MMA(0, 0, At, B0); PG8_BAR; PG8_SCHED;
;             PG8_LDB(B1, 0, 1); PG8_STAGE(PG8_SB(0, 0), b2, voffB);
;             PG8_BAR; PG8_WAIT_L(0); PG8_MMA(0, 1, At, B1); PG8_BAR;
;             PG8_LDA(At, 0, 1); PG8_STAGE(PG8_SA(0, 0), a2, voffA);
;             PG8_BAR; PG8_WAIT_L(0); PG8_MMA(1, 0, At, B0); PG8_BAR; PG8_SCHED;
;             PG8_STAGE(PG8_SB(0, 1), b2 + hstep, voffB);
;             PG8_WAIT_V(6); PG8_BAR; PG8_MMA(1, 1, At, B1); PG8_BAR;
.LBB0_780:
	ds_read_b128 v[144:147], v188
	ds_read_b128 v[148:151], v188 offset:1024
	ds_read_b128 v[152:155], v188 offset:2048
	ds_read_b128 v[156:159], v188 offset:3072
	s_add_u32 s28, s26, 0x100
	s_addc_u32 s29, s27, 0
	s_cmp_eq_u32 s50, 40
	s_cselect_b32 s35, s11, s29
	s_cselect_b32 s34, s10, s28
	s_cselect_b32 s31, s13, s49
	s_cselect_b32 s30, s12, s48
	v_lshl_add_u64 v[184:185], s[26:27], 0, v[136:137]
	s_add_i32 m0, s33, 0xc000
	ds_read_b128 v[160:163], v189
	ds_read_b128 v[164:167], v189 offset:1024
	ds_read_b128 v[168:171], v189 offset:2048
	ds_read_b128 v[172:175], v189 offset:3072
	ds_read_b128 v[180:183], v189 offset:4096
	ds_read_b128 v[192:195], v189 offset:5120
	ds_read_b128 v[196:199], v189 offset:6144
	ds_read_b128 v[200:203], v189 offset:7168
	global_load_lds_dwordx4 v[184:185], off
	v_lshl_add_u64 v[184:185], s[26:27], 0, v[138:139]
	s_add_i32 m0, s33, 0xe000
	s_nop 0
	global_load_lds_dwordx4 v[184:185], off
	s_waitcnt lgkmcnt(8)
	s_barrier
	s_waitcnt lgkmcnt(0)
	s_waitcnt lgkmcnt(0)
	v_mfma_f32_16x16x32_bf16 v[124:127], v[144:147], v[160:163], v[124:127]
	v_mfma_f32_16x16x32_bf16 v[120:123], v[152:155], v[160:163], v[120:123]
	v_mfma_f32_16x16x32_bf16 v[108:111], v[144:147], v[168:171], v[108:111]
	v_mfma_f32_16x16x32_bf16 v[104:107], v[152:155], v[168:171], v[104:107]
	v_mfma_f32_16x16x32_bf16 v[92:95], v[144:147], v[180:183], v[92:95]
	v_mfma_f32_16x16x32_bf16 v[88:91], v[152:155], v[180:183], v[88:91]
	v_mfma_f32_16x16x32_bf16 v[76:79], v[144:147], v[196:199], v[76:79]
	v_mfma_f32_16x16x32_bf16 v[72:75], v[152:155], v[196:199], v[72:75]
	v_mfma_f32_16x16x32_bf16 v[124:127], v[148:151], v[164:167], v[124:127]
	v_mfma_f32_16x16x32_bf16 v[120:123], v[156:159], v[164:167], v[120:123]
	v_mfma_f32_16x16x32_bf16 v[108:111], v[148:151], v[172:175], v[108:111]
	v_mfma_f32_16x16x32_bf16 v[104:107], v[156:159], v[172:175], v[104:107]
	v_mfma_f32_16x16x32_bf16 v[92:95], v[148:151], v[192:195], v[92:95]
	v_mfma_f32_16x16x32_bf16 v[88:91], v[156:159], v[192:195], v[88:91]
	v_mfma_f32_16x16x32_bf16 v[76:79], v[148:151], v[200:203], v[76:79]
	v_mfma_f32_16x16x32_bf16 v[72:75], v[156:159], v[200:203], v[72:75]
	s_barrier
	s_add_i32 s26, s42, s5
	v_lshl_add_u64 v[184:185], s[30:31], 0, v[130:131]
	s_mov_b32 m0, s26
	ds_read_b128 v[208:211], v190
	ds_read_b128 v[212:215], v190 offset:1024
	ds_read_b128 v[216:219], v190 offset:2048
	ds_read_b128 v[220:223], v190 offset:3072
	global_load_lds_dwordx4 v[184:185], off
	v_lshl_add_u64 v[204:205], s[30:31], 0, v[134:135]
	s_add_i32 m0, s26, 0x2000
	s_nop 0
	global_load_lds_dwordx4 v[204:205], off
	s_barrier
	s_waitcnt lgkmcnt(0)
	s_waitcnt lgkmcnt(0)
	v_mfma_f32_16x16x32_bf16 v[116:119], v[208:211], v[160:163], v[116:119]
	v_mfma_f32_16x16x32_bf16 v[112:115], v[216:219], v[160:163], v[112:115]
	v_mfma_f32_16x16x32_bf16 v[100:103], v[208:211], v[168:171], v[100:103]
	v_mfma_f32_16x16x32_bf16 v[96:99], v[216:219], v[168:171], v[96:99]
	v_mfma_f32_16x16x32_bf16 v[84:87], v[208:211], v[180:183], v[84:87]
	v_mfma_f32_16x16x32_bf16 v[80:83], v[216:219], v[180:183], v[80:83]
	v_mfma_f32_16x16x32_bf16 v[68:71], v[208:211], v[196:199], v[68:71]
	v_mfma_f32_16x16x32_bf16 v[64:67], v[216:219], v[196:199], v[64:67]
	v_mfma_f32_16x16x32_bf16 v[116:119], v[212:215], v[164:167], v[116:119]
	v_mfma_f32_16x16x32_bf16 v[112:115], v[220:223], v[164:167], v[112:115]
	v_mfma_f32_16x16x32_bf16 v[100:103], v[212:215], v[172:175], v[100:103]
	v_mfma_f32_16x16x32_bf16 v[96:99], v[220:223], v[172:175], v[96:99]
	v_mfma_f32_16x16x32_bf16 v[84:87], v[212:215], v[192:195], v[84:87]
	v_mfma_f32_16x16x32_bf16 v[80:83], v[220:223], v[192:195], v[80:83]
	v_mfma_f32_16x16x32_bf16 v[68:71], v[212:215], v[200:203], v[68:71]
	v_mfma_f32_16x16x32_bf16 v[64:67], v[220:223], v[200:203], v[64:67]
	s_mov_b32 m0, s33
	v_lshl_add_u64 v[224:225], s[34:35], 0, v[128:129]
	s_barrier
	ds_read_b128 v[160:163], v189 offset:16384
	ds_read_b128 v[164:167], v189 offset:17408
	ds_read_b128 v[168:171], v189 offset:18432
	ds_read_b128 v[172:175], v189 offset:19456
	ds_read_b128 v[180:183], v189 offset:20480
	ds_read_b128 v[192:195], v189 offset:21504
	ds_read_b128 v[196:199], v189 offset:22528
	ds_read_b128 v[200:203], v189 offset:23552
	global_load_lds_dwordx4 v[224:225], off
	v_lshl_add_u64 v[226:227], s[34:35], 0, v[132:133]
	s_mov_b32 m0, s36
	s_nop 0
	global_load_lds_dwordx4 v[226:227], off
	s_barrier
	s_waitcnt lgkmcnt(0)
	s_waitcnt lgkmcnt(0)
	v_mfma_f32_16x16x32_bf16 v[60:63], v[144:147], v[160:163], v[60:63]
	v_mfma_f32_16x16x32_bf16 v[56:59], v[152:155], v[160:163], v[56:59]
	v_mfma_f32_16x16x32_bf16 v[44:47], v[144:147], v[168:171], v[44:47]
	v_mfma_f32_16x16x32_bf16 v[40:43], v[152:155], v[168:171], v[40:43]
	v_mfma_f32_16x16x32_bf16 v[28:31], v[144:147], v[180:183], v[28:31]
	v_mfma_f32_16x16x32_bf16 v[24:27], v[152:155], v[180:183], v[24:27]
	v_mfma_f32_16x16x32_bf16 v[12:15], v[144:147], v[196:199], v[12:15]
	v_mfma_f32_16x16x32_bf16 v[8:11], v[152:155], v[196:199], v[8:11]
	v_mfma_f32_16x16x32_bf16 v[60:63], v[148:151], v[164:167], v[60:63]
	v_mfma_f32_16x16x32_bf16 v[56:59], v[156:159], v[164:167], v[56:59]
	v_mfma_f32_16x16x32_bf16 v[44:47], v[148:151], v[172:175], v[44:47]
	v_mfma_f32_16x16x32_bf16 v[40:43], v[156:159], v[172:175], v[40:43]
	v_mfma_f32_16x16x32_bf16 v[28:31], v[148:151], v[192:195], v[28:31]
	v_mfma_f32_16x16x32_bf16 v[24:27], v[156:159], v[192:195], v[24:27]
	v_mfma_f32_16x16x32_bf16 v[12:15], v[148:151], v[200:203], v[12:15]
	v_mfma_f32_16x16x32_bf16 v[8:11], v[156:159], v[200:203], v[8:11]
	s_barrier
; #define PG8_STAGE(bufoff, gbase, voff) do { _Pragma("unroll") for (int _i = 0; _i < 2; ++_i) \
;         __builtin_amdgcn_global_load_lds((const unsigned*)((const char*)(gbase) + (voff)[_i]), (PG8_LAS unsigned*)(lds + (bufoff) + ldsw + _i * 8192), 16, 0, 0); } while (0)
; #define PG8_LDA(dst, b, h) do { _Pragma("unroll") for (int m = 0; m < 4; ++m) _Pragma("unroll") for (int k = 0; k < 2; ++k) dst[m][k] = *(const PG8_LAS bf16x8*)(lds + PG8_SA(b, h) + aoff + m * 2048 + k * 1024); } while (0)
; #define PG8_LDB(dst, b, h) do { _Pragma("unroll") for (int n = 0; n < 2; ++n) _Pragma("unroll") for (int k = 0; k < 2; ++k) dst[n][k] = *(const PG8_LAS bf16x8*)(lds + PG8_SB(b, h) + boff + n * 2048 + k * 1024); } while (0)
; #define PG8_MMA(ai, bj, At, Bt) do { __builtin_amdgcn_s_setprio(1); _Pragma("unroll") for (int m = 0; m < 4; ++m) _Pragma("unroll") for (int n = 0; n < 2; ++n) _Pragma("unroll") for (int k = 0; k < 2; ++k) \
;         acc[ai][bj][m][n] = __builtin_amdgcn_mfma_f32_16x16x32_bf16(Bt[n][k], At[m][k], acc[ai][bj][m][n], 0, 0, 0); __builtin_amdgcn_s_setprio(0); } while (0)
; #define PG8_WAIT_V(n) asm volatile("s_waitcnt vmcnt(" #n ")" ::: "memory")
; #define PG8_WAIT_L(n) asm volatile("s_waitcnt lgkmcnt(" #n ")" ::: "memory")
; #define PG8_BAR __builtin_amdgcn_s_barrier()
; #define PG8_SCHED __builtin_amdgcn_sched_barrier(0)
; template <class Epi, class Sched>
; __device__ __forceinline__ void gemm_phase(PG8_LAS unsigned char* lds, const Gemm g, const Sched& S, const Epi& E) {
;     ...
;             PG8_STAGE(PG8_SB(0, 1), b2 + hstep, voffB);
;             PG8_WAIT_V(6); PG8_BAR; PG8_MMA(1, 1, At, B1); PG8_BAR;
;             PG8_LDB(B0, 1, 0); PG8_SCHED; PG8_LDA(At, 1, 0); PG8_STAGE(PG8_SA(0, 1), a2 + hstep, voffA);
;             PG8_WAIT_L(8); PG8_BAR; PG8_WAIT_L(0); PG8_MMA(0, 0, At, B0); PG8_BAR; PG8_SCHED;
;             PG8_LDB(B1, 1, 1); PG8_STAGE(PG8_SB(1, 0), b3, voffB);
;             PG8_BAR; PG8_WAIT_L(0); PG8_MMA(0, 1, At, B1); PG8_BAR;
;             PG8_LDA(At, 1, 1); PG8_STAGE(PG8_SA(1, 0), a3, voffA);
;             PG8_BAR; PG8_WAIT_L(0); PG8_MMA(1, 0, At, B0); PG8_BAR; PG8_SCHED;
	s_add_u32 s26, s30, 0xb0000
	s_addc_u32 s27, s31, 0
	s_add_i32 s51, s43, s5
	v_lshl_add_u64 v[144:145], s[26:27], 0, v[130:131]
	s_mov_b32 m0, s51
	s_nop 0
	global_load_lds_dwordx4 v[144:145], off
	v_lshl_add_u64 v[144:145], s[26:27], 0, v[134:135]
	s_add_i32 m0, s51, 0x2000
	s_nop 0
	global_load_lds_dwordx4 v[144:145], off
	s_waitcnt vmcnt(6)
	s_barrier
	v_mfma_f32_16x16x32_bf16 v[52:55], v[208:211], v[160:163], v[52:55]
	v_mfma_f32_16x16x32_bf16 v[48:51], v[216:219], v[160:163], v[48:51]
	v_mfma_f32_16x16x32_bf16 v[36:39], v[208:211], v[168:171], v[36:39]
	v_mfma_f32_16x16x32_bf16 v[32:35], v[216:219], v[168:171], v[32:35]
	v_mfma_f32_16x16x32_bf16 v[20:23], v[208:211], v[180:183], v[20:23]
	v_mfma_f32_16x16x32_bf16 v[16:19], v[216:219], v[180:183], v[16:19]
	v_mfma_f32_16x16x32_bf16 v[4:7], v[208:211], v[196:199], v[4:7]
	v_mfma_f32_16x16x32_bf16 v[0:3], v[216:219], v[196:199], v[0:3]
	v_mfma_f32_16x16x32_bf16 v[52:55], v[212:215], v[164:167], v[52:55]
	v_mfma_f32_16x16x32_bf16 v[48:51], v[220:223], v[164:167], v[48:51]
	v_mfma_f32_16x16x32_bf16 v[36:39], v[212:215], v[172:175], v[36:39]
	v_mfma_f32_16x16x32_bf16 v[32:35], v[220:223], v[172:175], v[32:35]
	v_mfma_f32_16x16x32_bf16 v[20:23], v[212:215], v[192:195], v[20:23]
	v_mfma_f32_16x16x32_bf16 v[16:19], v[220:223], v[192:195], v[16:19]
	v_mfma_f32_16x16x32_bf16 v[4:7], v[212:215], v[200:203], v[4:7]
	v_mfma_f32_16x16x32_bf16 v[0:3], v[220:223], v[200:203], v[0:3]
	s_add_i32 s51, 0, 0x18000
	v_add_u32_e32 v156, s51, v186
	s_barrier
	ds_read_b128 v[144:147], v156
	ds_read_b128 v[148:151], v156 offset:1024
	ds_read_b128 v[152:155], v156 offset:2048
	ds_read_b128 v[156:159], v156 offset:3072
	s_add_u32 s26, s34, 0xb0000
	s_addc_u32 s27, s35, 0
	s_mov_b32 m0, s37
	v_lshl_add_u64 v[208:209], s[26:27], 0, v[128:129]
	ds_read_b128 v[160:163], v189 offset:32768
	ds_read_b128 v[164:167], v189 offset:33792
	ds_read_b128 v[168:171], v189 offset:34816
	ds_read_b128 v[172:175], v189 offset:35840
	ds_read_b128 v[180:183], v189 offset:36864
	ds_read_b128 v[192:195], v189 offset:37888
	ds_read_b128 v[196:199], v189 offset:38912
	ds_read_b128 v[200:203], v189 offset:39936
	global_load_lds_dwordx4 v[208:209], off
	v_lshl_add_u64 v[208:209], s[26:27], 0, v[132:133]
	s_mov_b32 m0, s38
	s_nop 0
	global_load_lds_dwordx4 v[208:209], off
	s_waitcnt lgkmcnt(8)
	s_barrier
	s_waitcnt lgkmcnt(0)
	s_waitcnt lgkmcnt(0)
	v_mfma_f32_16x16x32_bf16 v[124:127], v[144:147], v[160:163], v[124:127]
	v_mfma_f32_16x16x32_bf16 v[120:123], v[152:155], v[160:163], v[120:123]
	v_mfma_f32_16x16x32_bf16 v[108:111], v[144:147], v[168:171], v[108:111]
	v_mfma_f32_16x16x32_bf16 v[104:107], v[152:155], v[168:171], v[104:107]
	v_mfma_f32_16x16x32_bf16 v[92:95], v[144:147], v[180:183], v[92:95]
	v_mfma_f32_16x16x32_bf16 v[88:91], v[152:155], v[180:183], v[88:91]
	v_mfma_f32_16x16x32_bf16 v[76:79], v[144:147], v[196:199], v[76:79]
	v_mfma_f32_16x16x32_bf16 v[72:75], v[152:155], v[196:199], v[72:75]
	v_mfma_f32_16x16x32_bf16 v[124:127], v[148:151], v[164:167], v[124:127]
	v_mfma_f32_16x16x32_bf16 v[120:123], v[156:159], v[164:167], v[120:123]
	v_mfma_f32_16x16x32_bf16 v[108:111], v[148:151], v[172:175], v[108:111]
	v_mfma_f32_16x16x32_bf16 v[104:107], v[156:159], v[172:175], v[104:107]
	v_mfma_f32_16x16x32_bf16 v[92:95], v[148:151], v[192:195], v[92:95]
	v_mfma_f32_16x16x32_bf16 v[88:91], v[156:159], v[192:195], v[88:91]
	v_mfma_f32_16x16x32_bf16 v[76:79], v[148:151], v[200:203], v[76:79]
	v_mfma_f32_16x16x32_bf16 v[72:75], v[156:159], v[200:203], v[72:75]
	s_barrier
	s_add_i32 s34, 0, 0x1c000
	s_add_i32 s26, s51, s5
	v_add_u32_e32 v207, s34, v186
	v_lshl_add_u64 v[184:185], v[184:185], 0, s[16:17]
	s_mov_b32 m0, s26
	ds_read_b128 v[208:211], v207
	ds_read_b128 v[212:215], v207 offset:1024
	ds_read_b128 v[216:219], v207 offset:2048
	ds_read_b128 v[220:223], v207 offset:3072
	global_load_lds_dwordx4 v[184:185], off
	v_lshl_add_u64 v[184:185], v[204:205], 0, s[16:17]
	s_add_i32 m0, s26, 0x2000
	s_nop 0
	global_load_lds_dwordx4 v[184:185], off
	s_barrier
	s_waitcnt lgkmcnt(0)
	s_waitcnt lgkmcnt(0)
	v_mfma_f32_16x16x32_bf16 v[116:119], v[208:211], v[160:163], v[116:119]
	v_mfma_f32_16x16x32_bf16 v[112:115], v[216:219], v[160:163], v[112:115]
	v_mfma_f32_16x16x32_bf16 v[100:103], v[208:211], v[168:171], v[100:103]
	v_mfma_f32_16x16x32_bf16 v[96:99], v[216:219], v[168:171], v[96:99]
	v_mfma_f32_16x16x32_bf16 v[84:87], v[208:211], v[180:183], v[84:87]
	v_mfma_f32_16x16x32_bf16 v[80:83], v[216:219], v[180:183], v[80:83]
	v_mfma_f32_16x16x32_bf16 v[68:71], v[208:211], v[196:199], v[68:71]
	v_mfma_f32_16x16x32_bf16 v[64:67], v[216:219], v[196:199], v[64:67]
	v_mfma_f32_16x16x32_bf16 v[116:119], v[212:215], v[164:167], v[116:119]
	v_mfma_f32_16x16x32_bf16 v[112:115], v[220:223], v[164:167], v[112:115]
	v_mfma_f32_16x16x32_bf16 v[100:103], v[212:215], v[172:175], v[100:103]
	v_mfma_f32_16x16x32_bf16 v[96:99], v[220:223], v[172:175], v[96:99]
	v_mfma_f32_16x16x32_bf16 v[84:87], v[212:215], v[192:195], v[84:87]
	v_mfma_f32_16x16x32_bf16 v[80:83], v[220:223], v[192:195], v[80:83]
	v_mfma_f32_16x16x32_bf16 v[68:71], v[212:215], v[200:203], v[68:71]
	v_mfma_f32_16x16x32_bf16 v[64:67], v[220:223], v[200:203], v[64:67]
	s_mov_b32 m0, s40
	v_lshl_add_u64 v[184:185], v[224:225], 0, s[16:17]
	s_barrier
	ds_read_b128 v[160:163], v189 offset:49152
	ds_read_b128 v[164:167], v189 offset:50176
	ds_read_b128 v[168:171], v189 offset:51200
	ds_read_b128 v[172:175], v189 offset:52224
	ds_read_b128 v[180:183], v189 offset:53248
	ds_read_b128 v[192:195], v189 offset:54272
	ds_read_b128 v[196:199], v189 offset:55296
	ds_read_b128 v[200:203], v189 offset:56320
	global_load_lds_dwordx4 v[184:185], off
	v_lshl_add_u64 v[184:185], v[226:227], 0, s[16:17]
	s_mov_b32 m0, s41
	s_nop 0
	global_load_lds_dwordx4 v[184:185], off
	s_barrier
; __device__ __forceinline__ unsigned cvt_pk_bf16(float lo, float hi) { unsigned r; asm volatile("v_cvt_pk_bf16_f32 %0, %1, %2" : "=v"(r) : "v"(lo), "v"(hi)); return r; }
; #define PG8_STAGE(bufoff, gbase, voff) do { _Pragma("unroll") for (int _i = 0; _i < 2; ++_i) \
;         __builtin_amdgcn_global_load_lds((const unsigned*)((const char*)(gbase) + (voff)[_i]), (PG8_LAS unsigned*)(lds + (bufoff) + ldsw + _i * 8192), 16, 0, 0); } while (0)
; template <class Epi, class Sched>
; __device__ __forceinline__ void gemm_phase(PG8_LAS unsigned char* lds, const Gemm g, const Sched& S, const Epi& E) {
;     ...
;             PG8_STAGE(PG8_SB(1, 1), b3 + hstep, voffB);
;             PG8_WAIT_V(6); PG8_BAR; PG8_MMA(1, 1, At, B1); PG8_BAR;
;     __device__ __forceinline__ void operator()(const f32x4 (&acc)[2][2][4][2], const Unit& u, int wr, int wc, int fr, int fq, const float (&epre)[1]) const {
;         const int row0 = u.pm * 256 + wr * 64 + fr, col0 = u.pn * 256 + wc * 32 + 8 * fq;
; #pragma unroll
;         for (int ai = 0; ai < 2; ++ai) {
;             float ssv[4];
;             f32x4 bv[4][2][2];
; #pragma unroll
;             for (int m = 0; m < 4; ++m) { const int row = row0 + ai * 128 + m * 16;
; #pragma unroll
;                 for (int bj = 0; bj < 2; ++bj) {
;                     if (BASEBF) { unpack8(*(const u32x4*)(HB + (size_t)row * DM + col0 + bj * 128), bv[m][bj][0], bv[m][bj][1]); }
;                     else { const float* bp = (row < MP ? base0 + (size_t)row * DM : base1 + (size_t)(row - MP) * DM) + col0 + bj * 128; bv[m][bj][0] = __builtin_nontemporal_load((const f32x4*)bp); bv[m][bj][1] = __builtin_nontemporal_load((const f32x4*)(bp + 4)); } } }
; #pragma unroll
;             for (int m = 0; m < 4; ++m) { const int row = row0 + ai * 128 + m * 16;
;                 float ss = 0.f;
; #pragma unroll
;                 for (int bj = 0; bj < 2; ++bj) { const f32x4 h0 = bv[m][bj][0] + acc[ai][bj][m][0], h1 = bv[m][bj][1] + acc[ai][bj][m][1];
;                     u32x4 w; w.x = cvt_pk_bf16(h0[0], h0[1]); w.y = cvt_pk_bf16(h0[2], h0[3]); w.z = cvt_pk_bf16(h1[0], h1[1]); w.w = cvt_pk_bf16(h1[2], h1[3]);
;                     *(u32x4*)(HBo + (size_t)row * DM + col0 + bj * 128) = w;
;                     ss += (h0[0] * h0[0] + h0[1] * h0[1]) + (h0[2] * h0[2] + h0[3] * h0[3]) + (h1[0] * h1[0] + h1[1] * h1[1]) + (h1[2] * h1[2] + h1[3] * h1[3]); }
	s_waitcnt lgkmcnt(0)
	s_waitcnt lgkmcnt(0)
	v_mfma_f32_16x16x32_bf16 v[60:63], v[144:147], v[160:163], v[60:63]
	v_mfma_f32_16x16x32_bf16 v[56:59], v[152:155], v[160:163], v[56:59]
	v_mfma_f32_16x16x32_bf16 v[44:47], v[144:147], v[168:171], v[44:47]
	v_mfma_f32_16x16x32_bf16 v[40:43], v[152:155], v[168:171], v[40:43]
	v_mfma_f32_16x16x32_bf16 v[28:31], v[144:147], v[180:183], v[28:31]
	v_mfma_f32_16x16x32_bf16 v[24:27], v[152:155], v[180:183], v[24:27]
	v_mfma_f32_16x16x32_bf16 v[12:15], v[144:147], v[196:199], v[12:15]
	v_mfma_f32_16x16x32_bf16 v[8:11], v[152:155], v[196:199], v[8:11]
	v_mfma_f32_16x16x32_bf16 v[60:63], v[148:151], v[164:167], v[60:63]
	v_mfma_f32_16x16x32_bf16 v[56:59], v[156:159], v[164:167], v[56:59]
	v_mfma_f32_16x16x32_bf16 v[44:47], v[148:151], v[172:175], v[44:47]
	v_mfma_f32_16x16x32_bf16 v[40:43], v[156:159], v[172:175], v[40:43]
	v_mfma_f32_16x16x32_bf16 v[28:31], v[148:151], v[192:195], v[28:31]
	v_mfma_f32_16x16x32_bf16 v[24:27], v[156:159], v[192:195], v[24:27]
	v_mfma_f32_16x16x32_bf16 v[12:15], v[148:151], v[200:203], v[12:15]
	v_mfma_f32_16x16x32_bf16 v[8:11], v[156:159], v[200:203], v[8:11]
	s_barrier
	s_add_u32 s26, s30, 0xb0080
	s_addc_u32 s27, s31, 0
	s_add_i32 s30, s34, s5
	v_lshl_add_u64 v[144:145], s[26:27], 0, v[130:131]
	s_mov_b32 m0, s30
	s_nop 0
	global_load_lds_dwordx4 v[144:145], off
	v_lshl_add_u64 v[144:145], s[26:27], 0, v[134:135]
	s_add_i32 m0, s30, 0x2000
	s_nop 0
	global_load_lds_dwordx4 v[144:145], off
	s_waitcnt vmcnt(6)
	s_barrier
	v_mfma_f32_16x16x32_bf16 v[52:55], v[208:211], v[160:163], v[52:55]
	v_mfma_f32_16x16x32_bf16 v[48:51], v[216:219], v[160:163], v[48:51]
	v_mfma_f32_16x16x32_bf16 v[36:39], v[208:211], v[168:171], v[36:39]
	v_mfma_f32_16x16x32_bf16 v[32:35], v[216:219], v[168:171], v[32:35]
	v_mfma_f32_16x16x32_bf16 v[20:23], v[208:211], v[180:183], v[20:23]
	v_mfma_f32_16x16x32_bf16 v[16:19], v[216:219], v[180:183], v[16:19]
	v_mfma_f32_16x16x32_bf16 v[4:7], v[208:211], v[196:199], v[4:7]
	v_mfma_f32_16x16x32_bf16 v[0:3], v[216:219], v[196:199], v[0:3]
	v_mfma_f32_16x16x32_bf16 v[52:55], v[212:215], v[164:167], v[52:55]
	v_mfma_f32_16x16x32_bf16 v[48:51], v[220:223], v[164:167], v[48:51]
	v_mfma_f32_16x16x32_bf16 v[36:39], v[212:215], v[172:175], v[36:39]
	v_mfma_f32_16x16x32_bf16 v[32:35], v[220:223], v[172:175], v[32:35]
	v_mfma_f32_16x16x32_bf16 v[20:23], v[212:215], v[192:195], v[20:23]
	v_mfma_f32_16x16x32_bf16 v[16:19], v[220:223], v[192:195], v[16:19]
	v_mfma_f32_16x16x32_bf16 v[4:7], v[212:215], v[200:203], v[4:7]
	v_mfma_f32_16x16x32_bf16 v[0:3], v[220:223], v[200:203], v[0:3]
	s_add_i32 s50, s50, 2
	s_add_u32 s48, s48, 0x100
	s_addc_u32 s49, s49, 0
	s_cmp_gt_u32 s50, 41
	s_mov_b64 s[26:27], s[28:29]
	s_barrier
	s_cbranch_scc0 .LBB0_780
	v_lshl_or_b32 v144, s47, 8, v187
	v_lshl_add_u32 v150, s46, 8, v177
	v_ashrrev_i32_e32 v145, 31, v144
	v_ashrrev_i32_e32 v151, 31, v150
	v_lshlrev_b64 v[144:145], 1, v[144:145]
	v_lshl_add_u64 v[146:147], s[84:85], 0, v[144:145]
	v_lshlrev_b64 v[148:149], 11, v[150:151]
	v_lshl_add_u64 v[152:153], v[146:147], 0, v[148:149]
	global_load_dwordx4 v[154:157], v[152:153], off
	global_load_dwordx4 v[158:161], v[152:153], off offset:256
	v_or_b32_e32 v152, 16, v150
	v_ashrrev_i32_e32 v153, 31, v152
	v_lshlrev_b64 v[184:185], 11, v[152:153]
	v_lshl_add_u64 v[152:153], v[146:147], 0, v[184:185]
	global_load_dwordx4 v[164:167], v[152:153], off
	global_load_dwordx4 v[168:171], v[152:153], off offset:256
	v_or_b32_e32 v152, 32, v150
	v_ashrrev_i32_e32 v153, 31, v152
	v_lshlrev_b64 v[162:163], 11, v[152:153]
	v_lshl_add_u64 v[152:153], v[146:147], 0, v[162:163]
	global_load_dwordx4 v[172:175], v[152:153], off
	global_load_dwordx4 v[192:195], v[152:153], off offset:256
	v_or_b32_e32 v152, 48, v150
	v_ashrrev_i32_e32 v153, 31, v152
	v_lshlrev_b64 v[152:153], 11, v[152:153]
	v_lshl_add_u64 v[180:181], v[146:147], 0, v[152:153]
	global_load_dwordx4 v[196:199], v[180:181], off
	global_load_dwordx4 v[200:203], v[180:181], off offset:256
	s_waitcnt vmcnt(0)
	v_lshlrev_b32_e32 v204, 16, v154
	v_and_b32_e32 v205, 0xffff0000, v154
	v_lshlrev_b32_e32 v208, 16, v155
	v_and_b32_e32 v209, 0xffff0000, v155
	v_lshlrev_b32_e32 v210, 16, v156
	v_and_b32_e32 v211, 0xffff0000, v156
	v_lshlrev_b32_e32 v226, 16, v166
	v_and_b32_e32 v227, 0xffff0000, v166
	v_lshlrev_b32_e32 v228, 16, v167
	v_and_b32_e32 v229, 0xffff0000, v167
	v_lshlrev_b32_e32 v234, 16, v170
	v_and_b32_e32 v235, 0xffff0000, v170
	v_lshlrev_b32_e32 v236, 16, v171
	v_and_b32_e32 v237, 0xffff0000, v171
	v_lshlrev_b32_e32 v212, 16, v157
	v_lshlrev_b32_e32 v166, 16, v196
	v_and_b32_e32 v167, 0xffff0000, v196
	v_lshlrev_b32_e32 v170, 16, v197
	v_and_b32_e32 v171, 0xffff0000, v197
	v_lshl_add_u64 v[196:197], s[84:85], 0, v[148:149]
	v_and_b32_e32 v213, 0xffff0000, v157
	v_lshlrev_b32_e32 v238, 16, v172
	v_and_b32_e32 v239, 0xffff0000, v172
	v_lshlrev_b32_e32 v240, 16, v173
	v_and_b32_e32 v241, 0xffff0000, v173
	v_lshlrev_b32_e32 v172, 16, v194
	v_and_b32_e32 v173, 0xffff0000, v194
	v_lshlrev_b32_e32 v180, 16, v195
	v_and_b32_e32 v181, 0xffff0000, v195
	v_pk_add_f32 v[126:127], v[126:127], v[208:209]
	v_pk_add_f32 v[124:125], v[124:125], v[204:205]
	v_pk_add_f32 v[194:195], v[120:121], v[210:211]
	v_cvt_pk_bf16_f32 v120, v124, v125
	v_cvt_pk_bf16_f32 v121, v126, v127
	v_lshl_add_u64 v[196:197], v[196:197], 0, v[144:145]
	v_lshlrev_b32_e32 v242, 16, v174
	v_and_b32_e32 v243, 0xffff0000, v174
	v_lshlrev_b32_e32 v244, 16, v175
	v_and_b32_e32 v245, 0xffff0000, v175
	v_lshlrev_b32_e32 v174, 16, v192
	v_and_b32_e32 v175, 0xffff0000, v192
	v_lshlrev_b32_e32 v182, 16, v193
	v_and_b32_e32 v183, 0xffff0000, v193
; __device__ __forceinline__ unsigned cvt_pk_bf16(float lo, float hi) { unsigned r; asm volatile("v_cvt_pk_bf16_f32 %0, %1, %2" : "=v"(r) : "v"(lo), "v"(hi)); return r; }
;     __device__ __forceinline__ void operator()(const f32x4 (&acc)[2][2][4][2], const Unit& u, int wr, int wc, int fr, int fq, const float (&epre)[1]) const {
;     ...
;             for (int m = 0; m < 4; ++m) { const int row = row0 + ai * 128 + m * 16;
;                 float ss = 0.f;
; #pragma unroll
;                 for (int bj = 0; bj < 2; ++bj) { const f32x4 h0 = bv[m][bj][0] + acc[ai][bj][m][0], h1 = bv[m][bj][1] + acc[ai][bj][m][1];
;                     u32x4 w; w.x = cvt_pk_bf16(h0[0], h0[1]); w.y = cvt_pk_bf16(h0[2], h0[3]); w.z = cvt_pk_bf16(h1[0], h1[1]); w.w = cvt_pk_bf16(h1[2], h1[3]);
;                     *(u32x4*)(HBo + (size_t)row * DM + col0 + bj * 128) = w;
;                     ss += (h0[0] * h0[0] + h0[1] * h0[1]) + (h0[2] * h0[2] + h0[3] * h0[3]) + (h1[0] * h1[0] + h1[1] * h1[1]) + (h1[2] * h1[2] + h1[3] * h1[3]); }
;                 ssv[m] = ss;
;             }
	v_pk_add_f32 v[192:193], v[122:123], v[212:213]
	v_cvt_pk_bf16_f32 v122, v194, v195
	v_lshlrev_b32_e32 v214, 16, v158
	v_cvt_pk_bf16_f32 v123, v192, v193
	global_store_dwordx4 v[196:197], v[120:123], off
	v_and_b32_e32 v215, 0xffff0000, v158
	v_lshlrev_b32_e32 v216, 16, v159
	v_mul_f32_e32 v120, v125, v125
	v_mul_f32_e32 v121, v127, v127
	v_fmac_f32_e32 v120, v124, v124
	v_fmac_f32_e32 v121, v126, v126
	v_add_f32_e32 v120, v120, v121
	v_mul_f32_e32 v121, v195, v195
	v_fmac_f32_e32 v121, v194, v194
	v_and_b32_e32 v217, 0xffff0000, v159
	v_lshlrev_b32_e32 v218, 16, v160
	v_and_b32_e32 v219, 0xffff0000, v160
	v_add_f32_e32 v120, v121, v120
	v_mul_f32_e32 v121, v193, v193
	v_lshlrev_b32_e32 v220, 16, v161
	v_and_b32_e32 v221, 0xffff0000, v161
	v_fmac_f32_e32 v121, v192, v192
	v_pk_add_f32 v[118:119], v[118:119], v[216:217]
	v_pk_add_f32 v[116:117], v[116:117], v[214:215]
	v_pk_add_f32 v[122:123], v[112:113], v[218:219]
	v_cvt_pk_bf16_f32 v112, v116, v117
	v_cvt_pk_bf16_f32 v113, v118, v119
	v_add_f32_e32 v124, v121, v120
	v_pk_add_f32 v[120:121], v[114:115], v[220:221]
	v_cvt_pk_bf16_f32 v114, v122, v123
	v_lshlrev_b32_e32 v222, 16, v164
	v_cvt_pk_bf16_f32 v115, v120, v121
	global_store_dwordx4 v[196:197], v[112:115], off offset:256
	v_and_b32_e32 v223, 0xffff0000, v164
	v_lshlrev_b32_e32 v224, 16, v165
	v_mul_f32_e32 v112, v117, v117
	v_mul_f32_e32 v113, v119, v119
	v_fmac_f32_e32 v112, v116, v116
	v_fmac_f32_e32 v113, v118, v118
	v_add_f32_e32 v112, v112, v113
	v_mul_f32_e32 v113, v123, v123
	v_fmac_f32_e32 v113, v122, v122
	v_add_f32_e32 v112, v113, v112
	v_mul_f32_e32 v113, v121, v121
	v_and_b32_e32 v225, 0xffff0000, v165
	v_fmac_f32_e32 v113, v120, v120
	v_lshl_add_u64 v[116:117], s[84:85], 0, v[184:185]
	v_add_f32_e32 v112, v113, v112
	v_pk_add_f32 v[110:111], v[110:111], v[224:225]
	v_pk_add_f32 v[108:109], v[108:109], v[222:223]
	v_pk_add_f32 v[114:115], v[104:105], v[226:227]
	v_cvt_pk_bf16_f32 v104, v108, v109
	v_cvt_pk_bf16_f32 v105, v110, v111
	v_lshl_add_u64 v[116:117], v[116:117], 0, v[144:145]
	v_add_f32_e32 v118, v124, v112
	v_pk_add_f32 v[112:113], v[106:107], v[228:229]
	v_cvt_pk_bf16_f32 v106, v114, v115
	v_lshlrev_b32_e32 v230, 16, v168
	v_cvt_pk_bf16_f32 v107, v112, v113
	global_store_dwordx4 v[116:117], v[104:107], off
	v_and_b32_e32 v231, 0xffff0000, v168
	v_lshlrev_b32_e32 v232, 16, v169
	v_mul_f32_e32 v104, v109, v109
	v_mul_f32_e32 v105, v111, v111
	v_fmac_f32_e32 v104, v108, v108
	v_fmac_f32_e32 v105, v110, v110
	v_add_f32_e32 v104, v104, v105
	v_mul_f32_e32 v105, v115, v115
	v_fmac_f32_e32 v105, v114, v114
	v_and_b32_e32 v233, 0xffff0000, v169
	v_add_f32_e32 v104, v105, v104
	v_mul_f32_e32 v105, v113, v113
	v_fmac_f32_e32 v105, v112, v112
	v_pk_add_f32 v[102:103], v[102:103], v[232:233]
	v_pk_add_f32 v[100:101], v[100:101], v[230:231]
	v_pk_add_f32 v[106:107], v[96:97], v[234:235]
	v_cvt_pk_bf16_f32 v96, v100, v101
	v_cvt_pk_bf16_f32 v97, v102, v103
	v_add_f32_e32 v108, v105, v104
	v_pk_add_f32 v[104:105], v[98:99], v[236:237]
	v_cvt_pk_bf16_f32 v98, v106, v107
	v_pk_add_f32 v[94:95], v[94:95], v[240:241]
	v_cvt_pk_bf16_f32 v99, v104, v105
	global_store_dwordx4 v[116:117], v[96:99], off offset:256
	v_pk_add_f32 v[92:93], v[92:93], v[238:239]
	v_pk_add_f32 v[86:87], v[86:87], v[182:183]
	v_mul_f32_e32 v96, v101, v101
	v_mul_f32_e32 v97, v103, v103
	v_fmac_f32_e32 v96, v100, v100
	v_fmac_f32_e32 v97, v102, v102
	v_add_f32_e32 v96, v96, v97
	v_mul_f32_e32 v97, v107, v107
	v_fmac_f32_e32 v97, v106, v106
	v_add_f32_e32 v96, v97, v96
	v_mul_f32_e32 v97, v105, v105
	v_fmac_f32_e32 v97, v104, v104
	v_lshl_add_u64 v[100:101], s[84:85], 0, v[162:163]
	v_add_f32_e32 v96, v97, v96
	v_pk_add_f32 v[98:99], v[88:89], v[242:243]
	v_cvt_pk_bf16_f32 v88, v92, v93
	v_cvt_pk_bf16_f32 v89, v94, v95
	v_lshl_add_u64 v[100:101], v[100:101], 0, v[144:145]
	v_add_f32_e32 v102, v108, v96
	v_pk_add_f32 v[96:97], v[90:91], v[244:245]
	v_cvt_pk_bf16_f32 v90, v98, v99
	v_pk_add_f32 v[84:85], v[84:85], v[174:175]
	v_cvt_pk_bf16_f32 v91, v96, v97
	global_store_dwordx4 v[100:101], v[88:91], off
; __device__ __forceinline__ unsigned cvt_pk_bf16(float lo, float hi) { unsigned r; asm volatile("v_cvt_pk_bf16_f32 %0, %1, %2" : "=v"(r) : "v"(lo), "v"(hi)); return r; }
;     __device__ __forceinline__ void operator()(const f32x4 (&acc)[2][2][4][2], const Unit& u, int wr, int wc, int fr, int fq, const float (&epre)[1]) const {
;     ...
;             for (int m = 0; m < 4; ++m) { const int row = row0 + ai * 128 + m * 16;
;                 float ss = 0.f;
; #pragma unroll
;                 for (int bj = 0; bj < 2; ++bj) { const f32x4 h0 = bv[m][bj][0] + acc[ai][bj][m][0], h1 = bv[m][bj][1] + acc[ai][bj][m][1];
;                     u32x4 w; w.x = cvt_pk_bf16(h0[0], h0[1]); w.y = cvt_pk_bf16(h0[2], h0[3]); w.z = cvt_pk_bf16(h1[0], h1[1]); w.w = cvt_pk_bf16(h1[2], h1[3]);
;                     *(u32x4*)(HBo + (size_t)row * DM + col0 + bj * 128) = w;
;                     ss += (h0[0] * h0[0] + h0[1] * h0[1]) + (h0[2] * h0[2] + h0[3] * h0[3]) + (h1[0] * h1[0] + h1[1] * h1[1]) + (h1[2] * h1[2] + h1[3] * h1[3]); }
;                 ssv[m] = ss;
;             }
; #pragma unroll
;             for (int m = 0; m < 4; ++m) ssv[m] += __shfl_xor(ssv[m], 16);
; #pragma unroll
;             for (int m = 0; m < 4; ++m) ssv[m] += __shfl_xor(ssv[m], 32);
;             if (fq == 0) {
; #pragma unroll
;                 for (int m = 0; m < 4; ++m) atomicAdd(sumsq + row0 + ai * 128 + m * 16, ssv[m]); }
	v_lshlrev_b32_e32 v164, 16, v198
	v_and_b32_e32 v165, 0xffff0000, v198
	v_mul_f32_e32 v88, v93, v93
	v_mul_f32_e32 v89, v95, v95
	v_fmac_f32_e32 v88, v92, v92
	v_fmac_f32_e32 v89, v94, v94
	v_add_f32_e32 v88, v88, v89
	v_mul_f32_e32 v89, v99, v99
	v_fmac_f32_e32 v89, v98, v98
	v_add_f32_e32 v88, v89, v88
	v_mul_f32_e32 v89, v97, v97
	v_fmac_f32_e32 v89, v96, v96
	v_pk_add_f32 v[90:91], v[80:81], v[172:173]
	v_cvt_pk_bf16_f32 v80, v84, v85
	v_cvt_pk_bf16_f32 v81, v86, v87
	v_add_f32_e32 v92, v89, v88
	v_pk_add_f32 v[88:89], v[82:83], v[180:181]
	v_cvt_pk_bf16_f32 v82, v90, v91
	v_lshlrev_b32_e32 v168, 16, v199
	v_cvt_pk_bf16_f32 v83, v88, v89
	global_store_dwordx4 v[100:101], v[80:83], off offset:256
	v_and_b32_e32 v169, 0xffff0000, v199
	v_lshlrev_b32_e32 v156, 16, v200
	v_mul_f32_e32 v80, v85, v85
	v_mul_f32_e32 v81, v87, v87
	v_fmac_f32_e32 v80, v84, v84
	v_fmac_f32_e32 v81, v86, v86
	v_add_f32_e32 v80, v80, v81
	v_mul_f32_e32 v81, v91, v91
	v_fmac_f32_e32 v81, v90, v90
	v_add_f32_e32 v80, v81, v80
	v_mul_f32_e32 v81, v89, v89
	v_fmac_f32_e32 v81, v88, v88
	v_lshl_add_u64 v[84:85], s[84:85], 0, v[152:153]
	v_and_b32_e32 v157, 0xffff0000, v200
	v_lshlrev_b32_e32 v160, 16, v201
	v_and_b32_e32 v161, 0xffff0000, v201
	v_add_f32_e32 v80, v81, v80
	v_pk_add_f32 v[78:79], v[78:79], v[170:171]
	v_pk_add_f32 v[76:77], v[76:77], v[166:167]
	v_pk_add_f32 v[82:83], v[72:73], v[164:165]
	v_cvt_pk_bf16_f32 v72, v76, v77
	v_cvt_pk_bf16_f32 v73, v78, v79
	v_lshl_add_u64 v[84:85], v[84:85], 0, v[144:145]
	v_lshlrev_b32_e32 v158, 16, v203
	v_and_b32_e32 v159, 0xffff0000, v203
	v_add_f32_e32 v86, v92, v80
	v_pk_add_f32 v[80:81], v[74:75], v[168:169]
	v_cvt_pk_bf16_f32 v74, v82, v83
	v_pk_add_f32 v[70:71], v[70:71], v[160:161]
	v_cvt_pk_bf16_f32 v75, v80, v81
	global_store_dwordx4 v[84:85], v[72:75], off
	v_pk_add_f32 v[68:69], v[68:69], v[156:157]
	v_lshlrev_b32_e32 v154, 16, v202
	v_mul_f32_e32 v73, v79, v79
	v_and_b32_e32 v155, 0xffff0000, v202
	v_mul_f32_e32 v72, v77, v77
	v_fmac_f32_e32 v73, v78, v78
	v_pk_add_f32 v[78:79], v[66:67], v[158:159]
	v_mul_f32_e32 v66, v69, v69
	v_mul_f32_e32 v67, v71, v71
	v_fmac_f32_e32 v72, v76, v76
	v_pk_add_f32 v[64:65], v[64:65], v[154:155]
	v_fmac_f32_e32 v66, v68, v68
	v_fmac_f32_e32 v67, v70, v70
	v_add_f32_e32 v72, v72, v73
	v_mul_f32_e32 v73, v83, v83
	v_add_f32_e32 v66, v66, v67
	v_mul_f32_e32 v67, v65, v65
	v_fmac_f32_e32 v73, v82, v82
	v_fmac_f32_e32 v67, v64, v64
	v_add_f32_e32 v72, v73, v72
	v_mul_f32_e32 v73, v81, v81
	v_add_f32_e32 v66, v67, v66
	v_mul_f32_e32 v67, v79, v79
	v_fmac_f32_e32 v73, v80, v80
	v_fmac_f32_e32 v67, v78, v78
	v_add_f32_e32 v72, v73, v72
	v_add_f32_e32 v66, v67, v66
	v_and_b32_e32 v67, 64, v191
	v_cvt_pk_bf16_f32 v74, v68, v69
	v_add_f32_e32 v69, v72, v66
	v_xor_b32_e32 v66, 16, v191
	v_add_u32_e32 v72, 64, v67
	v_cmp_lt_i32_e32 vcc, v66, v72
	v_cvt_pk_bf16_f32 v75, v70, v71
	v_xor_b32_e32 v70, 32, v191
	v_cvt_pk_bf16_f32 v76, v64, v65
	v_lshl_add_u64 v[64:65], v[150:151], 2, s[14:15]
	v_cndmask_b32_e32 v66, v191, v66, vcc
	v_lshlrev_b32_e32 v94, 2, v66
	ds_bpermute_b32 v66, v94, v118
	ds_bpermute_b32 v67, v94, v102
	ds_bpermute_b32 v68, v94, v86
	ds_bpermute_b32 v73, v94, v69
	v_cmp_lt_i32_e32 vcc, v70, v72
	s_waitcnt lgkmcnt(0)
	v_add_f32_e32 v66, v118, v66
	v_add_f32_e32 v67, v102, v67
	v_cndmask_b32_e32 v70, v191, v70, vcc
	v_add_f32_e32 v68, v86, v68
	v_add_f32_e32 v69, v69, v73
	v_lshlrev_b32_e32 v95, 2, v70
	ds_bpermute_b32 v70, v95, v66
	ds_bpermute_b32 v71, v95, v67
	ds_bpermute_b32 v72, v95, v68
	ds_bpermute_b32 v73, v95, v69
	v_cvt_pk_bf16_f32 v77, v78, v79
	global_store_dwordx4 v[84:85], v[74:77], off offset:256
	s_and_saveexec_b64 s[26:27], s[6:7]
	s_cbranch_execz .LBB0_783
	s_waitcnt lgkmcnt(3)
	v_add_f32_e32 v66, v66, v70
	s_waitcnt lgkmcnt(0)
	v_add_f32_e32 v69, v69, v73
	v_add_f32_e32 v68, v68, v72
	v_add_f32_e32 v67, v67, v71
	global_atomic_add_f32 v[64:65], v66, off
	global_atomic_add_f32 v[64:65], v67, off offset:64
	global_atomic_add_f32 v[64:65], v68, off offset:128
	global_atomic_add_f32 v[64:65], v69, off offset:192

; #define PG8_WAIT_V(n) asm volatile("s_waitcnt vmcnt(" #n ")" ::: "memory")
; #define PG8_BAR __builtin_amdgcn_s_barrier()
; template <class Epi, class Sched>
; __device__ __forceinline__ void gemm_phase(PG8_LAS unsigned char* lds, const Gemm g, const Sched& S, const Epi& E) {
;     ...
;     PG8_WAIT_V(0);
;     if (wr == 0) PG8_BAR;
;     PG8_BAR;
; __global__ void __launch_bounds__(512, 2) hymba_fwd(Params p) {
;     ...
;         for (int u = bx; u < 256; u += G) small_gemm<DFF>(lds, g.A, g.Bt, MP + 32 * (u >> 4), (u & 15) * 64, (u & 15) * 64 + 32, E);
.LBB0_787:
	v_and_b32_e32 v0, 7, v176
	v_cmp_eq_u32_e32 vcc, 0, v0
	s_lshl_b32 s0, s2, 1
	s_lshl_b32 s1, s66, 1
	s_movk_i32 s3, 0x100
	v_mov_b32_e32 v33, 0
	s_movk_i32 s4, 0x1600
	s_mov_b32 s5, 0x96f5000
	s_mov_b32 s12, 0x1300000
	s_movk_i32 s13, 0x90
	s_mov_b32 s16, s2
	s_barrier
	s_setprio 0
	s_branch .LBB0_789

; #define PG8_STAGE(bufoff, gbase, voff) do { _Pragma("unroll") for (int _i = 0; _i < 2; ++_i) \
;         __builtin_amdgcn_global_load_lds((const unsigned*)((const char*)(gbase) + (voff)[_i]), (PG8_LAS unsigned*)(lds + (bufoff) + ldsw + _i * 8192), 16, 0, 0); } while (0)
; #define PG8_WAIT_V(n) asm volatile("s_waitcnt vmcnt(" #n ")" ::: "memory")
; #define PG8_BAR __builtin_amdgcn_s_barrier()
; template <class Epi, class Sched>
; __device__ __forceinline__ void gemm_phase(PG8_LAS unsigned char* lds, const Gemm g, const Sched& S, const Epi& E) {
;     ...
;     for (int i = 0; i < 2; ++i) { int R, C; stage_rc(tid * 16 + i * 8192, R, C); const int Rb = Epi::PERM ? ((R & ~31) + perm32(R & 31)) : R;
;         voffA[i] = (unsigned)(R * K + C) * 2u; voffB[i] = (unsigned)(Rb * K + C) * 2u; }
;     const size_t kstep = (size_t)(BK * 2);
;     const size_t hstep = (size_t)HALF * K * 2;
;     const size_t tstep = 2 * hstep;
;     const unsigned ldsw = (unsigned)wid * 1024u;
;     const int aoff = lds_byte(wr * 64 + fr, fq * 8), boff = lds_byte(wc * 32 + fr, fq * 8);
;     ...
;     Unit cur, nxt; int ui = 0;
;     if (!S.next(0, cur)) return;
;     f32x4 acc[2][2][4][2];
; #pragma unroll
;     for (int a = 0; a < 2; ++a)
; #pragma unroll
;         for (int b = 0; b < 2; ++b)
; #pragma unroll
;             for (int m = 0; m < 4; ++m)
; #pragma unroll
;                 for (int n = 0; n < 2; ++n) acc[a][b][m][n] = (f32x4){0.f, 0.f, 0.f, 0.f};
;     bf16x8 At[4][2], B0[2][2], B1[2][2];
;     const char* cA = (const char*)g.A + (size_t)cur.pm * tstep; const char* cB = (const char*)g.Bt + (size_t)cur.pn * tstep;
;     float epre[Epi::NPRE]; E.preload(cur, wr, fr, epre);
;     S.a_ready(cur);
;     PG8_STAGE(PG8_SB(0, 0), cB, voffB); PG8_STAGE(PG8_SA(0, 0), cA, voffA); PG8_STAGE(PG8_SB(0, 1), cB + hstep, voffB); PG8_STAGE(PG8_SA(0, 1), cA + hstep, voffA);
;     if (wr == 1) PG8_BAR;
;     PG8_WAIT_V(4); PG8_BAR;
;     PG8_STAGE(PG8_SB(1, 0), cB + kstep, voffB); PG8_STAGE(PG8_SA(1, 0), cA + kstep, voffA); PG8_STAGE(PG8_SB(1, 1), cB + hstep + kstep, voffB);
;     PG8_WAIT_V(6); PG8_BAR;
.LBB0_853:
	v_bfe_i32 v2, v8, 27, 1
	v_lshlrev_b32_e32 v0, 4, v8
	v_lshrrev_b32_e32 v2, 22, v2
	v_add_u32_e32 v2, v0, v2
	v_and_b32_e32 v2, 0xfffffc00, v2
	v_sub_u32_e32 v2, v0, v2
	v_ashrrev_i32_e32 v1, 31, v8
	v_lshrrev_b32_e32 v3, 4, v2
	v_lshrrev_b32_e32 v1, 26, v1
	v_bitop3_b32 v2, v3, v2, 32 bitop3:0x6c
	v_add_u32_e32 v1, v8, v1
	v_ashrrev_i32_e32 v4, 31, v2
	v_ashrrev_i32_e32 v1, 6, v1
	v_lshrrev_b32_e32 v4, 26, v4
	v_lshlrev_b32_e32 v3, 3, v1
	v_add_u32_e32 v4, v2, v4
	v_and_b32_e32 v3, -16, v3
	v_ashrrev_i32_e32 v5, 6, v4
	v_and_b32_e32 v4, 0xc0, v4
	v_add_u32_e32 v3, v5, v3
	v_sub_u32_e32 v2, v2, v4
	v_mov_b32_e32 v4, 1
	s_ashr_i32 s5, s1, 3
	v_lshlrev_b32_e32 v1, 5, v1
	v_ashrrev_i16_sdwa v2, v4, sext(v2) dst_sel:DWORD dst_unused:UNUSED_PAD src0_sel:DWORD src1_sel:BYTE_0
	v_lshlrev_b32_e32 v6, 1, v3
	v_lshrrev_b32_e32 v7, 2, v3
	v_and_b32_e32 v5, 3, v5
	s_mov_b32 s1, 0x7fffe0
	s_add_u32 s8, s64, 0x1a80000
	v_and_b32_e32 v1, 32, v1
	v_bfe_i32 v2, v2, 0, 16
	v_and_b32_e32 v6, 24, v6
	v_and_b32_e32 v7, 4, v7
	v_and_or_b32 v5, v3, s1, v5
	s_addc_u32 s9, s65, 0
	v_or3_b32 v5, v5, v7, v6
	v_add_lshl_u32 v1, v1, v2, 1
	v_add_u32_e32 v0, 0x2000, v0
	s_add_i32 s4, s4, s5
	v_lshl_add_u32 v40, v3, 9, v1
	v_lshl_add_u32 v42, v5, 9, v1
	v_ashrrev_i32_e32 v1, 31, v0
	s_ashr_i32 s5, s4, 31
	v_lshrrev_b32_e32 v1, 22, v1
	s_lshr_b32 s5, s5, 27
	v_add_u32_e32 v1, v0, v1
	s_add_i32 s5, s4, s5
	v_ashrrev_i32_e32 v1, 10, v1
	s_ashr_i32 s6, s5, 5
	s_andn2_b32 s5, s5, 31
	v_mul_i32_i24_e32 v2, 0x400, v1
	s_sub_i32 s4, s4, s5
	v_sub_u32_e32 v0, v0, v2
	s_bfe_i32 s5, s4, 0x80000
	v_lshrrev_b32_e32 v2, 4, v0
	s_bfe_u32 s5, s5, 0x3000c
	v_bitop3_b32 v0, v2, v0, 32 bitop3:0x6c
	s_add_i32 s5, s4, s5
	v_ashrrev_i32_e32 v3, 31, v0
	s_lshl_b32 s11, s6, 3
	s_bfe_i32 s6, s5, 0x80000
	s_and_b32 s5, s5, 0xf8
	v_lshrrev_b32_e32 v3, 26, v3
	s_sub_i32 s4, s4, s5
	v_lshlrev_b32_e32 v2, 3, v1
	v_add_u32_e32 v3, v0, v3
	s_sext_i32_i16 s6, s6
	s_sext_i32_i8 s4, s4
	s_ashr_i32 s7, s0, 8
	v_and_b32_e32 v2, -16, v2
	v_ashrrev_i32_e32 v5, 6, v3
	s_lshr_b32 s6, s6, 3
	s_add_i32 s38, s11, s4
	v_add_u32_e32 v2, v5, v2
	v_and_b32_e32 v5, 3, v5
	s_ashr_i32 s10, s0, 6
	s_ashr_i32 s39, s38, 31
	s_bfe_i64 s[4:5], s[6:7], 0x100000
	v_and_b32_e32 v3, 0xc0, v3
	v_and_or_b32 v5, v2, s1, v5
	s_lshl_b32 s1, s10, 10
	s_lshl_b64 s[12:13], s[38:39], 17
	s_lshl_b64 s[4:5], s[4:5], 17
	v_sub_u32_e32 v0, v0, v3
	s_add_u32 s42, s8, s4
	v_lshlrev_b32_e32 v1, 5, v1
	v_ashrrev_i16_sdwa v0, v4, sext(v0) dst_sel:DWORD dst_unused:UNUSED_PAD src0_sel:DWORD src1_sel:BYTE_0
	v_lshlrev_b32_e32 v3, 1, v2
	v_lshrrev_b32_e32 v4, 2, v2
	s_addc_u32 s43, s9, s5
	s_add_i32 s4, s1, 0
	v_and_b32_e32 v1, 32, v1
	v_bfe_i32 v0, v0, 0, 16
	v_and_b32_e32 v3, 24, v3
	v_and_b32_e32 v4, 4, v4
	s_add_i32 m0, s4, 0x10000
	v_or3_b32 v3, v5, v4, v3
	v_add_lshl_u32 v0, v1, v0, 1
	global_load_lds_dwordx4 v42, s[42:43]
	s_add_i32 m0, s4, 0x12000
	v_lshl_add_u32 v46, v3, 9, v0
	s_add_u32 s40, s74, s12
	global_load_lds_dwordx4 v46, s[42:43]
	s_addc_u32 s41, s75, s13
	s_mov_b32 m0, s4
	s_add_i32 s5, s4, 0x2000
	v_lshl_add_u32 v44, v2, 9, v0
	global_load_lds_dwordx4 v40, s[40:41]
	s_mov_b32 m0, s5
	s_add_u32 s12, s42, 0x10000
	global_load_lds_dwordx4 v44, s[40:41]
	s_addc_u32 s13, s43, 0
	s_add_i32 m0, s4, 0x14000
	v_mov_b32_e32 v43, 0
	global_load_lds_dwordx4 v42, s[12:13]
	s_add_i32 m0, s4, 0x16000
	v_mov_b32_e32 v47, v43
	global_load_lds_dwordx4 v46, s[12:13]
	s_add_u32 s12, s40, 0x10000
	s_addc_u32 s13, s41, 0
	s_add_i32 s33, s4, 0x4000
	s_mov_b32 m0, s33
	s_add_i32 s39, s4, 0x6000
	global_load_lds_dwordx4 v40, s[12:13]
	s_mov_b32 m0, s39
	v_mov_b32_e32 v41, v43
	global_load_lds_dwordx4 v44, s[12:13]
	v_mov_b32_e32 v45, v43
	v_lshl_add_u64 v[6:7], s[42:43], 0, v[42:43]
	v_lshl_add_u64 v[4:5], s[42:43], 0, v[46:47]
	v_lshl_add_u64 v[2:3], s[40:41], 0, v[40:41]
	s_cmp_lg_u32 s7, 1
	v_lshl_add_u64 v[0:1], s[40:41], 0, v[44:45]
	s_cbranch_scc1 .LBB0_855
	s_barrier
	s_setprio 1

; #define PG8_STAGE(bufoff, gbase, voff) do { _Pragma("unroll") for (int _i = 0; _i < 2; ++_i) \
;         __builtin_amdgcn_global_load_lds((const unsigned*)((const char*)(gbase) + (voff)[_i]), (PG8_LAS unsigned*)(lds + (bufoff) + ldsw + _i * 8192), 16, 0, 0); } while (0)
; #define PG8_LDA(dst, b, h) do { _Pragma("unroll") for (int m = 0; m < 4; ++m) _Pragma("unroll") for (int k = 0; k < 2; ++k) dst[m][k] = *(const PG8_LAS bf16x8*)(lds + PG8_SA(b, h) + aoff + m * 2048 + k * 1024); } while (0)
; #define PG8_LDB(dst, b, h) do { _Pragma("unroll") for (int n = 0; n < 2; ++n) _Pragma("unroll") for (int k = 0; k < 2; ++k) dst[n][k] = *(const PG8_LAS bf16x8*)(lds + PG8_SB(b, h) + boff + n * 2048 + k * 1024); } while (0)
; #define PG8_MMA(ai, bj, At, Bt) do { __builtin_amdgcn_s_setprio(1); _Pragma("unroll") for (int m = 0; m < 4; ++m) _Pragma("unroll") for (int n = 0; n < 2; ++n) _Pragma("unroll") for (int k = 0; k < 2; ++k) \
;         acc[ai][bj][m][n] = __builtin_amdgcn_mfma_f32_16x16x32_bf16(Bt[n][k], At[m][k], acc[ai][bj][m][n], 0, 0, 0); __builtin_amdgcn_s_setprio(0); } while (0)
; #define PG8_BAR __builtin_amdgcn_s_barrier()
; template <class Epi, class Sched>
; __device__ __forceinline__ void gemm_phase(PG8_LAS unsigned char* lds, const Gemm g, const Sched& S, const Epi& E) {
;     ...
;             const char* a2 = last ? nA : cA + (size_t)(t + 2) * kstep; const char* b2 = last ? nB : cB + (size_t)(t + 2) * kstep;
;             const char* a3 = a2 + kstep; const char* b3 = b2 + kstep;
;             if (last && has_next) S.a_ready(nxt);
;             PG8_LDB(B0, 0, 0); PG8_SCHED; PG8_LDA(At, 0, 0); PG8_STAGE(PG8_SA(1, 1), a1 + hstep, voffA);
;             PG8_WAIT_L(8); PG8_BAR; PG8_WAIT_L(0); PG8_MMA(0, 0, At, B0); PG8_BAR; PG8_SCHED;
;             PG8_LDB(B1, 0, 1); PG8_STAGE(PG8_SB(0, 0), b2, voffB);
;             PG8_BAR; PG8_WAIT_L(0); PG8_MMA(0, 1, At, B1); PG8_BAR;
;             PG8_LDA(At, 0, 1); PG8_STAGE(PG8_SA(0, 0), a2, voffA);
;             PG8_BAR; PG8_WAIT_L(0); PG8_MMA(1, 0, At, B0); PG8_BAR; PG8_SCHED;
;             PG8_STAGE(PG8_SB(0, 1), b2 + hstep, voffB);
;             PG8_WAIT_V(6); PG8_BAR; PG8_MMA(1, 1, At, B1); PG8_BAR;
;             PG8_LDB(B0, 1, 0); PG8_SCHED; PG8_LDA(At, 1, 0); PG8_STAGE(PG8_SA(0, 1), a2 + hstep, voffA);
;             PG8_WAIT_L(8); PG8_BAR; PG8_WAIT_L(0); PG8_MMA(0, 0, At, B0); PG8_BAR; PG8_SCHED;
.LBB0_857:
	s_ashr_i32 s31, s30, 31
	s_lshl_b64 s[34:35], s[30:31], 17
	s_add_u32 s34, s74, s34
	v_cmp_lt_i64_e32 vcc, s[26:27], v[48:49]
	s_addc_u32 s35, s75, s35
	ds_read_b128 v[0:3], v57
	ds_read_b128 v[4:7], v57 offset:1024
	ds_read_b128 v[8:11], v57 offset:2048
	ds_read_b128 v[12:15], v57 offset:3072
	s_and_b64 s[36:37], vcc, exec
	s_cselect_b32 s47, s35, s41
	s_cselect_b32 s46, s34, s40
	s_ashr_i32 s29, s28, 31
	s_lshl_b64 s[36:37], s[28:29], 17
	s_add_u32 s36, s8, s36
	s_addc_u32 s37, s9, s37
	s_and_b64 s[44:45], vcc, exec
	s_cselect_b32 s45, s37, s43
	s_cselect_b32 s44, s36, s42
	s_add_u32 s64, s40, 0x10080
	s_addc_u32 s65, s41, 0
	s_mov_b32 m0, s51
	v_lshl_add_u64 v[52:53], s[64:65], 0, v[40:41]
	ds_read_b128 v[16:19], v58
	ds_read_b128 v[20:23], v58 offset:1024
	ds_read_b128 v[24:27], v58 offset:2048
	ds_read_b128 v[28:31], v58 offset:3072
	ds_read_b128 v[32:35], v58 offset:4096
	ds_read_b128 v[36:39], v58 offset:5120
	ds_read_b128 v[60:63], v58 offset:6144
	ds_read_b128 v[64:67], v58 offset:7168
	global_load_lds_dwordx4 v[52:53], off
	v_lshl_add_u64 v[52:53], s[64:65], 0, v[44:45]
	s_mov_b32 m0, s52
	s_nop 0
	global_load_lds_dwordx4 v[52:53], off
	s_waitcnt lgkmcnt(8)
	s_barrier
	s_waitcnt lgkmcnt(0)
	s_waitcnt lgkmcnt(0)
	v_mfma_f32_16x16x32_bf16 v[68:71], v[0:3], v[16:19], 0
	v_mfma_f32_16x16x32_bf16 v[72:75], v[8:11], v[16:19], 0
	v_mfma_f32_16x16x32_bf16 v[76:79], v[0:3], v[24:27], 0
	v_mfma_f32_16x16x32_bf16 v[80:83], v[8:11], v[24:27], 0
	v_mfma_f32_16x16x32_bf16 v[84:87], v[0:3], v[32:35], 0
	v_mfma_f32_16x16x32_bf16 v[88:91], v[8:11], v[32:35], 0
	v_mfma_f32_16x16x32_bf16 v[92:95], v[0:3], v[60:63], 0
	v_mfma_f32_16x16x32_bf16 v[96:99], v[8:11], v[60:63], 0
	v_mfma_f32_16x16x32_bf16 v[68:71], v[4:7], v[20:23], v[68:71]
	v_mfma_f32_16x16x32_bf16 v[72:75], v[12:15], v[20:23], v[72:75]
	v_mfma_f32_16x16x32_bf16 v[76:79], v[4:7], v[28:31], v[76:79]
	v_mfma_f32_16x16x32_bf16 v[80:83], v[12:15], v[28:31], v[80:83]
	v_mfma_f32_16x16x32_bf16 v[84:87], v[4:7], v[36:39], v[84:87]
	v_mfma_f32_16x16x32_bf16 v[88:91], v[12:15], v[36:39], v[88:91]
	v_mfma_f32_16x16x32_bf16 v[92:95], v[4:7], v[64:67], v[92:95]
	v_mfma_f32_16x16x32_bf16 v[96:99], v[12:15], v[64:67], v[96:99]
	s_barrier
	v_lshl_add_u64 v[52:53], s[42:43], 0, v[42:43]
	s_mov_b32 m0, s54
	v_lshl_add_u64 v[116:117], v[52:53], 0, s[12:13]
	v_lshl_add_u64 v[204:205], s[42:43], 0, v[46:47]
	s_add_i32 s3, s54, 0x2000
	ds_read_b128 v[100:103], v59
	ds_read_b128 v[104:107], v59 offset:1024
	ds_read_b128 v[108:111], v59 offset:2048
	ds_read_b128 v[112:115], v59 offset:3072
	global_load_lds_dwordx4 v[116:117], off
	v_lshl_add_u64 v[116:117], v[204:205], 0, s[12:13]
	s_mov_b32 m0, s3
	s_nop 0
	global_load_lds_dwordx4 v[116:117], off
	s_barrier
	s_waitcnt lgkmcnt(0)
	s_waitcnt lgkmcnt(0)
	v_mfma_f32_16x16x32_bf16 v[116:119], v[100:103], v[16:19], 0
	v_mfma_f32_16x16x32_bf16 v[16:19], v[108:111], v[16:19], 0
	v_mfma_f32_16x16x32_bf16 v[116:119], v[104:107], v[20:23], v[116:119]
	v_mfma_f32_16x16x32_bf16 v[16:19], v[112:115], v[20:23], v[16:19]
	v_mfma_f32_16x16x32_bf16 v[20:23], v[100:103], v[24:27], 0
	v_mfma_f32_16x16x32_bf16 v[24:27], v[108:111], v[24:27], 0
	v_mfma_f32_16x16x32_bf16 v[20:23], v[104:107], v[28:31], v[20:23]
	v_mfma_f32_16x16x32_bf16 v[24:27], v[112:115], v[28:31], v[24:27]
	v_mfma_f32_16x16x32_bf16 v[28:31], v[100:103], v[32:35], 0
	v_mfma_f32_16x16x32_bf16 v[32:35], v[108:111], v[32:35], 0
	v_mfma_f32_16x16x32_bf16 v[28:31], v[104:107], v[36:39], v[28:31]
	v_mfma_f32_16x16x32_bf16 v[32:35], v[112:115], v[36:39], v[32:35]
	v_mfma_f32_16x16x32_bf16 v[36:39], v[100:103], v[60:63], 0
	v_mfma_f32_16x16x32_bf16 v[60:63], v[108:111], v[60:63], 0
	v_mfma_f32_16x16x32_bf16 v[36:39], v[104:107], v[64:67], v[36:39]
	v_mfma_f32_16x16x32_bf16 v[60:63], v[112:115], v[64:67], v[60:63]
	v_lshl_add_u64 v[220:221], s[40:41], 0, v[40:41]
	s_mov_b32 m0, s4
	v_lshl_add_u64 v[148:149], v[220:221], 0, s[12:13]
	v_lshl_add_u64 v[222:223], s[40:41], 0, v[44:45]
	s_barrier
	ds_read_b128 v[64:67], v58 offset:16384
	ds_read_b128 v[120:123], v58 offset:17408
	ds_read_b128 v[124:127], v58 offset:18432
	ds_read_b128 v[128:131], v58 offset:19456
	ds_read_b128 v[132:135], v58 offset:20480
	ds_read_b128 v[136:139], v58 offset:21504
	ds_read_b128 v[140:143], v58 offset:22528
	ds_read_b128 v[144:147], v58 offset:23552
	global_load_lds_dwordx4 v[148:149], off
	v_lshl_add_u64 v[148:149], v[222:223], 0, s[12:13]
	s_mov_b32 m0, s5
	s_nop 0
	global_load_lds_dwordx4 v[148:149], off
	s_barrier
	s_waitcnt lgkmcnt(0)
	s_waitcnt lgkmcnt(0)
	v_mfma_f32_16x16x32_bf16 v[148:151], v[0:3], v[64:67], 0
	v_mfma_f32_16x16x32_bf16 v[156:159], v[0:3], v[124:127], 0
	v_mfma_f32_16x16x32_bf16 v[164:167], v[0:3], v[132:135], 0
	v_mfma_f32_16x16x32_bf16 v[0:3], v[0:3], v[140:143], 0
	v_mfma_f32_16x16x32_bf16 v[148:151], v[4:7], v[120:123], v[148:151]
	v_mfma_f32_16x16x32_bf16 v[152:155], v[8:11], v[64:67], 0
	v_mfma_f32_16x16x32_bf16 v[156:159], v[4:7], v[128:131], v[156:159]
	v_mfma_f32_16x16x32_bf16 v[160:163], v[8:11], v[124:127], 0
	v_mfma_f32_16x16x32_bf16 v[164:167], v[4:7], v[136:139], v[164:167]
	v_mfma_f32_16x16x32_bf16 v[168:171], v[8:11], v[132:135], 0
	v_mfma_f32_16x16x32_bf16 v[0:3], v[4:7], v[144:147], v[0:3]
	v_mfma_f32_16x16x32_bf16 v[4:7], v[8:11], v[140:143], 0
	v_mfma_f32_16x16x32_bf16 v[152:155], v[12:15], v[120:123], v[152:155]
	v_mfma_f32_16x16x32_bf16 v[160:163], v[12:15], v[128:131], v[160:163]
	v_mfma_f32_16x16x32_bf16 v[168:171], v[12:15], v[136:139], v[168:171]
	v_mfma_f32_16x16x32_bf16 v[4:7], v[12:15], v[144:147], v[4:7]
	s_barrier
; #define PG8_STAGE(bufoff, gbase, voff) do { _Pragma("unroll") for (int _i = 0; _i < 2; ++_i) \
;         __builtin_amdgcn_global_load_lds((const unsigned*)((const char*)(gbase) + (voff)[_i]), (PG8_LAS unsigned*)(lds + (bufoff) + ldsw + _i * 8192), 16, 0, 0); } while (0)
; #define PG8_LDA(dst, b, h) do { _Pragma("unroll") for (int m = 0; m < 4; ++m) _Pragma("unroll") for (int k = 0; k < 2; ++k) dst[m][k] = *(const PG8_LAS bf16x8*)(lds + PG8_SA(b, h) + aoff + m * 2048 + k * 1024); } while (0)
; #define PG8_LDB(dst, b, h) do { _Pragma("unroll") for (int n = 0; n < 2; ++n) _Pragma("unroll") for (int k = 0; k < 2; ++k) dst[n][k] = *(const PG8_LAS bf16x8*)(lds + PG8_SB(b, h) + boff + n * 2048 + k * 1024); } while (0)
; #define PG8_MMA(ai, bj, At, Bt) do { __builtin_amdgcn_s_setprio(1); _Pragma("unroll") for (int m = 0; m < 4; ++m) _Pragma("unroll") for (int n = 0; n < 2; ++n) _Pragma("unroll") for (int k = 0; k < 2; ++k) \
;         acc[ai][bj][m][n] = __builtin_amdgcn_mfma_f32_16x16x32_bf16(Bt[n][k], At[m][k], acc[ai][bj][m][n], 0, 0, 0); __builtin_amdgcn_s_setprio(0); } while (0)
; #define PG8_WAIT_V(n) asm volatile("s_waitcnt vmcnt(" #n ")" ::: "memory")
; #define PG8_WAIT_L(n) asm volatile("s_waitcnt lgkmcnt(" #n ")" ::: "memory")
; #define PG8_BAR __builtin_amdgcn_s_barrier()
; #define PG8_SCHED __builtin_amdgcn_sched_barrier(0)
; template <class Epi, class Sched>
; __device__ __forceinline__ void gemm_phase(PG8_LAS unsigned char* lds, const Gemm g, const Sched& S, const Epi& E) {
;     ...
;             PG8_STAGE(PG8_SB(0, 1), b2 + hstep, voffB);
;             PG8_WAIT_V(6); PG8_BAR; PG8_MMA(1, 1, At, B1); PG8_BAR;
;             PG8_LDB(B0, 1, 0); PG8_SCHED; PG8_LDA(At, 1, 0); PG8_STAGE(PG8_SA(0, 1), a2 + hstep, voffA);
;             PG8_WAIT_L(8); PG8_BAR; PG8_WAIT_L(0); PG8_MMA(0, 0, At, B0); PG8_BAR; PG8_SCHED;
;             PG8_LDB(B1, 1, 1); PG8_STAGE(PG8_SB(1, 0), b3, voffB);
;             PG8_BAR; PG8_WAIT_L(0); PG8_MMA(0, 1, At, B1); PG8_BAR;
;             PG8_LDA(At, 1, 1); PG8_STAGE(PG8_SA(1, 0), a3, voffA);
;             PG8_BAR; PG8_WAIT_L(0); PG8_MMA(1, 0, At, B0); PG8_BAR; PG8_SCHED;
	s_add_u32 s64, s42, 0x10100
	s_addc_u32 s65, s43, 0
	s_add_i32 s31, s53, s1
	v_lshl_add_u64 v[8:9], s[64:65], 0, v[42:43]
	s_mov_b32 m0, s31
	s_add_i32 s29, s31, 0x2000
	global_load_lds_dwordx4 v[8:9], off
	v_lshl_add_u64 v[8:9], s[64:65], 0, v[46:47]
	s_mov_b32 m0, s29
	s_nop 0
	global_load_lds_dwordx4 v[8:9], off
	s_waitcnt vmcnt(6)
	s_barrier
	v_mfma_f32_16x16x32_bf16 v[8:11], v[100:103], v[64:67], 0
	v_mfma_f32_16x16x32_bf16 v[12:15], v[108:111], v[64:67], 0
	v_mfma_f32_16x16x32_bf16 v[8:11], v[104:107], v[120:123], v[8:11]
	v_mfma_f32_16x16x32_bf16 v[12:15], v[112:115], v[120:123], v[12:15]
	v_mfma_f32_16x16x32_bf16 v[64:67], v[100:103], v[124:127], 0
	v_mfma_f32_16x16x32_bf16 v[120:123], v[108:111], v[124:127], 0
	v_mfma_f32_16x16x32_bf16 v[124:127], v[100:103], v[132:135], 0
	v_mfma_f32_16x16x32_bf16 v[100:103], v[100:103], v[140:143], 0
	v_mfma_f32_16x16x32_bf16 v[64:67], v[104:107], v[128:131], v[64:67]
	v_mfma_f32_16x16x32_bf16 v[120:123], v[112:115], v[128:131], v[120:123]
	v_mfma_f32_16x16x32_bf16 v[124:127], v[104:107], v[136:139], v[124:127]
	v_mfma_f32_16x16x32_bf16 v[128:131], v[108:111], v[132:135], 0
	v_mfma_f32_16x16x32_bf16 v[100:103], v[104:107], v[144:147], v[100:103]
	v_mfma_f32_16x16x32_bf16 v[104:107], v[108:111], v[140:143], 0
	v_mfma_f32_16x16x32_bf16 v[128:131], v[112:115], v[136:139], v[128:131]
	v_mfma_f32_16x16x32_bf16 v[104:107], v[112:115], v[144:147], v[104:107]
	s_add_i32 s56, 0, 0x18000
	v_add_u32_e32 v177, s56, v55
	s_barrier
	ds_read_b128 v[108:111], v177
	ds_read_b128 v[112:115], v177 offset:1024
	ds_read_b128 v[132:135], v177 offset:2048
	ds_read_b128 v[136:139], v177 offset:3072
	s_add_u32 s64, s40, 0x10100
	s_addc_u32 s65, s41, 0
	s_mov_b32 m0, s33
	v_lshl_add_u64 v[200:201], s[64:65], 0, v[40:41]
	ds_read_b128 v[140:143], v58 offset:32768
	ds_read_b128 v[144:147], v58 offset:33792
	ds_read_b128 v[172:175], v58 offset:34816
	ds_read_b128 v[180:183], v58 offset:35840
	ds_read_b128 v[184:187], v58 offset:36864
	ds_read_b128 v[188:191], v58 offset:37888
	ds_read_b128 v[192:195], v58 offset:38912
	ds_read_b128 v[196:199], v58 offset:39936
	global_load_lds_dwordx4 v[200:201], off
	v_lshl_add_u64 v[200:201], s[64:65], 0, v[44:45]
	s_mov_b32 m0, s39
	s_nop 0
	global_load_lds_dwordx4 v[200:201], off
	s_waitcnt lgkmcnt(8)
	s_barrier
	s_waitcnt lgkmcnt(0)
	s_waitcnt lgkmcnt(0)
	v_mfma_f32_16x16x32_bf16 v[68:71], v[108:111], v[140:143], v[68:71]
	v_mfma_f32_16x16x32_bf16 v[72:75], v[132:135], v[140:143], v[72:75]
	v_mfma_f32_16x16x32_bf16 v[76:79], v[108:111], v[172:175], v[76:79]
	v_mfma_f32_16x16x32_bf16 v[80:83], v[132:135], v[172:175], v[80:83]
	v_mfma_f32_16x16x32_bf16 v[84:87], v[108:111], v[184:187], v[84:87]
	v_mfma_f32_16x16x32_bf16 v[88:91], v[132:135], v[184:187], v[88:91]
	v_mfma_f32_16x16x32_bf16 v[92:95], v[108:111], v[192:195], v[92:95]
	v_mfma_f32_16x16x32_bf16 v[96:99], v[132:135], v[192:195], v[96:99]
	v_mfma_f32_16x16x32_bf16 v[68:71], v[112:115], v[144:147], v[68:71]
	v_mfma_f32_16x16x32_bf16 v[72:75], v[136:139], v[144:147], v[72:75]
	v_mfma_f32_16x16x32_bf16 v[76:79], v[112:115], v[180:183], v[76:79]
	v_mfma_f32_16x16x32_bf16 v[80:83], v[136:139], v[180:183], v[80:83]
	v_mfma_f32_16x16x32_bf16 v[84:87], v[112:115], v[188:191], v[84:87]
	v_mfma_f32_16x16x32_bf16 v[88:91], v[136:139], v[188:191], v[88:91]
	v_mfma_f32_16x16x32_bf16 v[92:95], v[112:115], v[196:199], v[92:95]
	v_mfma_f32_16x16x32_bf16 v[96:99], v[136:139], v[196:199], v[96:99]
	s_barrier
	s_add_i32 s57, 0, 0x1c000
	s_add_i32 s65, s56, s1
	v_add_u32_e32 v207, s57, v55
	v_lshl_add_u64 v[52:53], v[52:53], 0, s[16:17]
	s_mov_b32 m0, s65
	s_add_i32 s64, s65, 0x2000
	ds_read_b128 v[200:203], v207
	ds_read_b128 v[208:211], v207 offset:1024
	ds_read_b128 v[212:215], v207 offset:2048
	ds_read_b128 v[216:219], v207 offset:3072
	global_load_lds_dwordx4 v[52:53], off
	v_lshl_add_u64 v[52:53], v[204:205], 0, s[16:17]
	s_mov_b32 m0, s64
	s_nop 0
	global_load_lds_dwordx4 v[52:53], off
	s_barrier
	s_waitcnt lgkmcnt(0)
	s_waitcnt lgkmcnt(0)
	v_mfma_f32_16x16x32_bf16 v[116:119], v[200:203], v[140:143], v[116:119]
	v_mfma_f32_16x16x32_bf16 v[16:19], v[212:215], v[140:143], v[16:19]
	v_mfma_f32_16x16x32_bf16 v[20:23], v[200:203], v[172:175], v[20:23]
	v_mfma_f32_16x16x32_bf16 v[24:27], v[212:215], v[172:175], v[24:27]
	v_mfma_f32_16x16x32_bf16 v[28:31], v[200:203], v[184:187], v[28:31]
	v_mfma_f32_16x16x32_bf16 v[32:35], v[212:215], v[184:187], v[32:35]
	v_mfma_f32_16x16x32_bf16 v[36:39], v[200:203], v[192:195], v[36:39]
	v_mfma_f32_16x16x32_bf16 v[60:63], v[212:215], v[192:195], v[60:63]
	v_mfma_f32_16x16x32_bf16 v[116:119], v[208:211], v[144:147], v[116:119]
	v_mfma_f32_16x16x32_bf16 v[16:19], v[216:219], v[144:147], v[16:19]
	v_mfma_f32_16x16x32_bf16 v[20:23], v[208:211], v[180:183], v[20:23]
	v_mfma_f32_16x16x32_bf16 v[24:27], v[216:219], v[180:183], v[24:27]
	v_mfma_f32_16x16x32_bf16 v[28:31], v[208:211], v[188:191], v[28:31]
	v_mfma_f32_16x16x32_bf16 v[32:35], v[216:219], v[188:191], v[32:35]
	v_mfma_f32_16x16x32_bf16 v[36:39], v[208:211], v[196:199], v[36:39]
	v_mfma_f32_16x16x32_bf16 v[60:63], v[216:219], v[196:199], v[60:63]
	s_mov_b32 m0, s48
	v_lshl_add_u64 v[52:53], v[220:221], 0, s[16:17]
	s_barrier
	ds_read_b128 v[140:143], v58 offset:49152
	ds_read_b128 v[144:147], v58 offset:50176
	ds_read_b128 v[172:175], v58 offset:51200
	ds_read_b128 v[180:183], v58 offset:52224
	ds_read_b128 v[184:187], v58 offset:53248
	ds_read_b128 v[188:191], v58 offset:54272
	ds_read_b128 v[192:195], v58 offset:55296
	ds_read_b128 v[196:199], v58 offset:56320
	global_load_lds_dwordx4 v[52:53], off
	v_lshl_add_u64 v[52:53], v[222:223], 0, s[16:17]
	s_mov_b32 m0, s49
	s_nop 0
	global_load_lds_dwordx4 v[52:53], off
	s_barrier
; #define PG8_STAGE(bufoff, gbase, voff) do { _Pragma("unroll") for (int _i = 0; _i < 2; ++_i) \
;         __builtin_amdgcn_global_load_lds((const unsigned*)((const char*)(gbase) + (voff)[_i]), (PG8_LAS unsigned*)(lds + (bufoff) + ldsw + _i * 8192), 16, 0, 0); } while (0)
; #define PG8_LDA(dst, b, h) do { _Pragma("unroll") for (int m = 0; m < 4; ++m) _Pragma("unroll") for (int k = 0; k < 2; ++k) dst[m][k] = *(const PG8_LAS bf16x8*)(lds + PG8_SA(b, h) + aoff + m * 2048 + k * 1024); } while (0)
; #define PG8_LDB(dst, b, h) do { _Pragma("unroll") for (int n = 0; n < 2; ++n) _Pragma("unroll") for (int k = 0; k < 2; ++k) dst[n][k] = *(const PG8_LAS bf16x8*)(lds + PG8_SB(b, h) + boff + n * 2048 + k * 1024); } while (0)
; #define PG8_MMA(ai, bj, At, Bt) do { __builtin_amdgcn_s_setprio(1); _Pragma("unroll") for (int m = 0; m < 4; ++m) _Pragma("unroll") for (int n = 0; n < 2; ++n) _Pragma("unroll") for (int k = 0; k < 2; ++k) \
;         acc[ai][bj][m][n] = __builtin_amdgcn_mfma_f32_16x16x32_bf16(Bt[n][k], At[m][k], acc[ai][bj][m][n], 0, 0, 0); __builtin_amdgcn_s_setprio(0); } while (0)
; #define PG8_WAIT_V(n) asm volatile("s_waitcnt vmcnt(" #n ")" ::: "memory")
; #define PG8_WAIT_L(n) asm volatile("s_waitcnt lgkmcnt(" #n ")" ::: "memory")
; #define PG8_BAR __builtin_amdgcn_s_barrier()
; #define PG8_SCHED __builtin_amdgcn_sched_barrier(0)
; template <class Epi, class Sched>
; __device__ __forceinline__ void gemm_phase(PG8_LAS unsigned char* lds, const Gemm g, const Sched& S, const Epi& E) {
;     ...
;             PG8_LDB(B0, 0, 0); PG8_SCHED; PG8_LDA(At, 0, 0); PG8_STAGE(PG8_SA(1, 1), a1 + hstep, voffA);
;             PG8_WAIT_L(8); PG8_BAR; PG8_WAIT_L(0); PG8_MMA(0, 0, At, B0); PG8_BAR; PG8_SCHED;
;             PG8_LDB(B1, 0, 1); PG8_STAGE(PG8_SB(0, 0), b2, voffB);
;             PG8_BAR; PG8_WAIT_L(0); PG8_MMA(0, 1, At, B1); PG8_BAR;
;             PG8_LDA(At, 0, 1); PG8_STAGE(PG8_SA(0, 0), a2, voffA);
;             PG8_BAR; PG8_WAIT_L(0); PG8_MMA(1, 0, At, B0); PG8_BAR; PG8_SCHED;
;     ...
;             PG8_STAGE(PG8_SB(1, 1), b3 + hstep, voffB);
;             PG8_WAIT_V(6); PG8_BAR; PG8_MMA(1, 1, At, B1); PG8_BAR;
	s_waitcnt lgkmcnt(0)
	s_waitcnt lgkmcnt(0)
	v_mfma_f32_16x16x32_bf16 v[148:151], v[108:111], v[140:143], v[148:151]
	v_mfma_f32_16x16x32_bf16 v[152:155], v[132:135], v[140:143], v[152:155]
	v_mfma_f32_16x16x32_bf16 v[156:159], v[108:111], v[172:175], v[156:159]
	v_mfma_f32_16x16x32_bf16 v[160:163], v[132:135], v[172:175], v[160:163]
	v_mfma_f32_16x16x32_bf16 v[164:167], v[108:111], v[184:187], v[164:167]
	v_mfma_f32_16x16x32_bf16 v[168:171], v[132:135], v[184:187], v[168:171]
	v_mfma_f32_16x16x32_bf16 v[0:3], v[108:111], v[192:195], v[0:3]
	v_mfma_f32_16x16x32_bf16 v[4:7], v[132:135], v[192:195], v[4:7]
	v_mfma_f32_16x16x32_bf16 v[148:151], v[112:115], v[144:147], v[148:151]
	v_mfma_f32_16x16x32_bf16 v[152:155], v[136:139], v[144:147], v[152:155]
	v_mfma_f32_16x16x32_bf16 v[156:159], v[112:115], v[180:183], v[156:159]
	v_mfma_f32_16x16x32_bf16 v[160:163], v[136:139], v[180:183], v[160:163]
	v_mfma_f32_16x16x32_bf16 v[164:167], v[112:115], v[188:191], v[164:167]
	v_mfma_f32_16x16x32_bf16 v[168:171], v[136:139], v[188:191], v[168:171]
	v_mfma_f32_16x16x32_bf16 v[0:3], v[112:115], v[196:199], v[0:3]
	v_mfma_f32_16x16x32_bf16 v[4:7], v[136:139], v[196:199], v[4:7]
	s_barrier
	s_add_u32 s66, s42, 0x10180
	s_addc_u32 s67, s43, 0
	s_add_i32 s43, s57, s1
	v_lshl_add_u64 v[52:53], s[66:67], 0, v[42:43]
	s_mov_b32 m0, s43
	s_add_i32 s42, s43, 0x2000
	global_load_lds_dwordx4 v[52:53], off
	v_lshl_add_u64 v[52:53], s[66:67], 0, v[46:47]
	s_mov_b32 m0, s42
	s_nop 0
	global_load_lds_dwordx4 v[52:53], off
	s_waitcnt vmcnt(6)
	s_barrier
	v_mfma_f32_16x16x32_bf16 v[8:11], v[200:203], v[140:143], v[8:11]
	v_mfma_f32_16x16x32_bf16 v[12:15], v[212:215], v[140:143], v[12:15]
	v_mfma_f32_16x16x32_bf16 v[64:67], v[200:203], v[172:175], v[64:67]
	v_mfma_f32_16x16x32_bf16 v[108:111], v[212:215], v[172:175], v[120:123]
	v_mfma_f32_16x16x32_bf16 v[112:115], v[200:203], v[184:187], v[124:127]
	v_mfma_f32_16x16x32_bf16 v[120:123], v[212:215], v[184:187], v[128:131]
	v_mfma_f32_16x16x32_bf16 v[100:103], v[200:203], v[192:195], v[100:103]
	v_mfma_f32_16x16x32_bf16 v[104:107], v[212:215], v[192:195], v[104:107]
	v_mfma_f32_16x16x32_bf16 v[8:11], v[208:211], v[144:147], v[8:11]
	v_mfma_f32_16x16x32_bf16 v[12:15], v[216:219], v[144:147], v[12:15]
	v_mfma_f32_16x16x32_bf16 v[64:67], v[208:211], v[180:183], v[64:67]
	v_mfma_f32_16x16x32_bf16 v[108:111], v[216:219], v[180:183], v[108:111]
	v_mfma_f32_16x16x32_bf16 v[112:115], v[208:211], v[188:191], v[112:115]
	v_mfma_f32_16x16x32_bf16 v[120:123], v[216:219], v[188:191], v[120:123]
	v_mfma_f32_16x16x32_bf16 v[100:103], v[208:211], v[196:199], v[100:103]
	v_mfma_f32_16x16x32_bf16 v[104:107], v[216:219], v[196:199], v[104:107]
	s_barrier
	ds_read_b128 v[124:127], v57
	ds_read_b128 v[128:131], v57 offset:1024
	ds_read_b128 v[132:135], v57 offset:2048
	ds_read_b128 v[136:139], v57 offset:3072
	s_add_u32 s40, s40, 0x10180
	s_addc_u32 s41, s41, 0
	s_mov_b32 m0, s51
	v_lshl_add_u64 v[52:53], s[40:41], 0, v[40:41]
	ds_read_b128 v[140:143], v58
	ds_read_b128 v[144:147], v58 offset:1024
	ds_read_b128 v[172:175], v58 offset:2048
	ds_read_b128 v[180:183], v58 offset:3072
	ds_read_b128 v[184:187], v58 offset:4096
	ds_read_b128 v[188:191], v58 offset:5120
	ds_read_b128 v[192:195], v58 offset:6144
	ds_read_b128 v[196:199], v58 offset:7168
	global_load_lds_dwordx4 v[52:53], off
	v_lshl_add_u64 v[52:53], s[40:41], 0, v[44:45]
	s_mov_b32 m0, s52
	s_nop 0
	global_load_lds_dwordx4 v[52:53], off
	s_waitcnt lgkmcnt(8)
	s_barrier
	s_waitcnt lgkmcnt(0)
	s_waitcnt lgkmcnt(0)
	v_mfma_f32_16x16x32_bf16 v[68:71], v[124:127], v[140:143], v[68:71]
	v_mfma_f32_16x16x32_bf16 v[72:75], v[132:135], v[140:143], v[72:75]
	v_mfma_f32_16x16x32_bf16 v[76:79], v[124:127], v[172:175], v[76:79]
	v_mfma_f32_16x16x32_bf16 v[80:83], v[132:135], v[172:175], v[80:83]
	v_mfma_f32_16x16x32_bf16 v[84:87], v[124:127], v[184:187], v[84:87]
	v_mfma_f32_16x16x32_bf16 v[88:91], v[132:135], v[184:187], v[88:91]
	v_mfma_f32_16x16x32_bf16 v[92:95], v[124:127], v[192:195], v[92:95]
	v_mfma_f32_16x16x32_bf16 v[96:99], v[132:135], v[192:195], v[96:99]
	v_mfma_f32_16x16x32_bf16 v[68:71], v[128:131], v[144:147], v[68:71]
	v_mfma_f32_16x16x32_bf16 v[72:75], v[136:139], v[144:147], v[72:75]
	v_mfma_f32_16x16x32_bf16 v[76:79], v[128:131], v[180:183], v[76:79]
	v_mfma_f32_16x16x32_bf16 v[80:83], v[136:139], v[180:183], v[80:83]
	v_mfma_f32_16x16x32_bf16 v[84:87], v[128:131], v[188:191], v[84:87]
	v_mfma_f32_16x16x32_bf16 v[88:91], v[136:139], v[188:191], v[88:91]
	v_mfma_f32_16x16x32_bf16 v[92:95], v[128:131], v[196:199], v[92:95]
	v_mfma_f32_16x16x32_bf16 v[96:99], v[136:139], v[196:199], v[96:99]
	s_barrier
	s_mov_b32 m0, s54
	v_lshl_add_u64 v[52:53], s[44:45], 0, v[42:43]
	ds_read_b128 v[200:203], v59
	ds_read_b128 v[208:211], v59 offset:1024
	ds_read_b128 v[212:215], v59 offset:2048
	ds_read_b128 v[216:219], v59 offset:3072
	global_load_lds_dwordx4 v[52:53], off
	v_lshl_add_u64 v[204:205], s[44:45], 0, v[46:47]
	s_mov_b32 m0, s3
	s_nop 0
	global_load_lds_dwordx4 v[204:205], off
	s_barrier
; #define PG8_STAGE(bufoff, gbase, voff) do { _Pragma("unroll") for (int _i = 0; _i < 2; ++_i) \
;         __builtin_amdgcn_global_load_lds((const unsigned*)((const char*)(gbase) + (voff)[_i]), (PG8_LAS unsigned*)(lds + (bufoff) + ldsw + _i * 8192), 16, 0, 0); } while (0)
; #define PG8_LDA(dst, b, h) do { _Pragma("unroll") for (int m = 0; m < 4; ++m) _Pragma("unroll") for (int k = 0; k < 2; ++k) dst[m][k] = *(const PG8_LAS bf16x8*)(lds + PG8_SA(b, h) + aoff + m * 2048 + k * 1024); } while (0)
; #define PG8_LDB(dst, b, h) do { _Pragma("unroll") for (int n = 0; n < 2; ++n) _Pragma("unroll") for (int k = 0; k < 2; ++k) dst[n][k] = *(const PG8_LAS bf16x8*)(lds + PG8_SB(b, h) + boff + n * 2048 + k * 1024); } while (0)
; #define PG8_MMA(ai, bj, At, Bt) do { __builtin_amdgcn_s_setprio(1); _Pragma("unroll") for (int m = 0; m < 4; ++m) _Pragma("unroll") for (int n = 0; n < 2; ++n) _Pragma("unroll") for (int k = 0; k < 2; ++k) \
;         acc[ai][bj][m][n] = __builtin_amdgcn_mfma_f32_16x16x32_bf16(Bt[n][k], At[m][k], acc[ai][bj][m][n], 0, 0, 0); __builtin_amdgcn_s_setprio(0); } while (0)
; #define PG8_WAIT_V(n) asm volatile("s_waitcnt vmcnt(" #n ")" ::: "memory")
; #define PG8_WAIT_L(n) asm volatile("s_waitcnt lgkmcnt(" #n ")" ::: "memory")
; #define PG8_BAR __builtin_amdgcn_s_barrier()
; #define PG8_SCHED __builtin_amdgcn_sched_barrier(0)
; template <class Epi, class Sched>
; __device__ __forceinline__ void gemm_phase(PG8_LAS unsigned char* lds, const Gemm g, const Sched& S, const Epi& E) {
;     ...
;             PG8_BAR; PG8_WAIT_L(0); PG8_MMA(1, 0, At, B0); PG8_BAR; PG8_SCHED;
;             PG8_STAGE(PG8_SB(0, 1), b2 + hstep, voffB);
;             PG8_WAIT_V(6); PG8_BAR; PG8_MMA(1, 1, At, B1); PG8_BAR;
;             PG8_LDB(B0, 1, 0); PG8_SCHED; PG8_LDA(At, 1, 0); PG8_STAGE(PG8_SA(0, 1), a2 + hstep, voffA);
;             PG8_WAIT_L(8); PG8_BAR; PG8_WAIT_L(0); PG8_MMA(0, 0, At, B0); PG8_BAR; PG8_SCHED;
	s_waitcnt lgkmcnt(0)
	s_waitcnt lgkmcnt(0)
	v_mfma_f32_16x16x32_bf16 v[116:119], v[200:203], v[140:143], v[116:119]
	v_mfma_f32_16x16x32_bf16 v[16:19], v[212:215], v[140:143], v[16:19]
	v_mfma_f32_16x16x32_bf16 v[20:23], v[200:203], v[172:175], v[20:23]
	v_mfma_f32_16x16x32_bf16 v[24:27], v[212:215], v[172:175], v[24:27]
	v_mfma_f32_16x16x32_bf16 v[28:31], v[200:203], v[184:187], v[28:31]
	v_mfma_f32_16x16x32_bf16 v[32:35], v[212:215], v[184:187], v[32:35]
	v_mfma_f32_16x16x32_bf16 v[36:39], v[200:203], v[192:195], v[36:39]
	v_mfma_f32_16x16x32_bf16 v[60:63], v[212:215], v[192:195], v[60:63]
	v_mfma_f32_16x16x32_bf16 v[116:119], v[208:211], v[144:147], v[116:119]
	v_mfma_f32_16x16x32_bf16 v[16:19], v[216:219], v[144:147], v[16:19]
	v_mfma_f32_16x16x32_bf16 v[20:23], v[208:211], v[180:183], v[20:23]
	v_mfma_f32_16x16x32_bf16 v[24:27], v[216:219], v[180:183], v[24:27]
	v_mfma_f32_16x16x32_bf16 v[28:31], v[208:211], v[188:191], v[28:31]
	v_mfma_f32_16x16x32_bf16 v[32:35], v[216:219], v[188:191], v[32:35]
	v_mfma_f32_16x16x32_bf16 v[36:39], v[208:211], v[196:199], v[36:39]
	v_mfma_f32_16x16x32_bf16 v[60:63], v[216:219], v[196:199], v[60:63]
	s_mov_b32 m0, s4
	v_lshl_add_u64 v[236:237], s[46:47], 0, v[40:41]
	s_barrier
	ds_read_b128 v[140:143], v58 offset:16384
	ds_read_b128 v[144:147], v58 offset:17408
	ds_read_b128 v[172:175], v58 offset:18432
	ds_read_b128 v[180:183], v58 offset:19456
	ds_read_b128 v[184:187], v58 offset:20480
	ds_read_b128 v[188:191], v58 offset:21504
	ds_read_b128 v[192:195], v58 offset:22528
	ds_read_b128 v[196:199], v58 offset:23552
	global_load_lds_dwordx4 v[236:237], off
	v_lshl_add_u64 v[238:239], s[46:47], 0, v[44:45]
	s_mov_b32 m0, s5
	s_nop 0
	global_load_lds_dwordx4 v[238:239], off
	s_barrier
	s_waitcnt lgkmcnt(0)
	s_waitcnt lgkmcnt(0)
	v_mfma_f32_16x16x32_bf16 v[148:151], v[124:127], v[140:143], v[148:151]
	v_mfma_f32_16x16x32_bf16 v[152:155], v[132:135], v[140:143], v[152:155]
	v_mfma_f32_16x16x32_bf16 v[156:159], v[124:127], v[172:175], v[156:159]
	v_mfma_f32_16x16x32_bf16 v[160:163], v[132:135], v[172:175], v[160:163]
	v_mfma_f32_16x16x32_bf16 v[164:167], v[124:127], v[184:187], v[164:167]
	v_mfma_f32_16x16x32_bf16 v[168:171], v[132:135], v[184:187], v[168:171]
	v_mfma_f32_16x16x32_bf16 v[0:3], v[124:127], v[192:195], v[0:3]
	v_mfma_f32_16x16x32_bf16 v[4:7], v[132:135], v[192:195], v[4:7]
	v_mfma_f32_16x16x32_bf16 v[148:151], v[128:131], v[144:147], v[148:151]
	v_mfma_f32_16x16x32_bf16 v[152:155], v[136:139], v[144:147], v[152:155]
	v_mfma_f32_16x16x32_bf16 v[156:159], v[128:131], v[180:183], v[156:159]
	v_mfma_f32_16x16x32_bf16 v[160:163], v[136:139], v[180:183], v[160:163]
	v_mfma_f32_16x16x32_bf16 v[164:167], v[128:131], v[188:191], v[164:167]
	v_mfma_f32_16x16x32_bf16 v[168:171], v[136:139], v[188:191], v[168:171]
	v_mfma_f32_16x16x32_bf16 v[0:3], v[128:131], v[196:199], v[0:3]
	v_mfma_f32_16x16x32_bf16 v[124:127], v[136:139], v[196:199], v[4:7]
	s_barrier
	s_add_u32 s40, s44, 0x10000
	s_addc_u32 s41, s45, 0
	s_mov_b32 m0, s31
	v_lshl_add_u64 v[4:5], s[40:41], 0, v[42:43]
	global_load_lds_dwordx4 v[4:5], off
	v_lshl_add_u64 v[4:5], s[40:41], 0, v[46:47]
	s_mov_b32 m0, s29
	s_nop 0
	global_load_lds_dwordx4 v[4:5], off
	s_waitcnt vmcnt(6)
	s_barrier
	v_mfma_f32_16x16x32_bf16 v[4:7], v[200:203], v[140:143], v[8:11]
	v_mfma_f32_16x16x32_bf16 v[8:11], v[208:211], v[144:147], v[4:7]
	v_mfma_f32_16x16x32_bf16 v[4:7], v[212:215], v[140:143], v[12:15]
	v_mfma_f32_16x16x32_bf16 v[12:15], v[216:219], v[144:147], v[4:7]
	v_mfma_f32_16x16x32_bf16 v[4:7], v[200:203], v[172:175], v[64:67]
	v_mfma_f32_16x16x32_bf16 v[64:67], v[208:211], v[180:183], v[4:7]
	v_mfma_f32_16x16x32_bf16 v[4:7], v[212:215], v[172:175], v[108:111]
	v_mfma_f32_16x16x32_bf16 v[108:111], v[216:219], v[180:183], v[4:7]
	v_mfma_f32_16x16x32_bf16 v[4:7], v[200:203], v[184:187], v[112:115]
	v_mfma_f32_16x16x32_bf16 v[112:115], v[208:211], v[188:191], v[4:7]
	v_mfma_f32_16x16x32_bf16 v[4:7], v[212:215], v[184:187], v[120:123]
	v_mfma_f32_16x16x32_bf16 v[120:123], v[216:219], v[188:191], v[4:7]
	v_mfma_f32_16x16x32_bf16 v[4:7], v[200:203], v[192:195], v[100:103]
	v_mfma_f32_16x16x32_bf16 v[100:103], v[208:211], v[196:199], v[4:7]
	v_mfma_f32_16x16x32_bf16 v[4:7], v[212:215], v[192:195], v[104:107]
	v_mfma_f32_16x16x32_bf16 v[104:107], v[216:219], v[196:199], v[4:7]
	s_barrier
	s_nop 4
	ds_read_b128 v[4:7], v177
	ds_read_b128 v[128:131], v177 offset:1024
	ds_read_b128 v[132:135], v177 offset:2048
	ds_read_b128 v[136:139], v177 offset:3072
	s_add_u32 s40, s46, 0x10000
	s_addc_u32 s41, s47, 0
	s_mov_b32 m0, s33
	v_lshl_add_u64 v[200:201], s[40:41], 0, v[40:41]
	ds_read_b128 v[140:143], v58 offset:32768
	ds_read_b128 v[144:147], v58 offset:33792
	ds_read_b128 v[172:175], v58 offset:34816
	ds_read_b128 v[180:183], v58 offset:35840
	ds_read_b128 v[184:187], v58 offset:36864
	ds_read_b128 v[188:191], v58 offset:37888
	ds_read_b128 v[192:195], v58 offset:38912
	ds_read_b128 v[196:199], v58 offset:39936
	global_load_lds_dwordx4 v[200:201], off
	v_lshl_add_u64 v[200:201], s[40:41], 0, v[44:45]
	s_mov_b32 m0, s39
	s_nop 0
	global_load_lds_dwordx4 v[200:201], off
	s_waitcnt lgkmcnt(8)
	s_barrier
; #define PG8_STAGE(bufoff, gbase, voff) do { _Pragma("unroll") for (int _i = 0; _i < 2; ++_i) \
;         __builtin_amdgcn_global_load_lds((const unsigned*)((const char*)(gbase) + (voff)[_i]), (PG8_LAS unsigned*)(lds + (bufoff) + ldsw + _i * 8192), 16, 0, 0); } while (0)
; #define PG8_LDA(dst, b, h) do { _Pragma("unroll") for (int m = 0; m < 4; ++m) _Pragma("unroll") for (int k = 0; k < 2; ++k) dst[m][k] = *(const PG8_LAS bf16x8*)(lds + PG8_SA(b, h) + aoff + m * 2048 + k * 1024); } while (0)
; #define PG8_LDB(dst, b, h) do { _Pragma("unroll") for (int n = 0; n < 2; ++n) _Pragma("unroll") for (int k = 0; k < 2; ++k) dst[n][k] = *(const PG8_LAS bf16x8*)(lds + PG8_SB(b, h) + boff + n * 2048 + k * 1024); } while (0)
; #define PG8_MMA(ai, bj, At, Bt) do { __builtin_amdgcn_s_setprio(1); _Pragma("unroll") for (int m = 0; m < 4; ++m) _Pragma("unroll") for (int n = 0; n < 2; ++n) _Pragma("unroll") for (int k = 0; k < 2; ++k) \
;         acc[ai][bj][m][n] = __builtin_amdgcn_mfma_f32_16x16x32_bf16(Bt[n][k], At[m][k], acc[ai][bj][m][n], 0, 0, 0); __builtin_amdgcn_s_setprio(0); } while (0)
; #define PG8_WAIT_V(n) asm volatile("s_waitcnt vmcnt(" #n ")" ::: "memory")
; #define PG8_WAIT_L(n) asm volatile("s_waitcnt lgkmcnt(" #n ")" ::: "memory")
; #define PG8_BAR __builtin_amdgcn_s_barrier()
; #define PG8_SCHED __builtin_amdgcn_sched_barrier(0)
; template <class Epi, class Sched>
; __device__ __forceinline__ void gemm_phase(PG8_LAS unsigned char* lds, const Gemm g, const Sched& S, const Epi& E) {
;     ...
;             PG8_WAIT_L(8); PG8_BAR; PG8_WAIT_L(0); PG8_MMA(0, 0, At, B0); PG8_BAR; PG8_SCHED;
;             PG8_LDB(B1, 1, 1); PG8_STAGE(PG8_SB(1, 0), b3, voffB);
;             PG8_BAR; PG8_WAIT_L(0); PG8_MMA(0, 1, At, B1); PG8_BAR;
;             PG8_LDA(At, 1, 1); PG8_STAGE(PG8_SA(1, 0), a3, voffA);
;             PG8_BAR; PG8_WAIT_L(0); PG8_MMA(1, 0, At, B0); PG8_BAR; PG8_SCHED;
;             PG8_STAGE(PG8_SB(1, 1), b3 + hstep, voffB);
;             PG8_WAIT_V(6); PG8_BAR; PG8_MMA(1, 1, At, B1); PG8_BAR;
	s_waitcnt lgkmcnt(0)
	s_waitcnt lgkmcnt(0)
	v_mfma_f32_16x16x32_bf16 v[68:71], v[4:7], v[140:143], v[68:71]
	v_mfma_f32_16x16x32_bf16 v[72:75], v[132:135], v[140:143], v[72:75]
	v_mfma_f32_16x16x32_bf16 v[76:79], v[4:7], v[172:175], v[76:79]
	v_mfma_f32_16x16x32_bf16 v[80:83], v[132:135], v[172:175], v[80:83]
	v_mfma_f32_16x16x32_bf16 v[84:87], v[4:7], v[184:187], v[84:87]
	v_mfma_f32_16x16x32_bf16 v[88:91], v[132:135], v[184:187], v[88:91]
	v_mfma_f32_16x16x32_bf16 v[92:95], v[4:7], v[192:195], v[92:95]
	v_mfma_f32_16x16x32_bf16 v[96:99], v[132:135], v[192:195], v[96:99]
	v_mfma_f32_16x16x32_bf16 v[68:71], v[128:131], v[144:147], v[68:71]
	v_mfma_f32_16x16x32_bf16 v[72:75], v[136:139], v[144:147], v[72:75]
	v_mfma_f32_16x16x32_bf16 v[76:79], v[128:131], v[180:183], v[76:79]
	v_mfma_f32_16x16x32_bf16 v[80:83], v[136:139], v[180:183], v[80:83]
	v_mfma_f32_16x16x32_bf16 v[84:87], v[128:131], v[188:191], v[84:87]
	v_mfma_f32_16x16x32_bf16 v[88:91], v[136:139], v[188:191], v[88:91]
	v_mfma_f32_16x16x32_bf16 v[92:95], v[128:131], v[196:199], v[92:95]
	v_mfma_f32_16x16x32_bf16 v[96:99], v[136:139], v[196:199], v[96:99]
	s_barrier
	s_mov_b32 m0, s65
	v_lshl_add_u64 v[52:53], v[52:53], 0, s[10:11]
	ds_read_b128 v[200:203], v207
	ds_read_b128 v[208:211], v207 offset:1024
	ds_read_b128 v[212:215], v207 offset:2048
	ds_read_b128 v[216:219], v207 offset:3072
	global_load_lds_dwordx4 v[52:53], off
	v_lshl_add_u64 v[52:53], v[204:205], 0, s[10:11]
	s_mov_b32 m0, s64
	s_nop 0
	global_load_lds_dwordx4 v[52:53], off
	s_barrier
	s_waitcnt lgkmcnt(0)
	s_waitcnt lgkmcnt(0)
	v_mfma_f32_16x16x32_bf16 v[16:19], v[212:215], v[140:143], v[16:19]
	v_mfma_f32_16x16x32_bf16 v[116:119], v[200:203], v[140:143], v[116:119]
	v_mfma_f32_16x16x32_bf16 v[140:143], v[216:219], v[144:147], v[16:19]
	v_mfma_f32_16x16x32_bf16 v[16:19], v[200:203], v[172:175], v[20:23]
	v_mfma_f32_16x16x32_bf16 v[116:119], v[208:211], v[144:147], v[116:119]
	v_mfma_f32_16x16x32_bf16 v[144:147], v[208:211], v[180:183], v[16:19]
	v_mfma_f32_16x16x32_bf16 v[16:19], v[212:215], v[172:175], v[24:27]
	v_mfma_f32_16x16x32_bf16 v[172:175], v[216:219], v[180:183], v[16:19]
	v_mfma_f32_16x16x32_bf16 v[16:19], v[200:203], v[184:187], v[28:31]
	v_mfma_f32_16x16x32_bf16 v[180:183], v[208:211], v[188:191], v[16:19]
	v_mfma_f32_16x16x32_bf16 v[16:19], v[212:215], v[184:187], v[32:35]
	v_mfma_f32_16x16x32_bf16 v[184:187], v[216:219], v[188:191], v[16:19]
	v_mfma_f32_16x16x32_bf16 v[16:19], v[200:203], v[192:195], v[36:39]
	v_mfma_f32_16x16x32_bf16 v[188:191], v[208:211], v[196:199], v[16:19]
	v_mfma_f32_16x16x32_bf16 v[16:19], v[212:215], v[192:195], v[60:63]
	v_mfma_f32_16x16x32_bf16 v[60:63], v[216:219], v[196:199], v[16:19]
	s_mov_b32 m0, s48
	s_nop 4
	v_lshl_add_u64 v[16:17], v[236:237], 0, s[10:11]
	s_barrier
	ds_read_b128 v[24:27], v58 offset:49152
	ds_read_b128 v[28:31], v58 offset:50176
	ds_read_b128 v[192:195], v58 offset:51200
	ds_read_b128 v[196:199], v58 offset:52224
	ds_read_b128 v[220:223], v58 offset:53248
	ds_read_b128 v[224:227], v58 offset:54272
	ds_read_b128 v[228:231], v58 offset:55296
	ds_read_b128 v[232:235], v58 offset:56320
	global_load_lds_dwordx4 v[16:17], off
	v_lshl_add_u64 v[16:17], v[238:239], 0, s[10:11]
	s_mov_b32 m0, s49
	s_nop 0
	global_load_lds_dwordx4 v[16:17], off
	s_barrier
	s_waitcnt lgkmcnt(0)
	s_waitcnt lgkmcnt(0)
	v_mfma_f32_16x16x32_bf16 v[16:19], v[4:7], v[24:27], v[148:151]
	v_mfma_f32_16x16x32_bf16 v[148:151], v[128:131], v[28:31], v[16:19]
	v_mfma_f32_16x16x32_bf16 v[16:19], v[132:135], v[24:27], v[152:155]
	v_mfma_f32_16x16x32_bf16 v[152:155], v[136:139], v[28:31], v[16:19]
	v_mfma_f32_16x16x32_bf16 v[16:19], v[4:7], v[192:195], v[156:159]
	v_mfma_f32_16x16x32_bf16 v[36:39], v[128:131], v[196:199], v[16:19]
	v_mfma_f32_16x16x32_bf16 v[16:19], v[132:135], v[192:195], v[160:163]
	v_mfma_f32_16x16x32_bf16 v[32:35], v[136:139], v[196:199], v[16:19]
	v_mfma_f32_16x16x32_bf16 v[16:19], v[4:7], v[220:223], v[164:167]
	v_mfma_f32_16x16x32_bf16 v[0:3], v[4:7], v[228:231], v[0:3]
	v_mfma_f32_16x16x32_bf16 v[20:23], v[128:131], v[224:227], v[16:19]
	v_mfma_f32_16x16x32_bf16 v[16:19], v[132:135], v[220:223], v[168:171]
	v_mfma_f32_16x16x32_bf16 v[4:7], v[128:131], v[232:235], v[0:3]
	v_mfma_f32_16x16x32_bf16 v[0:3], v[132:135], v[228:231], v[124:127]
	v_mfma_f32_16x16x32_bf16 v[16:19], v[136:139], v[224:227], v[16:19]
	v_mfma_f32_16x16x32_bf16 v[0:3], v[136:139], v[232:235], v[0:3]
	s_barrier
	s_add_u32 s40, s44, 0x10080
	s_addc_u32 s41, s45, 0
	s_mov_b32 m0, s43
	v_lshl_add_u64 v[52:53], s[40:41], 0, v[42:43]
	global_load_lds_dwordx4 v[52:53], off
	v_lshl_add_u64 v[52:53], s[40:41], 0, v[46:47]
	s_mov_b32 m0, s42
	s_nop 0
	global_load_lds_dwordx4 v[52:53], off
	s_waitcnt vmcnt(6)
	s_barrier
; __device__ __forceinline__ unsigned cvt_pk_bf16(float lo, float hi) { unsigned r; asm volatile("v_cvt_pk_bf16_f32 %0, %1, %2" : "=v"(r) : "v"(lo), "v"(hi)); return r; }
; #define PG8_MMA(ai, bj, At, Bt) do { __builtin_amdgcn_s_setprio(1); _Pragma("unroll") for (int m = 0; m < 4; ++m) _Pragma("unroll") for (int n = 0; n < 2; ++n) _Pragma("unroll") for (int k = 0; k < 2; ++k) \
;         acc[ai][bj][m][n] = __builtin_amdgcn_mfma_f32_16x16x32_bf16(Bt[n][k], At[m][k], acc[ai][bj][m][n], 0, 0, 0); __builtin_amdgcn_s_setprio(0); } while (0)
; #define PG8_WAIT_V(n) asm volatile("s_waitcnt vmcnt(" #n ")" ::: "memory")
; #define PG8_BAR __builtin_amdgcn_s_barrier()
; template <class Epi, class Sched>
; __device__ __forceinline__ void gemm_phase(PG8_LAS unsigned char* lds, const Gemm g, const Sched& S, const Epi& E) {
;     ...
;             PG8_WAIT_V(6); PG8_BAR; PG8_MMA(1, 1, At, B1); PG8_BAR;
;         }
;         E(acc, cur, wr, wc, fr, fq, epre); S.done(cur);
;     __device__ __forceinline__ void operator()(const f32x4 (&acc)[2][2][4][2], const Unit& u, int wr, int wc, int fr, int fq, const float (&epre)[1]) const {
;         const int row0 = u.pm * 256 + wr * 64 + fr, col0 = u.pn * 256 + wc * 32 + 8 * fq;
; #pragma unroll
;         for (int ai = 0; ai < 2; ++ai)
; #pragma unroll
;             for (int m = 0; m < 4; ++m)
; #pragma unroll
;                 for (int bj = 0; bj < 2; ++bj) { const f32x4 v0 = acc[ai][bj][m][0], v1 = acc[ai][bj][m][1];
;                     u32x4 w; w.x = cvt_pk_bf16(v0[0], v0[1]); w.y = cvt_pk_bf16(v0[2], v0[3]); w.z = cvt_pk_bf16(v1[0], v1[1]); w.w = cvt_pk_bf16(v1[2], v1[3]);
;                     *(u32x4*)(O + (size_t)(row0 + ai * 128 + m * 16) * DM + col0 + bj * 128) = w; }
;     }
	v_mfma_f32_16x16x32_bf16 v[8:11], v[200:203], v[24:27], v[8:11]
	v_mfma_f32_16x16x32_bf16 v[124:127], v[208:211], v[28:31], v[8:11]
	v_mfma_f32_16x16x32_bf16 v[8:11], v[212:215], v[24:27], v[12:15]
	v_mfma_f32_16x16x32_bf16 v[128:131], v[216:219], v[28:31], v[8:11]
	v_mfma_f32_16x16x32_bf16 v[8:11], v[200:203], v[192:195], v[64:67]
	v_mfma_f32_16x16x32_bf16 v[64:67], v[208:211], v[196:199], v[8:11]
	v_mfma_f32_16x16x32_bf16 v[8:11], v[212:215], v[192:195], v[108:111]
	v_mfma_f32_16x16x32_bf16 v[108:111], v[216:219], v[196:199], v[8:11]
	v_mfma_f32_16x16x32_bf16 v[8:11], v[200:203], v[220:223], v[112:115]
	v_mfma_f32_16x16x32_bf16 v[28:31], v[208:211], v[224:227], v[8:11]
	v_mfma_f32_16x16x32_bf16 v[8:11], v[212:215], v[220:223], v[120:123]
	v_mfma_f32_16x16x32_bf16 v[24:27], v[216:219], v[224:227], v[8:11]
	v_mfma_f32_16x16x32_bf16 v[8:11], v[200:203], v[228:231], v[100:103]
	v_mfma_f32_16x16x32_bf16 v[12:15], v[208:211], v[232:235], v[8:11]
	v_mfma_f32_16x16x32_bf16 v[8:11], v[212:215], v[228:231], v[104:107]
	v_mfma_f32_16x16x32_bf16 v[8:11], v[216:219], v[232:235], v[8:11]
	v_lshl_add_u32 v100, s38, 8, v54
	v_lshl_or_b32 v52, s63, 8, v56
	v_ashrrev_i32_e32 v101, 31, v100
	v_ashrrev_i32_e32 v53, 31, v52
	v_lshlrev_b64 v[102:103], 11, v[100:101]
	s_barrier
	v_cvt_pk_bf16_f32 v68, v68, v69
	v_cvt_pk_bf16_f32 v69, v70, v71
	v_cvt_pk_bf16_f32 v70, v72, v73
	v_cvt_pk_bf16_f32 v71, v74, v75
	v_lshl_add_u64 v[72:73], s[82:83], 0, v[102:103]
	v_lshlrev_b64 v[74:75], 1, v[52:53]
	v_lshl_add_u64 v[52:53], v[72:73], 0, v[74:75]
	global_store_dwordx4 v[52:53], v[68:71], off
	v_readlane_b32 s64, v247, 38
	v_readlane_b32 s66, v247, 40
	v_cvt_pk_bf16_f32 v68, v116, v117
	v_cvt_pk_bf16_f32 v69, v118, v119
	v_cvt_pk_bf16_f32 v70, v140, v141
	v_cvt_pk_bf16_f32 v71, v142, v143
	global_store_dwordx4 v[52:53], v[68:71], off offset:256
	v_readlane_b32 s65, v247, 39
	v_readlane_b32 s67, v247, 41
	v_or_b32_e32 v68, 16, v100
	v_ashrrev_i32_e32 v69, 31, v68
	v_lshlrev_b64 v[72:73], 11, v[68:69]
	v_lshl_add_u64 v[72:73], s[82:83], 0, v[72:73]
	v_cvt_pk_bf16_f32 v68, v76, v77
	v_lshl_add_u64 v[72:73], v[72:73], 0, v[74:75]
	v_cvt_pk_bf16_f32 v69, v78, v79
	v_cvt_pk_bf16_f32 v70, v80, v81
	v_cvt_pk_bf16_f32 v71, v82, v83
	global_store_dwordx4 v[72:73], v[68:71], off
	s_add_i32 s50, s50, s66
	s_mov_b32 s38, s30
	v_cvt_pk_bf16_f32 v68, v144, v145
	v_cvt_pk_bf16_f32 v69, v146, v147
	v_cvt_pk_bf16_f32 v70, v172, v173
	v_cvt_pk_bf16_f32 v71, v174, v175
	global_store_dwordx4 v[72:73], v[68:71], off offset:256
	s_mov_b32 s63, s28
	s_mov_b64 s[42:43], s[36:37]
	v_or_b32_e32 v68, 32, v100
	v_ashrrev_i32_e32 v69, 31, v68
	v_lshlrev_b64 v[72:73], 11, v[68:69]
	v_lshl_add_u64 v[72:73], s[82:83], 0, v[72:73]
	v_cvt_pk_bf16_f32 v68, v84, v85
	v_lshl_add_u64 v[72:73], v[72:73], 0, v[74:75]
	v_cvt_pk_bf16_f32 v69, v86, v87
	v_cvt_pk_bf16_f32 v70, v88, v89
	v_cvt_pk_bf16_f32 v71, v90, v91
	global_store_dwordx4 v[72:73], v[68:71], off
	s_mov_b64 s[40:41], s[34:35]
	s_nop 0
	v_cvt_pk_bf16_f32 v68, v180, v181
	v_cvt_pk_bf16_f32 v69, v182, v183
	v_cvt_pk_bf16_f32 v70, v184, v185
	v_cvt_pk_bf16_f32 v71, v186, v187
	global_store_dwordx4 v[72:73], v[68:71], off offset:256
	s_nop 1
	v_or_b32_e32 v68, 48, v100
	v_ashrrev_i32_e32 v69, 31, v68
	v_lshlrev_b64 v[72:73], 11, v[68:69]
	v_lshl_add_u64 v[72:73], s[82:83], 0, v[72:73]
	v_cvt_pk_bf16_f32 v68, v92, v93
	v_cvt_pk_bf16_f32 v69, v94, v95
	v_cvt_pk_bf16_f32 v70, v96, v97
	v_lshl_add_u64 v[72:73], v[72:73], 0, v[74:75]
	v_cvt_pk_bf16_f32 v71, v98, v99
	global_store_dwordx4 v[72:73], v[68:71], off
	s_nop 1
	v_cvt_pk_bf16_f32 v68, v188, v189
	v_cvt_pk_bf16_f32 v69, v190, v191
	v_cvt_pk_bf16_f32 v70, v60, v61
	v_cvt_pk_bf16_f32 v71, v62, v63
	global_store_dwordx4 v[72:73], v[68:71], off offset:256
	v_cvt_pk_bf16_f32 v60, v148, v149
	v_cvt_pk_bf16_f32 v61, v150, v151
	v_cvt_pk_bf16_f32 v62, v152, v153
	v_cvt_pk_bf16_f32 v63, v154, v155
	s_nop 1
	v_add_co_u32_e32 v70, vcc, s55, v52
	v_lshl_add_u64 v[68:69], v[52:53], 0, s[18:19]
	s_nop 0
	v_addc_co_u32_e32 v71, vcc, 0, v53, vcc
	global_store_dwordx4 v[70:71], v[60:63], off
	s_nop 1
	v_cvt_pk_bf16_f32 v60, v124, v125
	v_cvt_pk_bf16_f32 v61, v126, v127
	v_cvt_pk_bf16_f32 v62, v128, v129
	v_cvt_pk_bf16_f32 v63, v130, v131
	global_store_dwordx4 v[68:69], v[60:63], off offset:256
	v_cvt_pk_bf16_f32 v36, v36, v37
	v_cvt_pk_bf16_f32 v37, v38, v39
	v_cvt_pk_bf16_f32 v38, v32, v33
	v_add_co_u32_e32 v32, vcc, s60, v52
	s_nop 0
	v_lshl_add_u64 v[60:61], v[52:53], 0, s[20:21]
	v_addc_co_u32_e32 v33, vcc, 0, v53, vcc
	v_cvt_pk_bf16_f32 v39, v34, v35
	global_store_dwordx4 v[32:33], v[36:39], off
	v_cvt_pk_bf16_f32 v32, v64, v65
	v_cvt_pk_bf16_f32 v33, v66, v67
	v_cvt_pk_bf16_f32 v34, v108, v109
	v_cvt_pk_bf16_f32 v35, v110, v111
	global_store_dwordx4 v[60:61], v[32:35], off offset:256
	v_cvt_pk_bf16_f32 v20, v20, v21
	v_cvt_pk_bf16_f32 v21, v22, v23
	v_cvt_pk_bf16_f32 v22, v16, v17
	v_add_co_u32_e32 v16, vcc, s61, v52
	s_nop 0
	v_lshl_add_u64 v[32:33], v[52:53], 0, s[22:23]
	v_addc_co_u32_e32 v17, vcc, 0, v53, vcc
	v_cvt_pk_bf16_f32 v23, v18, v19
	global_store_dwordx4 v[16:17], v[20:23], off
	v_cvt_pk_bf16_f32 v16, v28, v29
	v_cvt_pk_bf16_f32 v17, v30, v31
	v_cvt_pk_bf16_f32 v18, v24, v25
	v_cvt_pk_bf16_f32 v19, v26, v27
	global_store_dwordx4 v[32:33], v[16:19], off offset:256
	v_cvt_pk_bf16_f32 v4, v4, v5
	v_cvt_pk_bf16_f32 v5, v6, v7
	v_cvt_pk_bf16_f32 v6, v0, v1
	v_add_co_u32_e32 v0, vcc, s62, v52
	s_nop 0
	v_lshl_add_u64 v[16:17], v[52:53], 0, s[24:25]
	v_addc_co_u32_e32 v1, vcc, 0, v53, vcc
	s_andn2_b64 vcc, exec, s[6:7]
	v_cvt_pk_bf16_f32 v7, v2, v3
	global_store_dwordx4 v[0:1], v[4:7], off
	v_cvt_pk_bf16_f32 v0, v12, v13
	v_cvt_pk_bf16_f32 v1, v14, v15
	v_cvt_pk_bf16_f32 v2, v8, v9
	v_cvt_pk_bf16_f32 v3, v10, v11
	global_store_dwordx4 v[16:17], v[0:3], off offset:256
	s_cbranch_vccz .LBB0_863

; #define PG8_WAIT_V(n) asm volatile("s_waitcnt vmcnt(" #n ")" ::: "memory")
; #define PG8_BAR __builtin_amdgcn_s_barrier()
; template <class Epi, class Sched>
; __device__ __forceinline__ void gemm_phase(PG8_LAS unsigned char* lds, const Gemm g, const Sched& S, const Epi& E) {
;     ...
;     PG8_WAIT_V(0);
;     if (wr == 0) PG8_BAR;
;     PG8_BAR;
; __global__ void __launch_bounds__(512, 2) hymba_fwd(Params p) {
;     ...
;           for (int u = bx; u < 256; u += G) small_gemm<DPLE>(lds, g.A, g.Bt, MP + 32 * (u >> 4), (u & 15) * 64, (u & 15) * 64 + 32, E);
;           asm volatile("s_waitcnt vmcnt(0)" ::: "memory"); }
.LBB0_865:
	s_lshl_b32 s0, s2, 1
	s_lshl_b32 s1, s66, 1
	s_lshl_b32 s3, s2, 6
	s_lshl_b32 s4, s66, 6
	v_mov_b32_e32 v33, 0
	s_movk_i32 s5, 0x90
	s_movk_i32 s10, 0x100
	s_mov_b32 s11, s2
	s_barrier
	s_setprio 0
	s_branch .LBB0_867

; #define PG8_STAGE(bufoff, gbase, voff) do { _Pragma("unroll") for (int _i = 0; _i < 2; ++_i) \
;         __builtin_amdgcn_global_load_lds((const unsigned*)((const char*)(gbase) + (voff)[_i]), (PG8_LAS unsigned*)(lds + (bufoff) + ldsw + _i * 8192), 16, 0, 0); } while (0)
; #define PG8_WAIT_V(n) asm volatile("s_waitcnt vmcnt(" #n ")" ::: "memory")
; template <class Epi, class Sched>
; __device__ __forceinline__ void gemm_phase(PG8_LAS unsigned char* lds, const Gemm g, const Sched& S, const Epi& E) {
;     ...
;     for (int i = 0; i < 2; ++i) { int R, C; stage_rc(tid * 16 + i * 8192, R, C); const int Rb = Epi::PERM ? ((R & ~31) + perm32(R & 31)) : R;
;         voffA[i] = (unsigned)(R * K + C) * 2u; voffB[i] = (unsigned)(Rb * K + C) * 2u; }
;     const size_t kstep = (size_t)(BK * 2);
;     const size_t hstep = (size_t)HALF * K * 2;
;     const size_t tstep = 2 * hstep;
;     const unsigned ldsw = (unsigned)wid * 1024u;
;     const int aoff = lds_byte(wr * 64 + fr, fq * 8), boff = lds_byte(wc * 32 + fr, fq * 8);
;     ...
;     Unit cur, nxt; int ui = 0;
;     if (!S.next(0, cur)) return;
;     f32x4 acc[2][2][4][2];
; #pragma unroll
;     for (int a = 0; a < 2; ++a)
; #pragma unroll
;         for (int b = 0; b < 2; ++b)
; #pragma unroll
;             for (int m = 0; m < 4; ++m)
; #pragma unroll
;                 for (int n = 0; n < 2; ++n) acc[a][b][m][n] = (f32x4){0.f, 0.f, 0.f, 0.f};
;     bf16x8 At[4][2], B0[2][2], B1[2][2];
;     const char* cA = (const char*)g.A + (size_t)cur.pm * tstep; const char* cB = (const char*)g.Bt + (size_t)cur.pn * tstep;
;     float epre[Epi::NPRE]; E.preload(cur, wr, fr, epre);
;     S.a_ready(cur);
;     PG8_STAGE(PG8_SB(0, 0), cB, voffB); PG8_STAGE(PG8_SA(0, 0), cA, voffA); PG8_STAGE(PG8_SB(0, 1), cB + hstep, voffB); PG8_STAGE(PG8_SA(0, 1), cA + hstep, voffA);
;     if (wr == 1) PG8_BAR;
;     PG8_WAIT_V(4); PG8_BAR;
;     PG8_STAGE(PG8_SB(1, 0), cB + kstep, voffB); PG8_STAGE(PG8_SA(1, 0), cA + kstep, voffA); PG8_STAGE(PG8_SB(1, 1), cB + hstep + kstep, voffB);
;     PG8_WAIT_V(6); PG8_BAR;
;     __device__ __forceinline__ void preload(const Unit& u, int wr, int fr, float (&pre)[8]) const { const int row0 = u.pm * 256 + wr * 64 + fr;
; #pragma unroll
;         for (int ai = 0; ai < 2; ++ai)
; #pragma unroll
;             for (int m = 0; m < 4; ++m) pre[ai * 4 + m] = sumsq2[row0 + ai * 128 + m * 16]; }
.LBB0_874:
	v_ashrrev_i32_e32 v1, 31, v8
	v_lshrrev_b32_e32 v1, 26, v1
	v_add_u32_e32 v1, v8, v1
	v_ashrrev_i32_e32 v9, 6, v1
	v_bfe_i32 v1, v8, 27, 1
	v_lshlrev_b32_e32 v0, 4, v8
	v_lshrrev_b32_e32 v1, 22, v1
	v_add_u32_e32 v1, v0, v1
	v_and_b32_e32 v1, 0xfffffc00, v1
	v_sub_u32_e32 v1, v0, v1
	v_lshrrev_b32_e32 v2, 4, v1
	v_bitop3_b32 v1, v2, v1, 32 bitop3:0x6c
	v_ashrrev_i32_e32 v3, 31, v1
	v_lshrrev_b32_e32 v3, 26, v3
	v_add_u32_e32 v3, v1, v3
	v_lshlrev_b32_e32 v2, 3, v9
	v_ashrrev_i32_e32 v10, 6, v3
	v_and_b32_e32 v3, 0xc0, v3
	v_and_b32_e32 v2, -16, v2
	v_sub_u32_e32 v1, v1, v3
	v_mov_b32_e32 v3, 1
	v_add_u32_e32 v2, v10, v2
	v_ashrrev_i16_sdwa v1, v3, sext(v1) dst_sel:DWORD dst_unused:UNUSED_PAD src0_sel:DWORD src1_sel:BYTE_0
	v_lshlrev_b32_e32 v4, 5, v9
	v_bfe_i32 v11, v1, 0, 16
	v_lshlrev_b32_e32 v1, 1, v2
	v_lshrrev_b32_e32 v5, 2, v2
	v_and_b32_e32 v6, 3, v10
	s_mov_b32 s3, 0x1fffe0
	v_and_b32_e32 v4, 32, v4
	v_and_b32_e32 v1, 24, v1
	v_and_b32_e32 v5, 4, v5
	v_and_or_b32 v6, v2, s3, v6
	s_add_u32 s8, s64, 0x1880000
	v_or3_b32 v1, v6, v5, v1
	v_add_lshl_u32 v4, v4, v11, 1
	v_add_u32_e32 v0, 0x2000, v0
	s_addc_u32 s9, s65, 0
	v_lshl_add_u32 v182, v1, 11, v4
	v_ashrrev_i32_e32 v1, 31, v0
	s_add_i32 s4, s6, s4
	v_lshrrev_b32_e32 v1, 22, v1
	s_ashr_i32 s6, s4, 31
	v_add_u32_e32 v1, v0, v1
	s_lshr_b32 s6, s6, 27
	s_waitcnt vmcnt(0)
	v_ashrrev_i32_e32 v12, 10, v1
	s_add_i32 s6, s4, s6
	v_mul_i32_i24_e32 v1, 0x400, v12
	s_ashr_i32 s7, s6, 5
	s_and_b32 s6, s6, 0xffe0
	v_sub_u32_e32 v0, v0, v1
	s_sub_i32 s6, s4, s6
	v_lshrrev_b32_e32 v1, 4, v0
	s_bfe_i32 s4, s6, 0x80000
	v_bitop3_b32 v0, v1, v0, 32 bitop3:0x6c
	s_bfe_u32 s4, s4, 0x3000c
	v_lshl_add_u32 v180, v2, 11, v4
	v_ashrrev_i32_e32 v2, 31, v0
	s_add_i32 s10, s6, s4
	v_lshrrev_b32_e32 v2, 26, v2
	s_bfe_i32 s4, s10, 0x80000
	s_and_b32 s10, s10, 0xf8
	v_add_u32_e32 v2, v0, v2
	s_sub_i32 s6, s6, s10
	v_lshlrev_b32_e32 v1, 3, v12
	v_ashrrev_i32_e32 v13, 6, v2
	v_and_b32_e32 v2, 0xc0, v2
	s_lshl_b32 s7, s7, 3
	s_sext_i32_i16 s4, s4
	s_sext_i32_i8 s6, s6
	s_ashr_i32 s5, s0, 8
	v_and_b32_e32 v1, -16, v1
	v_sub_u32_e32 v0, v0, v2
	s_lshr_b32 s4, s4, 3
	s_add_i32 s6, s7, s6
	v_add_u32_e32 v1, v13, v1
	v_ashrrev_i16_sdwa v0, v3, sext(v0) dst_sel:DWORD dst_unused:UNUSED_PAD src0_sel:DWORD src1_sel:BYTE_0
	v_and_b32_e32 v3, 3, v13
	s_ashr_i32 s12, s0, 6
	s_ashr_i32 s7, s6, 31
	s_bfe_i64 s[18:19], s[4:5], 0x100000
	v_and_or_b32 v3, v1, s3, v3
	s_lshl_b32 s3, s12, 10
	s_lshl_b32 s16, s5, 6
	s_lshl_b64 s[10:11], s[6:7], 19
	s_lshl_b64 s[18:19], s[18:19], 19
	v_lshlrev_b32_e32 v4, 5, v12
	v_bfe_i32 v14, v0, 0, 16
	v_lshlrev_b32_e32 v0, 1, v1
	v_lshrrev_b32_e32 v2, 2, v1
	s_add_u32 s26, s8, s18
	v_and_b32_e32 v4, 32, v4
	v_and_b32_e32 v0, 24, v0
	v_and_b32_e32 v2, 4, v2
	s_addc_u32 s27, s9, s19
	s_lshl_b32 s7, s6, 8
	v_or3_b32 v0, v3, v2, v0
	v_add_lshl_u32 v2, v4, v14, 1
	v_and_b32_e32 v15, 15, v8
	s_add_i32 s7, s7, s16
	v_lshl_add_u32 v186, v0, 11, v2
	v_or_b32_e32 v0, s7, v15
	v_lshl_add_u32 v184, v1, 11, v2
	v_ashrrev_i32_e32 v1, 31, v0
	s_add_i32 s30, s3, 0
	v_lshl_add_u64 v[0:1], v[0:1], 2, s[14:15]
	s_add_i32 m0, s30, 0x10000
	global_load_dword v128, v[0:1], off
	global_load_dword v219, v[0:1], off offset:64
	global_load_dword v218, v[0:1], off offset:128
	global_load_dword v217, v[0:1], off offset:192
	global_load_dword v216, v[0:1], off offset:512
	global_load_dword v215, v[0:1], off offset:576
	global_load_dword v214, v[0:1], off offset:640
	global_load_dword v213, v[0:1], off offset:704
	v_mov_b32_e32 v183, 0
	global_load_lds_dwordx4 v182, s[26:27]
	s_add_i32 m0, s30, 0x12000
	s_add_u32 s24, s84, s10
	global_load_lds_dwordx4 v186, s[26:27]
	s_addc_u32 s25, s85, s11
	s_mov_b32 m0, s30
	s_add_i32 s31, s30, 0x2000
	global_load_lds_dwordx4 v180, s[24:25]
	s_mov_b32 m0, s31
	s_add_u32 s10, s26, 0x40000
	global_load_lds_dwordx4 v184, s[24:25]
	s_addc_u32 s11, s27, 0
	s_add_i32 m0, s30, 0x14000
	v_mov_b32_e32 v187, v183
	global_load_lds_dwordx4 v182, s[10:11]
	s_add_i32 m0, s30, 0x16000
	v_mov_b32_e32 v181, v183
	global_load_lds_dwordx4 v186, s[10:11]
	s_add_u32 s10, s24, 0x40000
	s_addc_u32 s11, s25, 0
	s_add_i32 s33, s30, 0x4000
	s_mov_b32 m0, s33
	s_add_i32 s34, s30, 0x6000
	global_load_lds_dwordx4 v180, s[10:11]
	s_mov_b32 m0, s34
	v_mov_b32_e32 v185, v183
	global_load_lds_dwordx4 v184, s[10:11]
	s_mov_b32 s35, 0
	v_lshl_add_u64 v[6:7], s[26:27], 0, v[182:183]
	v_lshl_add_u64 v[4:5], s[26:27], 0, v[186:187]
	v_lshl_add_u64 v[2:3], s[24:25], 0, v[180:181]
	s_cmp_lg_u32 s5, 1
	v_lshl_add_u64 v[0:1], s[24:25], 0, v[184:185]
	s_cbranch_scc1 .LBB0_876
	s_barrier
	s_setprio 1

; #define PG8_STAGE(bufoff, gbase, voff) do { _Pragma("unroll") for (int _i = 0; _i < 2; ++_i) \
;         __builtin_amdgcn_global_load_lds((const unsigned*)((const char*)(gbase) + (voff)[_i]), (PG8_LAS unsigned*)(lds + (bufoff) + ldsw + _i * 8192), 16, 0, 0); } while (0)
; #define PG8_LDA(dst, b, h) do { _Pragma("unroll") for (int m = 0; m < 4; ++m) _Pragma("unroll") for (int k = 0; k < 2; ++k) dst[m][k] = *(const PG8_LAS bf16x8*)(lds + PG8_SA(b, h) + aoff + m * 2048 + k * 1024); } while (0)
; #define PG8_LDB(dst, b, h) do { _Pragma("unroll") for (int n = 0; n < 2; ++n) _Pragma("unroll") for (int k = 0; k < 2; ++k) dst[n][k] = *(const PG8_LAS bf16x8*)(lds + PG8_SB(b, h) + boff + n * 2048 + k * 1024); } while (0)
; #define PG8_MMA(ai, bj, At, Bt) do { __builtin_amdgcn_s_setprio(1); _Pragma("unroll") for (int m = 0; m < 4; ++m) _Pragma("unroll") for (int n = 0; n < 2; ++n) _Pragma("unroll") for (int k = 0; k < 2; ++k) \
;         acc[ai][bj][m][n] = __builtin_amdgcn_mfma_f32_16x16x32_bf16(Bt[n][k], At[m][k], acc[ai][bj][m][n], 0, 0, 0); __builtin_amdgcn_s_setprio(0); } while (0)
; #define PG8_WAIT_L(n) asm volatile("s_waitcnt lgkmcnt(" #n ")" ::: "memory")
; #define PG8_BAR __builtin_amdgcn_s_barrier()
; #define PG8_SCHED __builtin_amdgcn_sched_barrier(0)
; template <class Epi, class Sched>
; __device__ __forceinline__ void gemm_phase(PG8_LAS unsigned char* lds, const Gemm g, const Sched& S, const Epi& E) {
;     ...
;             const char* a2 = last ? nA : cA + (size_t)(t + 2) * kstep; const char* b2 = last ? nB : cB + (size_t)(t + 2) * kstep;
;             const char* a3 = a2 + kstep; const char* b3 = b2 + kstep;
;             if (last && has_next) S.a_ready(nxt);
;             PG8_LDB(B0, 0, 0); PG8_SCHED; PG8_LDA(At, 0, 0); PG8_STAGE(PG8_SA(1, 1), a1 + hstep, voffA);
;             PG8_WAIT_L(8); PG8_BAR; PG8_WAIT_L(0); PG8_MMA(0, 0, At, B0); PG8_BAR; PG8_SCHED;
;             PG8_LDB(B1, 0, 1); PG8_STAGE(PG8_SB(0, 0), b2, voffB);
;             PG8_BAR; PG8_WAIT_L(0); PG8_MMA(0, 1, At, B1); PG8_BAR;
;             PG8_LDA(At, 0, 1); PG8_STAGE(PG8_SA(0, 0), a2, voffA);
;             PG8_BAR; PG8_WAIT_L(0); PG8_MMA(1, 0, At, B0); PG8_BAR; PG8_SCHED;
.LBB0_885:
	ds_read_b128 v[130:133], v209
	ds_read_b128 v[134:137], v209 offset:1024
	ds_read_b128 v[138:141], v209 offset:2048
	ds_read_b128 v[142:145], v209 offset:3072
	s_add_u32 s26, s24, 0xfffc0080
	s_addc_u32 s27, s25, -1
	s_cmp_eq_u32 s45, 12
	s_cselect_b32 s29, s19, s27
	s_cselect_b32 s28, s41, s26
	s_cselect_b32 s27, s17, s44
	s_cselect_b32 s26, s42, s43
	v_lshl_add_u64 v[174:175], s[24:25], 0, v[188:189]
	s_add_i32 m0, s30, 0xc000
	ds_read_b128 v[146:149], v210
	ds_read_b128 v[150:153], v210 offset:1024
	ds_read_b128 v[154:157], v210 offset:2048
	ds_read_b128 v[158:161], v210 offset:3072
	ds_read_b128 v[162:165], v210 offset:4096
	ds_read_b128 v[166:169], v210 offset:5120
	ds_read_b128 v[170:173], v210 offset:6144
	ds_read_b128 v[196:199], v210 offset:7168
	global_load_lds_dwordx4 v[174:175], off
	v_lshl_add_u64 v[174:175], s[24:25], 0, v[190:191]
	s_add_i32 m0, s30, 0xe000
	s_nop 0
	global_load_lds_dwordx4 v[174:175], off
	s_waitcnt lgkmcnt(8)
	s_barrier
	s_waitcnt lgkmcnt(0)
	s_waitcnt lgkmcnt(0)
	v_mfma_f32_16x16x32_bf16 v[124:127], v[130:133], v[146:149], v[124:127]
	v_mfma_f32_16x16x32_bf16 v[120:123], v[138:141], v[146:149], v[120:123]
	v_mfma_f32_16x16x32_bf16 v[108:111], v[130:133], v[154:157], v[108:111]
	v_mfma_f32_16x16x32_bf16 v[104:107], v[138:141], v[154:157], v[104:107]
	v_mfma_f32_16x16x32_bf16 v[92:95], v[130:133], v[162:165], v[92:95]
	v_mfma_f32_16x16x32_bf16 v[88:91], v[138:141], v[162:165], v[88:91]
	v_mfma_f32_16x16x32_bf16 v[76:79], v[130:133], v[170:173], v[76:79]
	v_mfma_f32_16x16x32_bf16 v[72:75], v[138:141], v[170:173], v[72:75]
	v_mfma_f32_16x16x32_bf16 v[124:127], v[134:137], v[150:153], v[124:127]
	v_mfma_f32_16x16x32_bf16 v[120:123], v[142:145], v[150:153], v[120:123]
	v_mfma_f32_16x16x32_bf16 v[108:111], v[134:137], v[158:161], v[108:111]
	v_mfma_f32_16x16x32_bf16 v[104:107], v[142:145], v[158:161], v[104:107]
	v_mfma_f32_16x16x32_bf16 v[92:95], v[134:137], v[166:169], v[92:95]
	v_mfma_f32_16x16x32_bf16 v[88:91], v[142:145], v[166:169], v[88:91]
	v_mfma_f32_16x16x32_bf16 v[76:79], v[134:137], v[196:199], v[76:79]
	v_mfma_f32_16x16x32_bf16 v[72:75], v[142:145], v[196:199], v[72:75]
	s_barrier
	s_add_i32 s46, s38, s3
	v_lshl_add_u64 v[174:175], s[26:27], 0, v[182:183]
	s_mov_b32 m0, s46
	ds_read_b128 v[200:203], v211
	ds_read_b128 v[220:223], v211 offset:1024
	ds_read_b128 v[224:227], v211 offset:2048
	ds_read_b128 v[228:231], v211 offset:3072
	global_load_lds_dwordx4 v[174:175], off
	v_lshl_add_u64 v[204:205], s[26:27], 0, v[186:187]
	s_add_i32 m0, s46, 0x2000
	s_nop 0
	global_load_lds_dwordx4 v[204:205], off
	s_barrier
	s_waitcnt lgkmcnt(0)
	s_waitcnt lgkmcnt(0)
	v_mfma_f32_16x16x32_bf16 v[116:119], v[200:203], v[146:149], v[116:119]
	v_mfma_f32_16x16x32_bf16 v[112:115], v[224:227], v[146:149], v[112:115]
	v_mfma_f32_16x16x32_bf16 v[100:103], v[200:203], v[154:157], v[100:103]
	v_mfma_f32_16x16x32_bf16 v[96:99], v[224:227], v[154:157], v[96:99]
	v_mfma_f32_16x16x32_bf16 v[84:87], v[200:203], v[162:165], v[84:87]
	v_mfma_f32_16x16x32_bf16 v[80:83], v[224:227], v[162:165], v[80:83]
	v_mfma_f32_16x16x32_bf16 v[68:71], v[200:203], v[170:173], v[68:71]
	v_mfma_f32_16x16x32_bf16 v[64:67], v[224:227], v[170:173], v[64:67]
	v_mfma_f32_16x16x32_bf16 v[116:119], v[220:223], v[150:153], v[116:119]
	v_mfma_f32_16x16x32_bf16 v[112:115], v[228:231], v[150:153], v[112:115]
	v_mfma_f32_16x16x32_bf16 v[100:103], v[220:223], v[158:161], v[100:103]
	v_mfma_f32_16x16x32_bf16 v[96:99], v[228:231], v[158:161], v[96:99]
	v_mfma_f32_16x16x32_bf16 v[84:87], v[220:223], v[166:169], v[84:87]
	v_mfma_f32_16x16x32_bf16 v[80:83], v[228:231], v[166:169], v[80:83]
	v_mfma_f32_16x16x32_bf16 v[68:71], v[220:223], v[196:199], v[68:71]
	v_mfma_f32_16x16x32_bf16 v[64:67], v[228:231], v[196:199], v[64:67]
	s_mov_b32 m0, s30
	v_lshl_add_u64 v[232:233], s[28:29], 0, v[180:181]
	s_barrier
	ds_read_b128 v[146:149], v210 offset:16384
	ds_read_b128 v[150:153], v210 offset:17408
	ds_read_b128 v[154:157], v210 offset:18432
	ds_read_b128 v[158:161], v210 offset:19456
	ds_read_b128 v[162:165], v210 offset:20480
	ds_read_b128 v[166:169], v210 offset:21504
	ds_read_b128 v[170:173], v210 offset:22528
	ds_read_b128 v[196:199], v210 offset:23552
	global_load_lds_dwordx4 v[232:233], off
	v_lshl_add_u64 v[234:235], s[28:29], 0, v[184:185]
	s_mov_b32 m0, s31
	s_nop 0
	global_load_lds_dwordx4 v[234:235], off
	s_barrier
	s_waitcnt lgkmcnt(0)
	s_waitcnt lgkmcnt(0)
	v_mfma_f32_16x16x32_bf16 v[60:63], v[130:133], v[146:149], v[60:63]
	v_mfma_f32_16x16x32_bf16 v[56:59], v[138:141], v[146:149], v[56:59]
	v_mfma_f32_16x16x32_bf16 v[44:47], v[130:133], v[154:157], v[44:47]
	v_mfma_f32_16x16x32_bf16 v[40:43], v[138:141], v[154:157], v[40:43]
	v_mfma_f32_16x16x32_bf16 v[28:31], v[130:133], v[162:165], v[28:31]
	v_mfma_f32_16x16x32_bf16 v[24:27], v[138:141], v[162:165], v[24:27]
	v_mfma_f32_16x16x32_bf16 v[12:15], v[130:133], v[170:173], v[12:15]
	v_mfma_f32_16x16x32_bf16 v[8:11], v[138:141], v[170:173], v[8:11]
	v_mfma_f32_16x16x32_bf16 v[60:63], v[134:137], v[150:153], v[60:63]
	v_mfma_f32_16x16x32_bf16 v[56:59], v[142:145], v[150:153], v[56:59]
	v_mfma_f32_16x16x32_bf16 v[44:47], v[134:137], v[158:161], v[44:47]
	v_mfma_f32_16x16x32_bf16 v[40:43], v[142:145], v[158:161], v[40:43]
	v_mfma_f32_16x16x32_bf16 v[28:31], v[134:137], v[166:169], v[28:31]
	v_mfma_f32_16x16x32_bf16 v[24:27], v[142:145], v[166:169], v[24:27]
	v_mfma_f32_16x16x32_bf16 v[12:15], v[134:137], v[196:199], v[12:15]
	v_mfma_f32_16x16x32_bf16 v[8:11], v[142:145], v[196:199], v[8:11]
	s_barrier
; #define PG8_STAGE(bufoff, gbase, voff) do { _Pragma("unroll") for (int _i = 0; _i < 2; ++_i) \
;         __builtin_amdgcn_global_load_lds((const unsigned*)((const char*)(gbase) + (voff)[_i]), (PG8_LAS unsigned*)(lds + (bufoff) + ldsw + _i * 8192), 16, 0, 0); } while (0)
; #define PG8_LDA(dst, b, h) do { _Pragma("unroll") for (int m = 0; m < 4; ++m) _Pragma("unroll") for (int k = 0; k < 2; ++k) dst[m][k] = *(const PG8_LAS bf16x8*)(lds + PG8_SA(b, h) + aoff + m * 2048 + k * 1024); } while (0)
; #define PG8_LDB(dst, b, h) do { _Pragma("unroll") for (int n = 0; n < 2; ++n) _Pragma("unroll") for (int k = 0; k < 2; ++k) dst[n][k] = *(const PG8_LAS bf16x8*)(lds + PG8_SB(b, h) + boff + n * 2048 + k * 1024); } while (0)
; #define PG8_MMA(ai, bj, At, Bt) do { __builtin_amdgcn_s_setprio(1); _Pragma("unroll") for (int m = 0; m < 4; ++m) _Pragma("unroll") for (int n = 0; n < 2; ++n) _Pragma("unroll") for (int k = 0; k < 2; ++k) \
;         acc[ai][bj][m][n] = __builtin_amdgcn_mfma_f32_16x16x32_bf16(Bt[n][k], At[m][k], acc[ai][bj][m][n], 0, 0, 0); __builtin_amdgcn_s_setprio(0); } while (0)
; #define PG8_WAIT_V(n) asm volatile("s_waitcnt vmcnt(" #n ")" ::: "memory")
; #define PG8_WAIT_L(n) asm volatile("s_waitcnt lgkmcnt(" #n ")" ::: "memory")
; #define PG8_BAR __builtin_amdgcn_s_barrier()
; #define PG8_SCHED __builtin_amdgcn_sched_barrier(0)
; template <class Epi, class Sched>
; __device__ __forceinline__ void gemm_phase(PG8_LAS unsigned char* lds, const Gemm g, const Sched& S, const Epi& E) {
;     ...
;             PG8_STAGE(PG8_SB(0, 1), b2 + hstep, voffB);
;             PG8_WAIT_V(6); PG8_BAR; PG8_MMA(1, 1, At, B1); PG8_BAR;
;             PG8_LDB(B0, 1, 0); PG8_SCHED; PG8_LDA(At, 1, 0); PG8_STAGE(PG8_SA(0, 1), a2 + hstep, voffA);
;             PG8_WAIT_L(8); PG8_BAR; PG8_WAIT_L(0); PG8_MMA(0, 0, At, B0); PG8_BAR; PG8_SCHED;
;             PG8_LDB(B1, 1, 1); PG8_STAGE(PG8_SB(1, 0), b3, voffB);
;             PG8_BAR; PG8_WAIT_L(0); PG8_MMA(0, 1, At, B1); PG8_BAR;
;             PG8_LDA(At, 1, 1); PG8_STAGE(PG8_SA(1, 0), a3, voffA);
	s_add_u32 s46, s26, 0x40000
	s_addc_u32 s47, s27, 0
	s_add_i32 s48, s39, s3
	v_lshl_add_u64 v[130:131], s[46:47], 0, v[182:183]
	s_mov_b32 m0, s48
	s_nop 0
	global_load_lds_dwordx4 v[130:131], off
	v_lshl_add_u64 v[130:131], s[46:47], 0, v[186:187]
	s_add_i32 m0, s48, 0x2000
	s_nop 0
	global_load_lds_dwordx4 v[130:131], off
	s_waitcnt vmcnt(6)
	s_barrier
	v_mfma_f32_16x16x32_bf16 v[52:55], v[200:203], v[146:149], v[52:55]
	v_mfma_f32_16x16x32_bf16 v[48:51], v[224:227], v[146:149], v[48:51]
	v_mfma_f32_16x16x32_bf16 v[36:39], v[200:203], v[154:157], v[36:39]
	v_mfma_f32_16x16x32_bf16 v[32:35], v[224:227], v[154:157], v[32:35]
	v_mfma_f32_16x16x32_bf16 v[20:23], v[200:203], v[162:165], v[20:23]
	v_mfma_f32_16x16x32_bf16 v[16:19], v[224:227], v[162:165], v[16:19]
	v_mfma_f32_16x16x32_bf16 v[4:7], v[200:203], v[170:173], v[4:7]
	v_mfma_f32_16x16x32_bf16 v[0:3], v[224:227], v[170:173], v[0:3]
	v_mfma_f32_16x16x32_bf16 v[52:55], v[220:223], v[150:153], v[52:55]
	v_mfma_f32_16x16x32_bf16 v[48:51], v[228:231], v[150:153], v[48:51]
	v_mfma_f32_16x16x32_bf16 v[36:39], v[220:223], v[158:161], v[36:39]
	v_mfma_f32_16x16x32_bf16 v[32:35], v[228:231], v[158:161], v[32:35]
	v_mfma_f32_16x16x32_bf16 v[20:23], v[220:223], v[166:169], v[20:23]
	v_mfma_f32_16x16x32_bf16 v[16:19], v[228:231], v[166:169], v[16:19]
	v_mfma_f32_16x16x32_bf16 v[4:7], v[220:223], v[196:199], v[4:7]
	v_mfma_f32_16x16x32_bf16 v[0:3], v[228:231], v[196:199], v[0:3]
	s_add_i32 s46, 0, 0x18000
	v_add_u32_e32 v129, s46, v207
	s_barrier
	ds_read_b128 v[130:133], v129
	ds_read_b128 v[134:137], v129 offset:1024
	ds_read_b128 v[138:141], v129 offset:2048
	ds_read_b128 v[142:145], v129 offset:3072
	s_add_u32 s28, s28, 0x40000
	s_addc_u32 s29, s29, 0
	s_mov_b32 m0, s33
	v_lshl_add_u64 v[200:201], s[28:29], 0, v[180:181]
	ds_read_b128 v[146:149], v210 offset:32768
	ds_read_b128 v[150:153], v210 offset:33792
	ds_read_b128 v[154:157], v210 offset:34816
	ds_read_b128 v[158:161], v210 offset:35840
	ds_read_b128 v[162:165], v210 offset:36864
	ds_read_b128 v[166:169], v210 offset:37888
	ds_read_b128 v[170:173], v210 offset:38912
	ds_read_b128 v[196:199], v210 offset:39936
	global_load_lds_dwordx4 v[200:201], off
	v_lshl_add_u64 v[200:201], s[28:29], 0, v[184:185]
	s_mov_b32 m0, s34
	s_nop 0
	global_load_lds_dwordx4 v[200:201], off
	s_waitcnt lgkmcnt(8)
	s_barrier
	s_waitcnt lgkmcnt(0)
	s_waitcnt lgkmcnt(0)
	v_mfma_f32_16x16x32_bf16 v[124:127], v[130:133], v[146:149], v[124:127]
	v_mfma_f32_16x16x32_bf16 v[120:123], v[138:141], v[146:149], v[120:123]
	v_mfma_f32_16x16x32_bf16 v[108:111], v[130:133], v[154:157], v[108:111]
	v_mfma_f32_16x16x32_bf16 v[104:107], v[138:141], v[154:157], v[104:107]
	v_mfma_f32_16x16x32_bf16 v[92:95], v[130:133], v[162:165], v[92:95]
	v_mfma_f32_16x16x32_bf16 v[88:91], v[138:141], v[162:165], v[88:91]
	v_mfma_f32_16x16x32_bf16 v[76:79], v[130:133], v[170:173], v[76:79]
	v_mfma_f32_16x16x32_bf16 v[72:75], v[138:141], v[170:173], v[72:75]
	v_mfma_f32_16x16x32_bf16 v[124:127], v[134:137], v[150:153], v[124:127]
	v_mfma_f32_16x16x32_bf16 v[120:123], v[142:145], v[150:153], v[120:123]
	v_mfma_f32_16x16x32_bf16 v[108:111], v[134:137], v[158:161], v[108:111]
	v_mfma_f32_16x16x32_bf16 v[104:107], v[142:145], v[158:161], v[104:107]
	v_mfma_f32_16x16x32_bf16 v[92:95], v[134:137], v[166:169], v[92:95]
	v_mfma_f32_16x16x32_bf16 v[88:91], v[142:145], v[166:169], v[88:91]
	v_mfma_f32_16x16x32_bf16 v[76:79], v[134:137], v[196:199], v[76:79]
	v_mfma_f32_16x16x32_bf16 v[72:75], v[142:145], v[196:199], v[72:75]
	s_barrier
	s_add_i32 s28, 0, 0x1c000
	s_add_i32 s29, s46, s3
	v_add_u32_e32 v129, s28, v207
	v_lshl_add_u64 v[174:175], v[174:175], 0, s[12:13]
	s_mov_b32 m0, s29
	ds_read_b128 v[200:203], v129
	ds_read_b128 v[220:223], v129 offset:1024
	ds_read_b128 v[224:227], v129 offset:2048
	ds_read_b128 v[228:231], v129 offset:3072
	global_load_lds_dwordx4 v[174:175], off
	v_lshl_add_u64 v[174:175], v[204:205], 0, s[12:13]
	s_add_i32 m0, s29, 0x2000
	s_nop 0
	global_load_lds_dwordx4 v[174:175], off
	s_barrier
	s_waitcnt lgkmcnt(0)
	s_waitcnt lgkmcnt(0)
	v_mfma_f32_16x16x32_bf16 v[116:119], v[200:203], v[146:149], v[116:119]
	v_mfma_f32_16x16x32_bf16 v[112:115], v[224:227], v[146:149], v[112:115]
	v_mfma_f32_16x16x32_bf16 v[100:103], v[200:203], v[154:157], v[100:103]
	v_mfma_f32_16x16x32_bf16 v[96:99], v[224:227], v[154:157], v[96:99]
	v_mfma_f32_16x16x32_bf16 v[84:87], v[200:203], v[162:165], v[84:87]
	v_mfma_f32_16x16x32_bf16 v[80:83], v[224:227], v[162:165], v[80:83]
	v_mfma_f32_16x16x32_bf16 v[68:71], v[200:203], v[170:173], v[68:71]
	v_mfma_f32_16x16x32_bf16 v[64:67], v[224:227], v[170:173], v[64:67]
	v_mfma_f32_16x16x32_bf16 v[116:119], v[220:223], v[150:153], v[116:119]
	v_mfma_f32_16x16x32_bf16 v[112:115], v[228:231], v[150:153], v[112:115]
	v_mfma_f32_16x16x32_bf16 v[100:103], v[220:223], v[158:161], v[100:103]
	v_mfma_f32_16x16x32_bf16 v[96:99], v[228:231], v[158:161], v[96:99]
	v_mfma_f32_16x16x32_bf16 v[84:87], v[220:223], v[166:169], v[84:87]
	v_mfma_f32_16x16x32_bf16 v[80:83], v[228:231], v[166:169], v[80:83]
	v_mfma_f32_16x16x32_bf16 v[68:71], v[220:223], v[196:199], v[68:71]
	v_mfma_f32_16x16x32_bf16 v[64:67], v[228:231], v[196:199], v[64:67]
	s_mov_b32 m0, s36
	v_lshl_add_u64 v[174:175], v[232:233], 0, s[12:13]
	s_barrier
	ds_read_b128 v[146:149], v210 offset:49152
	ds_read_b128 v[150:153], v210 offset:50176
	ds_read_b128 v[154:157], v210 offset:51200
	ds_read_b128 v[158:161], v210 offset:52224
	ds_read_b128 v[162:165], v210 offset:53248
	ds_read_b128 v[166:169], v210 offset:54272
	ds_read_b128 v[170:173], v210 offset:55296
	ds_read_b128 v[196:199], v210 offset:56320
	global_load_lds_dwordx4 v[174:175], off
	v_lshl_add_u64 v[174:175], v[234:235], 0, s[12:13]
	s_mov_b32 m0, s37
	s_nop 0
	global_load_lds_dwordx4 v[174:175], off
	s_barrier
; #define PG8_STAGE(bufoff, gbase, voff) do { _Pragma("unroll") for (int _i = 0; _i < 2; ++_i) \
;         __builtin_amdgcn_global_load_lds((const unsigned*)((const char*)(gbase) + (voff)[_i]), (PG8_LAS unsigned*)(lds + (bufoff) + ldsw + _i * 8192), 16, 0, 0); } while (0)
; #define PG8_MMA(ai, bj, At, Bt) do { __builtin_amdgcn_s_setprio(1); _Pragma("unroll") for (int m = 0; m < 4; ++m) _Pragma("unroll") for (int n = 0; n < 2; ++n) _Pragma("unroll") for (int k = 0; k < 2; ++k) \
;         acc[ai][bj][m][n] = __builtin_amdgcn_mfma_f32_16x16x32_bf16(Bt[n][k], At[m][k], acc[ai][bj][m][n], 0, 0, 0); __builtin_amdgcn_s_setprio(0); } while (0)
; #define PG8_WAIT_V(n) asm volatile("s_waitcnt vmcnt(" #n ")" ::: "memory")
; template <class Epi, class Sched>
; __device__ __forceinline__ void gemm_phase(PG8_LAS unsigned char* lds, const Gemm g, const Sched& S, const Epi& E) {
;     ...
;             PG8_BAR; PG8_WAIT_L(0); PG8_MMA(1, 0, At, B0); PG8_BAR; PG8_SCHED;
;             PG8_STAGE(PG8_SB(1, 1), b3 + hstep, voffB);
;             PG8_WAIT_V(6); PG8_BAR; PG8_MMA(1, 1, At, B1); PG8_BAR;
;     __device__ __forceinline__ void operator()(const f32x4 (&acc)[2][2][4][2], const Unit& u, int wr, int wc, int fr, int fq, const float (&epre)[8]) const {
;         const int row0 = u.pm * 256 + wr * 64 + fr, col0 = u.pn * 256 + wc * 32 + 8 * fq;
; #pragma unroll
;         for (int ai = 0; ai < 2; ++ai) {
;             float ssv[4];
;             u32x4 hw[4][2], pw[4][2];
; #pragma unroll
;             for (int m = 0; m < 4; ++m)
; #pragma unroll
;                 for (int bj = 0; bj < 2; ++bj) { const size_t o = (size_t)(row0 + ai * 128 + m * 16) * DM + col0 + bj * 128; hw[m][bj] = *(const u32x4*)(HB + o); pw[m][bj] = *(const u32x4*)(PPb + o); }
; #pragma unroll
;             for (int m = 0; m < 4; ++m) { const int row = row0 + ai * 128 + m * 16;
;                 const float rstd = rsqrtf(epre[ai * 4 + m] * (1.0f / DM) + EPS);
;                 float ss = 0.f;
; #pragma unroll
;                 for (int bj = 0; bj < 2; ++bj) { const size_t o = (size_t)row * DM + col0 + bj * 128;
;                     f32x4 h0, h1, p0, p1; unpack8(hw[m][bj], h0, h1); unpack8(pw[m][bj], p0, p1);
; #pragma unroll
;                     for (int j = 0; j < 4; ++j) { h0[j] += sigmoidf_(acc[ai][bj][m][0][j] * rstd) * p0[j]; h1[j] += sigmoidf_(acc[ai][bj][m][1][j] * rstd) * p1[j]; }
	s_waitcnt lgkmcnt(0)
	s_waitcnt lgkmcnt(0)
	v_mfma_f32_16x16x32_bf16 v[60:63], v[130:133], v[146:149], v[60:63]
	v_mfma_f32_16x16x32_bf16 v[56:59], v[138:141], v[146:149], v[56:59]
	v_mfma_f32_16x16x32_bf16 v[44:47], v[130:133], v[154:157], v[44:47]
	v_mfma_f32_16x16x32_bf16 v[40:43], v[138:141], v[154:157], v[40:43]
	v_mfma_f32_16x16x32_bf16 v[28:31], v[130:133], v[162:165], v[28:31]
	v_mfma_f32_16x16x32_bf16 v[24:27], v[138:141], v[162:165], v[24:27]
	v_mfma_f32_16x16x32_bf16 v[12:15], v[130:133], v[170:173], v[12:15]
	v_mfma_f32_16x16x32_bf16 v[8:11], v[138:141], v[170:173], v[8:11]
	v_mfma_f32_16x16x32_bf16 v[60:63], v[134:137], v[150:153], v[60:63]
	v_mfma_f32_16x16x32_bf16 v[56:59], v[142:145], v[150:153], v[56:59]
	v_mfma_f32_16x16x32_bf16 v[44:47], v[134:137], v[158:161], v[44:47]
	v_mfma_f32_16x16x32_bf16 v[40:43], v[142:145], v[158:161], v[40:43]
	v_mfma_f32_16x16x32_bf16 v[28:31], v[134:137], v[166:169], v[28:31]
	v_mfma_f32_16x16x32_bf16 v[24:27], v[142:145], v[166:169], v[24:27]
	v_mfma_f32_16x16x32_bf16 v[12:15], v[134:137], v[196:199], v[12:15]
	v_mfma_f32_16x16x32_bf16 v[8:11], v[142:145], v[196:199], v[8:11]
	s_barrier
	s_add_u32 s26, s26, 0x40080
	s_addc_u32 s27, s27, 0
	s_add_i32 s28, s28, s3
	v_lshl_add_u64 v[130:131], s[26:27], 0, v[182:183]
	s_mov_b32 m0, s28
	s_nop 0
	global_load_lds_dwordx4 v[130:131], off
	v_lshl_add_u64 v[130:131], s[26:27], 0, v[186:187]
	s_add_i32 m0, s28, 0x2000
	s_nop 0
	global_load_lds_dwordx4 v[130:131], off
	s_waitcnt vmcnt(6)
	s_barrier
	v_mfma_f32_16x16x32_bf16 v[52:55], v[200:203], v[146:149], v[52:55]
	v_mfma_f32_16x16x32_bf16 v[48:51], v[224:227], v[146:149], v[48:51]
	v_mfma_f32_16x16x32_bf16 v[36:39], v[200:203], v[154:157], v[36:39]
	v_mfma_f32_16x16x32_bf16 v[32:35], v[224:227], v[154:157], v[32:35]
	v_mfma_f32_16x16x32_bf16 v[20:23], v[200:203], v[162:165], v[20:23]
	v_mfma_f32_16x16x32_bf16 v[16:19], v[224:227], v[162:165], v[16:19]
	v_mfma_f32_16x16x32_bf16 v[4:7], v[200:203], v[170:173], v[4:7]
	v_mfma_f32_16x16x32_bf16 v[0:3], v[224:227], v[170:173], v[0:3]
	v_mfma_f32_16x16x32_bf16 v[52:55], v[220:223], v[150:153], v[52:55]
	v_mfma_f32_16x16x32_bf16 v[48:51], v[228:231], v[150:153], v[48:51]
	v_mfma_f32_16x16x32_bf16 v[36:39], v[220:223], v[158:161], v[36:39]
	v_mfma_f32_16x16x32_bf16 v[32:35], v[228:231], v[158:161], v[32:35]
	v_mfma_f32_16x16x32_bf16 v[20:23], v[220:223], v[166:169], v[20:23]
	v_mfma_f32_16x16x32_bf16 v[16:19], v[228:231], v[166:169], v[16:19]
	v_mfma_f32_16x16x32_bf16 v[4:7], v[220:223], v[196:199], v[4:7]
	v_mfma_f32_16x16x32_bf16 v[0:3], v[228:231], v[196:199], v[0:3]
	s_add_i32 s45, s45, 2
	s_add_u32 s24, s24, 0x100
	s_addc_u32 s25, s25, 0
	s_add_u32 s43, s43, 0x100
	s_addc_u32 s44, s44, 0
	s_cmp_gt_u32 s45, 13
	s_barrier
	s_cbranch_scc0 .LBB0_885
	v_lshl_add_u32 v198, s6, 8, v177
	v_lshl_or_b32 v196, s7, 8, v208
	v_ashrrev_i32_e32 v199, 31, v198
	v_ashrrev_i32_e32 v197, 31, v196
	v_lshlrev_b64 v[130:131], 10, v[198:199]
	v_lshl_add_u64 v[130:131], v[130:131], 0, v[196:197]
	v_lshlrev_b64 v[130:131], 1, v[130:131]
	v_lshl_add_u64 v[132:133], s[84:85], 0, v[130:131]
	global_load_dwordx4 v[220:223], v[132:133], off
	v_lshl_add_u64 v[132:133], s[82:83], 0, v[130:131]
	global_load_dwordx4 v[224:227], v[132:133], off
	s_waitcnt vmcnt(0)
	v_fmamk_f32 v128, v128, 0x3a800000, v212
	v_or_b32_e32 v204, 16, v198
	v_mul_f32_e32 v129, 0x4b800000, v128
	v_ashrrev_i32_e32 v205, 31, v204
	v_cmp_gt_f32_e64 s[6:7], s40, v128
	v_or_b32_e32 v130, 0x100, v130
	v_or_b32_e32 v200, 48, v198
	v_cndmask_b32_e64 v136, v128, v129, s[6:7]
	v_lshlrev_b64 v[128:129], 10, v[204:205]
	v_lshl_add_u64 v[128:129], v[128:129], 0, v[196:197]
	v_rsq_f32_e32 v242, v136
	v_lshlrev_b64 v[128:129], 1, v[128:129]
	v_lshl_add_u64 v[136:137], s[84:85], 0, v[130:131]
	v_lshl_add_u64 v[130:131], s[82:83], 0, v[130:131]
	v_lshl_add_u64 v[138:139], s[84:85], 0, v[128:129]
	v_lshl_add_u64 v[140:141], s[82:83], 0, v[128:129]
	global_load_dwordx4 v[228:231], v[136:137], off
	global_load_dwordx4 v[232:235], v[130:131], off
	global_load_dwordx4 v[172:175], v[138:139], off
	global_load_dwordx4 v[168:171], v[140:141], off
	v_ashrrev_i32_e32 v201, 31, v200
	v_lshlrev_b64 v[134:135], 10, v[200:201]
	v_lshl_add_u64 v[134:135], v[134:135], 0, v[196:197]
	v_lshlrev_b64 v[134:135], 1, v[134:135]
	v_lshl_add_u64 v[146:147], s[84:85], 0, v[134:135]
	v_lshl_add_u64 v[148:149], s[82:83], 0, v[134:135]
	v_or_b32_e32 v134, 0x100, v134
	v_lshl_add_u64 v[238:239], s[84:85], 0, v[134:135]
	v_lshl_add_u64 v[240:241], s[82:83], 0, v[134:135]
	v_mul_f32_e32 v134, 0x45800000, v242
	v_cndmask_b32_e64 v242, v242, v134, s[6:7]
	v_mul_f32_e32 v120, v242, v120
	v_mul_f32_e32 v120, 0xbfb8aa3b, v120
	v_exp_f32_e32 v120, v120
	v_or_b32_e32 v202, 32, v198
	v_ashrrev_i32_e32 v203, 31, v202
	v_lshlrev_b64 v[132:133], 10, v[202:203]
	v_mul_f32_e32 v121, v242, v121
	v_lshl_add_u64 v[132:133], v[132:133], 0, v[196:197]
	v_add_f32_e32 v120, 1.0, v120
	v_mul_f32_e32 v121, 0xbfb8aa3b, v121
	v_lshlrev_b64 v[132:133], 1, v[132:133]
	v_rcp_f32_e32 v120, v120
	v_exp_f32_e32 v121, v121
	v_or_b32_e32 v128, 0x100, v128
	v_lshl_add_u64 v[142:143], s[84:85], 0, v[132:133]
	v_lshl_add_u64 v[144:145], s[82:83], 0, v[132:133]
	v_or_b32_e32 v132, 0x100, v132
	v_lshl_add_u64 v[130:131], s[84:85], 0, v[128:129]
	v_lshl_add_u64 v[128:129], s[82:83], 0, v[128:129]
	global_load_dwordx4 v[156:159], v[142:143], off
	global_load_dwordx4 v[152:155], v[144:145], off
	v_lshl_add_u64 v[144:145], s[84:85], 0, v[132:133]
	v_lshl_add_u64 v[132:133], s[82:83], 0, v[132:133]
	global_load_dwordx4 v[140:143], v[146:147], off
	global_load_dwordx4 v[136:139], v[148:149], off
; __device__ __forceinline__ unsigned cvt_pk_bf16(float lo, float hi) { unsigned r; asm volatile("v_cvt_pk_bf16_f32 %0, %1, %2" : "=v"(r) : "v"(lo), "v"(hi)); return r; }
; __device__ __forceinline__ float sigmoidf_(float x) { return frcp(1.0f + __expf(-x)); }
;     __device__ __forceinline__ void operator()(const f32x4 (&acc)[2][2][4][2], const Unit& u, int wr, int wc, int fr, int fq, const float (&epre)[8]) const {
;     ...
;             for (int m = 0; m < 4; ++m) { const int row = row0 + ai * 128 + m * 16;
;                 const float rstd = rsqrtf(epre[ai * 4 + m] * (1.0f / DM) + EPS);
;                 float ss = 0.f;
; #pragma unroll
;                 for (int bj = 0; bj < 2; ++bj) { const size_t o = (size_t)row * DM + col0 + bj * 128;
;                     f32x4 h0, h1, p0, p1; unpack8(hw[m][bj], h0, h1); unpack8(pw[m][bj], p0, p1);
; #pragma unroll
;                     for (int j = 0; j < 4; ++j) { h0[j] += sigmoidf_(acc[ai][bj][m][0][j] * rstd) * p0[j]; h1[j] += sigmoidf_(acc[ai][bj][m][1][j] * rstd) * p1[j]; }
;                     u32x4 w; w.x = cvt_pk_bf16(h0[0], h0[1]); w.y = cvt_pk_bf16(h0[2], h0[3]); w.z = cvt_pk_bf16(h1[0], h1[1]); w.w = cvt_pk_bf16(h1[2], h1[3]);
;                     *(u32x4*)(H3 + o) = w;
;                     ss += (h0[0] * h0[0] + h0[1] * h0[1]) + (h0[2] * h0[2] + h0[3] * h0[3]) + (h1[0] * h1[0] + h1[1] * h1[1]) + (h1[2] * h1[2] + h1[3] * h1[3]); }
	global_load_dwordx4 v[164:167], v[130:131], off
	global_load_dwordx4 v[160:163], v[128:129], off
	s_nop 0
	global_load_dwordx4 v[148:151], v[144:145], off
	s_nop 0
	global_load_dwordx4 v[144:147], v[132:133], off
	s_nop 0
	global_load_dwordx4 v[132:135], v[238:239], off
	global_load_dwordx4 v[128:131], v[240:241], off
	v_mul_f32_e32 v122, v242, v122
	v_mul_f32_e32 v122, 0xbfb8aa3b, v122
	v_exp_f32_e32 v122, v122
	v_mul_f32_e32 v124, v242, v124
	v_mul_f32_e32 v125, v242, v125
	v_mul_f32_e32 v123, v242, v123
	v_mul_f32_e32 v124, 0xbfb8aa3b, v124
	v_mul_f32_e32 v125, 0xbfb8aa3b, v125
	v_mul_f32_e32 v123, 0xbfb8aa3b, v123
	v_exp_f32_e32 v124, v124
	v_exp_f32_e32 v125, v125
	v_exp_f32_e32 v123, v123
	v_mul_f32_e32 v112, v242, v112
	v_mul_f32_e32 v112, 0xbfb8aa3b, v112
	v_exp_f32_e32 v112, v112
	v_add_f32_e32 v124, 1.0, v124
	v_add_f32_e32 v125, 1.0, v125
	v_add_f32_e32 v123, 1.0, v123
	v_rcp_f32_e32 v124, v124
	v_rcp_f32_e32 v125, v125
	v_rcp_f32_e32 v123, v123
	v_mul_f32_e32 v113, v242, v113
	v_add_f32_e32 v112, 1.0, v112
	v_mul_f32_e32 v113, 0xbfb8aa3b, v113
	v_lshlrev_b32_e32 v240, 16, v222
	v_and_b32_e32 v222, 0xffff0000, v222
	v_lshlrev_b32_e32 v245, 16, v226
	v_fmac_f32_e32 v240, v120, v245
	v_add_f32_e32 v120, 1.0, v121
	v_mul_f32_e32 v121, v242, v126
	v_mul_f32_e32 v121, 0xbfb8aa3b, v121
	v_rcp_f32_e32 v120, v120
	v_exp_f32_e32 v121, v121
	v_and_b32_e32 v226, 0xffff0000, v226
	v_lshlrev_b64 v[236:237], 11, v[198:199]
	v_fmac_f32_e32 v222, v120, v226
	v_add_f32_e32 v120, 1.0, v121
	v_add_f32_e32 v121, 1.0, v122
	v_mul_f32_e32 v122, v242, v127
	v_mul_f32_e32 v122, 0xbfb8aa3b, v122
	v_exp_f32_e32 v122, v122
	v_rcp_f32_e32 v120, v120
	v_rcp_f32_e32 v121, v121
	v_lshlrev_b32_e32 v239, 16, v221
	v_add_f32_e32 v122, 1.0, v122
	v_rcp_f32_e32 v122, v122
	v_lshlrev_b32_e32 v241, 16, v223
	v_lshlrev_b32_e32 v244, 16, v225
	v_lshlrev_b32_e32 v246, 16, v227
	v_rcp_f32_e32 v112, v112
	v_exp_f32_e32 v113, v113
	v_lshlrev_b32_e32 v238, 16, v220
	v_and_b32_e32 v220, 0xffff0000, v220
	v_and_b32_e32 v221, 0xffff0000, v221
	v_and_b32_e32 v223, 0xffff0000, v223
	v_lshlrev_b32_e32 v243, 16, v224
	v_and_b32_e32 v224, 0xffff0000, v224
	v_and_b32_e32 v225, 0xffff0000, v225
	v_and_b32_e32 v227, 0xffff0000, v227
	v_fmac_f32_e32 v239, v120, v244
	v_fmac_f32_e32 v241, v121, v246
	v_lshl_add_u64 v[126:127], s[68:69], 0, v[236:237]
	v_lshlrev_b64 v[120:121], 1, v[196:197]
	v_fmac_f32_e32 v238, v124, v243
	v_fmac_f32_e32 v220, v125, v224
	v_fmac_f32_e32 v221, v122, v225
	v_fmac_f32_e32 v223, v123, v227
	v_cvt_pk_bf16_f32 v122, v238, v220
	v_cvt_pk_bf16_f32 v123, v239, v221
	v_cvt_pk_bf16_f32 v124, v240, v222
	v_cvt_pk_bf16_f32 v125, v241, v223
	v_lshl_add_u64 v[126:127], v[126:127], 0, v[120:121]
	global_store_dwordx4 v[126:127], v[122:125], off
	v_mul_f32_e32 v114, v242, v114
	v_mul_f32_e32 v114, 0xbfb8aa3b, v114
	v_mul_f32_e32 v122, v220, v220
	v_mul_f32_e32 v123, v221, v221
	s_waitcnt vmcnt(0)
	v_lshlrev_b32_e32 v125, 16, v229
	v_and_b32_e32 v220, 0xffff0000, v229
	v_lshlrev_b32_e32 v221, 16, v230
	v_lshlrev_b32_e32 v229, 16, v234
	v_fmac_f32_e32 v221, v112, v229
	v_add_f32_e32 v112, 1.0, v113
	v_mul_f32_e32 v113, v242, v118
	v_mul_f32_e32 v113, 0xbfb8aa3b, v113
	v_rcp_f32_e32 v112, v112
	v_exp_f32_e32 v113, v113
	v_exp_f32_e32 v114, v114
	v_fmac_f32_e32 v122, v238, v238
	v_fmac_f32_e32 v123, v239, v239
	v_add_f32_e32 v122, v122, v123
	v_mul_f32_e32 v123, v222, v222
	v_and_b32_e32 v222, 0xffff0000, v230
	v_and_b32_e32 v230, 0xffff0000, v234
	v_mul_f32_e32 v116, v242, v116
	v_mul_f32_e32 v117, v242, v117
	v_fmac_f32_e32 v222, v112, v230
	v_add_f32_e32 v112, 1.0, v113
	v_add_f32_e32 v113, 1.0, v114
	v_mul_f32_e32 v114, v242, v119
	v_mul_f32_e32 v116, 0xbfb8aa3b, v116
	v_mul_f32_e32 v117, 0xbfb8aa3b, v117
	v_mul_f32_e32 v114, 0xbfb8aa3b, v114
	v_mul_f32_e32 v115, v242, v115
	v_exp_f32_e32 v116, v116
	v_exp_f32_e32 v117, v117
	v_exp_f32_e32 v114, v114
	v_mul_f32_e32 v115, 0xbfb8aa3b, v115
	v_exp_f32_e32 v115, v115
	v_add_f32_e32 v116, 1.0, v116
	v_add_f32_e32 v117, 1.0, v117
	v_add_f32_e32 v114, 1.0, v114
	v_fmac_f32_e32 v123, v240, v240
	v_rcp_f32_e32 v116, v116
	v_rcp_f32_e32 v117, v117
	v_rcp_f32_e32 v112, v112
	v_rcp_f32_e32 v113, v113
	v_rcp_f32_e32 v114, v114
	v_add_f32_e32 v115, 1.0, v115
	v_add_f32_e32 v122, v123, v122
	v_mul_f32_e32 v123, v223, v223
	v_rcp_f32_e32 v115, v115
	v_fmac_f32_e32 v123, v241, v241
	v_add_f32_e32 v122, v123, v122
	v_lshlrev_b32_e32 v123, 16, v228
	v_and_b32_e32 v124, 0xffff0000, v228
	v_lshlrev_b32_e32 v223, 16, v231
	v_and_b32_e32 v224, 0xffff0000, v231
	v_lshlrev_b32_e32 v225, 16, v232
	v_and_b32_e32 v226, 0xffff0000, v232
	v_lshlrev_b32_e32 v227, 16, v233
	v_and_b32_e32 v228, 0xffff0000, v233
	v_lshlrev_b32_e32 v231, 16, v235
	v_and_b32_e32 v232, 0xffff0000, v235
	v_fmac_f32_e32 v123, v116, v225
	v_fmac_f32_e32 v124, v117, v226
	v_fmac_f32_e32 v125, v112, v227
	v_fmac_f32_e32 v223, v113, v231
	v_fmac_f32_e32 v220, v114, v228
	v_cvt_pk_bf16_f32 v112, v123, v124
	v_cvt_pk_bf16_f32 v113, v125, v220
	v_cvt_pk_bf16_f32 v114, v221, v222
	v_fmac_f32_e32 v224, v115, v232
	v_cvt_pk_bf16_f32 v115, v223, v224
	global_store_dwordx4 v[126:127], v[112:115], off offset:256
	v_lshlrev_b32_e32 v116, 16, v172
	v_and_b32_e32 v117, 0xffff0000, v172
	v_fmamk_f32 v114, v219, 0x3a800000, v212
	v_mul_f32_e32 v112, v124, v124
	v_mul_f32_e32 v113, v220, v220
	v_mul_f32_e32 v115, 0x4b800000, v114
	v_cmp_gt_f32_e64 s[6:7], s40, v114
	v_fmac_f32_e32 v112, v123, v123
	v_fmac_f32_e32 v113, v125, v125
	v_cndmask_b32_e64 v114, v114, v115, s[6:7]
	v_add_f32_e32 v112, v112, v113
	v_mul_f32_e32 v113, v222, v222
	v_rsq_f32_e32 v114, v114
	v_fmac_f32_e32 v113, v221, v221
; __device__ __forceinline__ unsigned cvt_pk_bf16(float lo, float hi) { unsigned r; asm volatile("v_cvt_pk_bf16_f32 %0, %1, %2" : "=v"(r) : "v"(lo), "v"(hi)); return r; }
; __device__ __forceinline__ float sigmoidf_(float x) { return frcp(1.0f + __expf(-x)); }
;     __device__ __forceinline__ void operator()(const f32x4 (&acc)[2][2][4][2], const Unit& u, int wr, int wc, int fr, int fq, const float (&epre)[8]) const {
;     ...
;             for (int m = 0; m < 4; ++m) { const int row = row0 + ai * 128 + m * 16;
;                 const float rstd = rsqrtf(epre[ai * 4 + m] * (1.0f / DM) + EPS);
;                 float ss = 0.f;
; #pragma unroll
;                 for (int bj = 0; bj < 2; ++bj) { const size_t o = (size_t)row * DM + col0 + bj * 128;
;                     f32x4 h0, h1, p0, p1; unpack8(hw[m][bj], h0, h1); unpack8(pw[m][bj], p0, p1);
; #pragma unroll
;                     for (int j = 0; j < 4; ++j) { h0[j] += sigmoidf_(acc[ai][bj][m][0][j] * rstd) * p0[j]; h1[j] += sigmoidf_(acc[ai][bj][m][1][j] * rstd) * p1[j]; }
;                     u32x4 w; w.x = cvt_pk_bf16(h0[0], h0[1]); w.y = cvt_pk_bf16(h0[2], h0[3]); w.z = cvt_pk_bf16(h1[0], h1[1]); w.w = cvt_pk_bf16(h1[2], h1[3]);
;                     *(u32x4*)(H3 + o) = w;
;                     ss += (h0[0] * h0[0] + h0[1] * h0[1]) + (h0[2] * h0[2] + h0[3] * h0[3]) + (h1[0] * h1[0] + h1[1] * h1[1]) + (h1[2] * h1[2] + h1[3] * h1[3]); }
	v_add_f32_e32 v112, v113, v112
	v_mul_f32_e32 v113, v224, v224
	v_fmac_f32_e32 v113, v223, v223
	v_add_f32_e32 v112, v113, v112
	v_mul_f32_e32 v113, 0x45800000, v114
	v_cndmask_b32_e64 v113, v114, v113, s[6:7]
	v_mul_f32_e32 v104, v113, v104
	v_mul_f32_e32 v104, 0xbfb8aa3b, v104
	v_exp_f32_e32 v104, v104
	v_mul_f32_e32 v105, v113, v105
	v_mul_f32_e32 v105, 0xbfb8aa3b, v105
	v_exp_f32_e32 v105, v105
	v_add_f32_e32 v104, 1.0, v104
	v_rcp_f32_e32 v104, v104
	v_add_f32_e32 v112, v122, v112
	v_lshlrev_b32_e32 v122, 16, v174
	v_lshlrev_b32_e32 v172, 16, v170
	v_fmac_f32_e32 v122, v104, v172
	v_add_f32_e32 v104, 1.0, v105
	v_mul_f32_e32 v105, v113, v110
	v_mul_f32_e32 v106, v113, v106
	v_mul_f32_e32 v105, 0xbfb8aa3b, v105
	v_mul_f32_e32 v106, 0xbfb8aa3b, v106
	v_rcp_f32_e32 v104, v104
	v_exp_f32_e32 v105, v105
	v_exp_f32_e32 v106, v106
	v_and_b32_e32 v123, 0xffff0000, v174
	v_mul_f32_e32 v108, v113, v108
	v_and_b32_e32 v170, 0xffff0000, v170
	v_mul_f32_e32 v109, v113, v109
	v_mul_f32_e32 v108, 0xbfb8aa3b, v108
	v_mul_f32_e32 v109, 0xbfb8aa3b, v109
	v_fmac_f32_e32 v123, v104, v170
	v_add_f32_e32 v104, 1.0, v105
	v_add_f32_e32 v105, 1.0, v106
	v_mul_f32_e32 v106, v113, v111
	v_exp_f32_e32 v108, v108
	v_exp_f32_e32 v109, v109
	v_mul_f32_e32 v106, 0xbfb8aa3b, v106
	v_mul_f32_e32 v107, v113, v107
	v_exp_f32_e32 v106, v106
	v_mul_f32_e32 v107, 0xbfb8aa3b, v107
	v_exp_f32_e32 v107, v107
	v_mul_f32_e32 v96, v113, v96
	v_add_f32_e32 v108, 1.0, v108
	v_add_f32_e32 v109, 1.0, v109
	v_mul_f32_e32 v96, 0xbfb8aa3b, v96
	v_rcp_f32_e32 v108, v108
	v_rcp_f32_e32 v109, v109
	v_add_f32_e32 v106, 1.0, v106
	v_exp_f32_e32 v96, v96
	v_rcp_f32_e32 v104, v104
	v_rcp_f32_e32 v105, v105
	v_rcp_f32_e32 v106, v106
	v_add_f32_e32 v107, 1.0, v107
	v_rcp_f32_e32 v107, v107
	v_lshlrev_b64 v[114:115], 11, v[204:205]
	v_lshlrev_b32_e32 v126, 16, v168
	v_and_b32_e32 v127, 0xffff0000, v168
	v_mul_f32_e32 v97, v113, v97
	v_lshlrev_b32_e32 v118, 16, v173
	v_and_b32_e32 v119, 0xffff0000, v173
	v_lshlrev_b32_e32 v124, 16, v175
	v_lshlrev_b32_e32 v168, 16, v169
	v_and_b32_e32 v169, 0xffff0000, v169
	v_lshlrev_b32_e32 v173, 16, v171
	v_fmac_f32_e32 v116, v108, v126
	v_fmac_f32_e32 v117, v109, v127
	v_lshl_add_u64 v[108:109], s[68:69], 0, v[114:115]
	v_add_f32_e32 v96, 1.0, v96
	v_mul_f32_e32 v97, 0xbfb8aa3b, v97
	v_and_b32_e32 v125, 0xffff0000, v175
	v_and_b32_e32 v171, 0xffff0000, v171
	v_fmac_f32_e32 v118, v104, v168
	v_fmac_f32_e32 v124, v105, v173
	v_fmac_f32_e32 v119, v106, v169
	v_cvt_pk_bf16_f32 v104, v116, v117
	v_cvt_pk_bf16_f32 v105, v118, v119
	v_lshl_add_u64 v[108:109], v[108:109], 0, v[120:121]
	v_rcp_f32_e32 v96, v96
	v_exp_f32_e32 v97, v97
	v_fmac_f32_e32 v125, v107, v171
	v_cvt_pk_bf16_f32 v106, v122, v123
	v_cvt_pk_bf16_f32 v107, v124, v125
	global_store_dwordx4 v[108:109], v[104:107], off
	v_lshlrev_b32_e32 v111, 16, v166
	v_mul_f32_e32 v98, v113, v98
	v_mul_f32_e32 v104, v117, v117
	v_mul_f32_e32 v105, v119, v119
	v_fmac_f32_e32 v104, v116, v116
	v_fmac_f32_e32 v105, v118, v118
	v_add_f32_e32 v104, v104, v105
	v_mul_f32_e32 v105, v123, v123
	v_lshlrev_b32_e32 v123, 16, v162
	v_fmac_f32_e32 v111, v96, v123
	v_add_f32_e32 v96, 1.0, v97
	v_mul_f32_e32 v97, v113, v102
	v_mul_f32_e32 v97, 0xbfb8aa3b, v97
	v_mul_f32_e32 v98, 0xbfb8aa3b, v98
	v_rcp_f32_e32 v96, v96
	v_exp_f32_e32 v97, v97
	v_exp_f32_e32 v98, v98
	v_fmac_f32_e32 v105, v122, v122
	v_add_f32_e32 v104, v105, v104
	v_mul_f32_e32 v105, v125, v125
	v_fmac_f32_e32 v105, v124, v124
	v_and_b32_e32 v114, 0xffff0000, v166
	v_and_b32_e32 v124, 0xffff0000, v162
	v_mul_f32_e32 v100, v113, v100
	v_mul_f32_e32 v101, v113, v101
	v_fmac_f32_e32 v114, v96, v124
	v_add_f32_e32 v96, 1.0, v97
	v_add_f32_e32 v97, 1.0, v98
	v_mul_f32_e32 v98, v113, v103
	v_mul_f32_e32 v100, 0xbfb8aa3b, v100
	v_mul_f32_e32 v101, 0xbfb8aa3b, v101
	v_mul_f32_e32 v98, 0xbfb8aa3b, v98
	v_mul_f32_e32 v99, v113, v99
	v_exp_f32_e32 v100, v100
	v_exp_f32_e32 v101, v101
	v_exp_f32_e32 v98, v98
	v_mul_f32_e32 v99, 0xbfb8aa3b, v99
	v_exp_f32_e32 v99, v99
	v_add_f32_e32 v100, 1.0, v100
	v_add_f32_e32 v101, 1.0, v101
	v_add_f32_e32 v98, 1.0, v98
	v_rcp_f32_e32 v100, v100
	v_rcp_f32_e32 v101, v101
	v_rcp_f32_e32 v96, v96
	v_rcp_f32_e32 v97, v97
	v_rcp_f32_e32 v98, v98
	v_add_f32_e32 v99, 1.0, v99
	v_rcp_f32_e32 v99, v99
	v_add_f32_e32 v104, v105, v104
	v_lshlrev_b32_e32 v105, 16, v164
	v_and_b32_e32 v106, 0xffff0000, v164
	v_lshlrev_b32_e32 v107, 16, v165
	v_and_b32_e32 v110, 0xffff0000, v165
	v_lshlrev_b32_e32 v115, 16, v167
	v_lshlrev_b32_e32 v117, 16, v160
	v_and_b32_e32 v118, 0xffff0000, v160
	v_lshlrev_b32_e32 v119, 16, v161
	v_and_b32_e32 v122, 0xffff0000, v161
	v_lshlrev_b32_e32 v125, 16, v163
	v_and_b32_e32 v116, 0xffff0000, v167
	v_and_b32_e32 v126, 0xffff0000, v163
	v_fmac_f32_e32 v105, v100, v117
	v_fmac_f32_e32 v106, v101, v118
	v_fmac_f32_e32 v107, v96, v119
	v_fmac_f32_e32 v115, v97, v125
	v_fmac_f32_e32 v110, v98, v122
	v_cvt_pk_bf16_f32 v96, v105, v106
	v_cvt_pk_bf16_f32 v97, v107, v110
	v_cvt_pk_bf16_f32 v98, v111, v114
	v_fmac_f32_e32 v116, v99, v126
	v_cvt_pk_bf16_f32 v99, v115, v116
	global_store_dwordx4 v[108:109], v[96:99], off offset:256
	v_lshlrev_b32_e32 v113, 16, v154
	v_lshlrev_b32_e32 v100, 16, v156
	v_mul_f32_e32 v96, v106, v106
	v_mul_f32_e32 v97, v110, v110
	v_fmamk_f32 v98, v218, 0x3a800000, v212
	v_fmac_f32_e32 v96, v105, v105
	v_fmac_f32_e32 v97, v107, v107
	v_mul_f32_e32 v99, 0x4b800000, v98
	v_cmp_gt_f32_e64 s[6:7], s40, v98
	v_add_f32_e32 v96, v96, v97
	v_mul_f32_e32 v97, v114, v114
	v_cndmask_b32_e64 v98, v98, v99, s[6:7]
	v_fmac_f32_e32 v97, v111, v111
	v_rsq_f32_e32 v98, v98
	v_add_f32_e32 v96, v97, v96
	v_mul_f32_e32 v97, v116, v116
; __device__ __forceinline__ unsigned cvt_pk_bf16(float lo, float hi) { unsigned r; asm volatile("v_cvt_pk_bf16_f32 %0, %1, %2" : "=v"(r) : "v"(lo), "v"(hi)); return r; }
; __device__ __forceinline__ float sigmoidf_(float x) { return frcp(1.0f + __expf(-x)); }
;     __device__ __forceinline__ void operator()(const f32x4 (&acc)[2][2][4][2], const Unit& u, int wr, int wc, int fr, int fq, const float (&epre)[8]) const {
;     ...
;             for (int m = 0; m < 4; ++m) { const int row = row0 + ai * 128 + m * 16;
;                 const float rstd = rsqrtf(epre[ai * 4 + m] * (1.0f / DM) + EPS);
;                 float ss = 0.f;
; #pragma unroll
;                 for (int bj = 0; bj < 2; ++bj) { const size_t o = (size_t)row * DM + col0 + bj * 128;
;                     f32x4 h0, h1, p0, p1; unpack8(hw[m][bj], h0, h1); unpack8(pw[m][bj], p0, p1);
; #pragma unroll
;                     for (int j = 0; j < 4; ++j) { h0[j] += sigmoidf_(acc[ai][bj][m][0][j] * rstd) * p0[j]; h1[j] += sigmoidf_(acc[ai][bj][m][1][j] * rstd) * p1[j]; }
;                     u32x4 w; w.x = cvt_pk_bf16(h0[0], h0[1]); w.y = cvt_pk_bf16(h0[2], h0[3]); w.z = cvt_pk_bf16(h1[0], h1[1]); w.w = cvt_pk_bf16(h1[2], h1[3]);
;                     *(u32x4*)(H3 + o) = w;
;                     ss += (h0[0] * h0[0] + h0[1] * h0[1]) + (h0[2] * h0[2] + h0[3] * h0[3]) + (h1[0] * h1[0] + h1[1] * h1[1]) + (h1[2] * h1[2] + h1[3] * h1[3]); }
	v_fmac_f32_e32 v97, v115, v115
	v_add_f32_e32 v96, v97, v96
	v_add_f32_e32 v99, v104, v96
	v_mul_f32_e32 v96, 0x45800000, v98
	v_cndmask_b32_e64 v98, v98, v96, s[6:7]
	v_mul_f32_e32 v88, v98, v88
	v_mul_f32_e32 v88, 0xbfb8aa3b, v88
	v_exp_f32_e32 v88, v88
	v_mul_f32_e32 v89, v98, v89
	v_mul_f32_e32 v89, 0xbfb8aa3b, v89
	v_exp_f32_e32 v89, v89
	v_add_f32_e32 v88, 1.0, v88
	v_rcp_f32_e32 v88, v88
	v_lshlrev_b32_e32 v104, 16, v158
	v_mul_f32_e32 v90, v98, v90
	v_mul_f32_e32 v90, 0xbfb8aa3b, v90
	v_fmac_f32_e32 v104, v88, v113
	v_add_f32_e32 v88, 1.0, v89
	v_mul_f32_e32 v89, v98, v94
	v_mul_f32_e32 v89, 0xbfb8aa3b, v89
	v_rcp_f32_e32 v88, v88
	v_exp_f32_e32 v89, v89
	v_exp_f32_e32 v90, v90
	v_and_b32_e32 v105, 0xffff0000, v158
	v_mul_f32_e32 v92, v98, v92
	v_and_b32_e32 v114, 0xffff0000, v154
	v_mul_f32_e32 v93, v98, v93
	v_mul_f32_e32 v92, 0xbfb8aa3b, v92
	v_mul_f32_e32 v93, 0xbfb8aa3b, v93
	v_fmac_f32_e32 v105, v88, v114
	v_add_f32_e32 v88, 1.0, v89
	v_add_f32_e32 v89, 1.0, v90
	v_mul_f32_e32 v90, v98, v95
	v_exp_f32_e32 v92, v92
	v_exp_f32_e32 v93, v93
	v_mul_f32_e32 v90, 0xbfb8aa3b, v90
	v_mul_f32_e32 v91, v98, v91
	v_exp_f32_e32 v90, v90
	v_mul_f32_e32 v91, 0xbfb8aa3b, v91
	v_exp_f32_e32 v91, v91
	v_mul_f32_e32 v80, v98, v80
	v_add_f32_e32 v92, 1.0, v92
	v_add_f32_e32 v93, 1.0, v93
	v_mul_f32_e32 v80, 0xbfb8aa3b, v80
	v_rcp_f32_e32 v92, v92
	v_rcp_f32_e32 v93, v93
	v_add_f32_e32 v90, 1.0, v90
	v_exp_f32_e32 v80, v80
	v_rcp_f32_e32 v88, v88
	v_rcp_f32_e32 v89, v89
	v_rcp_f32_e32 v90, v90
	v_add_f32_e32 v91, 1.0, v91
	v_rcp_f32_e32 v91, v91
	v_lshlrev_b64 v[96:97], 11, v[202:203]
	v_and_b32_e32 v101, 0xffff0000, v156
	v_lshlrev_b32_e32 v108, 16, v152
	v_and_b32_e32 v109, 0xffff0000, v152
	v_mul_f32_e32 v81, v98, v81
	v_lshlrev_b32_e32 v102, 16, v157
	v_and_b32_e32 v103, 0xffff0000, v157
	v_lshlrev_b32_e32 v106, 16, v159
	v_lshlrev_b32_e32 v110, 16, v153
	v_and_b32_e32 v111, 0xffff0000, v153
	v_lshlrev_b32_e32 v115, 16, v155
	v_fmac_f32_e32 v100, v92, v108
	v_fmac_f32_e32 v101, v93, v109
	v_lshl_add_u64 v[92:93], s[68:69], 0, v[96:97]
	v_add_f32_e32 v80, 1.0, v80
	v_mul_f32_e32 v81, 0xbfb8aa3b, v81
	v_and_b32_e32 v107, 0xffff0000, v159
	v_and_b32_e32 v116, 0xffff0000, v155
	v_fmac_f32_e32 v102, v88, v110
	v_fmac_f32_e32 v106, v89, v115
	v_fmac_f32_e32 v103, v90, v111
	v_cvt_pk_bf16_f32 v88, v100, v101
	v_cvt_pk_bf16_f32 v89, v102, v103
	v_lshl_add_u64 v[92:93], v[92:93], 0, v[120:121]
	v_rcp_f32_e32 v80, v80
	v_exp_f32_e32 v81, v81
	v_fmac_f32_e32 v107, v91, v116
	v_cvt_pk_bf16_f32 v90, v104, v105
	v_cvt_pk_bf16_f32 v91, v106, v107
	global_store_dwordx4 v[92:93], v[88:91], off
	v_lshlrev_b32_e32 v95, 16, v150
	v_mul_f32_e32 v82, v98, v82
	v_mul_f32_e32 v88, v101, v101
	v_mul_f32_e32 v89, v103, v103
	v_fmac_f32_e32 v88, v100, v100
	v_fmac_f32_e32 v89, v102, v102
	v_add_f32_e32 v88, v88, v89
	v_mul_f32_e32 v89, v105, v105
	v_lshlrev_b32_e32 v105, 16, v146
	v_fmac_f32_e32 v95, v80, v105
	v_add_f32_e32 v80, 1.0, v81
	v_mul_f32_e32 v81, v98, v86
	v_mul_f32_e32 v81, 0xbfb8aa3b, v81
	v_mul_f32_e32 v82, 0xbfb8aa3b, v82
	v_rcp_f32_e32 v80, v80
	v_exp_f32_e32 v81, v81
	v_exp_f32_e32 v82, v82
	v_fmac_f32_e32 v89, v104, v104
	v_add_f32_e32 v88, v89, v88
	v_mul_f32_e32 v89, v107, v107
	v_fmac_f32_e32 v89, v106, v106
	v_and_b32_e32 v96, 0xffff0000, v150
	v_and_b32_e32 v106, 0xffff0000, v146
	v_mul_f32_e32 v84, v98, v84
	v_mul_f32_e32 v85, v98, v85
	v_fmac_f32_e32 v96, v80, v106
	v_add_f32_e32 v80, 1.0, v81
	v_add_f32_e32 v81, 1.0, v82
	v_mul_f32_e32 v82, v98, v87
	v_mul_f32_e32 v84, 0xbfb8aa3b, v84
	v_mul_f32_e32 v85, 0xbfb8aa3b, v85
	v_mul_f32_e32 v82, 0xbfb8aa3b, v82
	v_mul_f32_e32 v83, v98, v83
	v_exp_f32_e32 v84, v84
	v_exp_f32_e32 v85, v85
	v_exp_f32_e32 v82, v82
	v_mul_f32_e32 v83, 0xbfb8aa3b, v83
	v_exp_f32_e32 v83, v83
	v_add_f32_e32 v84, 1.0, v84
	v_add_f32_e32 v85, 1.0, v85
	v_add_f32_e32 v82, 1.0, v82
	v_rcp_f32_e32 v84, v84
	v_rcp_f32_e32 v85, v85
	v_rcp_f32_e32 v80, v80
	v_rcp_f32_e32 v81, v81
	v_rcp_f32_e32 v82, v82
	v_add_f32_e32 v83, 1.0, v83
	v_rcp_f32_e32 v83, v83
	v_add_f32_e32 v88, v89, v88
	v_lshlrev_b32_e32 v89, 16, v148
	v_and_b32_e32 v90, 0xffff0000, v148
	v_lshlrev_b32_e32 v91, 16, v149
	v_and_b32_e32 v94, 0xffff0000, v149
	v_lshlrev_b32_e32 v97, 16, v151
	v_lshlrev_b32_e32 v101, 16, v144
	v_and_b32_e32 v102, 0xffff0000, v144
	v_lshlrev_b32_e32 v103, 16, v145
	v_and_b32_e32 v104, 0xffff0000, v145
	v_lshlrev_b32_e32 v107, 16, v147
	v_and_b32_e32 v100, 0xffff0000, v151
	v_and_b32_e32 v108, 0xffff0000, v147
	v_fmac_f32_e32 v89, v84, v101
	v_fmac_f32_e32 v90, v85, v102
	v_fmac_f32_e32 v91, v80, v103
	v_fmac_f32_e32 v97, v81, v107
	v_fmac_f32_e32 v94, v82, v104
	v_cvt_pk_bf16_f32 v80, v89, v90
	v_cvt_pk_bf16_f32 v81, v91, v94
	v_cvt_pk_bf16_f32 v82, v95, v96
	v_fmac_f32_e32 v100, v83, v108
	v_cvt_pk_bf16_f32 v83, v97, v100
	global_store_dwordx4 v[92:93], v[80:83], off offset:256
	v_lshlrev_b32_e32 v84, 16, v140
	v_and_b32_e32 v85, 0xffff0000, v140
	v_mul_f32_e32 v80, v90, v90
	v_mul_f32_e32 v81, v94, v94
	v_fmamk_f32 v82, v217, 0x3a800000, v212
	v_fmac_f32_e32 v80, v89, v89
	v_fmac_f32_e32 v81, v91, v91
	v_mul_f32_e32 v83, 0x4b800000, v82
	v_cmp_gt_f32_e64 s[6:7], s40, v82
	v_add_f32_e32 v80, v80, v81
	v_mul_f32_e32 v81, v96, v96
	v_cndmask_b32_e64 v82, v82, v83, s[6:7]
	v_fmac_f32_e32 v81, v95, v95
	v_rsq_f32_e32 v82, v82
	v_add_f32_e32 v80, v81, v80
	v_mul_f32_e32 v81, v100, v100
	v_fmac_f32_e32 v81, v97, v97
	v_add_f32_e32 v80, v81, v80
	v_add_f32_e32 v83, v88, v80
	v_mul_f32_e32 v80, 0x45800000, v82
	v_cndmask_b32_e64 v82, v82, v80, s[6:7]
	v_mul_f32_e32 v72, v82, v72
	v_mul_f32_e32 v72, 0xbfb8aa3b, v72
	v_exp_f32_e32 v72, v72
; __device__ __forceinline__ unsigned cvt_pk_bf16(float lo, float hi) { unsigned r; asm volatile("v_cvt_pk_bf16_f32 %0, %1, %2" : "=v"(r) : "v"(lo), "v"(hi)); return r; }
; __device__ __forceinline__ float sigmoidf_(float x) { return frcp(1.0f + __expf(-x)); }
;     __device__ __forceinline__ void operator()(const f32x4 (&acc)[2][2][4][2], const Unit& u, int wr, int wc, int fr, int fq, const float (&epre)[8]) const {
;     ...
;             for (int m = 0; m < 4; ++m) { const int row = row0 + ai * 128 + m * 16;
;                 const float rstd = rsqrtf(epre[ai * 4 + m] * (1.0f / DM) + EPS);
;                 float ss = 0.f;
; #pragma unroll
;                 for (int bj = 0; bj < 2; ++bj) { const size_t o = (size_t)row * DM + col0 + bj * 128;
;                     f32x4 h0, h1, p0, p1; unpack8(hw[m][bj], h0, h1); unpack8(pw[m][bj], p0, p1);
; #pragma unroll
;                     for (int j = 0; j < 4; ++j) { h0[j] += sigmoidf_(acc[ai][bj][m][0][j] * rstd) * p0[j]; h1[j] += sigmoidf_(acc[ai][bj][m][1][j] * rstd) * p1[j]; }
;                     u32x4 w; w.x = cvt_pk_bf16(h0[0], h0[1]); w.y = cvt_pk_bf16(h0[2], h0[3]); w.z = cvt_pk_bf16(h1[0], h1[1]); w.w = cvt_pk_bf16(h1[2], h1[3]);
;                     *(u32x4*)(H3 + o) = w;
;                     ss += (h0[0] * h0[0] + h0[1] * h0[1]) + (h0[2] * h0[2] + h0[3] * h0[3]) + (h1[0] * h1[0] + h1[1] * h1[1]) + (h1[2] * h1[2] + h1[3] * h1[3]); }
;                 ssv[m] = ss;
;             }
; #pragma unroll
;             for (int m = 0; m < 4; ++m) ssv[m] += __shfl_xor(ssv[m], 16);
; #pragma unroll
;             for (int m = 0; m < 4; ++m) ssv[m] += __shfl_xor(ssv[m], 32);
;             if (fq == 0) {
; #pragma unroll
;                 for (int m = 0; m < 4; ++m) atomicAdd(sumsq3 + row0 + ai * 128 + m * 16, ssv[m]); }
	v_mul_f32_e32 v73, v82, v73
	v_mul_f32_e32 v73, 0xbfb8aa3b, v73
	v_exp_f32_e32 v73, v73
	v_add_f32_e32 v72, 1.0, v72
	v_rcp_f32_e32 v72, v72
	v_lshlrev_b32_e32 v88, 16, v142
	v_lshlrev_b32_e32 v96, 16, v138
	v_mul_f32_e32 v74, v82, v74
	v_fmac_f32_e32 v88, v72, v96
	v_add_f32_e32 v72, 1.0, v73
	v_mul_f32_e32 v73, v82, v78
	v_mul_f32_e32 v73, 0xbfb8aa3b, v73
	v_mul_f32_e32 v74, 0xbfb8aa3b, v74
	v_rcp_f32_e32 v72, v72
	v_exp_f32_e32 v73, v73
	v_exp_f32_e32 v74, v74
	v_and_b32_e32 v89, 0xffff0000, v142
	v_mul_f32_e32 v76, v82, v76
	v_and_b32_e32 v97, 0xffff0000, v138
	v_mul_f32_e32 v77, v82, v77
	v_mul_f32_e32 v76, 0xbfb8aa3b, v76
	v_mul_f32_e32 v77, 0xbfb8aa3b, v77
	v_fmac_f32_e32 v89, v72, v97
	v_add_f32_e32 v72, 1.0, v73
	v_add_f32_e32 v73, 1.0, v74
	v_mul_f32_e32 v74, v82, v79
	v_exp_f32_e32 v76, v76
	v_exp_f32_e32 v77, v77
	v_mul_f32_e32 v74, 0xbfb8aa3b, v74
	v_mul_f32_e32 v75, v82, v75
	v_exp_f32_e32 v74, v74
	v_mul_f32_e32 v75, 0xbfb8aa3b, v75
	v_exp_f32_e32 v75, v75
	v_mul_f32_e32 v64, v82, v64
	v_add_f32_e32 v76, 1.0, v76
	v_add_f32_e32 v77, 1.0, v77
	v_mul_f32_e32 v64, 0xbfb8aa3b, v64
	v_rcp_f32_e32 v76, v76
	v_rcp_f32_e32 v77, v77
	v_add_f32_e32 v74, 1.0, v74
	v_exp_f32_e32 v64, v64
	v_rcp_f32_e32 v72, v72
	v_rcp_f32_e32 v73, v73
	v_rcp_f32_e32 v74, v74
	v_add_f32_e32 v75, 1.0, v75
	v_rcp_f32_e32 v75, v75
	v_lshlrev_b64 v[80:81], 11, v[200:201]
	v_lshlrev_b32_e32 v92, 16, v136
	v_and_b32_e32 v93, 0xffff0000, v136
	v_mul_f32_e32 v65, v82, v65
	v_lshlrev_b32_e32 v86, 16, v141
	v_and_b32_e32 v87, 0xffff0000, v141
	v_lshlrev_b32_e32 v90, 16, v143
	v_lshlrev_b32_e32 v94, 16, v137
	v_and_b32_e32 v95, 0xffff0000, v137
	v_lshlrev_b32_e32 v98, 16, v139
	v_fmac_f32_e32 v84, v76, v92
	v_fmac_f32_e32 v85, v77, v93
	v_lshl_add_u64 v[76:77], s[68:69], 0, v[80:81]
	v_add_f32_e32 v64, 1.0, v64
	v_mul_f32_e32 v65, 0xbfb8aa3b, v65
	v_and_b32_e32 v91, 0xffff0000, v143
	v_and_b32_e32 v100, 0xffff0000, v139
	v_fmac_f32_e32 v86, v72, v94
	v_fmac_f32_e32 v90, v73, v98
	v_fmac_f32_e32 v87, v74, v95
	v_cvt_pk_bf16_f32 v72, v84, v85
	v_cvt_pk_bf16_f32 v73, v86, v87
	v_lshl_add_u64 v[76:77], v[76:77], 0, v[120:121]
	v_rcp_f32_e32 v64, v64
	v_exp_f32_e32 v65, v65
	v_fmac_f32_e32 v91, v75, v100
	v_cvt_pk_bf16_f32 v74, v88, v89
	v_cvt_pk_bf16_f32 v75, v90, v91
	global_store_dwordx4 v[76:77], v[72:75], off
	v_lshlrev_b32_e32 v80, 16, v134
	v_mul_f32_e32 v66, v82, v66
	v_mul_f32_e32 v72, v85, v85
	v_mul_f32_e32 v73, v87, v87
	v_fmac_f32_e32 v72, v84, v84
	v_fmac_f32_e32 v73, v86, v86
	v_add_f32_e32 v72, v72, v73
	v_mul_f32_e32 v73, v89, v89
	v_lshlrev_b32_e32 v89, 16, v130
	v_fmac_f32_e32 v80, v64, v89
	v_add_f32_e32 v64, 1.0, v65
	v_mul_f32_e32 v65, v82, v70
	v_mul_f32_e32 v65, 0xbfb8aa3b, v65
	v_mul_f32_e32 v66, 0xbfb8aa3b, v66
	v_rcp_f32_e32 v64, v64
	v_exp_f32_e32 v65, v65
	v_exp_f32_e32 v66, v66
	v_fmac_f32_e32 v73, v88, v88
	v_add_f32_e32 v72, v73, v72
	v_mul_f32_e32 v73, v91, v91
	v_fmac_f32_e32 v73, v90, v90
	v_and_b32_e32 v81, 0xffff0000, v134
	v_and_b32_e32 v90, 0xffff0000, v130
	v_mul_f32_e32 v69, v82, v69
	v_fmac_f32_e32 v81, v64, v90
	v_add_f32_e32 v64, 1.0, v65
	v_add_f32_e32 v65, 1.0, v66
	v_mul_f32_e32 v66, v82, v71
	v_mul_f32_e32 v68, v82, v68
	v_mul_f32_e32 v69, 0xbfb8aa3b, v69
	v_mul_f32_e32 v66, 0xbfb8aa3b, v66
	v_mul_f32_e32 v68, 0xbfb8aa3b, v68
	v_exp_f32_e32 v69, v69
	v_exp_f32_e32 v66, v66
	v_exp_f32_e32 v68, v68
	v_mul_f32_e32 v67, v82, v67
	v_mul_f32_e32 v67, 0xbfb8aa3b, v67
	v_add_f32_e32 v69, 1.0, v69
	v_exp_f32_e32 v67, v67
	v_add_f32_e32 v66, 1.0, v66
	v_add_f32_e32 v68, 1.0, v68
	v_rcp_f32_e32 v69, v69
	v_rcp_f32_e32 v66, v66
	v_rcp_f32_e32 v68, v68
	v_rcp_f32_e32 v64, v64
	v_rcp_f32_e32 v65, v65
	v_and_b32_e32 v75, 0xffff0000, v132
	v_and_b32_e32 v79, 0xffff0000, v133
	v_and_b32_e32 v86, 0xffff0000, v128
	v_and_b32_e32 v88, 0xffff0000, v129
	v_add_f32_e32 v67, 1.0, v67
	v_add_f32_e32 v73, v73, v72
	v_lshlrev_b32_e32 v74, 16, v132
	v_lshlrev_b32_e32 v78, 16, v133
	v_lshlrev_b32_e32 v84, 16, v135
	v_lshlrev_b32_e32 v72, 16, v128
	v_lshlrev_b32_e32 v87, 16, v129
	v_lshlrev_b32_e32 v91, 16, v131
	v_fmac_f32_e32 v75, v69, v86
	v_rcp_f32_e32 v67, v67
	v_fmac_f32_e32 v79, v66, v88
	v_fmac_f32_e32 v74, v68, v72
	v_fmac_f32_e32 v78, v64, v87
	v_fmac_f32_e32 v84, v65, v91
	v_mul_f32_e32 v64, v75, v75
	v_mul_f32_e32 v65, v79, v79
	v_fmac_f32_e32 v64, v74, v74
	v_fmac_f32_e32 v65, v78, v78
	v_and_b32_e32 v85, 0xffff0000, v135
	v_and_b32_e32 v92, 0xffff0000, v131
	v_add_f32_e32 v64, v64, v65
	v_mul_f32_e32 v65, v81, v81
	v_fmac_f32_e32 v85, v67, v92
	v_fmac_f32_e32 v65, v80, v80
	v_add_f32_e32 v64, v65, v64
	v_mul_f32_e32 v65, v85, v85
	v_fmac_f32_e32 v65, v84, v84
	v_add_f32_e32 v64, v65, v64
	v_and_b32_e32 v65, 64, v179
	v_add_f32_e32 v67, v73, v64
	v_xor_b32_e32 v64, 16, v179
	v_add_u32_e32 v68, 64, v65
	v_cmp_lt_i32_e64 s[6:7], v64, v68
	v_cvt_pk_bf16_f32 v72, v74, v75
	v_cvt_pk_bf16_f32 v73, v78, v79
	v_cvt_pk_bf16_f32 v74, v80, v81
	v_cvt_pk_bf16_f32 v75, v84, v85
	global_store_dwordx4 v[76:77], v[72:75], off offset:256
	s_nop 0
	v_cndmask_b32_e64 v64, v179, v64, s[6:7]
	v_lshlrev_b32_e32 v122, 2, v64
	ds_bpermute_b32 v69, v122, v67
	ds_bpermute_b32 v64, v122, v112
	ds_bpermute_b32 v65, v122, v99
	ds_bpermute_b32 v66, v122, v83
	s_waitcnt lgkmcnt(0)
	v_add_f32_e32 v67, v67, v69
	v_xor_b32_e32 v69, 32, v179
	v_cmp_lt_i32_e64 s[6:7], v69, v68
	v_add_f32_e32 v64, v112, v64
	v_add_f32_e32 v65, v99, v65
	v_cndmask_b32_e64 v68, v179, v69, s[6:7]
	v_add_f32_e32 v66, v83, v66
	v_lshlrev_b32_e32 v123, 2, v68
	ds_bpermute_b32 v68, v123, v64
	ds_bpermute_b32 v69, v123, v65
	ds_bpermute_b32 v70, v123, v66
	ds_bpermute_b32 v71, v123, v67
	v_lshl_add_u64 v[112:113], v[198:199], 2, s[10:11]
	s_and_saveexec_b64 s[6:7], s[4:5]
	s_cbranch_execz .LBB0_888
	s_waitcnt lgkmcnt(3)
	v_add_f32_e32 v64, v64, v68
	s_waitcnt lgkmcnt(0)
	v_add_f32_e32 v67, v67, v71
	v_add_f32_e32 v66, v66, v70
	v_add_f32_e32 v65, v65, v69
	global_atomic_add_f32 v[112:113], v64, off
	global_atomic_add_f32 v[112:113], v65, off offset:64
	global_atomic_add_f32 v[112:113], v66, off offset:128
	global_atomic_add_f32 v[112:113], v67, off offset:192

; #define PG8_WAIT_V(n) asm volatile("s_waitcnt vmcnt(" #n ")" ::: "memory")
; #define PG8_BAR __builtin_amdgcn_s_barrier()
; template <class Epi, class Sched>
; __device__ __forceinline__ void gemm_phase(PG8_LAS unsigned char* lds, const Gemm g, const Sched& S, const Epi& E) {
;     ...
;     PG8_WAIT_V(0);
;     if (wr == 0) PG8_BAR;
;     PG8_BAR;
; __global__ void __launch_bounds__(512, 2) hymba_fwd(Params p) {
;     ...
;         { pg8::Gemm g{(const bf16_t*)(ws + WS_HB), (const bf16_t*)(ws + WS_W5), MT, DM, DM}; EpiPle E{(const float*)(ws + WS_SS2), (const bf16_t*)(ws + WS_PP), (const bf16_t*)(ws + WS_HB), (bf16_t*)(ws + WS_H3), (float*)(ws + WS_SS3)}; pg8::gemm_phase(glds, g, S, E);
;           for (int u = bx; u < 256; u += G) small_gemm<DM>(lds, g.A, g.Bt, MP + 32 * (u >> 4), (u & 15) * 64, (u & 15) * 64 + 32, E); }
.LBB0_894:
	v_and_b32_e32 v0, 7, v176
	v_cmp_eq_u32_e32 vcc, 0, v0
	s_lshl_b32 s0, s2, 1
	s_lshl_b32 s1, s66, 1
	s_lshl_b32 s3, s2, 6
	s_lshl_b32 s12, s66, 6
	s_movk_i32 s13, 0x100
	v_mov_b32_e32 v33, 0
	v_mov_b32_e32 v34, 0x358637bd
	s_movk_i32 s16, 0x90
	s_mov_b32 s17, 0x800000
	s_mov_b32 s18, s2
	s_barrier
	s_setprio 0
	s_branch .LBB0_896
